# K-loop LDS-DMA balance: SA(0,0) stage issued at the head of load segment P3 instead of the end of P2 (pieces 2/6/2/6 -> 2/4/4/6), P2 wait vmcnt(6)
# speedup vs baseline: 1.0117x; 1.0020x over previous
; #define PG8_STAGE(bufoff, gbase, voff) do { _Pragma("unroll") for (int _i = 0; _i < 2; ++_i) \
;         __builtin_amdgcn_global_load_lds((const unsigned*)((const char*)(gbase) + (voff)[_i]), (PG8_LAS unsigned*)(lds + (bufoff) + ldsw + _i * 8192), 16, 0, 0); } while (0)
; #define PG8_LDA(dst, b, h) do { _Pragma("unroll") for (int m = 0; m < 4; ++m) _Pragma("unroll") for (int k = 0; k < 2; ++k) dst[m][k] = *(const PG8_LAS bf16x8*)(lds + PG8_SA(b, h) + aoff + m * 2048 + k * 1024); } while (0)
; #define PG8_LDB(dst, b, h) do { _Pragma("unroll") for (int n = 0; n < 2; ++n) _Pragma("unroll") for (int k = 0; k < 2; ++k) dst[n][k] = *(const PG8_LAS bf16x8*)(lds + PG8_SB(b, h) + boff + n * 2048 + k * 1024); } while (0)
; #define PG8_WAIT_V(n) asm volatile("s_waitcnt vmcnt(" #n ")" ::: "memory")
; #define PG8_WAIT_L(n) asm volatile("s_waitcnt lgkmcnt(" #n ")" ::: "memory")
; #define PG8_BAR __builtin_amdgcn_s_barrier()
; #define PG8_SCHED __builtin_amdgcn_sched_barrier(0)
; template <class Epi, class Sched, bool ALIGN_EPI = false, bool SP2 = false, bool I8 = false>
; __device__ __forceinline__ void gemm_phase(PG8_LAS unsigned char* lds, const Gemm g, const Sched& S, const Epi& E) {
;     ...
;         const bool has_next = S.next(ui + 1, nxt);
;         const char* nA = has_next ? (const char*)g.A + (size_t)nxt.pm * tstep : cA; const char* nB = has_next ? (const char*)g.Bt + (size_t)nxt.pn * tstep : cB;
;         for (int t = 0; t < nt; t += 2) {
;             const bool last = (t == nt - 2);
;             const char* a1 = cA + (size_t)(t + 1) * kstep;
;             const char* a2 = last ? nA : cA + (size_t)(t + 2) * kstep; const char* b2 = last ? nB : cB + (size_t)(t + 2) * kstep;
;             const char* a3 = a2 + kstep; const char* b3 = b2 + kstep;
;             if (last && has_next) S.a_ready(nxt);
;             if constexpr (SP2) {
;             PG8_LDB(B0, 0, 0); PG8_LDB(B1, 0, 1); PG8_SCHED; PG8_LDA(At, 0, 0); PG8_STAGE(PG8_SA(1, 1), a1 + hstep, voffA);
;             PG8_WAIT_V(8); PG8_WAIT_L(0); PG8_BAR; PG8_MMA(0, 0, At, B0); PG8_MMA(0, 1, At, B1); PG8_BAR; PG8_SCHED;
;             PG8_LDA(At, 0, 1); PG8_STAGE(PG8_SB(0, 0), b2, voffB); PG8_STAGE(PG8_SB(0, 1), b2 + hstep, voffB); PG8_STAGE(PG8_SA(0, 0), a2, voffA);
;             PG8_WAIT_V(8); PG8_WAIT_L(0); PG8_BAR; PG8_MMA(1, 0, At, B0); PG8_MMA(1, 1, At, B1); PG8_BAR; PG8_SCHED;
.LBB0_207:
	s_ashr_i32 s19, s18, 31
	s_lshl_b64 s[22:23], s[18:19], 20
	s_add_u32 s22, s28, s22
	s_addc_u32 s23, s34, s23
	s_and_b64 s[24:25], s[6:7], exec
	s_cselect_b32 s19, s23, s27
	s_cselect_b32 s64, s22, s26
	s_ashr_i32 s17, s16, 31
	s_lshl_b64 s[24:25], s[16:17], 20
	s_add_u32 s24, s35, s24
	s_addc_u32 s25, s42, s25
	s_and_b64 s[40:41], s[6:7], exec
	s_cselect_b32 s17, s25, s37
	s_cselect_b32 s65, s24, s36
	s_add_u32 s26, s26, 0x80080
	s_addc_u32 s27, s27, 0
	s_add_u32 s72, s36, 0x100
	s_addc_u32 s73, s37, 0
	s_mov_b32 s76, -2
	s_add_u32 s36, s26, 0xfff80080
	s_addc_u32 s37, s27, -1
	s_add_i32 s50, 0, 0x10000
	s_cmp_eq_u32 s76, 28
	s_cselect_b32 s41, s19, s37
	s_cselect_b32 s40, s64, s36
	s_cselect_b32 s37, s17, s73
	s_cselect_b32 s36, s65, s72
	s_add_i32 s56, 0, 0x14000
	v_add_u32_e32 v136, s50, v175
	v_add_u32_e32 v172, s56, v175
	ds_read_b128 v[116:119], v136
	ds_read_b128 v[124:127], v136 offset:1024
	ds_read_b128 v[132:135], v136 offset:2048
	ds_read_b128 v[136:139], v136 offset:3072
	ds_read_b128 v[160:163], v172
	ds_read_b128 v[164:167], v172 offset:1024
	ds_read_b128 v[168:171], v172 offset:2048
	ds_read_b128 v[178:181], v172 offset:3072
	v_lshl_add_u64 v[172:173], s[26:27], 0, v[156:157]
	s_add_i32 m0, s44, 0xc000
	ds_read_b128 v[182:185], v177
	ds_read_b128 v[186:189], v177 offset:1024
	ds_read_b128 v[204:207], v177 offset:2048
	ds_read_b128 v[208:211], v177 offset:3072
	ds_read_b128 v[212:215], v177 offset:4096
	ds_read_b128 v[216:219], v177 offset:5120
	ds_read_b128 v[220:223], v177 offset:6144
	ds_read_b128 v[224:227], v177 offset:7168
	global_load_lds_dwordx4 v[172:173], off
	v_lshl_add_u64 v[172:173], s[26:27], 0, v[158:159]
	s_add_i32 m0, s44, 0xe000
	s_nop 0
	global_load_lds_dwordx4 v[172:173], off
	s_waitcnt vmcnt(8)
	s_waitcnt lgkmcnt(0)
	s_barrier
	s_setprio 1
	s_waitcnt lgkmcnt(0)
	v_mfma_i32_16x16x64_i8 v[144:147], v[116:119], v[182:185], 0
	v_mfma_i32_16x16x64_i8 v[144:147], v[124:127], v[186:189], v[144:147]
	v_mfma_i32_16x16x64_i8 v[112:115], v[124:127], v[208:211], 0
	v_mfma_i32_16x16x64_i8 v[112:115], v[116:119], v[204:207], v[112:115]
	v_mfma_i32_16x16x64_i8 v[96:99], v[116:119], v[212:215], 0
	v_mfma_i32_16x16x64_i8 v[96:99], v[124:127], v[216:219], v[96:99]
	v_mfma_i32_16x16x64_i8 v[80:83], v[124:127], v[224:227], 0
	v_mfma_i32_16x16x64_i8 v[80:83], v[116:119], v[220:223], v[80:83]
	v_mfma_i32_16x16x64_i8 v[76:79], v[132:135], v[220:223], 0
	v_mfma_i32_16x16x64_i8 v[76:79], v[136:139], v[224:227], v[76:79]
	v_mfma_i32_16x16x64_i8 v[92:95], v[136:139], v[216:219], 0
	v_mfma_i32_16x16x64_i8 v[92:95], v[132:135], v[212:215], v[92:95]
	v_mfma_i32_16x16x64_i8 v[108:111], v[132:135], v[204:207], 0
	v_mfma_i32_16x16x64_i8 v[108:111], v[136:139], v[208:211], v[108:111]
	v_mfma_i32_16x16x64_i8 v[140:143], v[136:139], v[186:189], 0
	v_mfma_i32_16x16x64_i8 v[140:143], v[132:135], v[182:185], v[140:143]
	v_mfma_i32_16x16x64_i8 v[128:131], v[160:163], v[182:185], 0
	v_mfma_i32_16x16x64_i8 v[128:131], v[164:167], v[186:189], v[128:131]
	v_mfma_i32_16x16x64_i8 v[104:107], v[164:167], v[208:211], 0
	v_mfma_i32_16x16x64_i8 v[104:107], v[160:163], v[204:207], v[104:107]
	v_mfma_i32_16x16x64_i8 v[88:91], v[160:163], v[212:215], 0
	v_mfma_i32_16x16x64_i8 v[88:91], v[164:167], v[216:219], v[88:91]
	v_mfma_i32_16x16x64_i8 v[72:75], v[164:167], v[224:227], 0
	v_mfma_i32_16x16x64_i8 v[72:75], v[160:163], v[220:223], v[72:75]
	v_mfma_i32_16x16x64_i8 v[68:71], v[168:171], v[220:223], 0
	v_mfma_i32_16x16x64_i8 v[68:71], v[178:181], v[224:227], v[68:71]
	v_mfma_i32_16x16x64_i8 v[84:87], v[178:181], v[216:219], 0
	v_mfma_i32_16x16x64_i8 v[84:87], v[168:171], v[212:215], v[84:87]
	v_mfma_i32_16x16x64_i8 v[100:103], v[168:171], v[204:207], 0
	v_mfma_i32_16x16x64_i8 v[100:103], v[178:181], v[208:211], v[100:103]
	v_mfma_i32_16x16x64_i8 v[120:123], v[178:181], v[186:189], 0
	v_mfma_i32_16x16x64_i8 v[120:123], v[168:171], v[182:185], v[120:123]
	s_setprio 0
	s_barrier
	s_add_i32 s50, s50, s43
	v_lshl_add_u64 v[172:173], s[36:37], 0, v[2:3]
	s_mov_b32 m0, s50
	ds_read_b128 v[182:185], v177 offset:16384
	ds_read_b128 v[186:189], v177 offset:17408
	ds_read_b128 v[204:207], v177 offset:18432
	ds_read_b128 v[208:211], v177 offset:19456
	ds_read_b128 v[212:215], v177 offset:20480
	ds_read_b128 v[216:219], v177 offset:21504
	ds_read_b128 v[220:223], v177 offset:22528
	ds_read_b128 v[224:227], v177 offset:23552
	global_load_lds_dwordx4 v[172:173], off
	s_add_i32 m0, s50, 0x2000
	s_add_u32 s50, s36, 0x80000
	v_lshl_add_u64 v[190:191], s[36:37], 0, v[148:149]
	s_addc_u32 s51, s37, 0
	s_add_i32 s56, s56, s43
	global_load_lds_dwordx4 v[190:191], off
	v_lshl_add_u64 v[228:229], s[50:51], 0, v[2:3]
	s_mov_b32 m0, s56
	v_lshl_add_u64 v[240:241], s[40:41], 0, v[150:151]
	global_load_lds_dwordx4 v[228:229], off
	v_lshl_add_u64 v[228:229], s[50:51], 0, v[148:149]
	s_add_i32 m0, s56, 0x2000
	s_nop 0
	global_load_lds_dwordx4 v[228:229], off
	v_lshl_add_u64 v[228:229], s[40:41], 0, v[152:153]
	s_waitcnt vmcnt(6)
	s_waitcnt lgkmcnt(0)
	s_barrier
; #define PG8_STAGE(bufoff, gbase, voff) do { _Pragma("unroll") for (int _i = 0; _i < 2; ++_i) \
;         __builtin_amdgcn_global_load_lds((const unsigned*)((const char*)(gbase) + (voff)[_i]), (PG8_LAS unsigned*)(lds + (bufoff) + ldsw + _i * 8192), 16, 0, 0); } while (0)
; #define PG8_LDA(dst, b, h) do { _Pragma("unroll") for (int m = 0; m < 4; ++m) _Pragma("unroll") for (int k = 0; k < 2; ++k) dst[m][k] = *(const PG8_LAS bf16x8*)(lds + PG8_SA(b, h) + aoff + m * 2048 + k * 1024); } while (0)
; #define PG8_LDB(dst, b, h) do { _Pragma("unroll") for (int n = 0; n < 2; ++n) _Pragma("unroll") for (int k = 0; k < 2; ++k) dst[n][k] = *(const PG8_LAS bf16x8*)(lds + PG8_SB(b, h) + boff + n * 2048 + k * 1024); } while (0)
; #define PG8_WAIT_V(n) asm volatile("s_waitcnt vmcnt(" #n ")" ::: "memory")
; #define PG8_WAIT_L(n) asm volatile("s_waitcnt lgkmcnt(" #n ")" ::: "memory")
; #define PG8_BAR __builtin_amdgcn_s_barrier()
; #define PG8_SCHED __builtin_amdgcn_sched_barrier(0)
; template <class Epi, class Sched, bool ALIGN_EPI = false, bool SP2 = false, bool I8 = false>
; __device__ __forceinline__ void gemm_phase(PG8_LAS unsigned char* lds, const Gemm g, const Sched& S, const Epi& E) {
;     ...
;             PG8_WAIT_V(8); PG8_WAIT_L(0); PG8_BAR; PG8_MMA(1, 0, At, B0); PG8_MMA(1, 1, At, B1); PG8_BAR; PG8_SCHED;
;             PG8_LDB(B0, 1, 0); PG8_LDB(B1, 1, 1); PG8_SCHED; PG8_LDA(At, 1, 0); PG8_STAGE(PG8_SA(0, 1), a2 + hstep, voffA);
;             PG8_WAIT_V(8); PG8_WAIT_L(0); PG8_BAR; PG8_MMA(0, 0, At, B0); PG8_MMA(0, 1, At, B1); PG8_BAR; PG8_SCHED;
	s_setprio 1
	s_waitcnt lgkmcnt(0)
	v_mfma_i32_16x16x64_i8 v[64:67], v[116:119], v[182:185], 0
	v_mfma_i32_16x16x64_i8 v[64:67], v[124:127], v[186:189], v[64:67]
	v_mfma_i32_16x16x64_i8 v[48:51], v[124:127], v[208:211], 0
	v_mfma_i32_16x16x64_i8 v[48:51], v[116:119], v[204:207], v[48:51]
	v_mfma_i32_16x16x64_i8 v[32:35], v[116:119], v[212:215], 0
	v_mfma_i32_16x16x64_i8 v[32:35], v[124:127], v[216:219], v[32:35]
	v_mfma_i32_16x16x64_i8 v[16:19], v[124:127], v[224:227], 0
	v_mfma_i32_16x16x64_i8 v[16:19], v[116:119], v[220:223], v[16:19]
	v_mfma_i32_16x16x64_i8 v[12:15], v[132:135], v[220:223], 0
	v_mfma_i32_16x16x64_i8 v[12:15], v[136:139], v[224:227], v[12:15]
	v_mfma_i32_16x16x64_i8 v[28:31], v[136:139], v[216:219], 0
	v_mfma_i32_16x16x64_i8 v[28:31], v[132:135], v[212:215], v[28:31]
	v_mfma_i32_16x16x64_i8 v[44:47], v[132:135], v[204:207], 0
	v_mfma_i32_16x16x64_i8 v[44:47], v[136:139], v[208:211], v[44:47]
	v_mfma_i32_16x16x64_i8 v[60:63], v[136:139], v[186:189], 0
	v_mfma_i32_16x16x64_i8 v[60:63], v[132:135], v[182:185], v[60:63]
	v_mfma_i32_16x16x64_i8 v[56:59], v[160:163], v[182:185], 0
	v_mfma_i32_16x16x64_i8 v[56:59], v[164:167], v[186:189], v[56:59]
	v_mfma_i32_16x16x64_i8 v[40:43], v[164:167], v[208:211], 0
	v_mfma_i32_16x16x64_i8 v[40:43], v[160:163], v[204:207], v[40:43]
	v_mfma_i32_16x16x64_i8 v[24:27], v[160:163], v[212:215], 0
	v_mfma_i32_16x16x64_i8 v[24:27], v[164:167], v[216:219], v[24:27]
	v_mfma_i32_16x16x64_i8 v[8:11], v[164:167], v[224:227], 0
	v_mfma_i32_16x16x64_i8 v[8:11], v[160:163], v[220:223], v[8:11]
	v_mfma_i32_16x16x64_i8 v[4:7], v[168:171], v[220:223], 0
	v_mfma_i32_16x16x64_i8 v[4:7], v[178:181], v[224:227], v[4:7]
	v_mfma_i32_16x16x64_i8 v[20:23], v[178:181], v[216:219], 0
	v_mfma_i32_16x16x64_i8 v[20:23], v[168:171], v[212:215], v[20:23]
	v_mfma_i32_16x16x64_i8 v[36:39], v[168:171], v[204:207], 0
	v_mfma_i32_16x16x64_i8 v[36:39], v[178:181], v[208:211], v[36:39]
	v_mfma_i32_16x16x64_i8 v[52:55], v[178:181], v[186:189], 0
	v_mfma_i32_16x16x64_i8 v[52:55], v[168:171], v[182:185], v[52:55]
	s_setprio 0
	s_barrier
	s_mov_b32 m0, s44
	s_nop 0
	global_load_lds_dwordx4 v[228:229], off
	s_mov_b32 m0, s45
	s_nop 0
	global_load_lds_dwordx4 v[240:241], off
	s_add_i32 s50, 0, 0x18000
	s_add_i32 s51, 0, 0x1c000
	v_add_u32_e32 v136, s50, v175
	v_add_u32_e32 v178, s51, v175
	ds_read_b128 v[116:119], v136
	ds_read_b128 v[124:127], v136 offset:1024
	ds_read_b128 v[132:135], v136 offset:2048
	ds_read_b128 v[136:139], v136 offset:3072
	ds_read_b128 v[160:163], v178
	ds_read_b128 v[164:167], v178 offset:1024
	ds_read_b128 v[168:171], v178 offset:2048
	ds_read_b128 v[178:181], v178 offset:3072
	s_add_u32 s40, s40, 0x80000
	s_addc_u32 s41, s41, 0
	s_mov_b32 m0, s46
	v_lshl_add_u64 v[242:243], s[40:41], 0, v[152:153]
	ds_read_b128 v[182:185], v177 offset:32768
	ds_read_b128 v[186:189], v177 offset:33792
	ds_read_b128 v[204:207], v177 offset:34816
	ds_read_b128 v[208:211], v177 offset:35840
	ds_read_b128 v[212:215], v177 offset:36864
	ds_read_b128 v[216:219], v177 offset:37888
	ds_read_b128 v[220:223], v177 offset:38912
	ds_read_b128 v[224:227], v177 offset:39936
	global_load_lds_dwordx4 v[242:243], off
	v_lshl_add_u64 v[242:243], s[40:41], 0, v[150:151]
	s_mov_b32 m0, s47
	s_nop 0
	global_load_lds_dwordx4 v[242:243], off
	s_waitcnt vmcnt(8)
	s_waitcnt lgkmcnt(0)
	s_barrier
	s_setprio 1
	s_waitcnt lgkmcnt(0)
	v_mfma_i32_16x16x64_i8 v[144:147], v[116:119], v[182:185], v[144:147]
	v_mfma_i32_16x16x64_i8 v[144:147], v[124:127], v[186:189], v[144:147]
	v_mfma_i32_16x16x64_i8 v[112:115], v[124:127], v[208:211], v[112:115]
	v_mfma_i32_16x16x64_i8 v[112:115], v[116:119], v[204:207], v[112:115]
	v_mfma_i32_16x16x64_i8 v[96:99], v[116:119], v[212:215], v[96:99]
	v_mfma_i32_16x16x64_i8 v[96:99], v[124:127], v[216:219], v[96:99]
	v_mfma_i32_16x16x64_i8 v[80:83], v[124:127], v[224:227], v[80:83]
	v_mfma_i32_16x16x64_i8 v[80:83], v[116:119], v[220:223], v[80:83]
	v_mfma_i32_16x16x64_i8 v[76:79], v[132:135], v[220:223], v[76:79]
	v_mfma_i32_16x16x64_i8 v[76:79], v[136:139], v[224:227], v[76:79]
	v_mfma_i32_16x16x64_i8 v[92:95], v[136:139], v[216:219], v[92:95]
	v_mfma_i32_16x16x64_i8 v[92:95], v[132:135], v[212:215], v[92:95]
	v_mfma_i32_16x16x64_i8 v[108:111], v[132:135], v[204:207], v[108:111]
	v_mfma_i32_16x16x64_i8 v[108:111], v[136:139], v[208:211], v[108:111]
	v_mfma_i32_16x16x64_i8 v[140:143], v[136:139], v[186:189], v[140:143]
	v_mfma_i32_16x16x64_i8 v[140:143], v[132:135], v[182:185], v[140:143]
	v_mfma_i32_16x16x64_i8 v[128:131], v[160:163], v[182:185], v[128:131]
	v_mfma_i32_16x16x64_i8 v[128:131], v[164:167], v[186:189], v[128:131]
	v_mfma_i32_16x16x64_i8 v[104:107], v[164:167], v[208:211], v[104:107]
	v_mfma_i32_16x16x64_i8 v[104:107], v[160:163], v[204:207], v[104:107]
	v_mfma_i32_16x16x64_i8 v[88:91], v[160:163], v[212:215], v[88:91]
	v_mfma_i32_16x16x64_i8 v[88:91], v[164:167], v[216:219], v[88:91]
	v_mfma_i32_16x16x64_i8 v[72:75], v[164:167], v[224:227], v[72:75]
	v_mfma_i32_16x16x64_i8 v[72:75], v[160:163], v[220:223], v[72:75]
	v_mfma_i32_16x16x64_i8 v[68:71], v[168:171], v[220:223], v[68:71]
	v_mfma_i32_16x16x64_i8 v[68:71], v[178:181], v[224:227], v[68:71]
	v_mfma_i32_16x16x64_i8 v[84:87], v[178:181], v[216:219], v[84:87]
	v_mfma_i32_16x16x64_i8 v[84:87], v[168:171], v[212:215], v[84:87]
	v_mfma_i32_16x16x64_i8 v[100:103], v[168:171], v[204:207], v[100:103]
	v_mfma_i32_16x16x64_i8 v[100:103], v[178:181], v[208:211], v[100:103]
	v_mfma_i32_16x16x64_i8 v[120:123], v[178:181], v[186:189], v[120:123]
	v_mfma_i32_16x16x64_i8 v[120:123], v[168:171], v[182:185], v[120:123]
	s_setprio 0
	s_barrier
; #define PG8_STAGE(bufoff, gbase, voff) do { _Pragma("unroll") for (int _i = 0; _i < 2; ++_i) \
;         __builtin_amdgcn_global_load_lds((const unsigned*)((const char*)(gbase) + (voff)[_i]), (PG8_LAS unsigned*)(lds + (bufoff) + ldsw + _i * 8192), 16, 0, 0); } while (0)
; #define PG8_LDA(dst, b, h) do { _Pragma("unroll") for (int m = 0; m < 4; ++m) _Pragma("unroll") for (int k = 0; k < 2; ++k) dst[m][k] = *(const PG8_LAS bf16x8*)(lds + PG8_SA(b, h) + aoff + m * 2048 + k * 1024); } while (0)
; #define PG8_LDB(dst, b, h) do { _Pragma("unroll") for (int n = 0; n < 2; ++n) _Pragma("unroll") for (int k = 0; k < 2; ++k) dst[n][k] = *(const PG8_LAS bf16x8*)(lds + PG8_SB(b, h) + boff + n * 2048 + k * 1024); } while (0)
; #define PG8_WAIT_V(n) asm volatile("s_waitcnt vmcnt(" #n ")" ::: "memory")
; #define PG8_WAIT_L(n) asm volatile("s_waitcnt lgkmcnt(" #n ")" ::: "memory")
; #define PG8_BAR __builtin_amdgcn_s_barrier()
; #define PG8_SCHED __builtin_amdgcn_sched_barrier(0)
; template <class Epi, class Sched, bool ALIGN_EPI = false, bool SP2 = false, bool I8 = false>
; __device__ __forceinline__ void gemm_phase(PG8_LAS unsigned char* lds, const Gemm g, const Sched& S, const Epi& E) {
;     ...
;             PG8_LDB(B0, 0, 0); PG8_LDB(B1, 0, 1); PG8_SCHED; PG8_LDA(At, 0, 0); PG8_STAGE(PG8_SA(1, 1), a1 + hstep, voffA);
;             PG8_WAIT_V(8); PG8_WAIT_L(0); PG8_BAR; PG8_MMA(0, 0, At, B0); PG8_MMA(0, 1, At, B1); PG8_BAR; PG8_SCHED;
;     ...
;             PG8_LDA(At, 1, 1); PG8_STAGE(PG8_SB(1, 0), b3, voffB); PG8_STAGE(PG8_SB(1, 1), b3 + hstep, voffB); PG8_STAGE(PG8_SA(1, 0), a3, voffA);
;             PG8_WAIT_V(8); PG8_WAIT_L(0); PG8_BAR; PG8_MMA(1, 0, At, B0); PG8_MMA(1, 1, At, B1); PG8_BAR; PG8_SCHED;
	s_add_i32 s40, s50, s43
	v_lshl_add_u64 v[172:173], v[172:173], 0, s[84:85]
	s_mov_b32 m0, s40
	ds_read_b128 v[182:185], v177 offset:49152
	ds_read_b128 v[186:189], v177 offset:50176
	ds_read_b128 v[204:207], v177 offset:51200
	ds_read_b128 v[208:211], v177 offset:52224
	ds_read_b128 v[212:215], v177 offset:53248
	ds_read_b128 v[216:219], v177 offset:54272
	ds_read_b128 v[220:223], v177 offset:55296
	ds_read_b128 v[224:227], v177 offset:56320
	global_load_lds_dwordx4 v[172:173], off
	s_add_i32 m0, s40, 0x2000
	s_add_u32 s36, s36, 0x80080
	v_lshl_add_u64 v[172:173], v[190:191], 0, s[84:85]
	s_addc_u32 s37, s37, 0
	s_add_i32 s40, s51, s43
	global_load_lds_dwordx4 v[172:173], off
	v_lshl_add_u64 v[172:173], s[36:37], 0, v[2:3]
	s_mov_b32 m0, s40
	s_nop 0
	global_load_lds_dwordx4 v[172:173], off
	v_lshl_add_u64 v[172:173], s[36:37], 0, v[148:149]
	s_add_i32 m0, s40, 0x2000
	s_nop 0
	global_load_lds_dwordx4 v[172:173], off
	v_lshl_add_u64 v[172:173], v[228:229], 0, s[84:85]
	s_mov_b32 m0, s52
	s_nop 0
	global_load_lds_dwordx4 v[172:173], off
	v_lshl_add_u64 v[172:173], v[240:241], 0, s[84:85]
	s_mov_b32 m0, s53
	s_nop 0
	global_load_lds_dwordx4 v[172:173], off
	s_waitcnt vmcnt(8)
	s_waitcnt lgkmcnt(0)
	s_barrier
	s_setprio 1
	s_waitcnt lgkmcnt(0)
	v_mfma_i32_16x16x64_i8 v[64:67], v[116:119], v[182:185], v[64:67]
	v_mfma_i32_16x16x64_i8 v[64:67], v[124:127], v[186:189], v[64:67]
	v_mfma_i32_16x16x64_i8 v[48:51], v[124:127], v[208:211], v[48:51]
	v_mfma_i32_16x16x64_i8 v[48:51], v[116:119], v[204:207], v[48:51]
	v_mfma_i32_16x16x64_i8 v[32:35], v[116:119], v[212:215], v[32:35]
	v_mfma_i32_16x16x64_i8 v[32:35], v[124:127], v[216:219], v[32:35]
	v_mfma_i32_16x16x64_i8 v[16:19], v[124:127], v[224:227], v[16:19]
	v_mfma_i32_16x16x64_i8 v[16:19], v[116:119], v[220:223], v[16:19]
	v_mfma_i32_16x16x64_i8 v[12:15], v[132:135], v[220:223], v[12:15]
	v_mfma_i32_16x16x64_i8 v[12:15], v[136:139], v[224:227], v[12:15]
	v_mfma_i32_16x16x64_i8 v[28:31], v[136:139], v[216:219], v[28:31]
	v_mfma_i32_16x16x64_i8 v[28:31], v[132:135], v[212:215], v[28:31]
	v_mfma_i32_16x16x64_i8 v[44:47], v[132:135], v[204:207], v[44:47]
	v_mfma_i32_16x16x64_i8 v[44:47], v[136:139], v[208:211], v[44:47]
	v_mfma_i32_16x16x64_i8 v[60:63], v[136:139], v[186:189], v[60:63]
	v_mfma_i32_16x16x64_i8 v[60:63], v[132:135], v[182:185], v[60:63]
	v_mfma_i32_16x16x64_i8 v[56:59], v[160:163], v[182:185], v[56:59]
	v_mfma_i32_16x16x64_i8 v[56:59], v[164:167], v[186:189], v[56:59]
	v_mfma_i32_16x16x64_i8 v[40:43], v[164:167], v[208:211], v[40:43]
	v_mfma_i32_16x16x64_i8 v[40:43], v[160:163], v[204:207], v[40:43]
	v_mfma_i32_16x16x64_i8 v[24:27], v[160:163], v[212:215], v[24:27]
	v_mfma_i32_16x16x64_i8 v[24:27], v[164:167], v[216:219], v[24:27]
	v_mfma_i32_16x16x64_i8 v[8:11], v[164:167], v[224:227], v[8:11]
	v_mfma_i32_16x16x64_i8 v[8:11], v[160:163], v[220:223], v[8:11]
	v_mfma_i32_16x16x64_i8 v[4:7], v[168:171], v[220:223], v[4:7]
	v_mfma_i32_16x16x64_i8 v[4:7], v[178:181], v[224:227], v[4:7]
	v_mfma_i32_16x16x64_i8 v[20:23], v[178:181], v[216:219], v[20:23]
	v_mfma_i32_16x16x64_i8 v[20:23], v[168:171], v[212:215], v[20:23]
	v_mfma_i32_16x16x64_i8 v[36:39], v[168:171], v[204:207], v[36:39]
	v_mfma_i32_16x16x64_i8 v[36:39], v[178:181], v[208:211], v[36:39]
	v_mfma_i32_16x16x64_i8 v[52:55], v[178:181], v[186:189], v[52:55]
	v_mfma_i32_16x16x64_i8 v[52:55], v[168:171], v[182:185], v[52:55]
	s_setprio 0
	s_barrier
	s_add_i32 s76, s76, 2
	s_add_u32 s26, s26, 0x100
	s_addc_u32 s27, s27, 0
	s_add_u32 s72, s72, 0x100
	s_addc_u32 s73, s73, 0
	s_cmp_gt_u32 s76, 29
	s_cbranch_scc1 .Lkloop_exit_0
.LBB0_208:
	s_add_u32 s36, s26, 0xfff80080
	s_addc_u32 s37, s27, -1
	s_add_i32 s50, 0, 0x10000
	s_cmp_eq_u32 s76, 28
	s_cselect_b32 s41, s19, s37
	s_cselect_b32 s40, s64, s36
	s_cselect_b32 s37, s17, s73
	s_cselect_b32 s36, s65, s72
	s_add_i32 s56, 0, 0x14000
	v_add_u32_e32 v136, s50, v175
	v_add_u32_e32 v172, s56, v175
	ds_read_b128 v[116:119], v136
	ds_read_b128 v[124:127], v136 offset:1024
	ds_read_b128 v[132:135], v136 offset:2048
	ds_read_b128 v[136:139], v136 offset:3072
	ds_read_b128 v[160:163], v172
	ds_read_b128 v[164:167], v172 offset:1024
	ds_read_b128 v[168:171], v172 offset:2048
	ds_read_b128 v[178:181], v172 offset:3072
	v_lshl_add_u64 v[172:173], s[26:27], 0, v[156:157]
	s_add_i32 m0, s44, 0xc000
	ds_read_b128 v[182:185], v177
	ds_read_b128 v[186:189], v177 offset:1024
	ds_read_b128 v[204:207], v177 offset:2048
	ds_read_b128 v[208:211], v177 offset:3072
	ds_read_b128 v[212:215], v177 offset:4096
	ds_read_b128 v[216:219], v177 offset:5120
	ds_read_b128 v[220:223], v177 offset:6144
	ds_read_b128 v[224:227], v177 offset:7168
	global_load_lds_dwordx4 v[172:173], off
	v_lshl_add_u64 v[172:173], s[26:27], 0, v[158:159]
	s_add_i32 m0, s44, 0xe000
	s_nop 0
	global_load_lds_dwordx4 v[172:173], off
	s_waitcnt vmcnt(8)
	s_waitcnt lgkmcnt(0)
	s_barrier
; #define PG8_STAGE(bufoff, gbase, voff) do { _Pragma("unroll") for (int _i = 0; _i < 2; ++_i) \
;         __builtin_amdgcn_global_load_lds((const unsigned*)((const char*)(gbase) + (voff)[_i]), (PG8_LAS unsigned*)(lds + (bufoff) + ldsw + _i * 8192), 16, 0, 0); } while (0)
; #define PG8_LDA(dst, b, h) do { _Pragma("unroll") for (int m = 0; m < 4; ++m) _Pragma("unroll") for (int k = 0; k < 2; ++k) dst[m][k] = *(const PG8_LAS bf16x8*)(lds + PG8_SA(b, h) + aoff + m * 2048 + k * 1024); } while (0)
; #define PG8_WAIT_V(n) asm volatile("s_waitcnt vmcnt(" #n ")" ::: "memory")
; #define PG8_WAIT_L(n) asm volatile("s_waitcnt lgkmcnt(" #n ")" ::: "memory")
; #define PG8_BAR __builtin_amdgcn_s_barrier()
; #define PG8_SCHED __builtin_amdgcn_sched_barrier(0)
; template <class Epi, class Sched, bool ALIGN_EPI = false, bool SP2 = false, bool I8 = false>
; __device__ __forceinline__ void gemm_phase(PG8_LAS unsigned char* lds, const Gemm g, const Sched& S, const Epi& E) {
;     ...
;             PG8_WAIT_V(8); PG8_WAIT_L(0); PG8_BAR; PG8_MMA(0, 0, At, B0); PG8_MMA(0, 1, At, B1); PG8_BAR; PG8_SCHED;
;             PG8_LDA(At, 0, 1); PG8_STAGE(PG8_SB(0, 0), b2, voffB); PG8_STAGE(PG8_SB(0, 1), b2 + hstep, voffB); PG8_STAGE(PG8_SA(0, 0), a2, voffA);
;             PG8_WAIT_V(8); PG8_WAIT_L(0); PG8_BAR; PG8_MMA(1, 0, At, B0); PG8_MMA(1, 1, At, B1); PG8_BAR; PG8_SCHED;
	s_setprio 1
	s_waitcnt lgkmcnt(0)
	v_mfma_i32_16x16x64_i8 v[144:147], v[116:119], v[182:185], v[144:147]
	v_mfma_i32_16x16x64_i8 v[144:147], v[124:127], v[186:189], v[144:147]
	v_mfma_i32_16x16x64_i8 v[112:115], v[124:127], v[208:211], v[112:115]
	v_mfma_i32_16x16x64_i8 v[112:115], v[116:119], v[204:207], v[112:115]
	v_mfma_i32_16x16x64_i8 v[96:99], v[116:119], v[212:215], v[96:99]
	v_mfma_i32_16x16x64_i8 v[96:99], v[124:127], v[216:219], v[96:99]
	v_mfma_i32_16x16x64_i8 v[80:83], v[124:127], v[224:227], v[80:83]
	v_mfma_i32_16x16x64_i8 v[80:83], v[116:119], v[220:223], v[80:83]
	v_mfma_i32_16x16x64_i8 v[76:79], v[132:135], v[220:223], v[76:79]
	v_mfma_i32_16x16x64_i8 v[76:79], v[136:139], v[224:227], v[76:79]
	v_mfma_i32_16x16x64_i8 v[92:95], v[136:139], v[216:219], v[92:95]
	v_mfma_i32_16x16x64_i8 v[92:95], v[132:135], v[212:215], v[92:95]
	v_mfma_i32_16x16x64_i8 v[108:111], v[132:135], v[204:207], v[108:111]
	v_mfma_i32_16x16x64_i8 v[108:111], v[136:139], v[208:211], v[108:111]
	v_mfma_i32_16x16x64_i8 v[140:143], v[136:139], v[186:189], v[140:143]
	v_mfma_i32_16x16x64_i8 v[140:143], v[132:135], v[182:185], v[140:143]
	v_mfma_i32_16x16x64_i8 v[128:131], v[160:163], v[182:185], v[128:131]
	v_mfma_i32_16x16x64_i8 v[128:131], v[164:167], v[186:189], v[128:131]
	v_mfma_i32_16x16x64_i8 v[104:107], v[164:167], v[208:211], v[104:107]
	v_mfma_i32_16x16x64_i8 v[104:107], v[160:163], v[204:207], v[104:107]
	v_mfma_i32_16x16x64_i8 v[88:91], v[160:163], v[212:215], v[88:91]
	v_mfma_i32_16x16x64_i8 v[88:91], v[164:167], v[216:219], v[88:91]
	v_mfma_i32_16x16x64_i8 v[72:75], v[164:167], v[224:227], v[72:75]
	v_mfma_i32_16x16x64_i8 v[72:75], v[160:163], v[220:223], v[72:75]
	v_mfma_i32_16x16x64_i8 v[68:71], v[168:171], v[220:223], v[68:71]
	v_mfma_i32_16x16x64_i8 v[68:71], v[178:181], v[224:227], v[68:71]
	v_mfma_i32_16x16x64_i8 v[84:87], v[178:181], v[216:219], v[84:87]
	v_mfma_i32_16x16x64_i8 v[84:87], v[168:171], v[212:215], v[84:87]
	v_mfma_i32_16x16x64_i8 v[100:103], v[168:171], v[204:207], v[100:103]
	v_mfma_i32_16x16x64_i8 v[100:103], v[178:181], v[208:211], v[100:103]
	v_mfma_i32_16x16x64_i8 v[120:123], v[178:181], v[186:189], v[120:123]
	v_mfma_i32_16x16x64_i8 v[120:123], v[168:171], v[182:185], v[120:123]
	s_setprio 0
	s_barrier
	s_add_i32 s50, s50, s43
	v_lshl_add_u64 v[172:173], s[36:37], 0, v[2:3]
	s_mov_b32 m0, s50
	ds_read_b128 v[182:185], v177 offset:16384
	ds_read_b128 v[186:189], v177 offset:17408
	ds_read_b128 v[204:207], v177 offset:18432
	ds_read_b128 v[208:211], v177 offset:19456
	ds_read_b128 v[212:215], v177 offset:20480
	ds_read_b128 v[216:219], v177 offset:21504
	ds_read_b128 v[220:223], v177 offset:22528
	ds_read_b128 v[224:227], v177 offset:23552
	global_load_lds_dwordx4 v[172:173], off
	s_add_i32 m0, s50, 0x2000
	s_add_u32 s50, s36, 0x80000
	v_lshl_add_u64 v[190:191], s[36:37], 0, v[148:149]
	s_addc_u32 s51, s37, 0
	s_add_i32 s56, s56, s43
	global_load_lds_dwordx4 v[190:191], off
	v_lshl_add_u64 v[228:229], s[50:51], 0, v[2:3]
	s_mov_b32 m0, s56
	v_lshl_add_u64 v[240:241], s[40:41], 0, v[150:151]
	global_load_lds_dwordx4 v[228:229], off
	v_lshl_add_u64 v[228:229], s[50:51], 0, v[148:149]
	s_add_i32 m0, s56, 0x2000
	s_nop 0
	global_load_lds_dwordx4 v[228:229], off
	v_lshl_add_u64 v[228:229], s[40:41], 0, v[152:153]
	s_waitcnt vmcnt(6)
	s_waitcnt lgkmcnt(0)
	s_barrier
	s_setprio 1
	s_waitcnt lgkmcnt(0)
	v_mfma_i32_16x16x64_i8 v[64:67], v[116:119], v[182:185], v[64:67]
	v_mfma_i32_16x16x64_i8 v[64:67], v[124:127], v[186:189], v[64:67]
	v_mfma_i32_16x16x64_i8 v[48:51], v[124:127], v[208:211], v[48:51]
	v_mfma_i32_16x16x64_i8 v[48:51], v[116:119], v[204:207], v[48:51]
	v_mfma_i32_16x16x64_i8 v[32:35], v[116:119], v[212:215], v[32:35]
	v_mfma_i32_16x16x64_i8 v[32:35], v[124:127], v[216:219], v[32:35]
	v_mfma_i32_16x16x64_i8 v[16:19], v[124:127], v[224:227], v[16:19]
	v_mfma_i32_16x16x64_i8 v[16:19], v[116:119], v[220:223], v[16:19]
	v_mfma_i32_16x16x64_i8 v[12:15], v[132:135], v[220:223], v[12:15]
	v_mfma_i32_16x16x64_i8 v[12:15], v[136:139], v[224:227], v[12:15]
	v_mfma_i32_16x16x64_i8 v[28:31], v[136:139], v[216:219], v[28:31]
	v_mfma_i32_16x16x64_i8 v[28:31], v[132:135], v[212:215], v[28:31]
	v_mfma_i32_16x16x64_i8 v[44:47], v[132:135], v[204:207], v[44:47]
	v_mfma_i32_16x16x64_i8 v[44:47], v[136:139], v[208:211], v[44:47]
	v_mfma_i32_16x16x64_i8 v[60:63], v[136:139], v[186:189], v[60:63]
	v_mfma_i32_16x16x64_i8 v[60:63], v[132:135], v[182:185], v[60:63]
	v_mfma_i32_16x16x64_i8 v[56:59], v[160:163], v[182:185], v[56:59]
	v_mfma_i32_16x16x64_i8 v[56:59], v[164:167], v[186:189], v[56:59]
	v_mfma_i32_16x16x64_i8 v[40:43], v[164:167], v[208:211], v[40:43]
	v_mfma_i32_16x16x64_i8 v[40:43], v[160:163], v[204:207], v[40:43]
	v_mfma_i32_16x16x64_i8 v[24:27], v[160:163], v[212:215], v[24:27]
	v_mfma_i32_16x16x64_i8 v[24:27], v[164:167], v[216:219], v[24:27]
	v_mfma_i32_16x16x64_i8 v[8:11], v[164:167], v[224:227], v[8:11]
	v_mfma_i32_16x16x64_i8 v[8:11], v[160:163], v[220:223], v[8:11]
	v_mfma_i32_16x16x64_i8 v[4:7], v[168:171], v[220:223], v[4:7]
	v_mfma_i32_16x16x64_i8 v[4:7], v[178:181], v[224:227], v[4:7]
	v_mfma_i32_16x16x64_i8 v[20:23], v[178:181], v[216:219], v[20:23]
	v_mfma_i32_16x16x64_i8 v[20:23], v[168:171], v[212:215], v[20:23]
	v_mfma_i32_16x16x64_i8 v[36:39], v[168:171], v[204:207], v[36:39]
	v_mfma_i32_16x16x64_i8 v[36:39], v[178:181], v[208:211], v[36:39]
	v_mfma_i32_16x16x64_i8 v[52:55], v[178:181], v[186:189], v[52:55]
	v_mfma_i32_16x16x64_i8 v[52:55], v[168:171], v[182:185], v[52:55]
	s_setprio 0
	s_barrier
; #define PG8_STAGE(bufoff, gbase, voff) do { _Pragma("unroll") for (int _i = 0; _i < 2; ++_i) \
;         __builtin_amdgcn_global_load_lds((const unsigned*)((const char*)(gbase) + (voff)[_i]), (PG8_LAS unsigned*)(lds + (bufoff) + ldsw + _i * 8192), 16, 0, 0); } while (0)
; #define PG8_LDA(dst, b, h) do { _Pragma("unroll") for (int m = 0; m < 4; ++m) _Pragma("unroll") for (int k = 0; k < 2; ++k) dst[m][k] = *(const PG8_LAS bf16x8*)(lds + PG8_SA(b, h) + aoff + m * 2048 + k * 1024); } while (0)
; #define PG8_LDB(dst, b, h) do { _Pragma("unroll") for (int n = 0; n < 2; ++n) _Pragma("unroll") for (int k = 0; k < 2; ++k) dst[n][k] = *(const PG8_LAS bf16x8*)(lds + PG8_SB(b, h) + boff + n * 2048 + k * 1024); } while (0)
; #define PG8_WAIT_V(n) asm volatile("s_waitcnt vmcnt(" #n ")" ::: "memory")
; #define PG8_WAIT_L(n) asm volatile("s_waitcnt lgkmcnt(" #n ")" ::: "memory")
; #define PG8_BAR __builtin_amdgcn_s_barrier()
; #define PG8_SCHED __builtin_amdgcn_sched_barrier(0)
; template <class Epi, class Sched, bool ALIGN_EPI = false, bool SP2 = false, bool I8 = false>
; __device__ __forceinline__ void gemm_phase(PG8_LAS unsigned char* lds, const Gemm g, const Sched& S, const Epi& E) {
;     ...
;             PG8_LDB(B0, 1, 0); PG8_LDB(B1, 1, 1); PG8_SCHED; PG8_LDA(At, 1, 0); PG8_STAGE(PG8_SA(0, 1), a2 + hstep, voffA);
;             PG8_WAIT_V(8); PG8_WAIT_L(0); PG8_BAR; PG8_MMA(0, 0, At, B0); PG8_MMA(0, 1, At, B1); PG8_BAR; PG8_SCHED;
	s_mov_b32 m0, s44
	s_nop 0
	global_load_lds_dwordx4 v[228:229], off
	s_mov_b32 m0, s45
	s_nop 0
	global_load_lds_dwordx4 v[240:241], off
	s_add_i32 s50, 0, 0x18000
	s_add_i32 s51, 0, 0x1c000
	v_add_u32_e32 v136, s50, v175
	v_add_u32_e32 v178, s51, v175
	ds_read_b128 v[116:119], v136
	ds_read_b128 v[124:127], v136 offset:1024
	ds_read_b128 v[132:135], v136 offset:2048
	ds_read_b128 v[136:139], v136 offset:3072
	ds_read_b128 v[160:163], v178
	ds_read_b128 v[164:167], v178 offset:1024
	ds_read_b128 v[168:171], v178 offset:2048
	ds_read_b128 v[178:181], v178 offset:3072
	s_add_u32 s40, s40, 0x80000
	s_addc_u32 s41, s41, 0
	s_mov_b32 m0, s46
	v_lshl_add_u64 v[242:243], s[40:41], 0, v[152:153]
	ds_read_b128 v[182:185], v177 offset:32768
	ds_read_b128 v[186:189], v177 offset:33792
	ds_read_b128 v[204:207], v177 offset:34816
	ds_read_b128 v[208:211], v177 offset:35840
	ds_read_b128 v[212:215], v177 offset:36864
	ds_read_b128 v[216:219], v177 offset:37888
	ds_read_b128 v[220:223], v177 offset:38912
	ds_read_b128 v[224:227], v177 offset:39936
	global_load_lds_dwordx4 v[242:243], off
	v_lshl_add_u64 v[242:243], s[40:41], 0, v[150:151]
	s_mov_b32 m0, s47
	s_nop 0
	global_load_lds_dwordx4 v[242:243], off
	s_waitcnt vmcnt(8)
	s_waitcnt lgkmcnt(0)
	s_barrier
	s_setprio 1
	s_waitcnt lgkmcnt(0)
	v_mfma_i32_16x16x64_i8 v[144:147], v[116:119], v[182:185], v[144:147]
	v_mfma_i32_16x16x64_i8 v[144:147], v[124:127], v[186:189], v[144:147]
	v_mfma_i32_16x16x64_i8 v[112:115], v[124:127], v[208:211], v[112:115]
	v_mfma_i32_16x16x64_i8 v[112:115], v[116:119], v[204:207], v[112:115]
	v_mfma_i32_16x16x64_i8 v[96:99], v[116:119], v[212:215], v[96:99]
	v_mfma_i32_16x16x64_i8 v[96:99], v[124:127], v[216:219], v[96:99]
	v_mfma_i32_16x16x64_i8 v[80:83], v[124:127], v[224:227], v[80:83]
	v_mfma_i32_16x16x64_i8 v[80:83], v[116:119], v[220:223], v[80:83]
	v_mfma_i32_16x16x64_i8 v[76:79], v[132:135], v[220:223], v[76:79]
	v_mfma_i32_16x16x64_i8 v[76:79], v[136:139], v[224:227], v[76:79]
	v_mfma_i32_16x16x64_i8 v[92:95], v[136:139], v[216:219], v[92:95]
	v_mfma_i32_16x16x64_i8 v[92:95], v[132:135], v[212:215], v[92:95]
	v_mfma_i32_16x16x64_i8 v[108:111], v[132:135], v[204:207], v[108:111]
	v_mfma_i32_16x16x64_i8 v[108:111], v[136:139], v[208:211], v[108:111]
	v_mfma_i32_16x16x64_i8 v[140:143], v[136:139], v[186:189], v[140:143]
	v_mfma_i32_16x16x64_i8 v[140:143], v[132:135], v[182:185], v[140:143]
	v_mfma_i32_16x16x64_i8 v[128:131], v[160:163], v[182:185], v[128:131]
	v_mfma_i32_16x16x64_i8 v[128:131], v[164:167], v[186:189], v[128:131]
	v_mfma_i32_16x16x64_i8 v[104:107], v[164:167], v[208:211], v[104:107]
	v_mfma_i32_16x16x64_i8 v[104:107], v[160:163], v[204:207], v[104:107]
	v_mfma_i32_16x16x64_i8 v[88:91], v[160:163], v[212:215], v[88:91]
	v_mfma_i32_16x16x64_i8 v[88:91], v[164:167], v[216:219], v[88:91]
	v_mfma_i32_16x16x64_i8 v[72:75], v[164:167], v[224:227], v[72:75]
	v_mfma_i32_16x16x64_i8 v[72:75], v[160:163], v[220:223], v[72:75]
	v_mfma_i32_16x16x64_i8 v[68:71], v[168:171], v[220:223], v[68:71]
	v_mfma_i32_16x16x64_i8 v[68:71], v[178:181], v[224:227], v[68:71]
	v_mfma_i32_16x16x64_i8 v[84:87], v[178:181], v[216:219], v[84:87]
	v_mfma_i32_16x16x64_i8 v[84:87], v[168:171], v[212:215], v[84:87]
	v_mfma_i32_16x16x64_i8 v[100:103], v[168:171], v[204:207], v[100:103]
	v_mfma_i32_16x16x64_i8 v[100:103], v[178:181], v[208:211], v[100:103]
	v_mfma_i32_16x16x64_i8 v[120:123], v[178:181], v[186:189], v[120:123]
	v_mfma_i32_16x16x64_i8 v[120:123], v[168:171], v[182:185], v[120:123]
	s_setprio 0
	s_barrier
; #define PG8_STAGE(bufoff, gbase, voff) do { _Pragma("unroll") for (int _i = 0; _i < 2; ++_i) \
;         __builtin_amdgcn_global_load_lds((const unsigned*)((const char*)(gbase) + (voff)[_i]), (PG8_LAS unsigned*)(lds + (bufoff) + ldsw + _i * 8192), 16, 0, 0); } while (0)
; #define PG8_LDA(dst, b, h) do { _Pragma("unroll") for (int m = 0; m < 4; ++m) _Pragma("unroll") for (int k = 0; k < 2; ++k) dst[m][k] = *(const PG8_LAS bf16x8*)(lds + PG8_SA(b, h) + aoff + m * 2048 + k * 1024); } while (0)
; #define PG8_WAIT_V(n) asm volatile("s_waitcnt vmcnt(" #n ")" ::: "memory")
; #define PG8_WAIT_L(n) asm volatile("s_waitcnt lgkmcnt(" #n ")" ::: "memory")
; #define PG8_BAR __builtin_amdgcn_s_barrier()
; #define PG8_SCHED __builtin_amdgcn_sched_barrier(0)
; template <class Epi, class Sched, bool ALIGN_EPI = false, bool SP2 = false, bool I8 = false>
; __device__ __forceinline__ void gemm_phase(PG8_LAS unsigned char* lds, const Gemm g, const Sched& S, const Epi& E) {
;     ...
;             PG8_LDA(At, 1, 1); PG8_STAGE(PG8_SB(1, 0), b3, voffB); PG8_STAGE(PG8_SB(1, 1), b3 + hstep, voffB); PG8_STAGE(PG8_SA(1, 0), a3, voffA);
;             PG8_WAIT_V(8); PG8_WAIT_L(0); PG8_BAR; PG8_MMA(1, 0, At, B0); PG8_MMA(1, 1, At, B1); PG8_BAR; PG8_SCHED;
	s_add_i32 s40, s50, s43
	v_lshl_add_u64 v[172:173], v[172:173], 0, s[84:85]
	s_mov_b32 m0, s40
	ds_read_b128 v[182:185], v177 offset:49152
	ds_read_b128 v[186:189], v177 offset:50176
	ds_read_b128 v[204:207], v177 offset:51200
	ds_read_b128 v[208:211], v177 offset:52224
	ds_read_b128 v[212:215], v177 offset:53248
	ds_read_b128 v[216:219], v177 offset:54272
	ds_read_b128 v[220:223], v177 offset:55296
	ds_read_b128 v[224:227], v177 offset:56320
	global_load_lds_dwordx4 v[172:173], off
	s_add_i32 m0, s40, 0x2000
	s_add_u32 s36, s36, 0x80080
	v_lshl_add_u64 v[172:173], v[190:191], 0, s[84:85]
	s_addc_u32 s37, s37, 0
	s_add_i32 s40, s51, s43
	global_load_lds_dwordx4 v[172:173], off
	v_lshl_add_u64 v[172:173], s[36:37], 0, v[2:3]
	s_mov_b32 m0, s40
	s_nop 0
	global_load_lds_dwordx4 v[172:173], off
	v_lshl_add_u64 v[172:173], s[36:37], 0, v[148:149]
	s_add_i32 m0, s40, 0x2000
	s_nop 0
	global_load_lds_dwordx4 v[172:173], off
	v_lshl_add_u64 v[172:173], v[228:229], 0, s[84:85]
	s_mov_b32 m0, s52
	s_nop 0
	global_load_lds_dwordx4 v[172:173], off
	v_lshl_add_u64 v[172:173], v[240:241], 0, s[84:85]
	s_mov_b32 m0, s53
	s_nop 0
	global_load_lds_dwordx4 v[172:173], off
	s_waitcnt vmcnt(8)
	s_waitcnt lgkmcnt(0)
	s_barrier
	s_setprio 1
	s_waitcnt lgkmcnt(0)
	v_mfma_i32_16x16x64_i8 v[64:67], v[116:119], v[182:185], v[64:67]
	v_mfma_i32_16x16x64_i8 v[64:67], v[124:127], v[186:189], v[64:67]
	v_mfma_i32_16x16x64_i8 v[48:51], v[124:127], v[208:211], v[48:51]
	v_mfma_i32_16x16x64_i8 v[48:51], v[116:119], v[204:207], v[48:51]
	v_mfma_i32_16x16x64_i8 v[32:35], v[116:119], v[212:215], v[32:35]
	v_mfma_i32_16x16x64_i8 v[32:35], v[124:127], v[216:219], v[32:35]
	v_mfma_i32_16x16x64_i8 v[16:19], v[124:127], v[224:227], v[16:19]
	v_mfma_i32_16x16x64_i8 v[16:19], v[116:119], v[220:223], v[16:19]
	v_mfma_i32_16x16x64_i8 v[12:15], v[132:135], v[220:223], v[12:15]
	v_mfma_i32_16x16x64_i8 v[12:15], v[136:139], v[224:227], v[12:15]
	v_mfma_i32_16x16x64_i8 v[28:31], v[136:139], v[216:219], v[28:31]
	v_mfma_i32_16x16x64_i8 v[28:31], v[132:135], v[212:215], v[28:31]
	v_mfma_i32_16x16x64_i8 v[44:47], v[132:135], v[204:207], v[44:47]
	v_mfma_i32_16x16x64_i8 v[44:47], v[136:139], v[208:211], v[44:47]
	v_mfma_i32_16x16x64_i8 v[60:63], v[136:139], v[186:189], v[60:63]
	v_mfma_i32_16x16x64_i8 v[60:63], v[132:135], v[182:185], v[60:63]
	v_mfma_i32_16x16x64_i8 v[56:59], v[160:163], v[182:185], v[56:59]
	v_mfma_i32_16x16x64_i8 v[56:59], v[164:167], v[186:189], v[56:59]
	v_mfma_i32_16x16x64_i8 v[40:43], v[164:167], v[208:211], v[40:43]
	v_mfma_i32_16x16x64_i8 v[40:43], v[160:163], v[204:207], v[40:43]
	v_mfma_i32_16x16x64_i8 v[24:27], v[160:163], v[212:215], v[24:27]
	v_mfma_i32_16x16x64_i8 v[24:27], v[164:167], v[216:219], v[24:27]
	v_mfma_i32_16x16x64_i8 v[8:11], v[164:167], v[224:227], v[8:11]
	v_mfma_i32_16x16x64_i8 v[8:11], v[160:163], v[220:223], v[8:11]
	v_mfma_i32_16x16x64_i8 v[4:7], v[168:171], v[220:223], v[4:7]
	v_mfma_i32_16x16x64_i8 v[4:7], v[178:181], v[224:227], v[4:7]
	v_mfma_i32_16x16x64_i8 v[20:23], v[178:181], v[216:219], v[20:23]
	v_mfma_i32_16x16x64_i8 v[20:23], v[168:171], v[212:215], v[20:23]
	v_mfma_i32_16x16x64_i8 v[36:39], v[168:171], v[204:207], v[36:39]
	v_mfma_i32_16x16x64_i8 v[36:39], v[178:181], v[208:211], v[36:39]
	v_mfma_i32_16x16x64_i8 v[52:55], v[178:181], v[186:189], v[52:55]
	v_mfma_i32_16x16x64_i8 v[52:55], v[168:171], v[182:185], v[52:55]
	s_setprio 0
	s_barrier
	s_add_i32 s76, s76, 2
	s_add_u32 s26, s26, 0x100
	s_addc_u32 s27, s27, 0
	s_add_u32 s72, s72, 0x100
	s_addc_u32 s73, s73, 0
	s_cmp_gt_u32 s76, 29
	s_cbranch_scc0 .LBB0_208

; #define PG8_STAGE(bufoff, gbase, voff) do { _Pragma("unroll") for (int _i = 0; _i < 2; ++_i) \
;         __builtin_amdgcn_global_load_lds((const unsigned*)((const char*)(gbase) + (voff)[_i]), (PG8_LAS unsigned*)(lds + (bufoff) + ldsw + _i * 8192), 16, 0, 0); } while (0)
; #define PG8_LDA(dst, b, h) do { _Pragma("unroll") for (int m = 0; m < 4; ++m) _Pragma("unroll") for (int k = 0; k < 2; ++k) dst[m][k] = *(const PG8_LAS bf16x8*)(lds + PG8_SA(b, h) + aoff + m * 2048 + k * 1024); } while (0)
; #define PG8_LDB(dst, b, h) do { _Pragma("unroll") for (int n = 0; n < 2; ++n) _Pragma("unroll") for (int k = 0; k < 2; ++k) dst[n][k] = *(const PG8_LAS bf16x8*)(lds + PG8_SB(b, h) + boff + n * 2048 + k * 1024); } while (0)
; #define PG8_WAIT_V(n) asm volatile("s_waitcnt vmcnt(" #n ")" ::: "memory")
; #define PG8_WAIT_L(n) asm volatile("s_waitcnt lgkmcnt(" #n ")" ::: "memory")
; #define PG8_BAR __builtin_amdgcn_s_barrier()
; #define PG8_SCHED __builtin_amdgcn_sched_barrier(0)
; template <class Epi, class Sched, bool ALIGN_EPI = false, bool SP2 = false, bool I8 = false>
; __device__ __forceinline__ void gemm_phase(PG8_LAS unsigned char* lds, const Gemm g, const Sched& S, const Epi& E) {
;     ...
;         const bool has_next = S.next(ui + 1, nxt);
;         const char* nA = has_next ? (const char*)g.A + (size_t)nxt.pm * tstep : cA; const char* nB = has_next ? (const char*)g.Bt + (size_t)nxt.pn * tstep : cB;
;         for (int t = 0; t < nt; t += 2) {
;             const bool last = (t == nt - 2);
;             const char* a1 = cA + (size_t)(t + 1) * kstep;
;             const char* a2 = last ? nA : cA + (size_t)(t + 2) * kstep; const char* b2 = last ? nB : cB + (size_t)(t + 2) * kstep;
;             const char* a3 = a2 + kstep; const char* b3 = b2 + kstep;
;             if (last && has_next) S.a_ready(nxt);
;             if constexpr (SP2) {
;             PG8_LDB(B0, 0, 0); PG8_LDB(B1, 0, 1); PG8_SCHED; PG8_LDA(At, 0, 0); PG8_STAGE(PG8_SA(1, 1), a1 + hstep, voffA);
;             PG8_WAIT_V(8); PG8_WAIT_L(0); PG8_BAR; PG8_MMA(0, 0, At, B0); PG8_MMA(0, 1, At, B1); PG8_BAR; PG8_SCHED;
;             PG8_LDA(At, 0, 1); PG8_STAGE(PG8_SB(0, 0), b2, voffB); PG8_STAGE(PG8_SB(0, 1), b2 + hstep, voffB); PG8_STAGE(PG8_SA(0, 0), a2, voffA);
;             PG8_WAIT_V(8); PG8_WAIT_L(0); PG8_BAR; PG8_MMA(1, 0, At, B0); PG8_MMA(1, 1, At, B1); PG8_BAR; PG8_SCHED;
.LBB0_229:
	s_ashr_i32 s37, s36, 31
	s_lshl_b64 s[34:35], s[36:37], 21
	s_add_u32 s40, s42, s34
	s_addc_u32 s41, s43, s35
	s_and_b64 s[34:35], s[8:9], exec
	s_cselect_b32 s11, s41, s13
	s_cselect_b32 s34, s40, s12
	s_ashr_i32 s27, s26, 31
	s_lshl_b64 s[50:51], s[26:27], 21
	s_add_u32 s54, s44, s50
	s_addc_u32 s55, s45, s51
	s_and_b64 s[50:51], s[8:9], exec
	s_cselect_b32 s27, s55, s73
	s_cselect_b32 s35, s54, s72
	s_add_u32 s12, s12, 0x100080
	s_addc_u32 s13, s13, 0
	s_add_u32 s37, s72, 0x100
	s_addc_u32 s61, s73, 0
	s_mov_b32 s97, -2
	s_add_u32 s50, s12, 0xfff00080
	s_addc_u32 s51, s13, -1
	s_add_i32 s56, 0, 0x10000
	s_cmp_eq_u32 s97, 60
	s_cselect_b32 s77, s11, s51
	s_cselect_b32 s76, s34, s50
	s_cselect_b32 s73, s27, s61
	s_cselect_b32 s72, s35, s37
	s_add_i32 s57, 0, 0x14000
	v_add_u32_e32 v156, s56, v171
	v_add_u32_e32 v168, s57, v171
	s_waitcnt vmcnt(0)
	ds_read_b128 v[112:115], v156
	ds_read_b128 v[120:123], v156 offset:1024
	ds_read_b128 v[152:155], v156 offset:2048
	ds_read_b128 v[156:159], v156 offset:3072
	ds_read_b128 v[160:163], v168
	ds_read_b128 v[164:167], v168 offset:1024
	s_waitcnt lgkmcnt(0)
	ds_read_b128 v[176:179], v168 offset:2048
	ds_read_b128 v[180:183], v168 offset:3072
	v_lshl_add_u64 v[168:169], s[12:13], 0, v[148:149]
	s_add_i32 m0, s47, 0xc000
	ds_read_b128 v[184:187], v173
	ds_read_b128 v[188:191], v173 offset:1024
	ds_read_b128 v[204:207], v173 offset:2048
	ds_read_b128 v[208:211], v173 offset:3072
	ds_read_b128 v[212:215], v173 offset:4096
	ds_read_b128 v[216:219], v173 offset:5120
	ds_read_b128 v[220:223], v173 offset:6144
	ds_read_b128 v[224:227], v173 offset:7168
	global_load_lds_dwordx4 v[168:169], off
	v_lshl_add_u64 v[168:169], s[12:13], 0, v[150:151]
	s_add_i32 m0, s47, 0xe000
	s_nop 0
	global_load_lds_dwordx4 v[168:169], off
	s_waitcnt vmcnt(8)
	s_waitcnt lgkmcnt(0)
	s_barrier
	s_setprio 1
	s_waitcnt lgkmcnt(0)
	v_mfma_f32_16x16x32_bf16 v[136:139], v[112:115], v[184:187], 0
	v_mfma_f32_16x16x32_bf16 v[136:139], v[120:123], v[188:191], v[136:139]
	v_mfma_f32_16x16x32_bf16 v[116:119], v[120:123], v[208:211], 0
	v_mfma_f32_16x16x32_bf16 v[116:119], v[112:115], v[204:207], v[116:119]
	v_mfma_f32_16x16x32_bf16 v[96:99], v[112:115], v[212:215], 0
	v_mfma_f32_16x16x32_bf16 v[96:99], v[120:123], v[216:219], v[96:99]
	v_mfma_f32_16x16x32_bf16 v[80:83], v[120:123], v[224:227], 0
	v_mfma_f32_16x16x32_bf16 v[80:83], v[112:115], v[220:223], v[80:83]
	v_mfma_f32_16x16x32_bf16 v[76:79], v[152:155], v[220:223], 0
	v_mfma_f32_16x16x32_bf16 v[76:79], v[156:159], v[224:227], v[76:79]
	v_mfma_f32_16x16x32_bf16 v[92:95], v[156:159], v[216:219], 0
	v_mfma_f32_16x16x32_bf16 v[92:95], v[152:155], v[212:215], v[92:95]
	v_mfma_f32_16x16x32_bf16 v[108:111], v[152:155], v[204:207], 0
	v_mfma_f32_16x16x32_bf16 v[108:111], v[156:159], v[208:211], v[108:111]
	v_mfma_f32_16x16x32_bf16 v[132:135], v[156:159], v[188:191], 0
	v_mfma_f32_16x16x32_bf16 v[132:135], v[152:155], v[184:187], v[132:135]
	v_mfma_f32_16x16x32_bf16 v[128:131], v[160:163], v[184:187], 0
	v_mfma_f32_16x16x32_bf16 v[128:131], v[164:167], v[188:191], v[128:131]
	v_mfma_f32_16x16x32_bf16 v[104:107], v[164:167], v[208:211], 0
	v_mfma_f32_16x16x32_bf16 v[104:107], v[160:163], v[204:207], v[104:107]
	v_mfma_f32_16x16x32_bf16 v[88:91], v[160:163], v[212:215], 0
	v_mfma_f32_16x16x32_bf16 v[88:91], v[164:167], v[216:219], v[88:91]
	v_mfma_f32_16x16x32_bf16 v[72:75], v[164:167], v[224:227], 0
	v_mfma_f32_16x16x32_bf16 v[72:75], v[160:163], v[220:223], v[72:75]
	v_mfma_f32_16x16x32_bf16 v[68:71], v[176:179], v[220:223], 0
	v_mfma_f32_16x16x32_bf16 v[68:71], v[180:183], v[224:227], v[68:71]
	v_mfma_f32_16x16x32_bf16 v[84:87], v[180:183], v[216:219], 0
	v_mfma_f32_16x16x32_bf16 v[84:87], v[176:179], v[212:215], v[84:87]
	v_mfma_f32_16x16x32_bf16 v[100:103], v[176:179], v[204:207], 0
	v_mfma_f32_16x16x32_bf16 v[100:103], v[180:183], v[208:211], v[100:103]
	v_mfma_f32_16x16x32_bf16 v[124:127], v[180:183], v[188:191], 0
	v_mfma_f32_16x16x32_bf16 v[124:127], v[176:179], v[184:187], v[124:127]
	s_setprio 0
	s_barrier
	s_add_i32 s50, s56, s46
	v_lshl_add_u64 v[168:169], s[72:73], 0, v[2:3]
	s_mov_b32 m0, s50
	ds_read_b128 v[184:187], v173 offset:16384
	ds_read_b128 v[188:191], v173 offset:17408
	ds_read_b128 v[204:207], v173 offset:18432
	ds_read_b128 v[208:211], v173 offset:19456
	ds_read_b128 v[212:215], v173 offset:20480
	ds_read_b128 v[216:219], v173 offset:21504
	ds_read_b128 v[220:223], v173 offset:22528
	ds_read_b128 v[224:227], v173 offset:23552
	global_load_lds_dwordx4 v[168:169], off
	s_add_i32 m0, s50, 0x2000
	s_add_u32 s50, s72, 0x100000
	v_lshl_add_u64 v[228:229], s[72:73], 0, v[144:145]
	s_addc_u32 s51, s73, 0
	s_add_i32 s56, s57, s46
	global_load_lds_dwordx4 v[228:229], off
	v_lshl_add_u64 v[240:241], s[50:51], 0, v[2:3]
	s_mov_b32 m0, s56
	v_lshl_add_u64 v[242:243], s[76:77], 0, v[142:143]
	global_load_lds_dwordx4 v[240:241], off
	v_lshl_add_u64 v[240:241], s[50:51], 0, v[144:145]
	s_add_i32 m0, s56, 0x2000
	s_nop 0
	global_load_lds_dwordx4 v[240:241], off
	v_lshl_add_u64 v[240:241], s[76:77], 0, v[140:141]
	s_waitcnt vmcnt(6)
	s_waitcnt lgkmcnt(0)
	s_barrier
; #define PG8_STAGE(bufoff, gbase, voff) do { _Pragma("unroll") for (int _i = 0; _i < 2; ++_i) \
;         __builtin_amdgcn_global_load_lds((const unsigned*)((const char*)(gbase) + (voff)[_i]), (PG8_LAS unsigned*)(lds + (bufoff) + ldsw + _i * 8192), 16, 0, 0); } while (0)
; #define PG8_LDA(dst, b, h) do { _Pragma("unroll") for (int m = 0; m < 4; ++m) _Pragma("unroll") for (int k = 0; k < 2; ++k) dst[m][k] = *(const PG8_LAS bf16x8*)(lds + PG8_SA(b, h) + aoff + m * 2048 + k * 1024); } while (0)
; #define PG8_LDB(dst, b, h) do { _Pragma("unroll") for (int n = 0; n < 2; ++n) _Pragma("unroll") for (int k = 0; k < 2; ++k) dst[n][k] = *(const PG8_LAS bf16x8*)(lds + PG8_SB(b, h) + boff + n * 2048 + k * 1024); } while (0)
; #define PG8_WAIT_V(n) asm volatile("s_waitcnt vmcnt(" #n ")" ::: "memory")
; #define PG8_WAIT_L(n) asm volatile("s_waitcnt lgkmcnt(" #n ")" ::: "memory")
; #define PG8_BAR __builtin_amdgcn_s_barrier()
; #define PG8_SCHED __builtin_amdgcn_sched_barrier(0)
; template <class Epi, class Sched, bool ALIGN_EPI = false, bool SP2 = false, bool I8 = false>
; __device__ __forceinline__ void gemm_phase(PG8_LAS unsigned char* lds, const Gemm g, const Sched& S, const Epi& E) {
;     ...
;             PG8_WAIT_V(8); PG8_WAIT_L(0); PG8_BAR; PG8_MMA(1, 0, At, B0); PG8_MMA(1, 1, At, B1); PG8_BAR; PG8_SCHED;
;             PG8_LDB(B0, 1, 0); PG8_LDB(B1, 1, 1); PG8_SCHED; PG8_LDA(At, 1, 0); PG8_STAGE(PG8_SA(0, 1), a2 + hstep, voffA);
;             PG8_WAIT_V(8); PG8_WAIT_L(0); PG8_BAR; PG8_MMA(0, 0, At, B0); PG8_MMA(0, 1, At, B1); PG8_BAR; PG8_SCHED;
	s_setprio 1
	s_waitcnt lgkmcnt(0)
	v_mfma_f32_16x16x32_bf16 v[64:67], v[112:115], v[184:187], 0
	v_mfma_f32_16x16x32_bf16 v[64:67], v[120:123], v[188:191], v[64:67]
	v_mfma_f32_16x16x32_bf16 v[48:51], v[120:123], v[208:211], 0
	v_mfma_f32_16x16x32_bf16 v[48:51], v[112:115], v[204:207], v[48:51]
	v_mfma_f32_16x16x32_bf16 v[32:35], v[112:115], v[212:215], 0
	v_mfma_f32_16x16x32_bf16 v[32:35], v[120:123], v[216:219], v[32:35]
	v_mfma_f32_16x16x32_bf16 v[16:19], v[120:123], v[224:227], 0
	v_mfma_f32_16x16x32_bf16 v[16:19], v[112:115], v[220:223], v[16:19]
	v_mfma_f32_16x16x32_bf16 v[12:15], v[152:155], v[220:223], 0
	v_mfma_f32_16x16x32_bf16 v[12:15], v[156:159], v[224:227], v[12:15]
	v_mfma_f32_16x16x32_bf16 v[28:31], v[156:159], v[216:219], 0
	v_mfma_f32_16x16x32_bf16 v[28:31], v[152:155], v[212:215], v[28:31]
	v_mfma_f32_16x16x32_bf16 v[44:47], v[152:155], v[204:207], 0
	v_mfma_f32_16x16x32_bf16 v[44:47], v[156:159], v[208:211], v[44:47]
	v_mfma_f32_16x16x32_bf16 v[60:63], v[156:159], v[188:191], 0
	v_mfma_f32_16x16x32_bf16 v[60:63], v[152:155], v[184:187], v[60:63]
	v_mfma_f32_16x16x32_bf16 v[56:59], v[160:163], v[184:187], 0
	v_mfma_f32_16x16x32_bf16 v[56:59], v[164:167], v[188:191], v[56:59]
	v_mfma_f32_16x16x32_bf16 v[40:43], v[164:167], v[208:211], 0
	v_mfma_f32_16x16x32_bf16 v[40:43], v[160:163], v[204:207], v[40:43]
	v_mfma_f32_16x16x32_bf16 v[24:27], v[160:163], v[212:215], 0
	v_mfma_f32_16x16x32_bf16 v[24:27], v[164:167], v[216:219], v[24:27]
	v_mfma_f32_16x16x32_bf16 v[8:11], v[164:167], v[224:227], 0
	v_mfma_f32_16x16x32_bf16 v[8:11], v[160:163], v[220:223], v[8:11]
	v_mfma_f32_16x16x32_bf16 v[4:7], v[176:179], v[220:223], 0
	v_mfma_f32_16x16x32_bf16 v[4:7], v[180:183], v[224:227], v[4:7]
	v_mfma_f32_16x16x32_bf16 v[20:23], v[180:183], v[216:219], 0
	v_mfma_f32_16x16x32_bf16 v[20:23], v[176:179], v[212:215], v[20:23]
	v_mfma_f32_16x16x32_bf16 v[36:39], v[176:179], v[204:207], 0
	v_mfma_f32_16x16x32_bf16 v[36:39], v[180:183], v[208:211], v[36:39]
	v_mfma_f32_16x16x32_bf16 v[52:55], v[180:183], v[188:191], 0
	v_mfma_f32_16x16x32_bf16 v[52:55], v[176:179], v[184:187], v[52:55]
	s_setprio 0
	s_barrier
	s_mov_b32 m0, s47
	s_nop 0
	global_load_lds_dwordx4 v[240:241], off
	s_mov_b32 m0, s52
	s_nop 0
	global_load_lds_dwordx4 v[242:243], off
	s_add_i32 s56, 0, 0x18000
	s_add_i32 s57, 0, 0x1c000
	v_add_u32_e32 v156, s56, v171
	v_add_u32_e32 v175, s57, v171
	ds_read_b128 v[112:115], v156
	ds_read_b128 v[120:123], v156 offset:1024
	ds_read_b128 v[152:155], v156 offset:2048
	ds_read_b128 v[156:159], v156 offset:3072
	ds_read_b128 v[160:163], v175
	ds_read_b128 v[164:167], v175 offset:1024
	ds_read_b128 v[176:179], v175 offset:2048
	ds_read_b128 v[180:183], v175 offset:3072
	s_add_u32 s50, s76, 0x100000
	s_addc_u32 s51, s77, 0
	s_mov_b32 m0, s53
	v_lshl_add_u64 v[244:245], s[50:51], 0, v[140:141]
	ds_read_b128 v[184:187], v173 offset:32768
	ds_read_b128 v[188:191], v173 offset:33792
	ds_read_b128 v[204:207], v173 offset:34816
	ds_read_b128 v[208:211], v173 offset:35840
	ds_read_b128 v[212:215], v173 offset:36864
	ds_read_b128 v[216:219], v173 offset:37888
	ds_read_b128 v[220:223], v173 offset:38912
	ds_read_b128 v[224:227], v173 offset:39936
	global_load_lds_dwordx4 v[244:245], off
	v_lshl_add_u64 v[244:245], s[50:51], 0, v[142:143]
	s_mov_b32 m0, s64
	s_nop 0
	global_load_lds_dwordx4 v[244:245], off
	s_waitcnt vmcnt(8)
	s_waitcnt lgkmcnt(0)
	s_barrier
	s_setprio 1
	s_waitcnt lgkmcnt(0)
	v_mfma_f32_16x16x32_bf16 v[136:139], v[112:115], v[184:187], v[136:139]
	v_mfma_f32_16x16x32_bf16 v[136:139], v[120:123], v[188:191], v[136:139]
	v_mfma_f32_16x16x32_bf16 v[116:119], v[120:123], v[208:211], v[116:119]
	v_mfma_f32_16x16x32_bf16 v[116:119], v[112:115], v[204:207], v[116:119]
	v_mfma_f32_16x16x32_bf16 v[96:99], v[112:115], v[212:215], v[96:99]
	v_mfma_f32_16x16x32_bf16 v[96:99], v[120:123], v[216:219], v[96:99]
	v_mfma_f32_16x16x32_bf16 v[80:83], v[120:123], v[224:227], v[80:83]
	v_mfma_f32_16x16x32_bf16 v[80:83], v[112:115], v[220:223], v[80:83]
	v_mfma_f32_16x16x32_bf16 v[76:79], v[152:155], v[220:223], v[76:79]
	v_mfma_f32_16x16x32_bf16 v[76:79], v[156:159], v[224:227], v[76:79]
	v_mfma_f32_16x16x32_bf16 v[92:95], v[156:159], v[216:219], v[92:95]
	v_mfma_f32_16x16x32_bf16 v[92:95], v[152:155], v[212:215], v[92:95]
	v_mfma_f32_16x16x32_bf16 v[108:111], v[152:155], v[204:207], v[108:111]
	v_mfma_f32_16x16x32_bf16 v[108:111], v[156:159], v[208:211], v[108:111]
	v_mfma_f32_16x16x32_bf16 v[132:135], v[156:159], v[188:191], v[132:135]
	v_mfma_f32_16x16x32_bf16 v[132:135], v[152:155], v[184:187], v[132:135]
	v_mfma_f32_16x16x32_bf16 v[128:131], v[160:163], v[184:187], v[128:131]
	v_mfma_f32_16x16x32_bf16 v[128:131], v[164:167], v[188:191], v[128:131]
	v_mfma_f32_16x16x32_bf16 v[104:107], v[164:167], v[208:211], v[104:107]
	v_mfma_f32_16x16x32_bf16 v[104:107], v[160:163], v[204:207], v[104:107]
	v_mfma_f32_16x16x32_bf16 v[88:91], v[160:163], v[212:215], v[88:91]
	v_mfma_f32_16x16x32_bf16 v[88:91], v[164:167], v[216:219], v[88:91]
	v_mfma_f32_16x16x32_bf16 v[72:75], v[164:167], v[224:227], v[72:75]
	v_mfma_f32_16x16x32_bf16 v[72:75], v[160:163], v[220:223], v[72:75]
	v_mfma_f32_16x16x32_bf16 v[68:71], v[176:179], v[220:223], v[68:71]
	v_mfma_f32_16x16x32_bf16 v[68:71], v[180:183], v[224:227], v[68:71]
	v_mfma_f32_16x16x32_bf16 v[84:87], v[180:183], v[216:219], v[84:87]
	v_mfma_f32_16x16x32_bf16 v[84:87], v[176:179], v[212:215], v[84:87]
	v_mfma_f32_16x16x32_bf16 v[100:103], v[176:179], v[204:207], v[100:103]
	v_mfma_f32_16x16x32_bf16 v[100:103], v[180:183], v[208:211], v[100:103]
	v_mfma_f32_16x16x32_bf16 v[124:127], v[180:183], v[188:191], v[124:127]
	v_mfma_f32_16x16x32_bf16 v[124:127], v[176:179], v[184:187], v[124:127]
	s_setprio 0
	s_barrier
; #define PG8_STAGE(bufoff, gbase, voff) do { _Pragma("unroll") for (int _i = 0; _i < 2; ++_i) \
;         __builtin_amdgcn_global_load_lds((const unsigned*)((const char*)(gbase) + (voff)[_i]), (PG8_LAS unsigned*)(lds + (bufoff) + ldsw + _i * 8192), 16, 0, 0); } while (0)
; #define PG8_LDA(dst, b, h) do { _Pragma("unroll") for (int m = 0; m < 4; ++m) _Pragma("unroll") for (int k = 0; k < 2; ++k) dst[m][k] = *(const PG8_LAS bf16x8*)(lds + PG8_SA(b, h) + aoff + m * 2048 + k * 1024); } while (0)
; #define PG8_LDB(dst, b, h) do { _Pragma("unroll") for (int n = 0; n < 2; ++n) _Pragma("unroll") for (int k = 0; k < 2; ++k) dst[n][k] = *(const PG8_LAS bf16x8*)(lds + PG8_SB(b, h) + boff + n * 2048 + k * 1024); } while (0)
; #define PG8_WAIT_V(n) asm volatile("s_waitcnt vmcnt(" #n ")" ::: "memory")
; #define PG8_WAIT_L(n) asm volatile("s_waitcnt lgkmcnt(" #n ")" ::: "memory")
; #define PG8_BAR __builtin_amdgcn_s_barrier()
; #define PG8_SCHED __builtin_amdgcn_sched_barrier(0)
; template <class Epi, class Sched, bool ALIGN_EPI = false, bool SP2 = false, bool I8 = false>
; __device__ __forceinline__ void gemm_phase(PG8_LAS unsigned char* lds, const Gemm g, const Sched& S, const Epi& E) {
;     ...
;             PG8_LDB(B0, 0, 0); PG8_LDB(B1, 0, 1); PG8_SCHED; PG8_LDA(At, 0, 0); PG8_STAGE(PG8_SA(1, 1), a1 + hstep, voffA);
;             PG8_WAIT_V(8); PG8_WAIT_L(0); PG8_BAR; PG8_MMA(0, 0, At, B0); PG8_MMA(0, 1, At, B1); PG8_BAR; PG8_SCHED;
;     ...
;             PG8_LDA(At, 1, 1); PG8_STAGE(PG8_SB(1, 0), b3, voffB); PG8_STAGE(PG8_SB(1, 1), b3 + hstep, voffB); PG8_STAGE(PG8_SA(1, 0), a3, voffA);
;             PG8_WAIT_V(8); PG8_WAIT_L(0); PG8_BAR; PG8_MMA(1, 0, At, B0); PG8_MMA(1, 1, At, B1); PG8_BAR; PG8_SCHED;
	s_add_i32 s50, s56, s46
	v_lshl_add_u64 v[168:169], v[168:169], 0, s[84:85]
	s_mov_b32 m0, s50
	ds_read_b128 v[184:187], v173 offset:49152
	ds_read_b128 v[188:191], v173 offset:50176
	ds_read_b128 v[204:207], v173 offset:51200
	ds_read_b128 v[208:211], v173 offset:52224
	ds_read_b128 v[212:215], v173 offset:53248
	ds_read_b128 v[216:219], v173 offset:54272
	ds_read_b128 v[220:223], v173 offset:55296
	ds_read_b128 v[224:227], v173 offset:56320
	global_load_lds_dwordx4 v[168:169], off
	s_add_i32 m0, s50, 0x2000
	s_add_u32 s50, s72, 0x100080
	v_lshl_add_u64 v[168:169], v[228:229], 0, s[84:85]
	s_addc_u32 s51, s73, 0
	s_add_i32 s56, s57, s46
	global_load_lds_dwordx4 v[168:169], off
	v_lshl_add_u64 v[168:169], s[50:51], 0, v[2:3]
	s_mov_b32 m0, s56
	s_nop 0
	global_load_lds_dwordx4 v[168:169], off
	v_lshl_add_u64 v[168:169], s[50:51], 0, v[144:145]
	s_add_i32 m0, s56, 0x2000
	s_nop 0
	global_load_lds_dwordx4 v[168:169], off
	v_lshl_add_u64 v[168:169], v[240:241], 0, s[84:85]
	s_mov_b32 m0, s28
	s_nop 0
	global_load_lds_dwordx4 v[168:169], off
	v_lshl_add_u64 v[168:169], v[242:243], 0, s[84:85]
	s_mov_b32 m0, s65
	s_nop 0
	global_load_lds_dwordx4 v[168:169], off
	s_waitcnt vmcnt(8)
	s_waitcnt lgkmcnt(0)
	s_barrier
	s_setprio 1
	s_waitcnt lgkmcnt(0)
	v_mfma_f32_16x16x32_bf16 v[64:67], v[112:115], v[184:187], v[64:67]
	v_mfma_f32_16x16x32_bf16 v[64:67], v[120:123], v[188:191], v[64:67]
	v_mfma_f32_16x16x32_bf16 v[48:51], v[120:123], v[208:211], v[48:51]
	v_mfma_f32_16x16x32_bf16 v[48:51], v[112:115], v[204:207], v[48:51]
	v_mfma_f32_16x16x32_bf16 v[32:35], v[112:115], v[212:215], v[32:35]
	v_mfma_f32_16x16x32_bf16 v[32:35], v[120:123], v[216:219], v[32:35]
	v_mfma_f32_16x16x32_bf16 v[16:19], v[120:123], v[224:227], v[16:19]
	v_mfma_f32_16x16x32_bf16 v[16:19], v[112:115], v[220:223], v[16:19]
	v_mfma_f32_16x16x32_bf16 v[12:15], v[152:155], v[220:223], v[12:15]
	v_mfma_f32_16x16x32_bf16 v[12:15], v[156:159], v[224:227], v[12:15]
	v_mfma_f32_16x16x32_bf16 v[28:31], v[156:159], v[216:219], v[28:31]
	v_mfma_f32_16x16x32_bf16 v[28:31], v[152:155], v[212:215], v[28:31]
	v_mfma_f32_16x16x32_bf16 v[44:47], v[152:155], v[204:207], v[44:47]
	v_mfma_f32_16x16x32_bf16 v[44:47], v[156:159], v[208:211], v[44:47]
	v_mfma_f32_16x16x32_bf16 v[60:63], v[156:159], v[188:191], v[60:63]
	v_mfma_f32_16x16x32_bf16 v[60:63], v[152:155], v[184:187], v[60:63]
	v_mfma_f32_16x16x32_bf16 v[56:59], v[160:163], v[184:187], v[56:59]
	v_mfma_f32_16x16x32_bf16 v[56:59], v[164:167], v[188:191], v[56:59]
	v_mfma_f32_16x16x32_bf16 v[40:43], v[164:167], v[208:211], v[40:43]
	v_mfma_f32_16x16x32_bf16 v[40:43], v[160:163], v[204:207], v[40:43]
	v_mfma_f32_16x16x32_bf16 v[24:27], v[160:163], v[212:215], v[24:27]
	v_mfma_f32_16x16x32_bf16 v[24:27], v[164:167], v[216:219], v[24:27]
	v_mfma_f32_16x16x32_bf16 v[8:11], v[164:167], v[224:227], v[8:11]
	v_mfma_f32_16x16x32_bf16 v[8:11], v[160:163], v[220:223], v[8:11]
	v_mfma_f32_16x16x32_bf16 v[4:7], v[176:179], v[220:223], v[4:7]
	v_mfma_f32_16x16x32_bf16 v[4:7], v[180:183], v[224:227], v[4:7]
	v_mfma_f32_16x16x32_bf16 v[20:23], v[180:183], v[216:219], v[20:23]
	v_mfma_f32_16x16x32_bf16 v[20:23], v[176:179], v[212:215], v[20:23]
	v_mfma_f32_16x16x32_bf16 v[36:39], v[176:179], v[204:207], v[36:39]
	v_mfma_f32_16x16x32_bf16 v[36:39], v[180:183], v[208:211], v[36:39]
	v_mfma_f32_16x16x32_bf16 v[52:55], v[180:183], v[188:191], v[52:55]
	v_mfma_f32_16x16x32_bf16 v[52:55], v[176:179], v[184:187], v[52:55]
	s_setprio 0
	s_barrier
	s_add_i32 s97, s97, 2
	s_add_u32 s12, s12, 0x100
	s_addc_u32 s13, s13, 0
	s_add_u32 s37, s37, 0x100
	s_addc_u32 s61, s61, 0
	s_cmp_gt_u32 s97, 61
	s_cbranch_scc1 .Lkloop_exit_1
.LBB0_230:
	s_add_u32 s50, s12, 0xfff00080
	s_addc_u32 s51, s13, -1
	s_add_i32 s56, 0, 0x10000
	s_cmp_eq_u32 s97, 60
	s_cselect_b32 s77, s11, s51
	s_cselect_b32 s76, s34, s50
	s_cselect_b32 s73, s27, s61
	s_cselect_b32 s72, s35, s37
	s_add_i32 s57, 0, 0x14000
	v_add_u32_e32 v156, s56, v171
	v_add_u32_e32 v168, s57, v171
	ds_read_b128 v[112:115], v156
	ds_read_b128 v[120:123], v156 offset:1024
	ds_read_b128 v[152:155], v156 offset:2048
	ds_read_b128 v[156:159], v156 offset:3072
	ds_read_b128 v[160:163], v168
	ds_read_b128 v[164:167], v168 offset:1024
	ds_read_b128 v[176:179], v168 offset:2048
	ds_read_b128 v[180:183], v168 offset:3072
	v_lshl_add_u64 v[168:169], s[12:13], 0, v[148:149]
	s_add_i32 m0, s47, 0xc000
	ds_read_b128 v[184:187], v173
	ds_read_b128 v[188:191], v173 offset:1024
	ds_read_b128 v[204:207], v173 offset:2048
	ds_read_b128 v[208:211], v173 offset:3072
	ds_read_b128 v[212:215], v173 offset:4096
	ds_read_b128 v[216:219], v173 offset:5120
	ds_read_b128 v[220:223], v173 offset:6144
	ds_read_b128 v[224:227], v173 offset:7168
	global_load_lds_dwordx4 v[168:169], off
	v_lshl_add_u64 v[168:169], s[12:13], 0, v[150:151]
	s_add_i32 m0, s47, 0xe000
	s_nop 0
	global_load_lds_dwordx4 v[168:169], off
	s_waitcnt vmcnt(8)
	s_waitcnt lgkmcnt(0)
	s_barrier
; #define PG8_STAGE(bufoff, gbase, voff) do { _Pragma("unroll") for (int _i = 0; _i < 2; ++_i) \
;         __builtin_amdgcn_global_load_lds((const unsigned*)((const char*)(gbase) + (voff)[_i]), (PG8_LAS unsigned*)(lds + (bufoff) + ldsw + _i * 8192), 16, 0, 0); } while (0)
; #define PG8_LDA(dst, b, h) do { _Pragma("unroll") for (int m = 0; m < 4; ++m) _Pragma("unroll") for (int k = 0; k < 2; ++k) dst[m][k] = *(const PG8_LAS bf16x8*)(lds + PG8_SA(b, h) + aoff + m * 2048 + k * 1024); } while (0)
; #define PG8_WAIT_V(n) asm volatile("s_waitcnt vmcnt(" #n ")" ::: "memory")
; #define PG8_WAIT_L(n) asm volatile("s_waitcnt lgkmcnt(" #n ")" ::: "memory")
; #define PG8_BAR __builtin_amdgcn_s_barrier()
; #define PG8_SCHED __builtin_amdgcn_sched_barrier(0)
; template <class Epi, class Sched, bool ALIGN_EPI = false, bool SP2 = false, bool I8 = false>
; __device__ __forceinline__ void gemm_phase(PG8_LAS unsigned char* lds, const Gemm g, const Sched& S, const Epi& E) {
;     ...
;             PG8_WAIT_V(8); PG8_WAIT_L(0); PG8_BAR; PG8_MMA(0, 0, At, B0); PG8_MMA(0, 1, At, B1); PG8_BAR; PG8_SCHED;
;             PG8_LDA(At, 0, 1); PG8_STAGE(PG8_SB(0, 0), b2, voffB); PG8_STAGE(PG8_SB(0, 1), b2 + hstep, voffB); PG8_STAGE(PG8_SA(0, 0), a2, voffA);
;             PG8_WAIT_V(8); PG8_WAIT_L(0); PG8_BAR; PG8_MMA(1, 0, At, B0); PG8_MMA(1, 1, At, B1); PG8_BAR; PG8_SCHED;
	s_setprio 1
	s_waitcnt lgkmcnt(0)
	v_mfma_f32_16x16x32_bf16 v[136:139], v[112:115], v[184:187], v[136:139]
	v_mfma_f32_16x16x32_bf16 v[136:139], v[120:123], v[188:191], v[136:139]
	v_mfma_f32_16x16x32_bf16 v[116:119], v[120:123], v[208:211], v[116:119]
	v_mfma_f32_16x16x32_bf16 v[116:119], v[112:115], v[204:207], v[116:119]
	v_mfma_f32_16x16x32_bf16 v[96:99], v[112:115], v[212:215], v[96:99]
	v_mfma_f32_16x16x32_bf16 v[96:99], v[120:123], v[216:219], v[96:99]
	v_mfma_f32_16x16x32_bf16 v[80:83], v[120:123], v[224:227], v[80:83]
	v_mfma_f32_16x16x32_bf16 v[80:83], v[112:115], v[220:223], v[80:83]
	v_mfma_f32_16x16x32_bf16 v[76:79], v[152:155], v[220:223], v[76:79]
	v_mfma_f32_16x16x32_bf16 v[76:79], v[156:159], v[224:227], v[76:79]
	v_mfma_f32_16x16x32_bf16 v[92:95], v[156:159], v[216:219], v[92:95]
	v_mfma_f32_16x16x32_bf16 v[92:95], v[152:155], v[212:215], v[92:95]
	v_mfma_f32_16x16x32_bf16 v[108:111], v[152:155], v[204:207], v[108:111]
	v_mfma_f32_16x16x32_bf16 v[108:111], v[156:159], v[208:211], v[108:111]
	v_mfma_f32_16x16x32_bf16 v[132:135], v[156:159], v[188:191], v[132:135]
	v_mfma_f32_16x16x32_bf16 v[132:135], v[152:155], v[184:187], v[132:135]
	v_mfma_f32_16x16x32_bf16 v[128:131], v[160:163], v[184:187], v[128:131]
	v_mfma_f32_16x16x32_bf16 v[128:131], v[164:167], v[188:191], v[128:131]
	v_mfma_f32_16x16x32_bf16 v[104:107], v[164:167], v[208:211], v[104:107]
	v_mfma_f32_16x16x32_bf16 v[104:107], v[160:163], v[204:207], v[104:107]
	v_mfma_f32_16x16x32_bf16 v[88:91], v[160:163], v[212:215], v[88:91]
	v_mfma_f32_16x16x32_bf16 v[88:91], v[164:167], v[216:219], v[88:91]
	v_mfma_f32_16x16x32_bf16 v[72:75], v[164:167], v[224:227], v[72:75]
	v_mfma_f32_16x16x32_bf16 v[72:75], v[160:163], v[220:223], v[72:75]
	v_mfma_f32_16x16x32_bf16 v[68:71], v[176:179], v[220:223], v[68:71]
	v_mfma_f32_16x16x32_bf16 v[68:71], v[180:183], v[224:227], v[68:71]
	v_mfma_f32_16x16x32_bf16 v[84:87], v[180:183], v[216:219], v[84:87]
	v_mfma_f32_16x16x32_bf16 v[84:87], v[176:179], v[212:215], v[84:87]
	v_mfma_f32_16x16x32_bf16 v[100:103], v[176:179], v[204:207], v[100:103]
	v_mfma_f32_16x16x32_bf16 v[100:103], v[180:183], v[208:211], v[100:103]
	v_mfma_f32_16x16x32_bf16 v[124:127], v[180:183], v[188:191], v[124:127]
	v_mfma_f32_16x16x32_bf16 v[124:127], v[176:179], v[184:187], v[124:127]
	s_setprio 0
	s_barrier
	s_add_i32 s50, s56, s46
	v_lshl_add_u64 v[168:169], s[72:73], 0, v[2:3]
	s_mov_b32 m0, s50
	ds_read_b128 v[184:187], v173 offset:16384
	ds_read_b128 v[188:191], v173 offset:17408
	ds_read_b128 v[204:207], v173 offset:18432
	ds_read_b128 v[208:211], v173 offset:19456
	ds_read_b128 v[212:215], v173 offset:20480
	ds_read_b128 v[216:219], v173 offset:21504
	ds_read_b128 v[220:223], v173 offset:22528
	ds_read_b128 v[224:227], v173 offset:23552
	global_load_lds_dwordx4 v[168:169], off
	s_add_i32 m0, s50, 0x2000
	s_add_u32 s50, s72, 0x100000
	v_lshl_add_u64 v[228:229], s[72:73], 0, v[144:145]
	s_addc_u32 s51, s73, 0
	s_add_i32 s56, s57, s46
	global_load_lds_dwordx4 v[228:229], off
	v_lshl_add_u64 v[240:241], s[50:51], 0, v[2:3]
	s_mov_b32 m0, s56
	v_lshl_add_u64 v[242:243], s[76:77], 0, v[142:143]
	global_load_lds_dwordx4 v[240:241], off
	v_lshl_add_u64 v[240:241], s[50:51], 0, v[144:145]
	s_add_i32 m0, s56, 0x2000
	s_nop 0
	global_load_lds_dwordx4 v[240:241], off
	v_lshl_add_u64 v[240:241], s[76:77], 0, v[140:141]
	s_waitcnt vmcnt(6)
	s_waitcnt lgkmcnt(0)
	s_barrier
	s_setprio 1
	s_waitcnt lgkmcnt(0)
	v_mfma_f32_16x16x32_bf16 v[64:67], v[112:115], v[184:187], v[64:67]
	v_mfma_f32_16x16x32_bf16 v[64:67], v[120:123], v[188:191], v[64:67]
	v_mfma_f32_16x16x32_bf16 v[48:51], v[120:123], v[208:211], v[48:51]
	v_mfma_f32_16x16x32_bf16 v[48:51], v[112:115], v[204:207], v[48:51]
	v_mfma_f32_16x16x32_bf16 v[32:35], v[112:115], v[212:215], v[32:35]
	v_mfma_f32_16x16x32_bf16 v[32:35], v[120:123], v[216:219], v[32:35]
	v_mfma_f32_16x16x32_bf16 v[16:19], v[120:123], v[224:227], v[16:19]
	v_mfma_f32_16x16x32_bf16 v[16:19], v[112:115], v[220:223], v[16:19]
	v_mfma_f32_16x16x32_bf16 v[12:15], v[152:155], v[220:223], v[12:15]
	v_mfma_f32_16x16x32_bf16 v[12:15], v[156:159], v[224:227], v[12:15]
	v_mfma_f32_16x16x32_bf16 v[28:31], v[156:159], v[216:219], v[28:31]
	v_mfma_f32_16x16x32_bf16 v[28:31], v[152:155], v[212:215], v[28:31]
	v_mfma_f32_16x16x32_bf16 v[44:47], v[152:155], v[204:207], v[44:47]
	v_mfma_f32_16x16x32_bf16 v[44:47], v[156:159], v[208:211], v[44:47]
	v_mfma_f32_16x16x32_bf16 v[60:63], v[156:159], v[188:191], v[60:63]
	v_mfma_f32_16x16x32_bf16 v[60:63], v[152:155], v[184:187], v[60:63]
	v_mfma_f32_16x16x32_bf16 v[56:59], v[160:163], v[184:187], v[56:59]
	v_mfma_f32_16x16x32_bf16 v[56:59], v[164:167], v[188:191], v[56:59]
	v_mfma_f32_16x16x32_bf16 v[40:43], v[164:167], v[208:211], v[40:43]
	v_mfma_f32_16x16x32_bf16 v[40:43], v[160:163], v[204:207], v[40:43]
	v_mfma_f32_16x16x32_bf16 v[24:27], v[160:163], v[212:215], v[24:27]
	v_mfma_f32_16x16x32_bf16 v[24:27], v[164:167], v[216:219], v[24:27]
	v_mfma_f32_16x16x32_bf16 v[8:11], v[164:167], v[224:227], v[8:11]
	v_mfma_f32_16x16x32_bf16 v[8:11], v[160:163], v[220:223], v[8:11]
	v_mfma_f32_16x16x32_bf16 v[4:7], v[176:179], v[220:223], v[4:7]
	v_mfma_f32_16x16x32_bf16 v[4:7], v[180:183], v[224:227], v[4:7]
	v_mfma_f32_16x16x32_bf16 v[20:23], v[180:183], v[216:219], v[20:23]
	v_mfma_f32_16x16x32_bf16 v[20:23], v[176:179], v[212:215], v[20:23]
	v_mfma_f32_16x16x32_bf16 v[36:39], v[176:179], v[204:207], v[36:39]
	v_mfma_f32_16x16x32_bf16 v[36:39], v[180:183], v[208:211], v[36:39]
	v_mfma_f32_16x16x32_bf16 v[52:55], v[180:183], v[188:191], v[52:55]
	v_mfma_f32_16x16x32_bf16 v[52:55], v[176:179], v[184:187], v[52:55]
	s_setprio 0
	s_barrier
; #define PG8_STAGE(bufoff, gbase, voff) do { _Pragma("unroll") for (int _i = 0; _i < 2; ++_i) \
;         __builtin_amdgcn_global_load_lds((const unsigned*)((const char*)(gbase) + (voff)[_i]), (PG8_LAS unsigned*)(lds + (bufoff) + ldsw + _i * 8192), 16, 0, 0); } while (0)
; #define PG8_LDA(dst, b, h) do { _Pragma("unroll") for (int m = 0; m < 4; ++m) _Pragma("unroll") for (int k = 0; k < 2; ++k) dst[m][k] = *(const PG8_LAS bf16x8*)(lds + PG8_SA(b, h) + aoff + m * 2048 + k * 1024); } while (0)
; #define PG8_LDB(dst, b, h) do { _Pragma("unroll") for (int n = 0; n < 2; ++n) _Pragma("unroll") for (int k = 0; k < 2; ++k) dst[n][k] = *(const PG8_LAS bf16x8*)(lds + PG8_SB(b, h) + boff + n * 2048 + k * 1024); } while (0)
; #define PG8_WAIT_V(n) asm volatile("s_waitcnt vmcnt(" #n ")" ::: "memory")
; #define PG8_WAIT_L(n) asm volatile("s_waitcnt lgkmcnt(" #n ")" ::: "memory")
; #define PG8_BAR __builtin_amdgcn_s_barrier()
; #define PG8_SCHED __builtin_amdgcn_sched_barrier(0)
; template <class Epi, class Sched, bool ALIGN_EPI = false, bool SP2 = false, bool I8 = false>
; __device__ __forceinline__ void gemm_phase(PG8_LAS unsigned char* lds, const Gemm g, const Sched& S, const Epi& E) {
;     ...
;             PG8_LDB(B0, 1, 0); PG8_LDB(B1, 1, 1); PG8_SCHED; PG8_LDA(At, 1, 0); PG8_STAGE(PG8_SA(0, 1), a2 + hstep, voffA);
;             PG8_WAIT_V(8); PG8_WAIT_L(0); PG8_BAR; PG8_MMA(0, 0, At, B0); PG8_MMA(0, 1, At, B1); PG8_BAR; PG8_SCHED;
	s_mov_b32 m0, s47
	s_nop 0
	global_load_lds_dwordx4 v[240:241], off
	s_mov_b32 m0, s52
	s_nop 0
	global_load_lds_dwordx4 v[242:243], off
	s_add_i32 s56, 0, 0x18000
	s_add_i32 s57, 0, 0x1c000
	v_add_u32_e32 v156, s56, v171
	v_add_u32_e32 v175, s57, v171
	ds_read_b128 v[112:115], v156
	ds_read_b128 v[120:123], v156 offset:1024
	ds_read_b128 v[152:155], v156 offset:2048
	ds_read_b128 v[156:159], v156 offset:3072
	ds_read_b128 v[160:163], v175
	ds_read_b128 v[164:167], v175 offset:1024
	ds_read_b128 v[176:179], v175 offset:2048
	ds_read_b128 v[180:183], v175 offset:3072
	s_add_u32 s50, s76, 0x100000
	s_addc_u32 s51, s77, 0
	s_mov_b32 m0, s53
	v_lshl_add_u64 v[244:245], s[50:51], 0, v[140:141]
	ds_read_b128 v[184:187], v173 offset:32768
	ds_read_b128 v[188:191], v173 offset:33792
	ds_read_b128 v[204:207], v173 offset:34816
	ds_read_b128 v[208:211], v173 offset:35840
	ds_read_b128 v[212:215], v173 offset:36864
	ds_read_b128 v[216:219], v173 offset:37888
	ds_read_b128 v[220:223], v173 offset:38912
	ds_read_b128 v[224:227], v173 offset:39936
	global_load_lds_dwordx4 v[244:245], off
	v_lshl_add_u64 v[244:245], s[50:51], 0, v[142:143]
	s_mov_b32 m0, s64
	s_nop 0
	global_load_lds_dwordx4 v[244:245], off
	s_waitcnt vmcnt(8)
	s_waitcnt lgkmcnt(0)
	s_barrier
	s_setprio 1
	s_waitcnt lgkmcnt(0)
	v_mfma_f32_16x16x32_bf16 v[136:139], v[112:115], v[184:187], v[136:139]
	v_mfma_f32_16x16x32_bf16 v[136:139], v[120:123], v[188:191], v[136:139]
	v_mfma_f32_16x16x32_bf16 v[116:119], v[120:123], v[208:211], v[116:119]
	v_mfma_f32_16x16x32_bf16 v[116:119], v[112:115], v[204:207], v[116:119]
	v_mfma_f32_16x16x32_bf16 v[96:99], v[112:115], v[212:215], v[96:99]
	v_mfma_f32_16x16x32_bf16 v[96:99], v[120:123], v[216:219], v[96:99]
	v_mfma_f32_16x16x32_bf16 v[80:83], v[120:123], v[224:227], v[80:83]
	v_mfma_f32_16x16x32_bf16 v[80:83], v[112:115], v[220:223], v[80:83]
	v_mfma_f32_16x16x32_bf16 v[76:79], v[152:155], v[220:223], v[76:79]
	v_mfma_f32_16x16x32_bf16 v[76:79], v[156:159], v[224:227], v[76:79]
	v_mfma_f32_16x16x32_bf16 v[92:95], v[156:159], v[216:219], v[92:95]
	v_mfma_f32_16x16x32_bf16 v[92:95], v[152:155], v[212:215], v[92:95]
	v_mfma_f32_16x16x32_bf16 v[108:111], v[152:155], v[204:207], v[108:111]
	v_mfma_f32_16x16x32_bf16 v[108:111], v[156:159], v[208:211], v[108:111]
	v_mfma_f32_16x16x32_bf16 v[132:135], v[156:159], v[188:191], v[132:135]
	v_mfma_f32_16x16x32_bf16 v[132:135], v[152:155], v[184:187], v[132:135]
	v_mfma_f32_16x16x32_bf16 v[128:131], v[160:163], v[184:187], v[128:131]
	v_mfma_f32_16x16x32_bf16 v[128:131], v[164:167], v[188:191], v[128:131]
	v_mfma_f32_16x16x32_bf16 v[104:107], v[164:167], v[208:211], v[104:107]
	v_mfma_f32_16x16x32_bf16 v[104:107], v[160:163], v[204:207], v[104:107]
	v_mfma_f32_16x16x32_bf16 v[88:91], v[160:163], v[212:215], v[88:91]
	v_mfma_f32_16x16x32_bf16 v[88:91], v[164:167], v[216:219], v[88:91]
	v_mfma_f32_16x16x32_bf16 v[72:75], v[164:167], v[224:227], v[72:75]
	v_mfma_f32_16x16x32_bf16 v[72:75], v[160:163], v[220:223], v[72:75]
	v_mfma_f32_16x16x32_bf16 v[68:71], v[176:179], v[220:223], v[68:71]
	v_mfma_f32_16x16x32_bf16 v[68:71], v[180:183], v[224:227], v[68:71]
	v_mfma_f32_16x16x32_bf16 v[84:87], v[180:183], v[216:219], v[84:87]
	v_mfma_f32_16x16x32_bf16 v[84:87], v[176:179], v[212:215], v[84:87]
	v_mfma_f32_16x16x32_bf16 v[100:103], v[176:179], v[204:207], v[100:103]
	v_mfma_f32_16x16x32_bf16 v[100:103], v[180:183], v[208:211], v[100:103]
	v_mfma_f32_16x16x32_bf16 v[124:127], v[180:183], v[188:191], v[124:127]
	v_mfma_f32_16x16x32_bf16 v[124:127], v[176:179], v[184:187], v[124:127]
	s_setprio 0
	s_barrier
; #define PG8_STAGE(bufoff, gbase, voff) do { _Pragma("unroll") for (int _i = 0; _i < 2; ++_i) \
;         __builtin_amdgcn_global_load_lds((const unsigned*)((const char*)(gbase) + (voff)[_i]), (PG8_LAS unsigned*)(lds + (bufoff) + ldsw + _i * 8192), 16, 0, 0); } while (0)
; #define PG8_LDA(dst, b, h) do { _Pragma("unroll") for (int m = 0; m < 4; ++m) _Pragma("unroll") for (int k = 0; k < 2; ++k) dst[m][k] = *(const PG8_LAS bf16x8*)(lds + PG8_SA(b, h) + aoff + m * 2048 + k * 1024); } while (0)
; #define PG8_WAIT_V(n) asm volatile("s_waitcnt vmcnt(" #n ")" ::: "memory")
; #define PG8_WAIT_L(n) asm volatile("s_waitcnt lgkmcnt(" #n ")" ::: "memory")
; #define PG8_BAR __builtin_amdgcn_s_barrier()
; #define PG8_SCHED __builtin_amdgcn_sched_barrier(0)
; template <class Epi, class Sched, bool ALIGN_EPI = false, bool SP2 = false, bool I8 = false>
; __device__ __forceinline__ void gemm_phase(PG8_LAS unsigned char* lds, const Gemm g, const Sched& S, const Epi& E) {
;     ...
;             PG8_LDA(At, 1, 1); PG8_STAGE(PG8_SB(1, 0), b3, voffB); PG8_STAGE(PG8_SB(1, 1), b3 + hstep, voffB); PG8_STAGE(PG8_SA(1, 0), a3, voffA);
;             PG8_WAIT_V(8); PG8_WAIT_L(0); PG8_BAR; PG8_MMA(1, 0, At, B0); PG8_MMA(1, 1, At, B1); PG8_BAR; PG8_SCHED;
	s_add_i32 s50, s56, s46
	v_lshl_add_u64 v[168:169], v[168:169], 0, s[84:85]
	s_mov_b32 m0, s50
	ds_read_b128 v[184:187], v173 offset:49152
	ds_read_b128 v[188:191], v173 offset:50176
	ds_read_b128 v[204:207], v173 offset:51200
	ds_read_b128 v[208:211], v173 offset:52224
	ds_read_b128 v[212:215], v173 offset:53248
	ds_read_b128 v[216:219], v173 offset:54272
	ds_read_b128 v[220:223], v173 offset:55296
	ds_read_b128 v[224:227], v173 offset:56320
	global_load_lds_dwordx4 v[168:169], off
	s_add_i32 m0, s50, 0x2000
	s_add_u32 s50, s72, 0x100080
	v_lshl_add_u64 v[168:169], v[228:229], 0, s[84:85]
	s_addc_u32 s51, s73, 0
	s_add_i32 s56, s57, s46
	global_load_lds_dwordx4 v[168:169], off
	v_lshl_add_u64 v[168:169], s[50:51], 0, v[2:3]
	s_mov_b32 m0, s56
	s_nop 0
	global_load_lds_dwordx4 v[168:169], off
	v_lshl_add_u64 v[168:169], s[50:51], 0, v[144:145]
	s_add_i32 m0, s56, 0x2000
	s_nop 0
	global_load_lds_dwordx4 v[168:169], off
	v_lshl_add_u64 v[168:169], v[240:241], 0, s[84:85]
	s_mov_b32 m0, s28
	s_nop 0
	global_load_lds_dwordx4 v[168:169], off
	v_lshl_add_u64 v[168:169], v[242:243], 0, s[84:85]
	s_mov_b32 m0, s65
	s_nop 0
	global_load_lds_dwordx4 v[168:169], off
	s_waitcnt vmcnt(8)
	s_waitcnt lgkmcnt(0)
	s_barrier
	s_setprio 1
	s_waitcnt lgkmcnt(0)
	v_mfma_f32_16x16x32_bf16 v[64:67], v[112:115], v[184:187], v[64:67]
	v_mfma_f32_16x16x32_bf16 v[64:67], v[120:123], v[188:191], v[64:67]
	v_mfma_f32_16x16x32_bf16 v[48:51], v[120:123], v[208:211], v[48:51]
	v_mfma_f32_16x16x32_bf16 v[48:51], v[112:115], v[204:207], v[48:51]
	v_mfma_f32_16x16x32_bf16 v[32:35], v[112:115], v[212:215], v[32:35]
	v_mfma_f32_16x16x32_bf16 v[32:35], v[120:123], v[216:219], v[32:35]
	v_mfma_f32_16x16x32_bf16 v[16:19], v[120:123], v[224:227], v[16:19]
	v_mfma_f32_16x16x32_bf16 v[16:19], v[112:115], v[220:223], v[16:19]
	v_mfma_f32_16x16x32_bf16 v[12:15], v[152:155], v[220:223], v[12:15]
	v_mfma_f32_16x16x32_bf16 v[12:15], v[156:159], v[224:227], v[12:15]
	v_mfma_f32_16x16x32_bf16 v[28:31], v[156:159], v[216:219], v[28:31]
	v_mfma_f32_16x16x32_bf16 v[28:31], v[152:155], v[212:215], v[28:31]
	v_mfma_f32_16x16x32_bf16 v[44:47], v[152:155], v[204:207], v[44:47]
	v_mfma_f32_16x16x32_bf16 v[44:47], v[156:159], v[208:211], v[44:47]
	v_mfma_f32_16x16x32_bf16 v[60:63], v[156:159], v[188:191], v[60:63]
	v_mfma_f32_16x16x32_bf16 v[60:63], v[152:155], v[184:187], v[60:63]
	v_mfma_f32_16x16x32_bf16 v[56:59], v[160:163], v[184:187], v[56:59]
	v_mfma_f32_16x16x32_bf16 v[56:59], v[164:167], v[188:191], v[56:59]
	v_mfma_f32_16x16x32_bf16 v[40:43], v[164:167], v[208:211], v[40:43]
	v_mfma_f32_16x16x32_bf16 v[40:43], v[160:163], v[204:207], v[40:43]
	v_mfma_f32_16x16x32_bf16 v[24:27], v[160:163], v[212:215], v[24:27]
	v_mfma_f32_16x16x32_bf16 v[24:27], v[164:167], v[216:219], v[24:27]
	v_mfma_f32_16x16x32_bf16 v[8:11], v[164:167], v[224:227], v[8:11]
	v_mfma_f32_16x16x32_bf16 v[8:11], v[160:163], v[220:223], v[8:11]
	v_mfma_f32_16x16x32_bf16 v[4:7], v[176:179], v[220:223], v[4:7]
	v_mfma_f32_16x16x32_bf16 v[4:7], v[180:183], v[224:227], v[4:7]
	v_mfma_f32_16x16x32_bf16 v[20:23], v[180:183], v[216:219], v[20:23]
	v_mfma_f32_16x16x32_bf16 v[20:23], v[176:179], v[212:215], v[20:23]
	v_mfma_f32_16x16x32_bf16 v[36:39], v[176:179], v[204:207], v[36:39]
	v_mfma_f32_16x16x32_bf16 v[36:39], v[180:183], v[208:211], v[36:39]
	v_mfma_f32_16x16x32_bf16 v[52:55], v[180:183], v[188:191], v[52:55]
	v_mfma_f32_16x16x32_bf16 v[52:55], v[176:179], v[184:187], v[52:55]
	s_setprio 0
	s_barrier
	s_add_i32 s97, s97, 2
	s_add_u32 s12, s12, 0x100
	s_addc_u32 s13, s13, 0
	s_add_u32 s37, s37, 0x100
	s_addc_u32 s61, s61, 0
	s_cmp_gt_u32 s97, 61
	s_cbranch_scc0 .LBB0_230

; #define PG8_STAGE(bufoff, gbase, voff) do { _Pragma("unroll") for (int _i = 0; _i < 2; ++_i) \
;         __builtin_amdgcn_global_load_lds((const unsigned*)((const char*)(gbase) + (voff)[_i]), (PG8_LAS unsigned*)(lds + (bufoff) + ldsw + _i * 8192), 16, 0, 0); } while (0)
; #define PG8_LDA(dst, b, h) do { _Pragma("unroll") for (int m = 0; m < 4; ++m) _Pragma("unroll") for (int k = 0; k < 2; ++k) dst[m][k] = *(const PG8_LAS bf16x8*)(lds + PG8_SA(b, h) + aoff + m * 2048 + k * 1024); } while (0)
; #define PG8_LDB(dst, b, h) do { _Pragma("unroll") for (int n = 0; n < 2; ++n) _Pragma("unroll") for (int k = 0; k < 2; ++k) dst[n][k] = *(const PG8_LAS bf16x8*)(lds + PG8_SB(b, h) + boff + n * 2048 + k * 1024); } while (0)
; #define PG8_WAIT_V(n) asm volatile("s_waitcnt vmcnt(" #n ")" ::: "memory")
; #define PG8_WAIT_L(n) asm volatile("s_waitcnt lgkmcnt(" #n ")" ::: "memory")
; #define PG8_BAR __builtin_amdgcn_s_barrier()
; #define PG8_SCHED __builtin_amdgcn_sched_barrier(0)
; template <class Epi, class Sched, bool ALIGN_EPI = false, bool SP2 = false, bool I8 = false>
; __device__ __forceinline__ void gemm_phase(PG8_LAS unsigned char* lds, const Gemm g, const Sched& S, const Epi& E) {
;     ...
;         const bool has_next = S.next(ui + 1, nxt);
;         const char* nA = has_next ? (const char*)g.A + (size_t)nxt.pm * tstep : cA; const char* nB = has_next ? (const char*)g.Bt + (size_t)nxt.pn * tstep : cB;
;         for (int t = 0; t < nt; t += 2) {
;             const bool last = (t == nt - 2);
;             const char* a1 = cA + (size_t)(t + 1) * kstep;
;             const char* a2 = last ? nA : cA + (size_t)(t + 2) * kstep; const char* b2 = last ? nB : cB + (size_t)(t + 2) * kstep;
;             const char* a3 = a2 + kstep; const char* b3 = b2 + kstep;
;             if (last && has_next) S.a_ready(nxt);
;             if constexpr (SP2) {
;             PG8_LDB(B0, 0, 0); PG8_LDB(B1, 0, 1); PG8_SCHED; PG8_LDA(At, 0, 0); PG8_STAGE(PG8_SA(1, 1), a1 + hstep, voffA);
;             PG8_WAIT_V(8); PG8_WAIT_L(0); PG8_BAR; PG8_MMA(0, 0, At, B0); PG8_MMA(0, 1, At, B1); PG8_BAR; PG8_SCHED;
;             PG8_LDA(At, 0, 1); PG8_STAGE(PG8_SB(0, 0), b2, voffB); PG8_STAGE(PG8_SB(0, 1), b2 + hstep, voffB); PG8_STAGE(PG8_SA(0, 0), a2, voffA);
;             PG8_WAIT_V(8); PG8_WAIT_L(0); PG8_BAR; PG8_MMA(1, 0, At, B0); PG8_MMA(1, 1, At, B1); PG8_BAR; PG8_SCHED;
.LBB0_1455:
	s_ashr_i32 s17, s16, 31
	s_lshl_b64 s[20:21], s[16:17], 21
	s_add_u32 s20, s28, s20
	s_addc_u32 s21, s34, s21
	s_and_b64 s[22:23], s[8:9], exec
	s_cselect_b32 s17, s21, s25
	s_cselect_b32 s51, s20, s24
	s_ashr_i32 s19, s18, 31
	s_lshl_b64 s[22:23], s[18:19], 21
	s_add_u32 s22, s35, s22
	s_addc_u32 s23, s39, s23
	s_and_b64 s[36:37], s[8:9], exec
	s_cselect_b32 s19, s23, s27
	s_cselect_b32 s52, s22, s26
	s_add_u32 s24, s24, 0x100080
	s_addc_u32 s25, s25, 0
	s_add_u32 s53, s26, 0x100
	s_addc_u32 s54, s27, 0
	s_mov_b32 s55, -2
	s_waitcnt vmcnt(0)
	s_add_u32 s26, s24, 0xfff00080
	s_addc_u32 s27, s25, -1
	s_add_i32 s56, 0, 0x10000
	s_cmp_eq_u32 s55, 60
	s_cselect_b32 s37, s17, s27
	s_cselect_b32 s36, s51, s26
	s_cselect_b32 s27, s19, s54
	s_cselect_b32 s26, s52, s53
	s_add_i32 s58, 0, 0x14000
	v_add_u32_e32 v144, s56, v240
	v_add_u32_e32 v160, s58, v240
	ds_read_b128 v[124:127], v144
	ds_read_b128 v[128:131], v144 offset:1024
	ds_read_b128 v[132:135], v144 offset:2048
	ds_read_b128 v[144:147], v144 offset:3072
	ds_read_b128 v[148:151], v160
	ds_read_b128 v[152:155], v160 offset:1024
	ds_read_b128 v[156:159], v160 offset:2048
	ds_read_b128 v[160:163], v160 offset:3072
	v_lshl_add_u64 v[218:219], s[24:25], 0, v[210:211]
	s_add_i32 m0, s41, 0xc000
	ds_read_b128 v[164:167], v242
	ds_read_b128 v[168:171], v242 offset:1024
	ds_read_b128 v[172:175], v242 offset:2048
	ds_read_b128 v[176:179], v242 offset:3072
	ds_read_b128 v[180:183], v242 offset:4096
	ds_read_b128 v[184:187], v242 offset:5120
	ds_read_b128 v[188:191], v242 offset:6144
	ds_read_b128 v[214:217], v242 offset:7168
	global_load_lds_dwordx4 v[218:219], off
	v_lshl_add_u64 v[218:219], s[24:25], 0, v[212:213]
	s_add_i32 m0, s41, 0xe000
	s_nop 0
	global_load_lds_dwordx4 v[218:219], off
	s_waitcnt vmcnt(8)
	s_waitcnt lgkmcnt(0)
	s_barrier
	s_setprio 1
	s_waitcnt lgkmcnt(0)
	v_mfma_f32_16x16x32_bf16 v[140:143], v[124:127], v[164:167], 0
	v_mfma_f32_16x16x32_bf16 v[140:143], v[128:131], v[168:171], v[140:143]
	v_mfma_f32_16x16x32_bf16 v[112:115], v[128:131], v[176:179], 0
	v_mfma_f32_16x16x32_bf16 v[112:115], v[124:127], v[172:175], v[112:115]
	v_mfma_f32_16x16x32_bf16 v[96:99], v[124:127], v[180:183], 0
	v_mfma_f32_16x16x32_bf16 v[96:99], v[128:131], v[184:187], v[96:99]
	v_mfma_f32_16x16x32_bf16 v[80:83], v[128:131], v[214:217], 0
	v_mfma_f32_16x16x32_bf16 v[80:83], v[124:127], v[188:191], v[80:83]
	v_mfma_f32_16x16x32_bf16 v[76:79], v[132:135], v[188:191], 0
	v_mfma_f32_16x16x32_bf16 v[76:79], v[144:147], v[214:217], v[76:79]
	v_mfma_f32_16x16x32_bf16 v[92:95], v[144:147], v[184:187], 0
	v_mfma_f32_16x16x32_bf16 v[92:95], v[132:135], v[180:183], v[92:95]
	v_mfma_f32_16x16x32_bf16 v[108:111], v[132:135], v[172:175], 0
	v_mfma_f32_16x16x32_bf16 v[108:111], v[144:147], v[176:179], v[108:111]
	v_mfma_f32_16x16x32_bf16 v[136:139], v[144:147], v[168:171], 0
	v_mfma_f32_16x16x32_bf16 v[136:139], v[132:135], v[164:167], v[136:139]
	v_mfma_f32_16x16x32_bf16 v[120:123], v[148:151], v[164:167], 0
	v_mfma_f32_16x16x32_bf16 v[120:123], v[152:155], v[168:171], v[120:123]
	v_mfma_f32_16x16x32_bf16 v[104:107], v[152:155], v[176:179], 0
	v_mfma_f32_16x16x32_bf16 v[104:107], v[148:151], v[172:175], v[104:107]
	v_mfma_f32_16x16x32_bf16 v[88:91], v[148:151], v[180:183], 0
	v_mfma_f32_16x16x32_bf16 v[88:91], v[152:155], v[184:187], v[88:91]
	v_mfma_f32_16x16x32_bf16 v[72:75], v[152:155], v[214:217], 0
	v_mfma_f32_16x16x32_bf16 v[72:75], v[148:151], v[188:191], v[72:75]
	v_mfma_f32_16x16x32_bf16 v[68:71], v[156:159], v[188:191], 0
	v_mfma_f32_16x16x32_bf16 v[68:71], v[160:163], v[214:217], v[68:71]
	v_mfma_f32_16x16x32_bf16 v[84:87], v[160:163], v[184:187], 0
	v_mfma_f32_16x16x32_bf16 v[84:87], v[156:159], v[180:183], v[84:87]
	v_mfma_f32_16x16x32_bf16 v[100:103], v[156:159], v[172:175], 0
	v_mfma_f32_16x16x32_bf16 v[100:103], v[160:163], v[176:179], v[100:103]
	v_mfma_f32_16x16x32_bf16 v[116:119], v[160:163], v[168:171], 0
	v_mfma_f32_16x16x32_bf16 v[116:119], v[156:159], v[164:167], v[116:119]
	s_setprio 0
	s_barrier
	s_add_i32 s56, s56, s40
	v_lshl_add_u64 v[218:219], s[26:27], 0, v[2:3]
	s_mov_b32 m0, s56
	ds_read_b128 v[164:167], v242 offset:16384
	ds_read_b128 v[168:171], v242 offset:17408
	ds_read_b128 v[172:175], v242 offset:18432
	ds_read_b128 v[176:179], v242 offset:19456
	ds_read_b128 v[180:183], v242 offset:20480
	ds_read_b128 v[184:187], v242 offset:21504
	ds_read_b128 v[188:191], v242 offset:22528
	ds_read_b128 v[214:217], v242 offset:23552
	global_load_lds_dwordx4 v[218:219], off
	s_add_i32 m0, s56, 0x2000
	s_add_u32 s56, s26, 0x100000
	v_lshl_add_u64 v[220:221], s[26:27], 0, v[204:205]
	s_addc_u32 s57, s27, 0
	s_add_i32 s58, s58, s40
	global_load_lds_dwordx4 v[220:221], off
	v_lshl_add_u64 v[222:223], s[56:57], 0, v[2:3]
	s_mov_b32 m0, s58
	v_lshl_add_u64 v[224:225], s[36:37], 0, v[206:207]
	global_load_lds_dwordx4 v[222:223], off
	v_lshl_add_u64 v[222:223], s[56:57], 0, v[204:205]
	s_add_i32 m0, s58, 0x2000
	s_nop 0
	global_load_lds_dwordx4 v[222:223], off
	v_lshl_add_u64 v[222:223], s[36:37], 0, v[208:209]
	s_waitcnt vmcnt(6)
	s_waitcnt lgkmcnt(0)
	s_barrier
; #define PG8_STAGE(bufoff, gbase, voff) do { _Pragma("unroll") for (int _i = 0; _i < 2; ++_i) \
;         __builtin_amdgcn_global_load_lds((const unsigned*)((const char*)(gbase) + (voff)[_i]), (PG8_LAS unsigned*)(lds + (bufoff) + ldsw + _i * 8192), 16, 0, 0); } while (0)
; #define PG8_LDA(dst, b, h) do { _Pragma("unroll") for (int m = 0; m < 4; ++m) _Pragma("unroll") for (int k = 0; k < 2; ++k) dst[m][k] = *(const PG8_LAS bf16x8*)(lds + PG8_SA(b, h) + aoff + m * 2048 + k * 1024); } while (0)
; #define PG8_LDB(dst, b, h) do { _Pragma("unroll") for (int n = 0; n < 2; ++n) _Pragma("unroll") for (int k = 0; k < 2; ++k) dst[n][k] = *(const PG8_LAS bf16x8*)(lds + PG8_SB(b, h) + boff + n * 2048 + k * 1024); } while (0)
; #define PG8_WAIT_V(n) asm volatile("s_waitcnt vmcnt(" #n ")" ::: "memory")
; #define PG8_WAIT_L(n) asm volatile("s_waitcnt lgkmcnt(" #n ")" ::: "memory")
; #define PG8_BAR __builtin_amdgcn_s_barrier()
; #define PG8_SCHED __builtin_amdgcn_sched_barrier(0)
; template <class Epi, class Sched, bool ALIGN_EPI = false, bool SP2 = false, bool I8 = false>
; __device__ __forceinline__ void gemm_phase(PG8_LAS unsigned char* lds, const Gemm g, const Sched& S, const Epi& E) {
;     ...
;             PG8_WAIT_V(8); PG8_WAIT_L(0); PG8_BAR; PG8_MMA(1, 0, At, B0); PG8_MMA(1, 1, At, B1); PG8_BAR; PG8_SCHED;
;             PG8_LDB(B0, 1, 0); PG8_LDB(B1, 1, 1); PG8_SCHED; PG8_LDA(At, 1, 0); PG8_STAGE(PG8_SA(0, 1), a2 + hstep, voffA);
;             PG8_WAIT_V(8); PG8_WAIT_L(0); PG8_BAR; PG8_MMA(0, 0, At, B0); PG8_MMA(0, 1, At, B1); PG8_BAR; PG8_SCHED;
	s_setprio 1
	s_waitcnt lgkmcnt(0)
	v_mfma_f32_16x16x32_bf16 v[64:67], v[124:127], v[164:167], 0
	v_mfma_f32_16x16x32_bf16 v[64:67], v[128:131], v[168:171], v[64:67]
	v_mfma_f32_16x16x32_bf16 v[48:51], v[128:131], v[176:179], 0
	v_mfma_f32_16x16x32_bf16 v[48:51], v[124:127], v[172:175], v[48:51]
	v_mfma_f32_16x16x32_bf16 v[32:35], v[124:127], v[180:183], 0
	v_mfma_f32_16x16x32_bf16 v[32:35], v[128:131], v[184:187], v[32:35]
	v_mfma_f32_16x16x32_bf16 v[16:19], v[128:131], v[214:217], 0
	v_mfma_f32_16x16x32_bf16 v[16:19], v[124:127], v[188:191], v[16:19]
	v_mfma_f32_16x16x32_bf16 v[12:15], v[132:135], v[188:191], 0
	v_mfma_f32_16x16x32_bf16 v[12:15], v[144:147], v[214:217], v[12:15]
	v_mfma_f32_16x16x32_bf16 v[28:31], v[144:147], v[184:187], 0
	v_mfma_f32_16x16x32_bf16 v[28:31], v[132:135], v[180:183], v[28:31]
	v_mfma_f32_16x16x32_bf16 v[44:47], v[132:135], v[172:175], 0
	v_mfma_f32_16x16x32_bf16 v[44:47], v[144:147], v[176:179], v[44:47]
	v_mfma_f32_16x16x32_bf16 v[60:63], v[144:147], v[168:171], 0
	v_mfma_f32_16x16x32_bf16 v[60:63], v[132:135], v[164:167], v[60:63]
	v_mfma_f32_16x16x32_bf16 v[56:59], v[148:151], v[164:167], 0
	v_mfma_f32_16x16x32_bf16 v[56:59], v[152:155], v[168:171], v[56:59]
	v_mfma_f32_16x16x32_bf16 v[40:43], v[152:155], v[176:179], 0
	v_mfma_f32_16x16x32_bf16 v[40:43], v[148:151], v[172:175], v[40:43]
	v_mfma_f32_16x16x32_bf16 v[24:27], v[148:151], v[180:183], 0
	v_mfma_f32_16x16x32_bf16 v[24:27], v[152:155], v[184:187], v[24:27]
	v_mfma_f32_16x16x32_bf16 v[8:11], v[152:155], v[214:217], 0
	v_mfma_f32_16x16x32_bf16 v[8:11], v[148:151], v[188:191], v[8:11]
	v_mfma_f32_16x16x32_bf16 v[4:7], v[156:159], v[188:191], 0
	v_mfma_f32_16x16x32_bf16 v[4:7], v[160:163], v[214:217], v[4:7]
	v_mfma_f32_16x16x32_bf16 v[20:23], v[160:163], v[184:187], 0
	v_mfma_f32_16x16x32_bf16 v[20:23], v[156:159], v[180:183], v[20:23]
	v_mfma_f32_16x16x32_bf16 v[36:39], v[156:159], v[172:175], 0
	v_mfma_f32_16x16x32_bf16 v[36:39], v[160:163], v[176:179], v[36:39]
	v_mfma_f32_16x16x32_bf16 v[52:55], v[160:163], v[168:171], 0
	v_mfma_f32_16x16x32_bf16 v[52:55], v[156:159], v[164:167], v[52:55]
	s_setprio 0
	s_barrier
	s_mov_b32 m0, s41
	s_nop 0
	global_load_lds_dwordx4 v[222:223], off
	s_mov_b32 m0, s42
	s_nop 0
	global_load_lds_dwordx4 v[224:225], off
	s_add_i32 s56, 0, 0x18000
	s_add_i32 s57, 0, 0x1c000
	v_add_u32_e32 v144, s56, v240
	v_add_u32_e32 v160, s57, v240
	ds_read_b128 v[124:127], v144
	ds_read_b128 v[128:131], v144 offset:1024
	ds_read_b128 v[132:135], v144 offset:2048
	ds_read_b128 v[144:147], v144 offset:3072
	ds_read_b128 v[148:151], v160
	ds_read_b128 v[152:155], v160 offset:1024
	ds_read_b128 v[156:159], v160 offset:2048
	ds_read_b128 v[160:163], v160 offset:3072
	s_add_u32 s36, s36, 0x100000
	s_addc_u32 s37, s37, 0
	s_mov_b32 m0, s43
	v_lshl_add_u64 v[226:227], s[36:37], 0, v[208:209]
	ds_read_b128 v[164:167], v242 offset:32768
	ds_read_b128 v[168:171], v242 offset:33792
	ds_read_b128 v[172:175], v242 offset:34816
	ds_read_b128 v[176:179], v242 offset:35840
	ds_read_b128 v[180:183], v242 offset:36864
	ds_read_b128 v[184:187], v242 offset:37888
	ds_read_b128 v[188:191], v242 offset:38912
	ds_read_b128 v[214:217], v242 offset:39936
	global_load_lds_dwordx4 v[226:227], off
	v_lshl_add_u64 v[226:227], s[36:37], 0, v[206:207]
	s_mov_b32 m0, s44
	s_nop 0
	global_load_lds_dwordx4 v[226:227], off
	s_waitcnt vmcnt(8)
	s_waitcnt lgkmcnt(0)
	s_barrier
	s_setprio 1
	s_waitcnt lgkmcnt(0)
	v_mfma_f32_16x16x32_bf16 v[140:143], v[124:127], v[164:167], v[140:143]
	v_mfma_f32_16x16x32_bf16 v[140:143], v[128:131], v[168:171], v[140:143]
	v_mfma_f32_16x16x32_bf16 v[112:115], v[128:131], v[176:179], v[112:115]
	v_mfma_f32_16x16x32_bf16 v[112:115], v[124:127], v[172:175], v[112:115]
	v_mfma_f32_16x16x32_bf16 v[96:99], v[124:127], v[180:183], v[96:99]
	v_mfma_f32_16x16x32_bf16 v[96:99], v[128:131], v[184:187], v[96:99]
	v_mfma_f32_16x16x32_bf16 v[80:83], v[128:131], v[214:217], v[80:83]
	v_mfma_f32_16x16x32_bf16 v[80:83], v[124:127], v[188:191], v[80:83]
	v_mfma_f32_16x16x32_bf16 v[76:79], v[132:135], v[188:191], v[76:79]
	v_mfma_f32_16x16x32_bf16 v[76:79], v[144:147], v[214:217], v[76:79]
	v_mfma_f32_16x16x32_bf16 v[92:95], v[144:147], v[184:187], v[92:95]
	v_mfma_f32_16x16x32_bf16 v[92:95], v[132:135], v[180:183], v[92:95]
	v_mfma_f32_16x16x32_bf16 v[108:111], v[132:135], v[172:175], v[108:111]
	v_mfma_f32_16x16x32_bf16 v[108:111], v[144:147], v[176:179], v[108:111]
	v_mfma_f32_16x16x32_bf16 v[136:139], v[144:147], v[168:171], v[136:139]
	v_mfma_f32_16x16x32_bf16 v[136:139], v[132:135], v[164:167], v[136:139]
	v_mfma_f32_16x16x32_bf16 v[120:123], v[148:151], v[164:167], v[120:123]
	v_mfma_f32_16x16x32_bf16 v[120:123], v[152:155], v[168:171], v[120:123]
	v_mfma_f32_16x16x32_bf16 v[104:107], v[152:155], v[176:179], v[104:107]
	v_mfma_f32_16x16x32_bf16 v[104:107], v[148:151], v[172:175], v[104:107]
	v_mfma_f32_16x16x32_bf16 v[88:91], v[148:151], v[180:183], v[88:91]
	v_mfma_f32_16x16x32_bf16 v[88:91], v[152:155], v[184:187], v[88:91]
	v_mfma_f32_16x16x32_bf16 v[72:75], v[152:155], v[214:217], v[72:75]
	v_mfma_f32_16x16x32_bf16 v[72:75], v[148:151], v[188:191], v[72:75]
	v_mfma_f32_16x16x32_bf16 v[68:71], v[156:159], v[188:191], v[68:71]
	v_mfma_f32_16x16x32_bf16 v[68:71], v[160:163], v[214:217], v[68:71]
	v_mfma_f32_16x16x32_bf16 v[84:87], v[160:163], v[184:187], v[84:87]
	v_mfma_f32_16x16x32_bf16 v[84:87], v[156:159], v[180:183], v[84:87]
	v_mfma_f32_16x16x32_bf16 v[100:103], v[156:159], v[172:175], v[100:103]
	v_mfma_f32_16x16x32_bf16 v[100:103], v[160:163], v[176:179], v[100:103]
	v_mfma_f32_16x16x32_bf16 v[116:119], v[160:163], v[168:171], v[116:119]
	v_mfma_f32_16x16x32_bf16 v[116:119], v[156:159], v[164:167], v[116:119]
	s_setprio 0
	s_barrier
; #define PG8_STAGE(bufoff, gbase, voff) do { _Pragma("unroll") for (int _i = 0; _i < 2; ++_i) \
;         __builtin_amdgcn_global_load_lds((const unsigned*)((const char*)(gbase) + (voff)[_i]), (PG8_LAS unsigned*)(lds + (bufoff) + ldsw + _i * 8192), 16, 0, 0); } while (0)
; #define PG8_LDA(dst, b, h) do { _Pragma("unroll") for (int m = 0; m < 4; ++m) _Pragma("unroll") for (int k = 0; k < 2; ++k) dst[m][k] = *(const PG8_LAS bf16x8*)(lds + PG8_SA(b, h) + aoff + m * 2048 + k * 1024); } while (0)
; #define PG8_LDB(dst, b, h) do { _Pragma("unroll") for (int n = 0; n < 2; ++n) _Pragma("unroll") for (int k = 0; k < 2; ++k) dst[n][k] = *(const PG8_LAS bf16x8*)(lds + PG8_SB(b, h) + boff + n * 2048 + k * 1024); } while (0)
; #define PG8_WAIT_V(n) asm volatile("s_waitcnt vmcnt(" #n ")" ::: "memory")
; #define PG8_WAIT_L(n) asm volatile("s_waitcnt lgkmcnt(" #n ")" ::: "memory")
; #define PG8_BAR __builtin_amdgcn_s_barrier()
; #define PG8_SCHED __builtin_amdgcn_sched_barrier(0)
; template <class Epi, class Sched, bool ALIGN_EPI = false, bool SP2 = false, bool I8 = false>
; __device__ __forceinline__ void gemm_phase(PG8_LAS unsigned char* lds, const Gemm g, const Sched& S, const Epi& E) {
;     ...
;             PG8_LDB(B0, 0, 0); PG8_LDB(B1, 0, 1); PG8_SCHED; PG8_LDA(At, 0, 0); PG8_STAGE(PG8_SA(1, 1), a1 + hstep, voffA);
;             PG8_WAIT_V(8); PG8_WAIT_L(0); PG8_BAR; PG8_MMA(0, 0, At, B0); PG8_MMA(0, 1, At, B1); PG8_BAR; PG8_SCHED;
;     ...
;             PG8_LDA(At, 1, 1); PG8_STAGE(PG8_SB(1, 0), b3, voffB); PG8_STAGE(PG8_SB(1, 1), b3 + hstep, voffB); PG8_STAGE(PG8_SA(1, 0), a3, voffA);
;             PG8_WAIT_V(8); PG8_WAIT_L(0); PG8_BAR; PG8_MMA(1, 0, At, B0); PG8_MMA(1, 1, At, B1); PG8_BAR; PG8_SCHED;
	s_add_i32 s36, s56, s40
	v_lshl_add_u64 v[218:219], v[218:219], 0, s[84:85]
	s_mov_b32 m0, s36
	ds_read_b128 v[164:167], v242 offset:49152
	ds_read_b128 v[168:171], v242 offset:50176
	ds_read_b128 v[172:175], v242 offset:51200
	ds_read_b128 v[176:179], v242 offset:52224
	ds_read_b128 v[180:183], v242 offset:53248
	ds_read_b128 v[184:187], v242 offset:54272
	ds_read_b128 v[188:191], v242 offset:55296
	ds_read_b128 v[214:217], v242 offset:56320
	global_load_lds_dwordx4 v[218:219], off
	s_add_i32 m0, s36, 0x2000
	s_add_u32 s26, s26, 0x100080
	v_lshl_add_u64 v[218:219], v[220:221], 0, s[84:85]
	s_addc_u32 s27, s27, 0
	s_add_i32 s36, s57, s40
	global_load_lds_dwordx4 v[218:219], off
	v_lshl_add_u64 v[218:219], s[26:27], 0, v[2:3]
	s_mov_b32 m0, s36
	s_nop 0
	global_load_lds_dwordx4 v[218:219], off
	v_lshl_add_u64 v[218:219], s[26:27], 0, v[204:205]
	s_add_i32 m0, s36, 0x2000
	s_nop 0
	global_load_lds_dwordx4 v[218:219], off
	v_lshl_add_u64 v[218:219], v[222:223], 0, s[84:85]
	s_mov_b32 m0, s45
	s_nop 0
	global_load_lds_dwordx4 v[218:219], off
	v_lshl_add_u64 v[218:219], v[224:225], 0, s[84:85]
	s_mov_b32 m0, s46
	s_nop 0
	global_load_lds_dwordx4 v[218:219], off
	s_waitcnt vmcnt(8)
	s_waitcnt lgkmcnt(0)
	s_barrier
	s_setprio 1
	s_waitcnt lgkmcnt(0)
	v_mfma_f32_16x16x32_bf16 v[64:67], v[124:127], v[164:167], v[64:67]
	v_mfma_f32_16x16x32_bf16 v[64:67], v[128:131], v[168:171], v[64:67]
	v_mfma_f32_16x16x32_bf16 v[48:51], v[128:131], v[176:179], v[48:51]
	v_mfma_f32_16x16x32_bf16 v[48:51], v[124:127], v[172:175], v[48:51]
	v_mfma_f32_16x16x32_bf16 v[32:35], v[124:127], v[180:183], v[32:35]
	v_mfma_f32_16x16x32_bf16 v[32:35], v[128:131], v[184:187], v[32:35]
	v_mfma_f32_16x16x32_bf16 v[16:19], v[128:131], v[214:217], v[16:19]
	v_mfma_f32_16x16x32_bf16 v[16:19], v[124:127], v[188:191], v[16:19]
	v_mfma_f32_16x16x32_bf16 v[12:15], v[132:135], v[188:191], v[12:15]
	v_mfma_f32_16x16x32_bf16 v[12:15], v[144:147], v[214:217], v[12:15]
	v_mfma_f32_16x16x32_bf16 v[28:31], v[144:147], v[184:187], v[28:31]
	v_mfma_f32_16x16x32_bf16 v[28:31], v[132:135], v[180:183], v[28:31]
	v_mfma_f32_16x16x32_bf16 v[44:47], v[132:135], v[172:175], v[44:47]
	v_mfma_f32_16x16x32_bf16 v[44:47], v[144:147], v[176:179], v[44:47]
	v_mfma_f32_16x16x32_bf16 v[60:63], v[144:147], v[168:171], v[60:63]
	v_mfma_f32_16x16x32_bf16 v[60:63], v[132:135], v[164:167], v[60:63]
	v_mfma_f32_16x16x32_bf16 v[56:59], v[148:151], v[164:167], v[56:59]
	v_mfma_f32_16x16x32_bf16 v[56:59], v[152:155], v[168:171], v[56:59]
	v_mfma_f32_16x16x32_bf16 v[40:43], v[152:155], v[176:179], v[40:43]
	v_mfma_f32_16x16x32_bf16 v[40:43], v[148:151], v[172:175], v[40:43]
	v_mfma_f32_16x16x32_bf16 v[24:27], v[148:151], v[180:183], v[24:27]
	v_mfma_f32_16x16x32_bf16 v[24:27], v[152:155], v[184:187], v[24:27]
	v_mfma_f32_16x16x32_bf16 v[8:11], v[152:155], v[214:217], v[8:11]
	v_mfma_f32_16x16x32_bf16 v[8:11], v[148:151], v[188:191], v[8:11]
	v_mfma_f32_16x16x32_bf16 v[4:7], v[156:159], v[188:191], v[4:7]
	v_mfma_f32_16x16x32_bf16 v[4:7], v[160:163], v[214:217], v[4:7]
	v_mfma_f32_16x16x32_bf16 v[20:23], v[160:163], v[184:187], v[20:23]
	v_mfma_f32_16x16x32_bf16 v[20:23], v[156:159], v[180:183], v[20:23]
	v_mfma_f32_16x16x32_bf16 v[36:39], v[156:159], v[172:175], v[36:39]
	v_mfma_f32_16x16x32_bf16 v[36:39], v[160:163], v[176:179], v[36:39]
	v_mfma_f32_16x16x32_bf16 v[52:55], v[160:163], v[168:171], v[52:55]
	v_mfma_f32_16x16x32_bf16 v[52:55], v[156:159], v[164:167], v[52:55]
	s_setprio 0
	s_barrier
	s_add_i32 s55, s55, 2
	s_add_u32 s24, s24, 0x100
	s_addc_u32 s25, s25, 0
	s_add_u32 s53, s53, 0x100
	s_addc_u32 s54, s54, 0
	s_cmp_gt_u32 s55, 61
	s_cbranch_scc1 .Lkloop_exit_2
.LBB0_1456:
	s_add_u32 s26, s24, 0xfff00080
	s_addc_u32 s27, s25, -1
	s_add_i32 s56, 0, 0x10000
	s_cmp_eq_u32 s55, 60
	s_cselect_b32 s37, s17, s27
	s_cselect_b32 s36, s51, s26
	s_cselect_b32 s27, s19, s54
	s_cselect_b32 s26, s52, s53
	s_add_i32 s58, 0, 0x14000
	v_add_u32_e32 v144, s56, v240
	v_add_u32_e32 v160, s58, v240
	ds_read_b128 v[124:127], v144
	ds_read_b128 v[128:131], v144 offset:1024
	ds_read_b128 v[132:135], v144 offset:2048
	ds_read_b128 v[144:147], v144 offset:3072
	ds_read_b128 v[148:151], v160
	ds_read_b128 v[152:155], v160 offset:1024
	ds_read_b128 v[156:159], v160 offset:2048
	ds_read_b128 v[160:163], v160 offset:3072
	v_lshl_add_u64 v[218:219], s[24:25], 0, v[210:211]
	s_add_i32 m0, s41, 0xc000
	ds_read_b128 v[164:167], v242
	ds_read_b128 v[168:171], v242 offset:1024
	ds_read_b128 v[172:175], v242 offset:2048
	ds_read_b128 v[176:179], v242 offset:3072
	ds_read_b128 v[180:183], v242 offset:4096
	ds_read_b128 v[184:187], v242 offset:5120
	ds_read_b128 v[188:191], v242 offset:6144
	ds_read_b128 v[214:217], v242 offset:7168
	global_load_lds_dwordx4 v[218:219], off
	v_lshl_add_u64 v[218:219], s[24:25], 0, v[212:213]
	s_add_i32 m0, s41, 0xe000
	s_nop 0
	global_load_lds_dwordx4 v[218:219], off
	s_waitcnt vmcnt(8)
	s_waitcnt lgkmcnt(0)
	s_barrier
; #define PG8_STAGE(bufoff, gbase, voff) do { _Pragma("unroll") for (int _i = 0; _i < 2; ++_i) \
;         __builtin_amdgcn_global_load_lds((const unsigned*)((const char*)(gbase) + (voff)[_i]), (PG8_LAS unsigned*)(lds + (bufoff) + ldsw + _i * 8192), 16, 0, 0); } while (0)
; #define PG8_LDA(dst, b, h) do { _Pragma("unroll") for (int m = 0; m < 4; ++m) _Pragma("unroll") for (int k = 0; k < 2; ++k) dst[m][k] = *(const PG8_LAS bf16x8*)(lds + PG8_SA(b, h) + aoff + m * 2048 + k * 1024); } while (0)
; #define PG8_LDB(dst, b, h) do { _Pragma("unroll") for (int n = 0; n < 2; ++n) _Pragma("unroll") for (int k = 0; k < 2; ++k) dst[n][k] = *(const PG8_LAS bf16x8*)(lds + PG8_SB(b, h) + boff + n * 2048 + k * 1024); } while (0)
; #define PG8_WAIT_V(n) asm volatile("s_waitcnt vmcnt(" #n ")" ::: "memory")
; #define PG8_WAIT_L(n) asm volatile("s_waitcnt lgkmcnt(" #n ")" ::: "memory")
; #define PG8_BAR __builtin_amdgcn_s_barrier()
; #define PG8_SCHED __builtin_amdgcn_sched_barrier(0)
; template <class Epi, class Sched, bool ALIGN_EPI = false, bool SP2 = false, bool I8 = false>
; __device__ __forceinline__ void gemm_phase(PG8_LAS unsigned char* lds, const Gemm g, const Sched& S, const Epi& E) {
;     ...
;             PG8_LDB(B0, 0, 0); PG8_LDB(B1, 0, 1); PG8_SCHED; PG8_LDA(At, 0, 0); PG8_STAGE(PG8_SA(1, 1), a1 + hstep, voffA);
;             PG8_WAIT_V(8); PG8_WAIT_L(0); PG8_BAR; PG8_MMA(0, 0, At, B0); PG8_MMA(0, 1, At, B1); PG8_BAR; PG8_SCHED;
;             PG8_LDA(At, 0, 1); PG8_STAGE(PG8_SB(0, 0), b2, voffB); PG8_STAGE(PG8_SB(0, 1), b2 + hstep, voffB); PG8_STAGE(PG8_SA(0, 0), a2, voffA);
;             PG8_WAIT_V(8); PG8_WAIT_L(0); PG8_BAR; PG8_MMA(1, 0, At, B0); PG8_MMA(1, 1, At, B1); PG8_BAR; PG8_SCHED;
	s_setprio 1
	s_waitcnt lgkmcnt(0)
	v_mfma_f32_16x16x32_bf16 v[140:143], v[124:127], v[164:167], v[140:143]
	v_mfma_f32_16x16x32_bf16 v[140:143], v[128:131], v[168:171], v[140:143]
	v_mfma_f32_16x16x32_bf16 v[112:115], v[128:131], v[176:179], v[112:115]
	v_mfma_f32_16x16x32_bf16 v[112:115], v[124:127], v[172:175], v[112:115]
	v_mfma_f32_16x16x32_bf16 v[96:99], v[124:127], v[180:183], v[96:99]
	v_mfma_f32_16x16x32_bf16 v[96:99], v[128:131], v[184:187], v[96:99]
	v_mfma_f32_16x16x32_bf16 v[80:83], v[128:131], v[214:217], v[80:83]
	v_mfma_f32_16x16x32_bf16 v[80:83], v[124:127], v[188:191], v[80:83]
	v_mfma_f32_16x16x32_bf16 v[76:79], v[132:135], v[188:191], v[76:79]
	v_mfma_f32_16x16x32_bf16 v[76:79], v[144:147], v[214:217], v[76:79]
	v_mfma_f32_16x16x32_bf16 v[92:95], v[144:147], v[184:187], v[92:95]
	v_mfma_f32_16x16x32_bf16 v[92:95], v[132:135], v[180:183], v[92:95]
	v_mfma_f32_16x16x32_bf16 v[108:111], v[132:135], v[172:175], v[108:111]
	v_mfma_f32_16x16x32_bf16 v[108:111], v[144:147], v[176:179], v[108:111]
	v_mfma_f32_16x16x32_bf16 v[136:139], v[144:147], v[168:171], v[136:139]
	v_mfma_f32_16x16x32_bf16 v[136:139], v[132:135], v[164:167], v[136:139]
	v_mfma_f32_16x16x32_bf16 v[120:123], v[148:151], v[164:167], v[120:123]
	v_mfma_f32_16x16x32_bf16 v[120:123], v[152:155], v[168:171], v[120:123]
	v_mfma_f32_16x16x32_bf16 v[104:107], v[152:155], v[176:179], v[104:107]
	v_mfma_f32_16x16x32_bf16 v[104:107], v[148:151], v[172:175], v[104:107]
	v_mfma_f32_16x16x32_bf16 v[88:91], v[148:151], v[180:183], v[88:91]
	v_mfma_f32_16x16x32_bf16 v[88:91], v[152:155], v[184:187], v[88:91]
	v_mfma_f32_16x16x32_bf16 v[72:75], v[152:155], v[214:217], v[72:75]
	v_mfma_f32_16x16x32_bf16 v[72:75], v[148:151], v[188:191], v[72:75]
	v_mfma_f32_16x16x32_bf16 v[68:71], v[156:159], v[188:191], v[68:71]
	v_mfma_f32_16x16x32_bf16 v[68:71], v[160:163], v[214:217], v[68:71]
	v_mfma_f32_16x16x32_bf16 v[84:87], v[160:163], v[184:187], v[84:87]
	v_mfma_f32_16x16x32_bf16 v[84:87], v[156:159], v[180:183], v[84:87]
	v_mfma_f32_16x16x32_bf16 v[100:103], v[156:159], v[172:175], v[100:103]
	v_mfma_f32_16x16x32_bf16 v[100:103], v[160:163], v[176:179], v[100:103]
	v_mfma_f32_16x16x32_bf16 v[116:119], v[160:163], v[168:171], v[116:119]
	v_mfma_f32_16x16x32_bf16 v[116:119], v[156:159], v[164:167], v[116:119]
	s_setprio 0
	s_barrier
	s_add_i32 s56, s56, s40
	v_lshl_add_u64 v[218:219], s[26:27], 0, v[2:3]
	s_mov_b32 m0, s56
	ds_read_b128 v[164:167], v242 offset:16384
	ds_read_b128 v[168:171], v242 offset:17408
	ds_read_b128 v[172:175], v242 offset:18432
	ds_read_b128 v[176:179], v242 offset:19456
	ds_read_b128 v[180:183], v242 offset:20480
	ds_read_b128 v[184:187], v242 offset:21504
	ds_read_b128 v[188:191], v242 offset:22528
	ds_read_b128 v[214:217], v242 offset:23552
	global_load_lds_dwordx4 v[218:219], off
	s_add_i32 m0, s56, 0x2000
	s_add_u32 s56, s26, 0x100000
	v_lshl_add_u64 v[220:221], s[26:27], 0, v[204:205]
	s_addc_u32 s57, s27, 0
	s_add_i32 s58, s58, s40
	global_load_lds_dwordx4 v[220:221], off
	v_lshl_add_u64 v[222:223], s[56:57], 0, v[2:3]
	s_mov_b32 m0, s58
	v_lshl_add_u64 v[224:225], s[36:37], 0, v[206:207]
	global_load_lds_dwordx4 v[222:223], off
	v_lshl_add_u64 v[222:223], s[56:57], 0, v[204:205]
	s_add_i32 m0, s58, 0x2000
	s_nop 0
	global_load_lds_dwordx4 v[222:223], off
	v_lshl_add_u64 v[222:223], s[36:37], 0, v[208:209]
	s_waitcnt vmcnt(6)
	s_waitcnt lgkmcnt(0)
	s_barrier
	s_setprio 1
	s_waitcnt lgkmcnt(0)
	v_mfma_f32_16x16x32_bf16 v[64:67], v[124:127], v[164:167], v[64:67]
	v_mfma_f32_16x16x32_bf16 v[64:67], v[128:131], v[168:171], v[64:67]
	v_mfma_f32_16x16x32_bf16 v[48:51], v[128:131], v[176:179], v[48:51]
	v_mfma_f32_16x16x32_bf16 v[48:51], v[124:127], v[172:175], v[48:51]
	v_mfma_f32_16x16x32_bf16 v[32:35], v[124:127], v[180:183], v[32:35]
	v_mfma_f32_16x16x32_bf16 v[32:35], v[128:131], v[184:187], v[32:35]
	v_mfma_f32_16x16x32_bf16 v[16:19], v[128:131], v[214:217], v[16:19]
	v_mfma_f32_16x16x32_bf16 v[16:19], v[124:127], v[188:191], v[16:19]
	v_mfma_f32_16x16x32_bf16 v[12:15], v[132:135], v[188:191], v[12:15]
	v_mfma_f32_16x16x32_bf16 v[12:15], v[144:147], v[214:217], v[12:15]
	v_mfma_f32_16x16x32_bf16 v[28:31], v[144:147], v[184:187], v[28:31]
	v_mfma_f32_16x16x32_bf16 v[28:31], v[132:135], v[180:183], v[28:31]
	v_mfma_f32_16x16x32_bf16 v[44:47], v[132:135], v[172:175], v[44:47]
	v_mfma_f32_16x16x32_bf16 v[44:47], v[144:147], v[176:179], v[44:47]
	v_mfma_f32_16x16x32_bf16 v[60:63], v[144:147], v[168:171], v[60:63]
	v_mfma_f32_16x16x32_bf16 v[60:63], v[132:135], v[164:167], v[60:63]
	v_mfma_f32_16x16x32_bf16 v[56:59], v[148:151], v[164:167], v[56:59]
	v_mfma_f32_16x16x32_bf16 v[56:59], v[152:155], v[168:171], v[56:59]
	v_mfma_f32_16x16x32_bf16 v[40:43], v[152:155], v[176:179], v[40:43]
	v_mfma_f32_16x16x32_bf16 v[40:43], v[148:151], v[172:175], v[40:43]
	v_mfma_f32_16x16x32_bf16 v[24:27], v[148:151], v[180:183], v[24:27]
	v_mfma_f32_16x16x32_bf16 v[24:27], v[152:155], v[184:187], v[24:27]
	v_mfma_f32_16x16x32_bf16 v[8:11], v[152:155], v[214:217], v[8:11]
	v_mfma_f32_16x16x32_bf16 v[8:11], v[148:151], v[188:191], v[8:11]
	v_mfma_f32_16x16x32_bf16 v[4:7], v[156:159], v[188:191], v[4:7]
	v_mfma_f32_16x16x32_bf16 v[4:7], v[160:163], v[214:217], v[4:7]
	v_mfma_f32_16x16x32_bf16 v[20:23], v[160:163], v[184:187], v[20:23]
	v_mfma_f32_16x16x32_bf16 v[20:23], v[156:159], v[180:183], v[20:23]
	v_mfma_f32_16x16x32_bf16 v[36:39], v[156:159], v[172:175], v[36:39]
	v_mfma_f32_16x16x32_bf16 v[36:39], v[160:163], v[176:179], v[36:39]
	v_mfma_f32_16x16x32_bf16 v[52:55], v[160:163], v[168:171], v[52:55]
	v_mfma_f32_16x16x32_bf16 v[52:55], v[156:159], v[164:167], v[52:55]
	s_setprio 0
	s_barrier
; #define PG8_STAGE(bufoff, gbase, voff) do { _Pragma("unroll") for (int _i = 0; _i < 2; ++_i) \
;         __builtin_amdgcn_global_load_lds((const unsigned*)((const char*)(gbase) + (voff)[_i]), (PG8_LAS unsigned*)(lds + (bufoff) + ldsw + _i * 8192), 16, 0, 0); } while (0)
; #define PG8_LDA(dst, b, h) do { _Pragma("unroll") for (int m = 0; m < 4; ++m) _Pragma("unroll") for (int k = 0; k < 2; ++k) dst[m][k] = *(const PG8_LAS bf16x8*)(lds + PG8_SA(b, h) + aoff + m * 2048 + k * 1024); } while (0)
; #define PG8_LDB(dst, b, h) do { _Pragma("unroll") for (int n = 0; n < 2; ++n) _Pragma("unroll") for (int k = 0; k < 2; ++k) dst[n][k] = *(const PG8_LAS bf16x8*)(lds + PG8_SB(b, h) + boff + n * 2048 + k * 1024); } while (0)
; #define PG8_WAIT_V(n) asm volatile("s_waitcnt vmcnt(" #n ")" ::: "memory")
; #define PG8_WAIT_L(n) asm volatile("s_waitcnt lgkmcnt(" #n ")" ::: "memory")
; #define PG8_BAR __builtin_amdgcn_s_barrier()
; #define PG8_SCHED __builtin_amdgcn_sched_barrier(0)
; template <class Epi, class Sched, bool ALIGN_EPI = false, bool SP2 = false, bool I8 = false>
; __device__ __forceinline__ void gemm_phase(PG8_LAS unsigned char* lds, const Gemm g, const Sched& S, const Epi& E) {
;     ...
;             PG8_LDA(At, 0, 1); PG8_STAGE(PG8_SB(0, 0), b2, voffB); PG8_STAGE(PG8_SB(0, 1), b2 + hstep, voffB); PG8_STAGE(PG8_SA(0, 0), a2, voffA);
;             PG8_WAIT_V(8); PG8_WAIT_L(0); PG8_BAR; PG8_MMA(1, 0, At, B0); PG8_MMA(1, 1, At, B1); PG8_BAR; PG8_SCHED;
;             PG8_LDB(B0, 1, 0); PG8_LDB(B1, 1, 1); PG8_SCHED; PG8_LDA(At, 1, 0); PG8_STAGE(PG8_SA(0, 1), a2 + hstep, voffA);
;             PG8_WAIT_V(8); PG8_WAIT_L(0); PG8_BAR; PG8_MMA(0, 0, At, B0); PG8_MMA(0, 1, At, B1); PG8_BAR; PG8_SCHED;
	s_mov_b32 m0, s41
	s_nop 0
	global_load_lds_dwordx4 v[222:223], off
	s_mov_b32 m0, s42
	s_nop 0
	global_load_lds_dwordx4 v[224:225], off
	s_add_i32 s56, 0, 0x18000
	s_add_i32 s57, 0, 0x1c000
	v_add_u32_e32 v144, s56, v240
	v_add_u32_e32 v160, s57, v240
	ds_read_b128 v[124:127], v144
	ds_read_b128 v[128:131], v144 offset:1024
	ds_read_b128 v[132:135], v144 offset:2048
	ds_read_b128 v[144:147], v144 offset:3072
	ds_read_b128 v[148:151], v160
	ds_read_b128 v[152:155], v160 offset:1024
	ds_read_b128 v[156:159], v160 offset:2048
	ds_read_b128 v[160:163], v160 offset:3072
	s_add_u32 s36, s36, 0x100000
	s_addc_u32 s37, s37, 0
	s_mov_b32 m0, s43
	v_lshl_add_u64 v[226:227], s[36:37], 0, v[208:209]
	ds_read_b128 v[164:167], v242 offset:32768
	ds_read_b128 v[168:171], v242 offset:33792
	ds_read_b128 v[172:175], v242 offset:34816
	ds_read_b128 v[176:179], v242 offset:35840
	ds_read_b128 v[180:183], v242 offset:36864
	ds_read_b128 v[184:187], v242 offset:37888
	ds_read_b128 v[188:191], v242 offset:38912
	ds_read_b128 v[214:217], v242 offset:39936
	global_load_lds_dwordx4 v[226:227], off
	v_lshl_add_u64 v[226:227], s[36:37], 0, v[206:207]
	s_mov_b32 m0, s44
	s_nop 0
	global_load_lds_dwordx4 v[226:227], off
	s_waitcnt vmcnt(8)
	s_waitcnt lgkmcnt(0)
	s_barrier
	s_setprio 1
	s_waitcnt lgkmcnt(0)
	v_mfma_f32_16x16x32_bf16 v[140:143], v[124:127], v[164:167], v[140:143]
	v_mfma_f32_16x16x32_bf16 v[140:143], v[128:131], v[168:171], v[140:143]
	v_mfma_f32_16x16x32_bf16 v[112:115], v[128:131], v[176:179], v[112:115]
	v_mfma_f32_16x16x32_bf16 v[112:115], v[124:127], v[172:175], v[112:115]
	v_mfma_f32_16x16x32_bf16 v[96:99], v[124:127], v[180:183], v[96:99]
	v_mfma_f32_16x16x32_bf16 v[96:99], v[128:131], v[184:187], v[96:99]
	v_mfma_f32_16x16x32_bf16 v[80:83], v[128:131], v[214:217], v[80:83]
	v_mfma_f32_16x16x32_bf16 v[80:83], v[124:127], v[188:191], v[80:83]
	v_mfma_f32_16x16x32_bf16 v[76:79], v[132:135], v[188:191], v[76:79]
	v_mfma_f32_16x16x32_bf16 v[76:79], v[144:147], v[214:217], v[76:79]
	v_mfma_f32_16x16x32_bf16 v[92:95], v[144:147], v[184:187], v[92:95]
	v_mfma_f32_16x16x32_bf16 v[92:95], v[132:135], v[180:183], v[92:95]
	v_mfma_f32_16x16x32_bf16 v[108:111], v[132:135], v[172:175], v[108:111]
	v_mfma_f32_16x16x32_bf16 v[108:111], v[144:147], v[176:179], v[108:111]
	v_mfma_f32_16x16x32_bf16 v[136:139], v[144:147], v[168:171], v[136:139]
	v_mfma_f32_16x16x32_bf16 v[136:139], v[132:135], v[164:167], v[136:139]
	v_mfma_f32_16x16x32_bf16 v[120:123], v[148:151], v[164:167], v[120:123]
	v_mfma_f32_16x16x32_bf16 v[120:123], v[152:155], v[168:171], v[120:123]
	v_mfma_f32_16x16x32_bf16 v[104:107], v[152:155], v[176:179], v[104:107]
	v_mfma_f32_16x16x32_bf16 v[104:107], v[148:151], v[172:175], v[104:107]
	v_mfma_f32_16x16x32_bf16 v[88:91], v[148:151], v[180:183], v[88:91]
	v_mfma_f32_16x16x32_bf16 v[88:91], v[152:155], v[184:187], v[88:91]
	v_mfma_f32_16x16x32_bf16 v[72:75], v[152:155], v[214:217], v[72:75]
	v_mfma_f32_16x16x32_bf16 v[72:75], v[148:151], v[188:191], v[72:75]
	v_mfma_f32_16x16x32_bf16 v[68:71], v[156:159], v[188:191], v[68:71]
	v_mfma_f32_16x16x32_bf16 v[68:71], v[160:163], v[214:217], v[68:71]
	v_mfma_f32_16x16x32_bf16 v[84:87], v[160:163], v[184:187], v[84:87]
	v_mfma_f32_16x16x32_bf16 v[84:87], v[156:159], v[180:183], v[84:87]
	v_mfma_f32_16x16x32_bf16 v[100:103], v[156:159], v[172:175], v[100:103]
	v_mfma_f32_16x16x32_bf16 v[100:103], v[160:163], v[176:179], v[100:103]
	v_mfma_f32_16x16x32_bf16 v[116:119], v[160:163], v[168:171], v[116:119]
	v_mfma_f32_16x16x32_bf16 v[116:119], v[156:159], v[164:167], v[116:119]
	s_setprio 0
	s_barrier
; #define PG8_STAGE(bufoff, gbase, voff) do { _Pragma("unroll") for (int _i = 0; _i < 2; ++_i) \
;         __builtin_amdgcn_global_load_lds((const unsigned*)((const char*)(gbase) + (voff)[_i]), (PG8_LAS unsigned*)(lds + (bufoff) + ldsw + _i * 8192), 16, 0, 0); } while (0)
; #define PG8_LDA(dst, b, h) do { _Pragma("unroll") for (int m = 0; m < 4; ++m) _Pragma("unroll") for (int k = 0; k < 2; ++k) dst[m][k] = *(const PG8_LAS bf16x8*)(lds + PG8_SA(b, h) + aoff + m * 2048 + k * 1024); } while (0)
; #define PG8_WAIT_V(n) asm volatile("s_waitcnt vmcnt(" #n ")" ::: "memory")
; #define PG8_WAIT_L(n) asm volatile("s_waitcnt lgkmcnt(" #n ")" ::: "memory")
; #define PG8_BAR __builtin_amdgcn_s_barrier()
; template <class Epi, class Sched, bool ALIGN_EPI = false, bool SP2 = false, bool I8 = false>
; __device__ __forceinline__ void gemm_phase(PG8_LAS unsigned char* lds, const Gemm g, const Sched& S, const Epi& E) {
;     ...
;         for (int t = 0; t < nt; t += 2) {
;             const bool last = (t == nt - 2);
;             const char* a1 = cA + (size_t)(t + 1) * kstep;
;             const char* a2 = last ? nA : cA + (size_t)(t + 2) * kstep; const char* b2 = last ? nB : cB + (size_t)(t + 2) * kstep;
;             const char* a3 = a2 + kstep; const char* b3 = b2 + kstep;
;             if (last && has_next) S.a_ready(nxt);
;             if constexpr (SP2) {
;             PG8_LDB(B0, 0, 0); PG8_LDB(B1, 0, 1); PG8_SCHED; PG8_LDA(At, 0, 0); PG8_STAGE(PG8_SA(1, 1), a1 + hstep, voffA);
;             PG8_WAIT_V(8); PG8_WAIT_L(0); PG8_BAR; PG8_MMA(0, 0, At, B0); PG8_MMA(0, 1, At, B1); PG8_BAR; PG8_SCHED;
;             PG8_LDA(At, 0, 1); PG8_STAGE(PG8_SB(0, 0), b2, voffB); PG8_STAGE(PG8_SB(0, 1), b2 + hstep, voffB); PG8_STAGE(PG8_SA(0, 0), a2, voffA);
;             PG8_WAIT_V(8); PG8_WAIT_L(0); PG8_BAR; PG8_MMA(1, 0, At, B0); PG8_MMA(1, 1, At, B1); PG8_BAR; PG8_SCHED;
;             PG8_LDB(B0, 1, 0); PG8_LDB(B1, 1, 1); PG8_SCHED; PG8_LDA(At, 1, 0); PG8_STAGE(PG8_SA(0, 1), a2 + hstep, voffA);
;             PG8_WAIT_V(8); PG8_WAIT_L(0); PG8_BAR; PG8_MMA(0, 0, At, B0); PG8_MMA(0, 1, At, B1); PG8_BAR; PG8_SCHED;
;             PG8_LDA(At, 1, 1); PG8_STAGE(PG8_SB(1, 0), b3, voffB); PG8_STAGE(PG8_SB(1, 1), b3 + hstep, voffB); PG8_STAGE(PG8_SA(1, 0), a3, voffA);
;             PG8_WAIT_V(8); PG8_WAIT_L(0); PG8_BAR; PG8_MMA(1, 0, At, B0); PG8_MMA(1, 1, At, B1); PG8_BAR; PG8_SCHED;
	s_add_i32 s36, s56, s40
	v_lshl_add_u64 v[218:219], v[218:219], 0, s[84:85]
	s_mov_b32 m0, s36
	ds_read_b128 v[164:167], v242 offset:49152
	ds_read_b128 v[168:171], v242 offset:50176
	ds_read_b128 v[172:175], v242 offset:51200
	ds_read_b128 v[176:179], v242 offset:52224
	ds_read_b128 v[180:183], v242 offset:53248
	ds_read_b128 v[184:187], v242 offset:54272
	ds_read_b128 v[188:191], v242 offset:55296
	ds_read_b128 v[214:217], v242 offset:56320
	global_load_lds_dwordx4 v[218:219], off
	s_add_i32 m0, s36, 0x2000
	s_add_u32 s26, s26, 0x100080
	v_lshl_add_u64 v[218:219], v[220:221], 0, s[84:85]
	s_addc_u32 s27, s27, 0
	s_add_i32 s36, s57, s40
	global_load_lds_dwordx4 v[218:219], off
	v_lshl_add_u64 v[218:219], s[26:27], 0, v[2:3]
	s_mov_b32 m0, s36
	s_nop 0
	global_load_lds_dwordx4 v[218:219], off
	v_lshl_add_u64 v[218:219], s[26:27], 0, v[204:205]
	s_add_i32 m0, s36, 0x2000
	s_nop 0
	global_load_lds_dwordx4 v[218:219], off
	v_lshl_add_u64 v[218:219], v[222:223], 0, s[84:85]
	s_mov_b32 m0, s45
	s_nop 0
	global_load_lds_dwordx4 v[218:219], off
	v_lshl_add_u64 v[218:219], v[224:225], 0, s[84:85]
	s_mov_b32 m0, s46
	s_nop 0
	global_load_lds_dwordx4 v[218:219], off
	s_waitcnt vmcnt(8)
	s_waitcnt lgkmcnt(0)
	s_barrier
	s_setprio 1
	s_waitcnt lgkmcnt(0)
	v_mfma_f32_16x16x32_bf16 v[64:67], v[124:127], v[164:167], v[64:67]
	v_mfma_f32_16x16x32_bf16 v[64:67], v[128:131], v[168:171], v[64:67]
	v_mfma_f32_16x16x32_bf16 v[48:51], v[128:131], v[176:179], v[48:51]
	v_mfma_f32_16x16x32_bf16 v[48:51], v[124:127], v[172:175], v[48:51]
	v_mfma_f32_16x16x32_bf16 v[32:35], v[124:127], v[180:183], v[32:35]
	v_mfma_f32_16x16x32_bf16 v[32:35], v[128:131], v[184:187], v[32:35]
	v_mfma_f32_16x16x32_bf16 v[16:19], v[128:131], v[214:217], v[16:19]
	v_mfma_f32_16x16x32_bf16 v[16:19], v[124:127], v[188:191], v[16:19]
	v_mfma_f32_16x16x32_bf16 v[12:15], v[132:135], v[188:191], v[12:15]
	v_mfma_f32_16x16x32_bf16 v[12:15], v[144:147], v[214:217], v[12:15]
	v_mfma_f32_16x16x32_bf16 v[28:31], v[144:147], v[184:187], v[28:31]
	v_mfma_f32_16x16x32_bf16 v[28:31], v[132:135], v[180:183], v[28:31]
	v_mfma_f32_16x16x32_bf16 v[44:47], v[132:135], v[172:175], v[44:47]
	v_mfma_f32_16x16x32_bf16 v[44:47], v[144:147], v[176:179], v[44:47]
	v_mfma_f32_16x16x32_bf16 v[60:63], v[144:147], v[168:171], v[60:63]
	v_mfma_f32_16x16x32_bf16 v[60:63], v[132:135], v[164:167], v[60:63]
	v_mfma_f32_16x16x32_bf16 v[56:59], v[148:151], v[164:167], v[56:59]
	v_mfma_f32_16x16x32_bf16 v[56:59], v[152:155], v[168:171], v[56:59]
	v_mfma_f32_16x16x32_bf16 v[40:43], v[152:155], v[176:179], v[40:43]
	v_mfma_f32_16x16x32_bf16 v[40:43], v[148:151], v[172:175], v[40:43]
	v_mfma_f32_16x16x32_bf16 v[24:27], v[148:151], v[180:183], v[24:27]
	v_mfma_f32_16x16x32_bf16 v[24:27], v[152:155], v[184:187], v[24:27]
	v_mfma_f32_16x16x32_bf16 v[8:11], v[152:155], v[214:217], v[8:11]
	v_mfma_f32_16x16x32_bf16 v[8:11], v[148:151], v[188:191], v[8:11]
	v_mfma_f32_16x16x32_bf16 v[4:7], v[156:159], v[188:191], v[4:7]
	v_mfma_f32_16x16x32_bf16 v[4:7], v[160:163], v[214:217], v[4:7]
	v_mfma_f32_16x16x32_bf16 v[20:23], v[160:163], v[184:187], v[20:23]
	v_mfma_f32_16x16x32_bf16 v[20:23], v[156:159], v[180:183], v[20:23]
	v_mfma_f32_16x16x32_bf16 v[36:39], v[156:159], v[172:175], v[36:39]
	v_mfma_f32_16x16x32_bf16 v[36:39], v[160:163], v[176:179], v[36:39]
	v_mfma_f32_16x16x32_bf16 v[52:55], v[160:163], v[168:171], v[52:55]
	v_mfma_f32_16x16x32_bf16 v[52:55], v[156:159], v[164:167], v[52:55]
	s_setprio 0
	s_barrier
	s_add_i32 s55, s55, 2
	s_add_u32 s24, s24, 0x100
	s_addc_u32 s25, s25, 0
	s_add_u32 s53, s53, 0x100
	s_addc_u32 s54, s54, 0
	s_cmp_gt_u32 s55, 61
	s_cbranch_scc0 .LBB0_1456

; #define PG8_STAGE(bufoff, gbase, voff) do { _Pragma("unroll") for (int _i = 0; _i < 2; ++_i) \
;         __builtin_amdgcn_global_load_lds((const unsigned*)((const char*)(gbase) + (voff)[_i]), (PG8_LAS unsigned*)(lds + (bufoff) + ldsw + _i * 8192), 16, 0, 0); } while (0)
; #define PG8_LDA(dst, b, h) do { _Pragma("unroll") for (int m = 0; m < 4; ++m) _Pragma("unroll") for (int k = 0; k < 2; ++k) dst[m][k] = *(const PG8_LAS bf16x8*)(lds + PG8_SA(b, h) + aoff + m * 2048 + k * 1024); } while (0)
; #define PG8_LDB(dst, b, h) do { _Pragma("unroll") for (int n = 0; n < 2; ++n) _Pragma("unroll") for (int k = 0; k < 2; ++k) dst[n][k] = *(const PG8_LAS bf16x8*)(lds + PG8_SB(b, h) + boff + n * 2048 + k * 1024); } while (0)
; #define PG8_WAIT_V(n) asm volatile("s_waitcnt vmcnt(" #n ")" ::: "memory")
; #define PG8_WAIT_L(n) asm volatile("s_waitcnt lgkmcnt(" #n ")" ::: "memory")
; #define PG8_BAR __builtin_amdgcn_s_barrier()
; #define PG8_SCHED __builtin_amdgcn_sched_barrier(0)
; template <class Epi, class Sched, bool ALIGN_EPI = false, bool SP2 = false, bool I8 = false>
; __device__ __forceinline__ void gemm_phase(PG8_LAS unsigned char* lds, const Gemm g, const Sched& S, const Epi& E) {
;     ...
;         const bool has_next = S.next(ui + 1, nxt);
;         const char* nA = has_next ? (const char*)g.A + (size_t)nxt.pm * tstep : cA; const char* nB = has_next ? (const char*)g.Bt + (size_t)nxt.pn * tstep : cB;
;         for (int t = 0; t < nt; t += 2) {
;             const bool last = (t == nt - 2);
;             const char* a1 = cA + (size_t)(t + 1) * kstep;
;             const char* a2 = last ? nA : cA + (size_t)(t + 2) * kstep; const char* b2 = last ? nB : cB + (size_t)(t + 2) * kstep;
;             const char* a3 = a2 + kstep; const char* b3 = b2 + kstep;
;             if (last && has_next) S.a_ready(nxt);
;             if constexpr (SP2) {
;             PG8_LDB(B0, 0, 0); PG8_LDB(B1, 0, 1); PG8_SCHED; PG8_LDA(At, 0, 0); PG8_STAGE(PG8_SA(1, 1), a1 + hstep, voffA);
;             PG8_WAIT_V(8); PG8_WAIT_L(0); PG8_BAR; PG8_MMA(0, 0, At, B0); PG8_MMA(0, 1, At, B1); PG8_BAR; PG8_SCHED;
;             PG8_LDA(At, 0, 1); PG8_STAGE(PG8_SB(0, 0), b2, voffB); PG8_STAGE(PG8_SB(0, 1), b2 + hstep, voffB); PG8_STAGE(PG8_SA(0, 0), a2, voffA);
;             PG8_WAIT_V(8); PG8_WAIT_L(0); PG8_BAR; PG8_MMA(1, 0, At, B0); PG8_MMA(1, 1, At, B1); PG8_BAR; PG8_SCHED;
.LBB0_1590:
	s_ashr_i32 s25, s24, 31
	s_lshl_b64 s[26:27], s[24:25], 20
	s_add_u32 s26, s28, s26
	s_addc_u32 s27, s42, s27
	s_and_b64 s[36:37], s[10:11], exec
	s_cselect_b32 s25, s27, s41
	s_cselect_b32 s57, s26, s40
	s_ashr_i32 s23, s22, 31
	s_lshl_b64 s[36:37], s[22:23], 20
	s_add_u32 s36, s43, s36
	s_addc_u32 s37, s46, s37
	s_and_b64 s[48:49], s[10:11], exec
	s_cselect_b32 s23, s37, s45
	s_cselect_b32 s58, s36, s44
	s_add_u32 s40, s40, 0x80080
	s_addc_u32 s41, s41, 0
	s_add_u32 s59, s44, 0x100
	s_addc_u32 s60, s45, 0
	s_mov_b32 s61, -2
	s_add_u32 s44, s40, 0xfff80080
	s_addc_u32 s45, s41, -1
	s_add_i32 s64, 0, 0x10000
	s_cmp_eq_u32 s61, 28
	s_cselect_b32 s49, s25, s45
	s_cselect_b32 s48, s57, s44
	s_cselect_b32 s45, s23, s60
	s_cselect_b32 s44, s58, s59
	s_add_i32 s67, 0, 0x14000
	v_add_u32_e32 v144, s64, v167
	v_add_u32_e32 v158, s67, v167
	ds_read_b128 v[36:39], v144
	ds_read_b128 v[44:47], v144 offset:1024
	ds_read_b128 v[140:143], v144 offset:2048
	ds_read_b128 v[144:147], v144 offset:3072
	ds_read_b128 v[160:163], v158
	ds_read_b128 v[172:175], v158 offset:1024
	ds_read_b128 v[176:179], v158 offset:2048
	ds_read_b128 v[180:183], v158 offset:3072
	v_lshl_add_u64 v[164:165], s[40:41], 0, v[154:155]
	s_add_i32 m0, s50, 0xc000
	ds_read_b128 v[184:187], v171
	ds_read_b128 v[188:191], v171 offset:1024
	ds_read_b128 v[204:207], v171 offset:2048
	ds_read_b128 v[208:211], v171 offset:3072
	ds_read_b128 v[212:215], v171 offset:4096
	ds_read_b128 v[216:219], v171 offset:5120
	ds_read_b128 v[220:223], v171 offset:6144
	ds_read_b128 v[224:227], v171 offset:7168
	global_load_lds_dwordx4 v[164:165], off
	v_lshl_add_u64 v[164:165], s[40:41], 0, v[156:157]
	s_add_i32 m0, s50, 0xe000
	s_nop 0
	global_load_lds_dwordx4 v[164:165], off
	s_waitcnt vmcnt(8)
	s_waitcnt lgkmcnt(0)
	s_barrier
	s_setprio 1
	s_waitcnt lgkmcnt(0)
	v_mfma_i32_16x16x64_i8 v[136:139], v[36:39], v[184:187], 0
	v_mfma_i32_16x16x64_i8 v[136:139], v[44:47], v[188:191], v[136:139]
	v_mfma_i32_16x16x64_i8 v[120:123], v[44:47], v[208:211], 0
	v_mfma_i32_16x16x64_i8 v[120:123], v[36:39], v[204:207], v[120:123]
	v_mfma_i32_16x16x64_i8 v[104:107], v[36:39], v[212:215], 0
	v_mfma_i32_16x16x64_i8 v[104:107], v[44:47], v[216:219], v[104:107]
	v_mfma_i32_16x16x64_i8 v[88:91], v[44:47], v[224:227], 0
	v_mfma_i32_16x16x64_i8 v[88:91], v[36:39], v[220:223], v[88:91]
	v_mfma_i32_16x16x64_i8 v[80:83], v[140:143], v[220:223], 0
	v_mfma_i32_16x16x64_i8 v[80:83], v[144:147], v[224:227], v[80:83]
	v_mfma_i32_16x16x64_i8 v[96:99], v[144:147], v[216:219], 0
	v_mfma_i32_16x16x64_i8 v[96:99], v[140:143], v[212:215], v[96:99]
	v_mfma_i32_16x16x64_i8 v[112:115], v[140:143], v[204:207], 0
	v_mfma_i32_16x16x64_i8 v[112:115], v[144:147], v[208:211], v[112:115]
	v_mfma_i32_16x16x64_i8 v[128:131], v[144:147], v[188:191], 0
	v_mfma_i32_16x16x64_i8 v[128:131], v[140:143], v[184:187], v[128:131]
	v_mfma_i32_16x16x64_i8 v[132:135], v[160:163], v[184:187], 0
	v_mfma_i32_16x16x64_i8 v[132:135], v[172:175], v[188:191], v[132:135]
	v_mfma_i32_16x16x64_i8 v[116:119], v[172:175], v[208:211], 0
	v_mfma_i32_16x16x64_i8 v[116:119], v[160:163], v[204:207], v[116:119]
	v_mfma_i32_16x16x64_i8 v[100:103], v[160:163], v[212:215], 0
	v_mfma_i32_16x16x64_i8 v[100:103], v[172:175], v[216:219], v[100:103]
	v_mfma_i32_16x16x64_i8 v[84:87], v[172:175], v[224:227], 0
	v_mfma_i32_16x16x64_i8 v[84:87], v[160:163], v[220:223], v[84:87]
	v_mfma_i32_16x16x64_i8 v[76:79], v[176:179], v[220:223], 0
	v_mfma_i32_16x16x64_i8 v[76:79], v[180:183], v[224:227], v[76:79]
	v_mfma_i32_16x16x64_i8 v[92:95], v[180:183], v[216:219], 0
	v_mfma_i32_16x16x64_i8 v[92:95], v[176:179], v[212:215], v[92:95]
	v_mfma_i32_16x16x64_i8 v[108:111], v[176:179], v[204:207], 0
	v_mfma_i32_16x16x64_i8 v[108:111], v[180:183], v[208:211], v[108:111]
	v_mfma_i32_16x16x64_i8 v[124:127], v[180:183], v[188:191], 0
	v_mfma_i32_16x16x64_i8 v[124:127], v[176:179], v[184:187], v[124:127]
	s_setprio 0
	s_barrier
	s_add_i32 s64, s64, s47
	v_lshl_add_u64 v[164:165], s[44:45], 0, v[2:3]
	s_mov_b32 m0, s64
	ds_read_b128 v[184:187], v171 offset:16384
	ds_read_b128 v[188:191], v171 offset:17408
	ds_read_b128 v[204:207], v171 offset:18432
	ds_read_b128 v[208:211], v171 offset:19456
	ds_read_b128 v[212:215], v171 offset:20480
	ds_read_b128 v[216:219], v171 offset:21504
	ds_read_b128 v[220:223], v171 offset:22528
	ds_read_b128 v[224:227], v171 offset:23552
	global_load_lds_dwordx4 v[164:165], off
	s_add_i32 m0, s64, 0x2000
	s_add_u32 s64, s44, 0x80000
	v_lshl_add_u64 v[228:229], s[44:45], 0, v[148:149]
	s_addc_u32 s65, s45, 0
	s_add_i32 s67, s67, s47
	global_load_lds_dwordx4 v[228:229], off
	v_lshl_add_u64 v[240:241], s[64:65], 0, v[2:3]
	s_mov_b32 m0, s67
	v_lshl_add_u64 v[242:243], s[48:49], 0, v[150:151]
	global_load_lds_dwordx4 v[240:241], off
	v_lshl_add_u64 v[240:241], s[64:65], 0, v[148:149]
	s_add_i32 m0, s67, 0x2000
	s_nop 0
	global_load_lds_dwordx4 v[240:241], off
	v_lshl_add_u64 v[240:241], s[48:49], 0, v[152:153]
	s_waitcnt vmcnt(6)
	s_waitcnt lgkmcnt(0)
	s_barrier
; #define PG8_STAGE(bufoff, gbase, voff) do { _Pragma("unroll") for (int _i = 0; _i < 2; ++_i) \
;         __builtin_amdgcn_global_load_lds((const unsigned*)((const char*)(gbase) + (voff)[_i]), (PG8_LAS unsigned*)(lds + (bufoff) + ldsw + _i * 8192), 16, 0, 0); } while (0)
; #define PG8_LDA(dst, b, h) do { _Pragma("unroll") for (int m = 0; m < 4; ++m) _Pragma("unroll") for (int k = 0; k < 2; ++k) dst[m][k] = *(const PG8_LAS bf16x8*)(lds + PG8_SA(b, h) + aoff + m * 2048 + k * 1024); } while (0)
; #define PG8_LDB(dst, b, h) do { _Pragma("unroll") for (int n = 0; n < 2; ++n) _Pragma("unroll") for (int k = 0; k < 2; ++k) dst[n][k] = *(const PG8_LAS bf16x8*)(lds + PG8_SB(b, h) + boff + n * 2048 + k * 1024); } while (0)
; #define PG8_WAIT_V(n) asm volatile("s_waitcnt vmcnt(" #n ")" ::: "memory")
; #define PG8_WAIT_L(n) asm volatile("s_waitcnt lgkmcnt(" #n ")" ::: "memory")
; #define PG8_BAR __builtin_amdgcn_s_barrier()
; #define PG8_SCHED __builtin_amdgcn_sched_barrier(0)
; template <class Epi, class Sched, bool ALIGN_EPI = false, bool SP2 = false, bool I8 = false>
; __device__ __forceinline__ void gemm_phase(PG8_LAS unsigned char* lds, const Gemm g, const Sched& S, const Epi& E) {
;     ...
;             PG8_WAIT_V(8); PG8_WAIT_L(0); PG8_BAR; PG8_MMA(0, 0, At, B0); PG8_MMA(0, 1, At, B1); PG8_BAR; PG8_SCHED;
;             PG8_LDA(At, 0, 1); PG8_STAGE(PG8_SB(0, 0), b2, voffB); PG8_STAGE(PG8_SB(0, 1), b2 + hstep, voffB); PG8_STAGE(PG8_SA(0, 0), a2, voffA);
;             PG8_WAIT_V(8); PG8_WAIT_L(0); PG8_BAR; PG8_MMA(1, 0, At, B0); PG8_MMA(1, 1, At, B1); PG8_BAR; PG8_SCHED;
;             PG8_LDB(B0, 1, 0); PG8_LDB(B1, 1, 1); PG8_SCHED; PG8_LDA(At, 1, 0); PG8_STAGE(PG8_SA(0, 1), a2 + hstep, voffA);
;             PG8_WAIT_V(8); PG8_WAIT_L(0); PG8_BAR; PG8_MMA(0, 0, At, B0); PG8_MMA(0, 1, At, B1); PG8_BAR; PG8_SCHED;
	s_setprio 1
	s_waitcnt lgkmcnt(0)
	v_mfma_i32_16x16x64_i8 v[72:75], v[36:39], v[184:187], 0
	v_mfma_i32_16x16x64_i8 v[72:75], v[44:47], v[188:191], v[72:75]
	v_mfma_i32_16x16x64_i8 v[56:59], v[44:47], v[208:211], 0
	v_mfma_i32_16x16x64_i8 v[56:59], v[36:39], v[204:207], v[56:59]
	v_mfma_i32_16x16x64_i8 v[32:35], v[36:39], v[212:215], 0
	v_mfma_i32_16x16x64_i8 v[32:35], v[44:47], v[216:219], v[32:35]
	v_mfma_i32_16x16x64_i8 v[16:19], v[44:47], v[224:227], 0
	v_mfma_i32_16x16x64_i8 v[16:19], v[36:39], v[220:223], v[16:19]
	v_mfma_i32_16x16x64_i8 v[8:11], v[140:143], v[220:223], 0
	v_mfma_i32_16x16x64_i8 v[8:11], v[144:147], v[224:227], v[8:11]
	v_mfma_i32_16x16x64_i8 v[24:27], v[144:147], v[216:219], 0
	v_mfma_i32_16x16x64_i8 v[24:27], v[140:143], v[212:215], v[24:27]
	v_mfma_i32_16x16x64_i8 v[48:51], v[140:143], v[204:207], 0
	v_mfma_i32_16x16x64_i8 v[48:51], v[144:147], v[208:211], v[48:51]
	v_mfma_i32_16x16x64_i8 v[64:67], v[144:147], v[188:191], 0
	v_mfma_i32_16x16x64_i8 v[64:67], v[140:143], v[184:187], v[64:67]
	v_mfma_i32_16x16x64_i8 v[36:39], v[160:163], v[184:187], 0
	v_mfma_i32_16x16x64_i8 v[36:39], v[172:175], v[188:191], v[36:39]
	v_mfma_i32_16x16x64_i8 v[52:55], v[172:175], v[208:211], 0
	v_mfma_i32_16x16x64_i8 v[52:55], v[160:163], v[204:207], v[52:55]
	v_mfma_i32_16x16x64_i8 v[28:31], v[160:163], v[212:215], 0
	v_mfma_i32_16x16x64_i8 v[28:31], v[172:175], v[216:219], v[28:31]
	v_mfma_i32_16x16x64_i8 v[12:15], v[172:175], v[224:227], 0
	v_mfma_i32_16x16x64_i8 v[12:15], v[160:163], v[220:223], v[12:15]
	v_mfma_i32_16x16x64_i8 v[4:7], v[176:179], v[220:223], 0
	v_mfma_i32_16x16x64_i8 v[4:7], v[180:183], v[224:227], v[4:7]
	v_mfma_i32_16x16x64_i8 v[20:23], v[180:183], v[216:219], 0
	v_mfma_i32_16x16x64_i8 v[20:23], v[176:179], v[212:215], v[20:23]
	v_mfma_i32_16x16x64_i8 v[40:43], v[176:179], v[204:207], 0
	v_mfma_i32_16x16x64_i8 v[40:43], v[180:183], v[208:211], v[40:43]
	v_mfma_i32_16x16x64_i8 v[44:47], v[180:183], v[188:191], 0
	v_mfma_i32_16x16x64_i8 v[44:47], v[176:179], v[184:187], v[44:47]
	s_setprio 0
	s_barrier
	s_mov_b32 m0, s50
	s_nop 0
	global_load_lds_dwordx4 v[240:241], off
	s_mov_b32 m0, s51
	s_nop 0
	global_load_lds_dwordx4 v[242:243], off
	s_add_i32 s64, 0, 0x18000
	s_add_i32 s65, 0, 0x1c000
	v_add_u32_e32 v144, s64, v167
	v_add_u32_e32 v158, s65, v167
	ds_read_b128 v[60:63], v144
	ds_read_b128 v[68:71], v144 offset:1024
	ds_read_b128 v[140:143], v144 offset:2048
	ds_read_b128 v[144:147], v144 offset:3072
	ds_read_b128 v[160:163], v158
	ds_read_b128 v[172:175], v158 offset:1024
	ds_read_b128 v[176:179], v158 offset:2048
	ds_read_b128 v[180:183], v158 offset:3072
	s_add_u32 s48, s48, 0x80000
	s_addc_u32 s49, s49, 0
	s_mov_b32 m0, s52
	v_lshl_add_u64 v[244:245], s[48:49], 0, v[152:153]
	ds_read_b128 v[184:187], v171 offset:32768
	ds_read_b128 v[188:191], v171 offset:33792
	ds_read_b128 v[204:207], v171 offset:34816
	ds_read_b128 v[208:211], v171 offset:35840
	ds_read_b128 v[212:215], v171 offset:36864
	ds_read_b128 v[216:219], v171 offset:37888
	ds_read_b128 v[220:223], v171 offset:38912
	ds_read_b128 v[224:227], v171 offset:39936
	global_load_lds_dwordx4 v[244:245], off
	v_lshl_add_u64 v[244:245], s[48:49], 0, v[150:151]
	s_mov_b32 m0, s53
	s_nop 0
	global_load_lds_dwordx4 v[244:245], off
	s_waitcnt vmcnt(8)
	s_waitcnt lgkmcnt(0)
	s_barrier
	s_setprio 1
	s_waitcnt lgkmcnt(0)
	v_mfma_i32_16x16x64_i8 v[136:139], v[60:63], v[184:187], v[136:139]
	v_mfma_i32_16x16x64_i8 v[136:139], v[68:71], v[188:191], v[136:139]
	v_mfma_i32_16x16x64_i8 v[120:123], v[68:71], v[208:211], v[120:123]
	v_mfma_i32_16x16x64_i8 v[120:123], v[60:63], v[204:207], v[120:123]
	v_mfma_i32_16x16x64_i8 v[104:107], v[60:63], v[212:215], v[104:107]
	v_mfma_i32_16x16x64_i8 v[104:107], v[68:71], v[216:219], v[104:107]
	v_mfma_i32_16x16x64_i8 v[88:91], v[68:71], v[224:227], v[88:91]
	v_mfma_i32_16x16x64_i8 v[88:91], v[60:63], v[220:223], v[88:91]
	v_mfma_i32_16x16x64_i8 v[80:83], v[140:143], v[220:223], v[80:83]
	v_mfma_i32_16x16x64_i8 v[80:83], v[144:147], v[224:227], v[80:83]
	v_mfma_i32_16x16x64_i8 v[96:99], v[144:147], v[216:219], v[96:99]
	v_mfma_i32_16x16x64_i8 v[96:99], v[140:143], v[212:215], v[96:99]
	v_mfma_i32_16x16x64_i8 v[112:115], v[140:143], v[204:207], v[112:115]
	v_mfma_i32_16x16x64_i8 v[112:115], v[144:147], v[208:211], v[112:115]
	v_mfma_i32_16x16x64_i8 v[128:131], v[144:147], v[188:191], v[128:131]
	v_mfma_i32_16x16x64_i8 v[128:131], v[140:143], v[184:187], v[128:131]
	v_mfma_i32_16x16x64_i8 v[132:135], v[160:163], v[184:187], v[132:135]
	v_mfma_i32_16x16x64_i8 v[132:135], v[172:175], v[188:191], v[132:135]
	v_mfma_i32_16x16x64_i8 v[116:119], v[172:175], v[208:211], v[116:119]
	v_mfma_i32_16x16x64_i8 v[116:119], v[160:163], v[204:207], v[116:119]
	v_mfma_i32_16x16x64_i8 v[100:103], v[160:163], v[212:215], v[100:103]
	v_mfma_i32_16x16x64_i8 v[100:103], v[172:175], v[216:219], v[100:103]
	v_mfma_i32_16x16x64_i8 v[84:87], v[172:175], v[224:227], v[84:87]
	v_mfma_i32_16x16x64_i8 v[84:87], v[160:163], v[220:223], v[84:87]
	v_mfma_i32_16x16x64_i8 v[76:79], v[176:179], v[220:223], v[76:79]
	v_mfma_i32_16x16x64_i8 v[76:79], v[180:183], v[224:227], v[76:79]
	v_mfma_i32_16x16x64_i8 v[92:95], v[180:183], v[216:219], v[92:95]
	v_mfma_i32_16x16x64_i8 v[92:95], v[176:179], v[212:215], v[92:95]
	v_mfma_i32_16x16x64_i8 v[108:111], v[176:179], v[204:207], v[108:111]
	v_mfma_i32_16x16x64_i8 v[108:111], v[180:183], v[208:211], v[108:111]
	v_mfma_i32_16x16x64_i8 v[124:127], v[180:183], v[188:191], v[124:127]
	v_mfma_i32_16x16x64_i8 v[124:127], v[176:179], v[184:187], v[124:127]
	s_setprio 0
	s_barrier
; #define PG8_STAGE(bufoff, gbase, voff) do { _Pragma("unroll") for (int _i = 0; _i < 2; ++_i) \
;         __builtin_amdgcn_global_load_lds((const unsigned*)((const char*)(gbase) + (voff)[_i]), (PG8_LAS unsigned*)(lds + (bufoff) + ldsw + _i * 8192), 16, 0, 0); } while (0)
; #define PG8_LDA(dst, b, h) do { _Pragma("unroll") for (int m = 0; m < 4; ++m) _Pragma("unroll") for (int k = 0; k < 2; ++k) dst[m][k] = *(const PG8_LAS bf16x8*)(lds + PG8_SA(b, h) + aoff + m * 2048 + k * 1024); } while (0)
; #define PG8_LDB(dst, b, h) do { _Pragma("unroll") for (int n = 0; n < 2; ++n) _Pragma("unroll") for (int k = 0; k < 2; ++k) dst[n][k] = *(const PG8_LAS bf16x8*)(lds + PG8_SB(b, h) + boff + n * 2048 + k * 1024); } while (0)
; #define PG8_WAIT_V(n) asm volatile("s_waitcnt vmcnt(" #n ")" ::: "memory")
; #define PG8_WAIT_L(n) asm volatile("s_waitcnt lgkmcnt(" #n ")" ::: "memory")
; #define PG8_BAR __builtin_amdgcn_s_barrier()
; #define PG8_SCHED __builtin_amdgcn_sched_barrier(0)
; template <class Epi, class Sched, bool ALIGN_EPI = false, bool SP2 = false, bool I8 = false>
; __device__ __forceinline__ void gemm_phase(PG8_LAS unsigned char* lds, const Gemm g, const Sched& S, const Epi& E) {
;     ...
;             PG8_LDB(B0, 0, 0); PG8_LDB(B1, 0, 1); PG8_SCHED; PG8_LDA(At, 0, 0); PG8_STAGE(PG8_SA(1, 1), a1 + hstep, voffA);
;             PG8_WAIT_V(8); PG8_WAIT_L(0); PG8_BAR; PG8_MMA(0, 0, At, B0); PG8_MMA(0, 1, At, B1); PG8_BAR; PG8_SCHED;
;             PG8_LDA(At, 0, 1); PG8_STAGE(PG8_SB(0, 0), b2, voffB); PG8_STAGE(PG8_SB(0, 1), b2 + hstep, voffB); PG8_STAGE(PG8_SA(0, 0), a2, voffA);
;             PG8_WAIT_V(8); PG8_WAIT_L(0); PG8_BAR; PG8_MMA(1, 0, At, B0); PG8_MMA(1, 1, At, B1); PG8_BAR; PG8_SCHED;
;             PG8_LDB(B0, 1, 0); PG8_LDB(B1, 1, 1); PG8_SCHED; PG8_LDA(At, 1, 0); PG8_STAGE(PG8_SA(0, 1), a2 + hstep, voffA);
;             PG8_WAIT_V(8); PG8_WAIT_L(0); PG8_BAR; PG8_MMA(0, 0, At, B0); PG8_MMA(0, 1, At, B1); PG8_BAR; PG8_SCHED;
;             PG8_LDA(At, 1, 1); PG8_STAGE(PG8_SB(1, 0), b3, voffB); PG8_STAGE(PG8_SB(1, 1), b3 + hstep, voffB); PG8_STAGE(PG8_SA(1, 0), a3, voffA);
;             PG8_WAIT_V(8); PG8_WAIT_L(0); PG8_BAR; PG8_MMA(1, 0, At, B0); PG8_MMA(1, 1, At, B1); PG8_BAR; PG8_SCHED;
	s_add_i32 s48, s64, s47
	v_lshl_add_u64 v[164:165], v[164:165], 0, s[84:85]
	s_mov_b32 m0, s48
	ds_read_b128 v[184:187], v171 offset:49152
	ds_read_b128 v[188:191], v171 offset:50176
	ds_read_b128 v[204:207], v171 offset:51200
	ds_read_b128 v[208:211], v171 offset:52224
	ds_read_b128 v[212:215], v171 offset:53248
	ds_read_b128 v[216:219], v171 offset:54272
	ds_read_b128 v[220:223], v171 offset:55296
	ds_read_b128 v[224:227], v171 offset:56320
	global_load_lds_dwordx4 v[164:165], off
	s_add_i32 m0, s48, 0x2000
	s_add_u32 s44, s44, 0x80080
	v_lshl_add_u64 v[164:165], v[228:229], 0, s[84:85]
	s_addc_u32 s45, s45, 0
	s_add_i32 s48, s65, s47
	global_load_lds_dwordx4 v[164:165], off
	v_lshl_add_u64 v[164:165], s[44:45], 0, v[2:3]
	s_mov_b32 m0, s48
	s_nop 0
	global_load_lds_dwordx4 v[164:165], off
	v_lshl_add_u64 v[164:165], s[44:45], 0, v[148:149]
	s_add_i32 m0, s48, 0x2000
	s_nop 0
	global_load_lds_dwordx4 v[164:165], off
	v_lshl_add_u64 v[164:165], v[240:241], 0, s[84:85]
	s_mov_b32 m0, s54
	s_nop 0
	global_load_lds_dwordx4 v[164:165], off
	v_lshl_add_u64 v[164:165], v[242:243], 0, s[84:85]
	s_mov_b32 m0, s55
	s_nop 0
	global_load_lds_dwordx4 v[164:165], off
	s_waitcnt vmcnt(8)
	s_waitcnt lgkmcnt(0)
	s_barrier
	s_setprio 1
	s_waitcnt lgkmcnt(0)
	v_mfma_i32_16x16x64_i8 v[72:75], v[60:63], v[184:187], v[72:75]
	v_mfma_i32_16x16x64_i8 v[72:75], v[68:71], v[188:191], v[72:75]
	v_mfma_i32_16x16x64_i8 v[56:59], v[68:71], v[208:211], v[56:59]
	v_mfma_i32_16x16x64_i8 v[56:59], v[60:63], v[204:207], v[56:59]
	v_mfma_i32_16x16x64_i8 v[32:35], v[60:63], v[212:215], v[32:35]
	v_mfma_i32_16x16x64_i8 v[32:35], v[68:71], v[216:219], v[32:35]
	v_mfma_i32_16x16x64_i8 v[16:19], v[68:71], v[224:227], v[16:19]
	v_mfma_i32_16x16x64_i8 v[16:19], v[60:63], v[220:223], v[16:19]
	v_mfma_i32_16x16x64_i8 v[8:11], v[140:143], v[220:223], v[8:11]
	v_mfma_i32_16x16x64_i8 v[8:11], v[144:147], v[224:227], v[8:11]
	v_mfma_i32_16x16x64_i8 v[24:27], v[144:147], v[216:219], v[24:27]
	v_mfma_i32_16x16x64_i8 v[24:27], v[140:143], v[212:215], v[24:27]
	v_mfma_i32_16x16x64_i8 v[48:51], v[140:143], v[204:207], v[48:51]
	v_mfma_i32_16x16x64_i8 v[48:51], v[144:147], v[208:211], v[48:51]
	v_mfma_i32_16x16x64_i8 v[64:67], v[144:147], v[188:191], v[64:67]
	v_mfma_i32_16x16x64_i8 v[64:67], v[140:143], v[184:187], v[64:67]
	v_mfma_i32_16x16x64_i8 v[36:39], v[160:163], v[184:187], v[36:39]
	v_mfma_i32_16x16x64_i8 v[68:71], v[172:175], v[188:191], v[36:39]
	v_mfma_i32_16x16x64_i8 v[36:39], v[172:175], v[208:211], v[52:55]
	v_mfma_i32_16x16x64_i8 v[52:55], v[160:163], v[204:207], v[36:39]
	v_mfma_i32_16x16x64_i8 v[28:31], v[160:163], v[212:215], v[28:31]
	v_mfma_i32_16x16x64_i8 v[28:31], v[172:175], v[216:219], v[28:31]
	v_mfma_i32_16x16x64_i8 v[12:15], v[172:175], v[224:227], v[12:15]
	v_mfma_i32_16x16x64_i8 v[12:15], v[160:163], v[220:223], v[12:15]
	v_mfma_i32_16x16x64_i8 v[4:7], v[176:179], v[220:223], v[4:7]
	v_mfma_i32_16x16x64_i8 v[4:7], v[180:183], v[224:227], v[4:7]
	v_mfma_i32_16x16x64_i8 v[20:23], v[180:183], v[216:219], v[20:23]
	v_mfma_i32_16x16x64_i8 v[20:23], v[176:179], v[212:215], v[20:23]
	v_mfma_i32_16x16x64_i8 v[36:39], v[176:179], v[204:207], v[40:43]
	v_mfma_i32_16x16x64_i8 v[40:43], v[180:183], v[208:211], v[36:39]
	v_mfma_i32_16x16x64_i8 v[36:39], v[180:183], v[188:191], v[44:47]
	v_mfma_i32_16x16x64_i8 v[60:63], v[176:179], v[184:187], v[36:39]
	s_setprio 0
	s_barrier
	s_add_i32 s61, s61, 2
	s_add_u32 s40, s40, 0x100
	s_addc_u32 s41, s41, 0
	s_add_u32 s59, s59, 0x100
	s_addc_u32 s60, s60, 0
	s_cmp_gt_u32 s61, 29
	s_cbranch_scc1 .Lkloop_exit_3
.LBB0_1591:
	s_add_u32 s44, s40, 0xfff80080
	s_addc_u32 s45, s41, -1
	s_add_i32 s64, 0, 0x10000
	s_cmp_eq_u32 s61, 28
	s_cselect_b32 s49, s25, s45
	s_cselect_b32 s48, s57, s44
	s_cselect_b32 s45, s23, s60
	s_cselect_b32 s44, s58, s59
	s_add_i32 s67, 0, 0x14000
	v_add_u32_e32 v144, s64, v167
	v_add_u32_e32 v158, s67, v167
	ds_read_b128 v[36:39], v144
	ds_read_b128 v[44:47], v144 offset:1024
	ds_read_b128 v[140:143], v144 offset:2048
	ds_read_b128 v[144:147], v144 offset:3072
	ds_read_b128 v[160:163], v158
	ds_read_b128 v[172:175], v158 offset:1024
	ds_read_b128 v[176:179], v158 offset:2048
	ds_read_b128 v[180:183], v158 offset:3072
	v_lshl_add_u64 v[164:165], s[40:41], 0, v[154:155]
	s_add_i32 m0, s50, 0xc000
	ds_read_b128 v[184:187], v171
	ds_read_b128 v[188:191], v171 offset:1024
	ds_read_b128 v[204:207], v171 offset:2048
	ds_read_b128 v[208:211], v171 offset:3072
	ds_read_b128 v[212:215], v171 offset:4096
	ds_read_b128 v[216:219], v171 offset:5120
	ds_read_b128 v[220:223], v171 offset:6144
	ds_read_b128 v[224:227], v171 offset:7168
	global_load_lds_dwordx4 v[164:165], off
	v_lshl_add_u64 v[164:165], s[40:41], 0, v[156:157]
	s_add_i32 m0, s50, 0xe000
	s_nop 0
	global_load_lds_dwordx4 v[164:165], off
	s_waitcnt vmcnt(8)
	s_waitcnt lgkmcnt(0)
	s_barrier
; #define PG8_STAGE(bufoff, gbase, voff) do { _Pragma("unroll") for (int _i = 0; _i < 2; ++_i) \
;         __builtin_amdgcn_global_load_lds((const unsigned*)((const char*)(gbase) + (voff)[_i]), (PG8_LAS unsigned*)(lds + (bufoff) + ldsw + _i * 8192), 16, 0, 0); } while (0)
; #define PG8_LDA(dst, b, h) do { _Pragma("unroll") for (int m = 0; m < 4; ++m) _Pragma("unroll") for (int k = 0; k < 2; ++k) dst[m][k] = *(const PG8_LAS bf16x8*)(lds + PG8_SA(b, h) + aoff + m * 2048 + k * 1024); } while (0)
; #define PG8_WAIT_V(n) asm volatile("s_waitcnt vmcnt(" #n ")" ::: "memory")
; #define PG8_WAIT_L(n) asm volatile("s_waitcnt lgkmcnt(" #n ")" ::: "memory")
; #define PG8_BAR __builtin_amdgcn_s_barrier()
; #define PG8_SCHED __builtin_amdgcn_sched_barrier(0)
; template <class Epi, class Sched, bool ALIGN_EPI = false, bool SP2 = false, bool I8 = false>
; __device__ __forceinline__ void gemm_phase(PG8_LAS unsigned char* lds, const Gemm g, const Sched& S, const Epi& E) {
;     ...
;             PG8_WAIT_V(8); PG8_WAIT_L(0); PG8_BAR; PG8_MMA(0, 0, At, B0); PG8_MMA(0, 1, At, B1); PG8_BAR; PG8_SCHED;
;             PG8_LDA(At, 0, 1); PG8_STAGE(PG8_SB(0, 0), b2, voffB); PG8_STAGE(PG8_SB(0, 1), b2 + hstep, voffB); PG8_STAGE(PG8_SA(0, 0), a2, voffA);
;             PG8_WAIT_V(8); PG8_WAIT_L(0); PG8_BAR; PG8_MMA(1, 0, At, B0); PG8_MMA(1, 1, At, B1); PG8_BAR; PG8_SCHED;
	s_setprio 1
	s_waitcnt lgkmcnt(0)
	v_mfma_i32_16x16x64_i8 v[136:139], v[36:39], v[184:187], v[136:139]
	v_mfma_i32_16x16x64_i8 v[136:139], v[44:47], v[188:191], v[136:139]
	v_mfma_i32_16x16x64_i8 v[120:123], v[44:47], v[208:211], v[120:123]
	v_mfma_i32_16x16x64_i8 v[120:123], v[36:39], v[204:207], v[120:123]
	v_mfma_i32_16x16x64_i8 v[104:107], v[36:39], v[212:215], v[104:107]
	v_mfma_i32_16x16x64_i8 v[104:107], v[44:47], v[216:219], v[104:107]
	v_mfma_i32_16x16x64_i8 v[88:91], v[44:47], v[224:227], v[88:91]
	v_mfma_i32_16x16x64_i8 v[88:91], v[36:39], v[220:223], v[88:91]
	v_mfma_i32_16x16x64_i8 v[80:83], v[140:143], v[220:223], v[80:83]
	v_mfma_i32_16x16x64_i8 v[80:83], v[144:147], v[224:227], v[80:83]
	v_mfma_i32_16x16x64_i8 v[96:99], v[144:147], v[216:219], v[96:99]
	v_mfma_i32_16x16x64_i8 v[96:99], v[140:143], v[212:215], v[96:99]
	v_mfma_i32_16x16x64_i8 v[112:115], v[140:143], v[204:207], v[112:115]
	v_mfma_i32_16x16x64_i8 v[112:115], v[144:147], v[208:211], v[112:115]
	v_mfma_i32_16x16x64_i8 v[128:131], v[144:147], v[188:191], v[128:131]
	v_mfma_i32_16x16x64_i8 v[128:131], v[140:143], v[184:187], v[128:131]
	v_mfma_i32_16x16x64_i8 v[132:135], v[160:163], v[184:187], v[132:135]
	v_mfma_i32_16x16x64_i8 v[132:135], v[172:175], v[188:191], v[132:135]
	v_mfma_i32_16x16x64_i8 v[116:119], v[172:175], v[208:211], v[116:119]
	v_mfma_i32_16x16x64_i8 v[116:119], v[160:163], v[204:207], v[116:119]
	v_mfma_i32_16x16x64_i8 v[100:103], v[160:163], v[212:215], v[100:103]
	v_mfma_i32_16x16x64_i8 v[100:103], v[172:175], v[216:219], v[100:103]
	v_mfma_i32_16x16x64_i8 v[84:87], v[172:175], v[224:227], v[84:87]
	v_mfma_i32_16x16x64_i8 v[84:87], v[160:163], v[220:223], v[84:87]
	v_mfma_i32_16x16x64_i8 v[76:79], v[176:179], v[220:223], v[76:79]
	v_mfma_i32_16x16x64_i8 v[76:79], v[180:183], v[224:227], v[76:79]
	v_mfma_i32_16x16x64_i8 v[92:95], v[180:183], v[216:219], v[92:95]
	v_mfma_i32_16x16x64_i8 v[92:95], v[176:179], v[212:215], v[92:95]
	v_mfma_i32_16x16x64_i8 v[108:111], v[176:179], v[204:207], v[108:111]
	v_mfma_i32_16x16x64_i8 v[108:111], v[180:183], v[208:211], v[108:111]
	v_mfma_i32_16x16x64_i8 v[124:127], v[180:183], v[188:191], v[124:127]
	v_mfma_i32_16x16x64_i8 v[124:127], v[176:179], v[184:187], v[124:127]
	s_setprio 0
	s_barrier
	s_add_i32 s64, s64, s47
	v_lshl_add_u64 v[164:165], s[44:45], 0, v[2:3]
	s_mov_b32 m0, s64
	ds_read_b128 v[184:187], v171 offset:16384
	ds_read_b128 v[188:191], v171 offset:17408
	ds_read_b128 v[204:207], v171 offset:18432
	ds_read_b128 v[208:211], v171 offset:19456
	ds_read_b128 v[212:215], v171 offset:20480
	ds_read_b128 v[216:219], v171 offset:21504
	ds_read_b128 v[220:223], v171 offset:22528
	ds_read_b128 v[224:227], v171 offset:23552
	global_load_lds_dwordx4 v[164:165], off
	s_add_i32 m0, s64, 0x2000
	s_add_u32 s64, s44, 0x80000
	v_lshl_add_u64 v[228:229], s[44:45], 0, v[148:149]
	s_addc_u32 s65, s45, 0
	s_add_i32 s67, s67, s47
	global_load_lds_dwordx4 v[228:229], off
	v_lshl_add_u64 v[240:241], s[64:65], 0, v[2:3]
	s_mov_b32 m0, s67
	v_lshl_add_u64 v[242:243], s[48:49], 0, v[150:151]
	global_load_lds_dwordx4 v[240:241], off
	v_lshl_add_u64 v[240:241], s[64:65], 0, v[148:149]
	s_add_i32 m0, s67, 0x2000
	s_nop 0
	global_load_lds_dwordx4 v[240:241], off
	v_lshl_add_u64 v[240:241], s[48:49], 0, v[152:153]
	s_waitcnt vmcnt(6)
	s_waitcnt lgkmcnt(0)
	s_barrier
	s_setprio 1
	s_waitcnt lgkmcnt(0)
	v_mfma_i32_16x16x64_i8 v[72:75], v[36:39], v[184:187], v[72:75]
	v_mfma_i32_16x16x64_i8 v[72:75], v[44:47], v[188:191], v[72:75]
	v_mfma_i32_16x16x64_i8 v[56:59], v[44:47], v[208:211], v[56:59]
	v_mfma_i32_16x16x64_i8 v[56:59], v[36:39], v[204:207], v[56:59]
	v_mfma_i32_16x16x64_i8 v[32:35], v[36:39], v[212:215], v[32:35]
	v_mfma_i32_16x16x64_i8 v[32:35], v[44:47], v[216:219], v[32:35]
	v_mfma_i32_16x16x64_i8 v[16:19], v[44:47], v[224:227], v[16:19]
	v_mfma_i32_16x16x64_i8 v[16:19], v[36:39], v[220:223], v[16:19]
	v_mfma_i32_16x16x64_i8 v[8:11], v[140:143], v[220:223], v[8:11]
	v_mfma_i32_16x16x64_i8 v[8:11], v[144:147], v[224:227], v[8:11]
	v_mfma_i32_16x16x64_i8 v[24:27], v[144:147], v[216:219], v[24:27]
	v_mfma_i32_16x16x64_i8 v[24:27], v[140:143], v[212:215], v[24:27]
	v_mfma_i32_16x16x64_i8 v[48:51], v[140:143], v[204:207], v[48:51]
	v_mfma_i32_16x16x64_i8 v[48:51], v[144:147], v[208:211], v[48:51]
	v_mfma_i32_16x16x64_i8 v[64:67], v[144:147], v[188:191], v[64:67]
	v_mfma_i32_16x16x64_i8 v[64:67], v[140:143], v[184:187], v[64:67]
	v_mfma_i32_16x16x64_i8 v[36:39], v[160:163], v[184:187], v[68:71]
	v_mfma_i32_16x16x64_i8 v[36:39], v[172:175], v[188:191], v[36:39]
	v_mfma_i32_16x16x64_i8 v[52:55], v[172:175], v[208:211], v[52:55]
	v_mfma_i32_16x16x64_i8 v[52:55], v[160:163], v[204:207], v[52:55]
	v_mfma_i32_16x16x64_i8 v[28:31], v[160:163], v[212:215], v[28:31]
	v_mfma_i32_16x16x64_i8 v[28:31], v[172:175], v[216:219], v[28:31]
	v_mfma_i32_16x16x64_i8 v[12:15], v[172:175], v[224:227], v[12:15]
	v_mfma_i32_16x16x64_i8 v[12:15], v[160:163], v[220:223], v[12:15]
	v_mfma_i32_16x16x64_i8 v[4:7], v[176:179], v[220:223], v[4:7]
	v_mfma_i32_16x16x64_i8 v[4:7], v[180:183], v[224:227], v[4:7]
	v_mfma_i32_16x16x64_i8 v[20:23], v[180:183], v[216:219], v[20:23]
	v_mfma_i32_16x16x64_i8 v[20:23], v[176:179], v[212:215], v[20:23]
	v_mfma_i32_16x16x64_i8 v[40:43], v[176:179], v[204:207], v[40:43]
	v_mfma_i32_16x16x64_i8 v[40:43], v[180:183], v[208:211], v[40:43]
	v_mfma_i32_16x16x64_i8 v[44:47], v[180:183], v[188:191], v[60:63]
	v_mfma_i32_16x16x64_i8 v[44:47], v[176:179], v[184:187], v[44:47]
	s_setprio 0
	s_barrier
; #define PG8_STAGE(bufoff, gbase, voff) do { _Pragma("unroll") for (int _i = 0; _i < 2; ++_i) \
;         __builtin_amdgcn_global_load_lds((const unsigned*)((const char*)(gbase) + (voff)[_i]), (PG8_LAS unsigned*)(lds + (bufoff) + ldsw + _i * 8192), 16, 0, 0); } while (0)
; #define PG8_LDA(dst, b, h) do { _Pragma("unroll") for (int m = 0; m < 4; ++m) _Pragma("unroll") for (int k = 0; k < 2; ++k) dst[m][k] = *(const PG8_LAS bf16x8*)(lds + PG8_SA(b, h) + aoff + m * 2048 + k * 1024); } while (0)
; #define PG8_LDB(dst, b, h) do { _Pragma("unroll") for (int n = 0; n < 2; ++n) _Pragma("unroll") for (int k = 0; k < 2; ++k) dst[n][k] = *(const PG8_LAS bf16x8*)(lds + PG8_SB(b, h) + boff + n * 2048 + k * 1024); } while (0)
; #define PG8_WAIT_V(n) asm volatile("s_waitcnt vmcnt(" #n ")" ::: "memory")
; #define PG8_WAIT_L(n) asm volatile("s_waitcnt lgkmcnt(" #n ")" ::: "memory")
; #define PG8_BAR __builtin_amdgcn_s_barrier()
; #define PG8_SCHED __builtin_amdgcn_sched_barrier(0)
; template <class Epi, class Sched, bool ALIGN_EPI = false, bool SP2 = false, bool I8 = false>
; __device__ __forceinline__ void gemm_phase(PG8_LAS unsigned char* lds, const Gemm g, const Sched& S, const Epi& E) {
;     ...
;             PG8_LDA(At, 0, 1); PG8_STAGE(PG8_SB(0, 0), b2, voffB); PG8_STAGE(PG8_SB(0, 1), b2 + hstep, voffB); PG8_STAGE(PG8_SA(0, 0), a2, voffA);
;             PG8_WAIT_V(8); PG8_WAIT_L(0); PG8_BAR; PG8_MMA(1, 0, At, B0); PG8_MMA(1, 1, At, B1); PG8_BAR; PG8_SCHED;
;             PG8_LDB(B0, 1, 0); PG8_LDB(B1, 1, 1); PG8_SCHED; PG8_LDA(At, 1, 0); PG8_STAGE(PG8_SA(0, 1), a2 + hstep, voffA);
;             PG8_WAIT_V(8); PG8_WAIT_L(0); PG8_BAR; PG8_MMA(0, 0, At, B0); PG8_MMA(0, 1, At, B1); PG8_BAR; PG8_SCHED;
	s_mov_b32 m0, s50
	s_nop 0
	global_load_lds_dwordx4 v[240:241], off
	s_mov_b32 m0, s51
	s_nop 0
	global_load_lds_dwordx4 v[242:243], off
	s_add_i32 s64, 0, 0x18000
	s_add_i32 s65, 0, 0x1c000
	v_add_u32_e32 v144, s64, v167
	v_add_u32_e32 v158, s65, v167
	ds_read_b128 v[60:63], v144
	ds_read_b128 v[68:71], v144 offset:1024
	ds_read_b128 v[140:143], v144 offset:2048
	ds_read_b128 v[144:147], v144 offset:3072
	ds_read_b128 v[160:163], v158
	ds_read_b128 v[172:175], v158 offset:1024
	ds_read_b128 v[176:179], v158 offset:2048
	ds_read_b128 v[180:183], v158 offset:3072
	s_add_u32 s48, s48, 0x80000
	s_addc_u32 s49, s49, 0
	s_mov_b32 m0, s52
	v_lshl_add_u64 v[244:245], s[48:49], 0, v[152:153]
	ds_read_b128 v[184:187], v171 offset:32768
	ds_read_b128 v[188:191], v171 offset:33792
	ds_read_b128 v[204:207], v171 offset:34816
	ds_read_b128 v[208:211], v171 offset:35840
	ds_read_b128 v[212:215], v171 offset:36864
	ds_read_b128 v[216:219], v171 offset:37888
	ds_read_b128 v[220:223], v171 offset:38912
	ds_read_b128 v[224:227], v171 offset:39936
	global_load_lds_dwordx4 v[244:245], off
	v_lshl_add_u64 v[244:245], s[48:49], 0, v[150:151]
	s_mov_b32 m0, s53
	s_nop 0
	global_load_lds_dwordx4 v[244:245], off
	s_waitcnt vmcnt(8)
	s_waitcnt lgkmcnt(0)
	s_barrier
	s_setprio 1
	s_waitcnt lgkmcnt(0)
	v_mfma_i32_16x16x64_i8 v[136:139], v[60:63], v[184:187], v[136:139]
	v_mfma_i32_16x16x64_i8 v[136:139], v[68:71], v[188:191], v[136:139]
	v_mfma_i32_16x16x64_i8 v[120:123], v[68:71], v[208:211], v[120:123]
	v_mfma_i32_16x16x64_i8 v[120:123], v[60:63], v[204:207], v[120:123]
	v_mfma_i32_16x16x64_i8 v[104:107], v[60:63], v[212:215], v[104:107]
	v_mfma_i32_16x16x64_i8 v[104:107], v[68:71], v[216:219], v[104:107]
	v_mfma_i32_16x16x64_i8 v[88:91], v[68:71], v[224:227], v[88:91]
	v_mfma_i32_16x16x64_i8 v[88:91], v[60:63], v[220:223], v[88:91]
	v_mfma_i32_16x16x64_i8 v[80:83], v[140:143], v[220:223], v[80:83]
	v_mfma_i32_16x16x64_i8 v[80:83], v[144:147], v[224:227], v[80:83]
	v_mfma_i32_16x16x64_i8 v[96:99], v[144:147], v[216:219], v[96:99]
	v_mfma_i32_16x16x64_i8 v[96:99], v[140:143], v[212:215], v[96:99]
	v_mfma_i32_16x16x64_i8 v[112:115], v[140:143], v[204:207], v[112:115]
	v_mfma_i32_16x16x64_i8 v[112:115], v[144:147], v[208:211], v[112:115]
	v_mfma_i32_16x16x64_i8 v[128:131], v[144:147], v[188:191], v[128:131]
	v_mfma_i32_16x16x64_i8 v[128:131], v[140:143], v[184:187], v[128:131]
	v_mfma_i32_16x16x64_i8 v[132:135], v[160:163], v[184:187], v[132:135]
	v_mfma_i32_16x16x64_i8 v[132:135], v[172:175], v[188:191], v[132:135]
	v_mfma_i32_16x16x64_i8 v[116:119], v[172:175], v[208:211], v[116:119]
	v_mfma_i32_16x16x64_i8 v[116:119], v[160:163], v[204:207], v[116:119]
	v_mfma_i32_16x16x64_i8 v[100:103], v[160:163], v[212:215], v[100:103]
	v_mfma_i32_16x16x64_i8 v[100:103], v[172:175], v[216:219], v[100:103]
	v_mfma_i32_16x16x64_i8 v[84:87], v[172:175], v[224:227], v[84:87]
	v_mfma_i32_16x16x64_i8 v[84:87], v[160:163], v[220:223], v[84:87]
	v_mfma_i32_16x16x64_i8 v[76:79], v[176:179], v[220:223], v[76:79]
	v_mfma_i32_16x16x64_i8 v[76:79], v[180:183], v[224:227], v[76:79]
	v_mfma_i32_16x16x64_i8 v[92:95], v[180:183], v[216:219], v[92:95]
	v_mfma_i32_16x16x64_i8 v[92:95], v[176:179], v[212:215], v[92:95]
	v_mfma_i32_16x16x64_i8 v[108:111], v[176:179], v[204:207], v[108:111]
	v_mfma_i32_16x16x64_i8 v[108:111], v[180:183], v[208:211], v[108:111]
	v_mfma_i32_16x16x64_i8 v[124:127], v[180:183], v[188:191], v[124:127]
	v_mfma_i32_16x16x64_i8 v[124:127], v[176:179], v[184:187], v[124:127]
	s_setprio 0
	s_barrier
; #define PG8_STAGE(bufoff, gbase, voff) do { _Pragma("unroll") for (int _i = 0; _i < 2; ++_i) \
;         __builtin_amdgcn_global_load_lds((const unsigned*)((const char*)(gbase) + (voff)[_i]), (PG8_LAS unsigned*)(lds + (bufoff) + ldsw + _i * 8192), 16, 0, 0); } while (0)
; #define PG8_LDA(dst, b, h) do { _Pragma("unroll") for (int m = 0; m < 4; ++m) _Pragma("unroll") for (int k = 0; k < 2; ++k) dst[m][k] = *(const PG8_LAS bf16x8*)(lds + PG8_SA(b, h) + aoff + m * 2048 + k * 1024); } while (0)
; #define PG8_WAIT_V(n) asm volatile("s_waitcnt vmcnt(" #n ")" ::: "memory")
; #define PG8_WAIT_L(n) asm volatile("s_waitcnt lgkmcnt(" #n ")" ::: "memory")
; #define PG8_BAR __builtin_amdgcn_s_barrier()
; #define PG8_SCHED __builtin_amdgcn_sched_barrier(0)
; template <class Epi, class Sched, bool ALIGN_EPI = false, bool SP2 = false, bool I8 = false>
; __device__ __forceinline__ void gemm_phase(PG8_LAS unsigned char* lds, const Gemm g, const Sched& S, const Epi& E) {
;     ...
;         for (int t = 0; t < nt; t += 2) {
;             const bool last = (t == nt - 2);
;             const char* a1 = cA + (size_t)(t + 1) * kstep;
;             const char* a2 = last ? nA : cA + (size_t)(t + 2) * kstep; const char* b2 = last ? nB : cB + (size_t)(t + 2) * kstep;
;     ...
;             PG8_LDA(At, 1, 1); PG8_STAGE(PG8_SB(1, 0), b3, voffB); PG8_STAGE(PG8_SB(1, 1), b3 + hstep, voffB); PG8_STAGE(PG8_SA(1, 0), a3, voffA);
;             PG8_WAIT_V(8); PG8_WAIT_L(0); PG8_BAR; PG8_MMA(1, 0, At, B0); PG8_MMA(1, 1, At, B1); PG8_BAR; PG8_SCHED;
	s_add_i32 s48, s64, s47
	v_lshl_add_u64 v[164:165], v[164:165], 0, s[84:85]
	s_mov_b32 m0, s48
	ds_read_b128 v[184:187], v171 offset:49152
	ds_read_b128 v[188:191], v171 offset:50176
	ds_read_b128 v[204:207], v171 offset:51200
	ds_read_b128 v[208:211], v171 offset:52224
	ds_read_b128 v[212:215], v171 offset:53248
	ds_read_b128 v[216:219], v171 offset:54272
	ds_read_b128 v[220:223], v171 offset:55296
	ds_read_b128 v[224:227], v171 offset:56320
	global_load_lds_dwordx4 v[164:165], off
	s_add_i32 m0, s48, 0x2000
	s_add_u32 s44, s44, 0x80080
	v_lshl_add_u64 v[164:165], v[228:229], 0, s[84:85]
	s_addc_u32 s45, s45, 0
	s_add_i32 s48, s65, s47
	global_load_lds_dwordx4 v[164:165], off
	v_lshl_add_u64 v[164:165], s[44:45], 0, v[2:3]
	s_mov_b32 m0, s48
	s_nop 0
	global_load_lds_dwordx4 v[164:165], off
	v_lshl_add_u64 v[164:165], s[44:45], 0, v[148:149]
	s_add_i32 m0, s48, 0x2000
	s_nop 0
	global_load_lds_dwordx4 v[164:165], off
	v_lshl_add_u64 v[164:165], v[240:241], 0, s[84:85]
	s_mov_b32 m0, s54
	s_nop 0
	global_load_lds_dwordx4 v[164:165], off
	v_lshl_add_u64 v[164:165], v[242:243], 0, s[84:85]
	s_mov_b32 m0, s55
	s_nop 0
	global_load_lds_dwordx4 v[164:165], off
	s_waitcnt vmcnt(8)
	s_waitcnt lgkmcnt(0)
	s_barrier
	s_setprio 1
	s_waitcnt lgkmcnt(0)
	v_mfma_i32_16x16x64_i8 v[72:75], v[60:63], v[184:187], v[72:75]
	v_mfma_i32_16x16x64_i8 v[72:75], v[68:71], v[188:191], v[72:75]
	v_mfma_i32_16x16x64_i8 v[56:59], v[68:71], v[208:211], v[56:59]
	v_mfma_i32_16x16x64_i8 v[56:59], v[60:63], v[204:207], v[56:59]
	v_mfma_i32_16x16x64_i8 v[32:35], v[60:63], v[212:215], v[32:35]
	v_mfma_i32_16x16x64_i8 v[32:35], v[68:71], v[216:219], v[32:35]
	v_mfma_i32_16x16x64_i8 v[16:19], v[68:71], v[224:227], v[16:19]
	v_mfma_i32_16x16x64_i8 v[16:19], v[60:63], v[220:223], v[16:19]
	v_mfma_i32_16x16x64_i8 v[8:11], v[140:143], v[220:223], v[8:11]
	v_mfma_i32_16x16x64_i8 v[8:11], v[144:147], v[224:227], v[8:11]
	v_mfma_i32_16x16x64_i8 v[24:27], v[144:147], v[216:219], v[24:27]
	v_mfma_i32_16x16x64_i8 v[24:27], v[140:143], v[212:215], v[24:27]
	v_mfma_i32_16x16x64_i8 v[48:51], v[140:143], v[204:207], v[48:51]
	v_mfma_i32_16x16x64_i8 v[48:51], v[144:147], v[208:211], v[48:51]
	v_mfma_i32_16x16x64_i8 v[64:67], v[144:147], v[188:191], v[64:67]
	v_mfma_i32_16x16x64_i8 v[64:67], v[140:143], v[184:187], v[64:67]
	v_mfma_i32_16x16x64_i8 v[36:39], v[160:163], v[184:187], v[36:39]
	v_mfma_i32_16x16x64_i8 v[68:71], v[172:175], v[188:191], v[36:39]
	v_mfma_i32_16x16x64_i8 v[36:39], v[172:175], v[208:211], v[52:55]
	v_mfma_i32_16x16x64_i8 v[52:55], v[160:163], v[204:207], v[36:39]
	v_mfma_i32_16x16x64_i8 v[28:31], v[160:163], v[212:215], v[28:31]
	v_mfma_i32_16x16x64_i8 v[28:31], v[172:175], v[216:219], v[28:31]
	v_mfma_i32_16x16x64_i8 v[12:15], v[172:175], v[224:227], v[12:15]
	v_mfma_i32_16x16x64_i8 v[12:15], v[160:163], v[220:223], v[12:15]
	v_mfma_i32_16x16x64_i8 v[4:7], v[176:179], v[220:223], v[4:7]
	v_mfma_i32_16x16x64_i8 v[4:7], v[180:183], v[224:227], v[4:7]
	v_mfma_i32_16x16x64_i8 v[20:23], v[180:183], v[216:219], v[20:23]
	v_mfma_i32_16x16x64_i8 v[20:23], v[176:179], v[212:215], v[20:23]
	v_mfma_i32_16x16x64_i8 v[36:39], v[176:179], v[204:207], v[40:43]
	v_mfma_i32_16x16x64_i8 v[40:43], v[180:183], v[208:211], v[36:39]
	v_mfma_i32_16x16x64_i8 v[36:39], v[180:183], v[188:191], v[44:47]
	v_mfma_i32_16x16x64_i8 v[60:63], v[176:179], v[184:187], v[36:39]
	s_setprio 0
	s_barrier
	s_add_i32 s61, s61, 2
	s_add_u32 s40, s40, 0x100
	s_addc_u32 s41, s41, 0
	s_add_u32 s59, s59, 0x100
	s_addc_u32 s60, s60, 0
	s_cmp_gt_u32 s61, 29
	s_cbranch_scc0 .LBB0_1591

; #define PG8_STAGE(bufoff, gbase, voff) do { _Pragma("unroll") for (int _i = 0; _i < 2; ++_i) \
;         __builtin_amdgcn_global_load_lds((const unsigned*)((const char*)(gbase) + (voff)[_i]), (PG8_LAS unsigned*)(lds + (bufoff) + ldsw + _i * 8192), 16, 0, 0); } while (0)
; #define PG8_LDA(dst, b, h) do { _Pragma("unroll") for (int m = 0; m < 4; ++m) _Pragma("unroll") for (int k = 0; k < 2; ++k) dst[m][k] = *(const PG8_LAS bf16x8*)(lds + PG8_SA(b, h) + aoff + m * 2048 + k * 1024); } while (0)
; #define PG8_LDB(dst, b, h) do { _Pragma("unroll") for (int n = 0; n < 2; ++n) _Pragma("unroll") for (int k = 0; k < 2; ++k) dst[n][k] = *(const PG8_LAS bf16x8*)(lds + PG8_SB(b, h) + boff + n * 2048 + k * 1024); } while (0)
; #define PG8_WAIT_V(n) asm volatile("s_waitcnt vmcnt(" #n ")" ::: "memory")
; #define PG8_WAIT_L(n) asm volatile("s_waitcnt lgkmcnt(" #n ")" ::: "memory")
; #define PG8_BAR __builtin_amdgcn_s_barrier()
; #define PG8_SCHED __builtin_amdgcn_sched_barrier(0)
; template <class Epi, class Sched, bool ALIGN_EPI = false, bool SP2 = false, bool I8 = false>
; __device__ __forceinline__ void gemm_phase(PG8_LAS unsigned char* lds, const Gemm g, const Sched& S, const Epi& E) {
;     ...
;         const char* nA = has_next ? (const char*)g.A + (size_t)nxt.pm * tstep : cA; const char* nB = has_next ? (const char*)g.Bt + (size_t)nxt.pn * tstep : cB;
;         for (int t = 0; t < nt; t += 2) {
;             const bool last = (t == nt - 2);
;             const char* a1 = cA + (size_t)(t + 1) * kstep;
;             const char* a2 = last ? nA : cA + (size_t)(t + 2) * kstep; const char* b2 = last ? nB : cB + (size_t)(t + 2) * kstep;
;             const char* a3 = a2 + kstep; const char* b3 = b2 + kstep;
;             if (last && has_next) S.a_ready(nxt);
;             if constexpr (SP2) {
;             PG8_LDB(B0, 0, 0); PG8_LDB(B1, 0, 1); PG8_SCHED; PG8_LDA(At, 0, 0); PG8_STAGE(PG8_SA(1, 1), a1 + hstep, voffA);
;             PG8_WAIT_V(8); PG8_WAIT_L(0); PG8_BAR; PG8_MMA(0, 0, At, B0); PG8_MMA(0, 1, At, B1); PG8_BAR; PG8_SCHED;
;     ...
;         for (int a = 0; a < 2; ++a)
; #pragma unroll
;             for (int b = 0; b < 2; ++b)
; #pragma unroll
;                 for (int m = 0; m < 4; ++m)
; #pragma unroll
;                     for (int n = 0; n < 2; ++n) acc[a][b][m][n] = (acc_t){0, 0, 0, 0};
.LBB0_1621:
	v_mov_b32_e32 v127, 0
	s_andn2_b64 vcc, exec, s[26:27]
	v_mov_b32_e32 v126, v127
	v_mov_b32_e32 v125, v127
	v_mov_b32_e32 v124, v127
	v_mov_b32_e32 v131, v127
	v_mov_b32_e32 v130, v127
	v_mov_b32_e32 v129, v127
	v_mov_b32_e32 v128, v127
	v_mov_b32_e32 v115, v127
	v_mov_b32_e32 v114, v127
	v_mov_b32_e32 v113, v127
	v_mov_b32_e32 v112, v127
	v_mov_b32_e32 v111, v127
	v_mov_b32_e32 v110, v127
	v_mov_b32_e32 v109, v127
	v_mov_b32_e32 v108, v127
	v_mov_b32_e32 v99, v127
	v_mov_b32_e32 v98, v127
	v_mov_b32_e32 v97, v127
	v_mov_b32_e32 v96, v127
	v_mov_b32_e32 v95, v127
	v_mov_b32_e32 v94, v127
	v_mov_b32_e32 v93, v127
	v_mov_b32_e32 v92, v127
	v_mov_b32_e32 v83, v127
	v_mov_b32_e32 v82, v127
	v_mov_b32_e32 v81, v127
	v_mov_b32_e32 v80, v127
	v_mov_b32_e32 v79, v127
	v_mov_b32_e32 v78, v127
	v_mov_b32_e32 v77, v127
	v_mov_b32_e32 v76, v127
	v_mov_b32_e32 v123, v127
	v_mov_b32_e32 v122, v127
	v_mov_b32_e32 v121, v127
	v_mov_b32_e32 v120, v127
	v_mov_b32_e32 v119, v127
	v_mov_b32_e32 v118, v127
	v_mov_b32_e32 v117, v127
	v_mov_b32_e32 v116, v127
	v_mov_b32_e32 v107, v127
	v_mov_b32_e32 v106, v127
	v_mov_b32_e32 v105, v127
	v_mov_b32_e32 v104, v127
	v_mov_b32_e32 v103, v127
	v_mov_b32_e32 v102, v127
	v_mov_b32_e32 v101, v127
	v_mov_b32_e32 v100, v127
	v_mov_b32_e32 v91, v127
	v_mov_b32_e32 v90, v127
	v_mov_b32_e32 v89, v127
	v_mov_b32_e32 v88, v127
	v_mov_b32_e32 v87, v127
	v_mov_b32_e32 v86, v127
	v_mov_b32_e32 v85, v127
	v_mov_b32_e32 v84, v127
	v_mov_b32_e32 v75, v127
	v_mov_b32_e32 v74, v127
	v_mov_b32_e32 v73, v127
	v_mov_b32_e32 v72, v127
	v_mov_b32_e32 v71, v127
	v_mov_b32_e32 v70, v127
	v_mov_b32_e32 v69, v127
	v_mov_b32_e32 v68, v127
	v_mov_b32_e32 v67, v127
	v_mov_b32_e32 v66, v127
	v_mov_b32_e32 v65, v127
	v_mov_b32_e32 v64, v127
	v_mov_b32_e32 v63, v127
	v_mov_b32_e32 v62, v127
	v_mov_b32_e32 v61, v127
	v_mov_b32_e32 v60, v127
	v_mov_b32_e32 v51, v127
	v_mov_b32_e32 v50, v127
	v_mov_b32_e32 v49, v127
	v_mov_b32_e32 v48, v127
	v_mov_b32_e32 v47, v127
	v_mov_b32_e32 v46, v127
	v_mov_b32_e32 v45, v127
	v_mov_b32_e32 v44, v127
	v_mov_b32_e32 v35, v127
	v_mov_b32_e32 v34, v127
	v_mov_b32_e32 v33, v127
	v_mov_b32_e32 v32, v127
	v_mov_b32_e32 v31, v127
	v_mov_b32_e32 v30, v127
	v_mov_b32_e32 v29, v127
	v_mov_b32_e32 v28, v127
	v_mov_b32_e32 v19, v127
	v_mov_b32_e32 v18, v127
	v_mov_b32_e32 v17, v127
	v_mov_b32_e32 v16, v127
	v_mov_b32_e32 v15, v127
	v_mov_b32_e32 v14, v127
	v_mov_b32_e32 v13, v127
	v_mov_b32_e32 v12, v127
	v_mov_b32_e32 v59, v127
	v_mov_b32_e32 v58, v127
	v_mov_b32_e32 v57, v127
	v_mov_b32_e32 v56, v127
	v_mov_b32_e32 v55, v127
	v_mov_b32_e32 v54, v127
	v_mov_b32_e32 v53, v127
	v_mov_b32_e32 v52, v127
	v_mov_b32_e32 v43, v127
	v_mov_b32_e32 v42, v127
	v_mov_b32_e32 v41, v127
	v_mov_b32_e32 v40, v127
	v_mov_b32_e32 v39, v127
	v_mov_b32_e32 v38, v127
	v_mov_b32_e32 v37, v127
	v_mov_b32_e32 v36, v127
	v_mov_b32_e32 v27, v127
	v_mov_b32_e32 v26, v127
	v_mov_b32_e32 v25, v127
	v_mov_b32_e32 v24, v127
	v_mov_b32_e32 v23, v127
	v_mov_b32_e32 v22, v127
	v_mov_b32_e32 v21, v127
	v_mov_b32_e32 v20, v127
	v_mov_b32_e32 v11, v127
	v_mov_b32_e32 v10, v127
	v_mov_b32_e32 v9, v127
	v_mov_b32_e32 v8, v127
	v_mov_b32_e32 v7, v127
	v_mov_b32_e32 v6, v127
	v_mov_b32_e32 v5, v127
	v_mov_b32_e32 v4, v127
	s_cbranch_vccnz .LBB0_1625
	s_add_u32 s44, s44, 0x80
	s_addc_u32 s45, s45, 0
	s_add_u32 s65, s48, 0x100
	s_addc_u32 s67, s49, 0
	s_mov_b32 s48, 0
	s_add_i32 s72, s48, 2
	s_add_u32 s73, s44, 0x80
	s_addc_u32 s49, s45, 0
	s_add_i32 s86, 0, 0x10000
	s_cmp_eq_u32 s57, s48
	s_cselect_b32 s49, s13, s49
	s_cselect_b32 s48, s12, s73
	s_cselect_b32 s77, s41, s67
	s_cselect_b32 s76, s40, s65
	s_add_i32 s73, 0, 0x14000
	v_add_u32_e32 v158, s86, v143
	v_add_u32_e32 v174, s73, v143
	ds_read_b128 v[146:149], v158
	ds_read_b128 v[150:153], v158 offset:1024
	ds_read_b128 v[154:157], v158 offset:2048
	ds_read_b128 v[158:161], v158 offset:3072
	ds_read_b128 v[162:165], v174
	ds_read_b128 v[166:169], v174 offset:1024
	ds_read_b128 v[170:173], v174 offset:2048
	ds_read_b128 v[174:177], v174 offset:3072
	v_lshl_add_u64 v[190:191], s[44:45], 0, v[138:139]
	s_add_i32 m0, s47, 0xc000
	ds_read_b128 v[178:181], v145
	ds_read_b128 v[182:185], v145 offset:1024
	ds_read_b128 v[186:189], v145 offset:2048
	ds_read_b128 v[204:207], v145 offset:3072
	ds_read_b128 v[208:211], v145 offset:4096
	ds_read_b128 v[212:215], v145 offset:5120
	ds_read_b128 v[216:219], v145 offset:6144
	ds_read_b128 v[220:223], v145 offset:7168
	global_load_lds_dwordx4 v[190:191], off
	v_lshl_add_u64 v[190:191], s[44:45], 0, v[140:141]
	s_add_i32 m0, s47, 0xe000
	s_nop 0
	global_load_lds_dwordx4 v[190:191], off
	s_waitcnt vmcnt(8)
	s_waitcnt lgkmcnt(0)
	s_barrier
; #define PG8_STAGE(bufoff, gbase, voff) do { _Pragma("unroll") for (int _i = 0; _i < 2; ++_i) \
;         __builtin_amdgcn_global_load_lds((const unsigned*)((const char*)(gbase) + (voff)[_i]), (PG8_LAS unsigned*)(lds + (bufoff) + ldsw + _i * 8192), 16, 0, 0); } while (0)
; #define PG8_LDA(dst, b, h) do { _Pragma("unroll") for (int m = 0; m < 4; ++m) _Pragma("unroll") for (int k = 0; k < 2; ++k) dst[m][k] = *(const PG8_LAS bf16x8*)(lds + PG8_SA(b, h) + aoff + m * 2048 + k * 1024); } while (0)
; #define PG8_WAIT_V(n) asm volatile("s_waitcnt vmcnt(" #n ")" ::: "memory")
; #define PG8_WAIT_L(n) asm volatile("s_waitcnt lgkmcnt(" #n ")" ::: "memory")
; #define PG8_BAR __builtin_amdgcn_s_barrier()
; #define PG8_SCHED __builtin_amdgcn_sched_barrier(0)
; template <class Epi, class Sched, bool ALIGN_EPI = false, bool SP2 = false, bool I8 = false>
; __device__ __forceinline__ void gemm_phase(PG8_LAS unsigned char* lds, const Gemm g, const Sched& S, const Epi& E) {
;     ...
;             PG8_WAIT_V(8); PG8_WAIT_L(0); PG8_BAR; PG8_MMA(0, 0, At, B0); PG8_MMA(0, 1, At, B1); PG8_BAR; PG8_SCHED;
;             PG8_LDA(At, 0, 1); PG8_STAGE(PG8_SB(0, 0), b2, voffB); PG8_STAGE(PG8_SB(0, 1), b2 + hstep, voffB); PG8_STAGE(PG8_SA(0, 0), a2, voffA);
;             PG8_WAIT_V(8); PG8_WAIT_L(0); PG8_BAR; PG8_MMA(1, 0, At, B0); PG8_MMA(1, 1, At, B1); PG8_BAR; PG8_SCHED;
	s_setprio 1
	s_waitcnt lgkmcnt(0)
	v_mfma_f32_16x16x32_bf16 v[124:127], v[146:149], v[178:181], 0
	v_mfma_f32_16x16x32_bf16 v[124:127], v[150:153], v[182:185], v[124:127]
	v_mfma_f32_16x16x32_bf16 v[112:115], v[150:153], v[204:207], 0
	v_mfma_f32_16x16x32_bf16 v[112:115], v[146:149], v[186:189], v[112:115]
	v_mfma_f32_16x16x32_bf16 v[96:99], v[146:149], v[208:211], 0
	v_mfma_f32_16x16x32_bf16 v[96:99], v[150:153], v[212:215], v[96:99]
	v_mfma_f32_16x16x32_bf16 v[80:83], v[150:153], v[220:223], 0
	v_mfma_f32_16x16x32_bf16 v[80:83], v[146:149], v[216:219], v[80:83]
	v_mfma_f32_16x16x32_bf16 v[76:79], v[154:157], v[216:219], 0
	v_mfma_f32_16x16x32_bf16 v[76:79], v[158:161], v[220:223], v[76:79]
	v_mfma_f32_16x16x32_bf16 v[92:95], v[158:161], v[212:215], 0
	v_mfma_f32_16x16x32_bf16 v[92:95], v[154:157], v[208:211], v[92:95]
	v_mfma_f32_16x16x32_bf16 v[108:111], v[154:157], v[186:189], 0
	v_mfma_f32_16x16x32_bf16 v[108:111], v[158:161], v[204:207], v[108:111]
	v_mfma_f32_16x16x32_bf16 v[128:131], v[158:161], v[182:185], 0
	v_mfma_f32_16x16x32_bf16 v[128:131], v[154:157], v[178:181], v[128:131]
	v_mfma_f32_16x16x32_bf16 v[120:123], v[162:165], v[178:181], 0
	v_mfma_f32_16x16x32_bf16 v[120:123], v[166:169], v[182:185], v[120:123]
	v_mfma_f32_16x16x32_bf16 v[104:107], v[166:169], v[204:207], 0
	v_mfma_f32_16x16x32_bf16 v[104:107], v[162:165], v[186:189], v[104:107]
	v_mfma_f32_16x16x32_bf16 v[88:91], v[162:165], v[208:211], 0
	v_mfma_f32_16x16x32_bf16 v[88:91], v[166:169], v[212:215], v[88:91]
	v_mfma_f32_16x16x32_bf16 v[72:75], v[166:169], v[220:223], 0
	v_mfma_f32_16x16x32_bf16 v[72:75], v[162:165], v[216:219], v[72:75]
	v_mfma_f32_16x16x32_bf16 v[68:71], v[170:173], v[216:219], 0
	v_mfma_f32_16x16x32_bf16 v[68:71], v[174:177], v[220:223], v[68:71]
	v_mfma_f32_16x16x32_bf16 v[84:87], v[174:177], v[212:215], 0
	v_mfma_f32_16x16x32_bf16 v[84:87], v[170:173], v[208:211], v[84:87]
	v_mfma_f32_16x16x32_bf16 v[100:103], v[170:173], v[186:189], 0
	v_mfma_f32_16x16x32_bf16 v[100:103], v[174:177], v[204:207], v[100:103]
	v_mfma_f32_16x16x32_bf16 v[116:119], v[174:177], v[182:185], 0
	v_mfma_f32_16x16x32_bf16 v[116:119], v[170:173], v[178:181], v[116:119]
	s_setprio 0
	s_barrier
	s_add_i32 s86, s86, s28
	v_lshl_add_u64 v[190:191], s[76:77], 0, v[2:3]
	s_mov_b32 m0, s86
	ds_read_b128 v[178:181], v145 offset:16384
	ds_read_b128 v[182:185], v145 offset:17408
	ds_read_b128 v[186:189], v145 offset:18432
	ds_read_b128 v[204:207], v145 offset:19456
	ds_read_b128 v[208:211], v145 offset:20480
	ds_read_b128 v[212:215], v145 offset:21504
	ds_read_b128 v[216:219], v145 offset:22528
	ds_read_b128 v[220:223], v145 offset:23552
	global_load_lds_dwordx4 v[190:191], off
	s_add_i32 m0, s86, 0x2000
	v_lshl_add_u64 v[224:225], s[76:77], 0, v[136:137]
	s_add_u32 s76, s76, s18
	s_addc_u32 s77, s77, s19
	s_add_i32 s73, s73, s28
	global_load_lds_dwordx4 v[224:225], off
	v_lshl_add_u64 v[226:227], s[76:77], 0, v[2:3]
	s_mov_b32 m0, s73
	v_lshl_add_u64 v[228:229], s[76:77], 0, v[136:137]
	global_load_lds_dwordx4 v[226:227], off
	s_add_i32 m0, s73, 0x2000
	v_lshl_add_u64 v[240:241], s[48:49], 0, v[132:133]
	global_load_lds_dwordx4 v[228:229], off
	v_lshl_add_u64 v[242:243], s[48:49], 0, v[134:135]
	s_waitcnt vmcnt(6)
	s_waitcnt lgkmcnt(0)
	s_barrier
	s_setprio 1
	s_waitcnt lgkmcnt(0)
	v_mfma_f32_16x16x32_bf16 v[64:67], v[146:149], v[178:181], 0
	v_mfma_f32_16x16x32_bf16 v[64:67], v[150:153], v[182:185], v[64:67]
	v_mfma_f32_16x16x32_bf16 v[48:51], v[150:153], v[204:207], 0
	v_mfma_f32_16x16x32_bf16 v[48:51], v[146:149], v[186:189], v[48:51]
	v_mfma_f32_16x16x32_bf16 v[32:35], v[146:149], v[208:211], 0
	v_mfma_f32_16x16x32_bf16 v[32:35], v[150:153], v[212:215], v[32:35]
	v_mfma_f32_16x16x32_bf16 v[16:19], v[150:153], v[220:223], 0
	v_mfma_f32_16x16x32_bf16 v[16:19], v[146:149], v[216:219], v[16:19]
	v_mfma_f32_16x16x32_bf16 v[12:15], v[154:157], v[216:219], 0
	v_mfma_f32_16x16x32_bf16 v[12:15], v[158:161], v[220:223], v[12:15]
	v_mfma_f32_16x16x32_bf16 v[28:31], v[158:161], v[212:215], 0
	v_mfma_f32_16x16x32_bf16 v[28:31], v[154:157], v[208:211], v[28:31]
	v_mfma_f32_16x16x32_bf16 v[44:47], v[154:157], v[186:189], 0
	v_mfma_f32_16x16x32_bf16 v[44:47], v[158:161], v[204:207], v[44:47]
	v_mfma_f32_16x16x32_bf16 v[60:63], v[158:161], v[182:185], 0
	v_mfma_f32_16x16x32_bf16 v[60:63], v[154:157], v[178:181], v[60:63]
	v_mfma_f32_16x16x32_bf16 v[56:59], v[162:165], v[178:181], 0
	v_mfma_f32_16x16x32_bf16 v[56:59], v[166:169], v[182:185], v[56:59]
	v_mfma_f32_16x16x32_bf16 v[40:43], v[166:169], v[204:207], 0
	v_mfma_f32_16x16x32_bf16 v[40:43], v[162:165], v[186:189], v[40:43]
	v_mfma_f32_16x16x32_bf16 v[24:27], v[162:165], v[208:211], 0
	v_mfma_f32_16x16x32_bf16 v[24:27], v[166:169], v[212:215], v[24:27]
	v_mfma_f32_16x16x32_bf16 v[8:11], v[166:169], v[220:223], 0
	v_mfma_f32_16x16x32_bf16 v[8:11], v[162:165], v[216:219], v[8:11]
	v_mfma_f32_16x16x32_bf16 v[4:7], v[170:173], v[216:219], 0
	v_mfma_f32_16x16x32_bf16 v[4:7], v[174:177], v[220:223], v[4:7]
	v_mfma_f32_16x16x32_bf16 v[20:23], v[174:177], v[212:215], 0
	v_mfma_f32_16x16x32_bf16 v[20:23], v[170:173], v[208:211], v[20:23]
	v_mfma_f32_16x16x32_bf16 v[36:39], v[170:173], v[186:189], 0
	v_mfma_f32_16x16x32_bf16 v[36:39], v[174:177], v[204:207], v[36:39]
	v_mfma_f32_16x16x32_bf16 v[52:55], v[174:177], v[182:185], 0
	v_mfma_f32_16x16x32_bf16 v[52:55], v[170:173], v[178:181], v[52:55]
	s_setprio 0
	s_barrier
; #define PG8_STAGE(bufoff, gbase, voff) do { _Pragma("unroll") for (int _i = 0; _i < 2; ++_i) \
;         __builtin_amdgcn_global_load_lds((const unsigned*)((const char*)(gbase) + (voff)[_i]), (PG8_LAS unsigned*)(lds + (bufoff) + ldsw + _i * 8192), 16, 0, 0); } while (0)
; #define PG8_LDA(dst, b, h) do { _Pragma("unroll") for (int m = 0; m < 4; ++m) _Pragma("unroll") for (int k = 0; k < 2; ++k) dst[m][k] = *(const PG8_LAS bf16x8*)(lds + PG8_SA(b, h) + aoff + m * 2048 + k * 1024); } while (0)
; #define PG8_LDB(dst, b, h) do { _Pragma("unroll") for (int n = 0; n < 2; ++n) _Pragma("unroll") for (int k = 0; k < 2; ++k) dst[n][k] = *(const PG8_LAS bf16x8*)(lds + PG8_SB(b, h) + boff + n * 2048 + k * 1024); } while (0)
; #define PG8_WAIT_V(n) asm volatile("s_waitcnt vmcnt(" #n ")" ::: "memory")
; #define PG8_WAIT_L(n) asm volatile("s_waitcnt lgkmcnt(" #n ")" ::: "memory")
; #define PG8_BAR __builtin_amdgcn_s_barrier()
; #define PG8_SCHED __builtin_amdgcn_sched_barrier(0)
; template <class Epi, class Sched, bool ALIGN_EPI = false, bool SP2 = false, bool I8 = false>
; __device__ __forceinline__ void gemm_phase(PG8_LAS unsigned char* lds, const Gemm g, const Sched& S, const Epi& E) {
;     ...
;             PG8_LDA(At, 0, 1); PG8_STAGE(PG8_SB(0, 0), b2, voffB); PG8_STAGE(PG8_SB(0, 1), b2 + hstep, voffB); PG8_STAGE(PG8_SA(0, 0), a2, voffA);
;             PG8_WAIT_V(8); PG8_WAIT_L(0); PG8_BAR; PG8_MMA(1, 0, At, B0); PG8_MMA(1, 1, At, B1); PG8_BAR; PG8_SCHED;
;             PG8_LDB(B0, 1, 0); PG8_LDB(B1, 1, 1); PG8_SCHED; PG8_LDA(At, 1, 0); PG8_STAGE(PG8_SA(0, 1), a2 + hstep, voffA);
;             PG8_WAIT_V(8); PG8_WAIT_L(0); PG8_BAR; PG8_MMA(0, 0, At, B0); PG8_MMA(0, 1, At, B1); PG8_BAR; PG8_SCHED;
;             PG8_LDA(At, 1, 1); PG8_STAGE(PG8_SB(1, 0), b3, voffB); PG8_STAGE(PG8_SB(1, 1), b3 + hstep, voffB); PG8_STAGE(PG8_SA(1, 0), a3, voffA);
	s_mov_b32 m0, s47
	s_nop 0
	global_load_lds_dwordx4 v[240:241], off
	s_mov_b32 m0, s50
	s_nop 0
	global_load_lds_dwordx4 v[242:243], off
	s_add_i32 s73, 0, 0x18000
	s_add_i32 s76, 0, 0x1c000
	v_add_u32_e32 v158, s73, v143
	v_add_u32_e32 v174, s76, v143
	ds_read_b128 v[146:149], v158
	ds_read_b128 v[150:153], v158 offset:1024
	ds_read_b128 v[154:157], v158 offset:2048
	ds_read_b128 v[158:161], v158 offset:3072
	ds_read_b128 v[162:165], v174
	ds_read_b128 v[166:169], v174 offset:1024
	ds_read_b128 v[170:173], v174 offset:2048
	ds_read_b128 v[174:177], v174 offset:3072
	s_add_u32 s48, s48, s18
	s_addc_u32 s49, s49, s19
	s_mov_b32 m0, s51
	v_lshl_add_u64 v[244:245], s[48:49], 0, v[132:133]
	ds_read_b128 v[178:181], v145 offset:32768
	ds_read_b128 v[182:185], v145 offset:33792
	ds_read_b128 v[186:189], v145 offset:34816
	ds_read_b128 v[204:207], v145 offset:35840
	ds_read_b128 v[208:211], v145 offset:36864
	ds_read_b128 v[212:215], v145 offset:37888
	ds_read_b128 v[216:219], v145 offset:38912
	ds_read_b128 v[220:223], v145 offset:39936
	global_load_lds_dwordx4 v[244:245], off
	v_lshl_add_u64 v[244:245], s[48:49], 0, v[134:135]
	s_mov_b32 m0, s52
	s_nop 0
	global_load_lds_dwordx4 v[244:245], off
	s_waitcnt vmcnt(8)
	s_waitcnt lgkmcnt(0)
	s_barrier
	s_setprio 1
	s_waitcnt lgkmcnt(0)
	v_mfma_f32_16x16x32_bf16 v[124:127], v[146:149], v[178:181], v[124:127]
	v_mfma_f32_16x16x32_bf16 v[124:127], v[150:153], v[182:185], v[124:127]
	v_mfma_f32_16x16x32_bf16 v[112:115], v[150:153], v[204:207], v[112:115]
	v_mfma_f32_16x16x32_bf16 v[112:115], v[146:149], v[186:189], v[112:115]
	v_mfma_f32_16x16x32_bf16 v[96:99], v[146:149], v[208:211], v[96:99]
	v_mfma_f32_16x16x32_bf16 v[96:99], v[150:153], v[212:215], v[96:99]
	v_mfma_f32_16x16x32_bf16 v[80:83], v[150:153], v[220:223], v[80:83]
	v_mfma_f32_16x16x32_bf16 v[80:83], v[146:149], v[216:219], v[80:83]
	v_mfma_f32_16x16x32_bf16 v[76:79], v[154:157], v[216:219], v[76:79]
	v_mfma_f32_16x16x32_bf16 v[76:79], v[158:161], v[220:223], v[76:79]
	v_mfma_f32_16x16x32_bf16 v[92:95], v[158:161], v[212:215], v[92:95]
	v_mfma_f32_16x16x32_bf16 v[92:95], v[154:157], v[208:211], v[92:95]
	v_mfma_f32_16x16x32_bf16 v[108:111], v[154:157], v[186:189], v[108:111]
	v_mfma_f32_16x16x32_bf16 v[108:111], v[158:161], v[204:207], v[108:111]
	v_mfma_f32_16x16x32_bf16 v[128:131], v[158:161], v[182:185], v[128:131]
	v_mfma_f32_16x16x32_bf16 v[128:131], v[154:157], v[178:181], v[128:131]
	v_mfma_f32_16x16x32_bf16 v[120:123], v[162:165], v[178:181], v[120:123]
	v_mfma_f32_16x16x32_bf16 v[120:123], v[166:169], v[182:185], v[120:123]
	v_mfma_f32_16x16x32_bf16 v[104:107], v[166:169], v[204:207], v[104:107]
	v_mfma_f32_16x16x32_bf16 v[104:107], v[162:165], v[186:189], v[104:107]
	v_mfma_f32_16x16x32_bf16 v[88:91], v[162:165], v[208:211], v[88:91]
	v_mfma_f32_16x16x32_bf16 v[88:91], v[166:169], v[212:215], v[88:91]
	v_mfma_f32_16x16x32_bf16 v[72:75], v[166:169], v[220:223], v[72:75]
	v_mfma_f32_16x16x32_bf16 v[72:75], v[162:165], v[216:219], v[72:75]
	v_mfma_f32_16x16x32_bf16 v[68:71], v[170:173], v[216:219], v[68:71]
	v_mfma_f32_16x16x32_bf16 v[68:71], v[174:177], v[220:223], v[68:71]
	v_mfma_f32_16x16x32_bf16 v[84:87], v[174:177], v[212:215], v[84:87]
	v_mfma_f32_16x16x32_bf16 v[84:87], v[170:173], v[208:211], v[84:87]
	v_mfma_f32_16x16x32_bf16 v[100:103], v[170:173], v[186:189], v[100:103]
	v_mfma_f32_16x16x32_bf16 v[100:103], v[174:177], v[204:207], v[100:103]
	v_mfma_f32_16x16x32_bf16 v[116:119], v[174:177], v[182:185], v[116:119]
	v_mfma_f32_16x16x32_bf16 v[116:119], v[170:173], v[178:181], v[116:119]
	s_setprio 0
	s_barrier
	s_add_i32 s48, s73, s28
	v_lshl_add_u64 v[190:191], v[190:191], 0, s[84:85]
	s_mov_b32 m0, s48
	ds_read_b128 v[178:181], v145 offset:49152
	ds_read_b128 v[182:185], v145 offset:50176
	ds_read_b128 v[186:189], v145 offset:51200
	ds_read_b128 v[204:207], v145 offset:52224
	ds_read_b128 v[208:211], v145 offset:53248
	ds_read_b128 v[212:215], v145 offset:54272
	ds_read_b128 v[216:219], v145 offset:55296
	ds_read_b128 v[220:223], v145 offset:56320
	global_load_lds_dwordx4 v[190:191], off
	v_lshl_add_u64 v[190:191], v[224:225], 0, s[84:85]
	s_add_i32 m0, s48, 0x2000
	s_add_i32 s48, s76, s28
	global_load_lds_dwordx4 v[190:191], off
	v_lshl_add_u64 v[190:191], v[226:227], 0, s[84:85]
	s_mov_b32 m0, s48
	s_nop 0
	global_load_lds_dwordx4 v[190:191], off
	v_lshl_add_u64 v[190:191], v[228:229], 0, s[84:85]
	s_add_i32 m0, s48, 0x2000
	s_nop 0
	global_load_lds_dwordx4 v[190:191], off
	v_lshl_add_u64 v[190:191], v[240:241], 0, s[84:85]
	s_mov_b32 m0, s55
	s_nop 0
	global_load_lds_dwordx4 v[190:191], off
	v_lshl_add_u64 v[190:191], v[242:243], 0, s[84:85]
	s_mov_b32 m0, s56
	s_nop 0
	global_load_lds_dwordx4 v[190:191], off
	s_waitcnt vmcnt(8)
	s_waitcnt lgkmcnt(0)
	s_barrier
; #define PG8_STAGE(bufoff, gbase, voff) do { _Pragma("unroll") for (int _i = 0; _i < 2; ++_i) \
;         __builtin_amdgcn_global_load_lds((const unsigned*)((const char*)(gbase) + (voff)[_i]), (PG8_LAS unsigned*)(lds + (bufoff) + ldsw + _i * 8192), 16, 0, 0); } while (0)
; #define PG8_LDA(dst, b, h) do { _Pragma("unroll") for (int m = 0; m < 4; ++m) _Pragma("unroll") for (int k = 0; k < 2; ++k) dst[m][k] = *(const PG8_LAS bf16x8*)(lds + PG8_SA(b, h) + aoff + m * 2048 + k * 1024); } while (0)
; #define PG8_WAIT_V(n) asm volatile("s_waitcnt vmcnt(" #n ")" ::: "memory")
; #define PG8_WAIT_L(n) asm volatile("s_waitcnt lgkmcnt(" #n ")" ::: "memory")
; #define PG8_BAR __builtin_amdgcn_s_barrier()
; template <class Epi, class Sched, bool ALIGN_EPI = false, bool SP2 = false, bool I8 = false>
; __device__ __forceinline__ void gemm_phase(PG8_LAS unsigned char* lds, const Gemm g, const Sched& S, const Epi& E) {
;     ...
;         for (int t = 0; t < nt; t += 2) {
;             const bool last = (t == nt - 2);
;             const char* a1 = cA + (size_t)(t + 1) * kstep;
;             const char* a2 = last ? nA : cA + (size_t)(t + 2) * kstep; const char* b2 = last ? nB : cB + (size_t)(t + 2) * kstep;
;             const char* a3 = a2 + kstep; const char* b3 = b2 + kstep;
;             if (last && has_next) S.a_ready(nxt);
;             if constexpr (SP2) {
;             PG8_LDB(B0, 0, 0); PG8_LDB(B1, 0, 1); PG8_SCHED; PG8_LDA(At, 0, 0); PG8_STAGE(PG8_SA(1, 1), a1 + hstep, voffA);
;             PG8_WAIT_V(8); PG8_WAIT_L(0); PG8_BAR; PG8_MMA(0, 0, At, B0); PG8_MMA(0, 1, At, B1); PG8_BAR; PG8_SCHED;
;             PG8_LDA(At, 0, 1); PG8_STAGE(PG8_SB(0, 0), b2, voffB); PG8_STAGE(PG8_SB(0, 1), b2 + hstep, voffB); PG8_STAGE(PG8_SA(0, 0), a2, voffA);
;             PG8_WAIT_V(8); PG8_WAIT_L(0); PG8_BAR; PG8_MMA(1, 0, At, B0); PG8_MMA(1, 1, At, B1); PG8_BAR; PG8_SCHED;
;             PG8_LDB(B0, 1, 0); PG8_LDB(B1, 1, 1); PG8_SCHED; PG8_LDA(At, 1, 0); PG8_STAGE(PG8_SA(0, 1), a2 + hstep, voffA);
;             PG8_WAIT_V(8); PG8_WAIT_L(0); PG8_BAR; PG8_MMA(0, 0, At, B0); PG8_MMA(0, 1, At, B1); PG8_BAR; PG8_SCHED;
;             PG8_LDA(At, 1, 1); PG8_STAGE(PG8_SB(1, 0), b3, voffB); PG8_STAGE(PG8_SB(1, 1), b3 + hstep, voffB); PG8_STAGE(PG8_SA(1, 0), a3, voffA);
;             PG8_WAIT_V(8); PG8_WAIT_L(0); PG8_BAR; PG8_MMA(1, 0, At, B0); PG8_MMA(1, 1, At, B1); PG8_BAR; PG8_SCHED;
	s_setprio 1
	s_waitcnt lgkmcnt(0)
	v_mfma_f32_16x16x32_bf16 v[64:67], v[146:149], v[178:181], v[64:67]
	v_mfma_f32_16x16x32_bf16 v[64:67], v[150:153], v[182:185], v[64:67]
	v_mfma_f32_16x16x32_bf16 v[48:51], v[150:153], v[204:207], v[48:51]
	v_mfma_f32_16x16x32_bf16 v[48:51], v[146:149], v[186:189], v[48:51]
	v_mfma_f32_16x16x32_bf16 v[32:35], v[146:149], v[208:211], v[32:35]
	v_mfma_f32_16x16x32_bf16 v[32:35], v[150:153], v[212:215], v[32:35]
	v_mfma_f32_16x16x32_bf16 v[16:19], v[150:153], v[220:223], v[16:19]
	v_mfma_f32_16x16x32_bf16 v[16:19], v[146:149], v[216:219], v[16:19]
	v_mfma_f32_16x16x32_bf16 v[12:15], v[154:157], v[216:219], v[12:15]
	v_mfma_f32_16x16x32_bf16 v[12:15], v[158:161], v[220:223], v[12:15]
	v_mfma_f32_16x16x32_bf16 v[28:31], v[158:161], v[212:215], v[28:31]
	v_mfma_f32_16x16x32_bf16 v[28:31], v[154:157], v[208:211], v[28:31]
	v_mfma_f32_16x16x32_bf16 v[44:47], v[154:157], v[186:189], v[44:47]
	v_mfma_f32_16x16x32_bf16 v[44:47], v[158:161], v[204:207], v[44:47]
	v_mfma_f32_16x16x32_bf16 v[60:63], v[158:161], v[182:185], v[60:63]
	v_mfma_f32_16x16x32_bf16 v[60:63], v[154:157], v[178:181], v[60:63]
	v_mfma_f32_16x16x32_bf16 v[56:59], v[162:165], v[178:181], v[56:59]
	v_mfma_f32_16x16x32_bf16 v[56:59], v[166:169], v[182:185], v[56:59]
	v_mfma_f32_16x16x32_bf16 v[40:43], v[166:169], v[204:207], v[40:43]
	v_mfma_f32_16x16x32_bf16 v[40:43], v[162:165], v[186:189], v[40:43]
	v_mfma_f32_16x16x32_bf16 v[24:27], v[162:165], v[208:211], v[24:27]
	v_mfma_f32_16x16x32_bf16 v[24:27], v[166:169], v[212:215], v[24:27]
	v_mfma_f32_16x16x32_bf16 v[8:11], v[166:169], v[220:223], v[8:11]
	v_mfma_f32_16x16x32_bf16 v[8:11], v[162:165], v[216:219], v[8:11]
	v_mfma_f32_16x16x32_bf16 v[4:7], v[170:173], v[216:219], v[4:7]
	v_mfma_f32_16x16x32_bf16 v[4:7], v[174:177], v[220:223], v[4:7]
	v_mfma_f32_16x16x32_bf16 v[20:23], v[174:177], v[212:215], v[20:23]
	v_mfma_f32_16x16x32_bf16 v[20:23], v[170:173], v[208:211], v[20:23]
	v_mfma_f32_16x16x32_bf16 v[36:39], v[170:173], v[186:189], v[36:39]
	v_mfma_f32_16x16x32_bf16 v[36:39], v[174:177], v[204:207], v[36:39]
	v_mfma_f32_16x16x32_bf16 v[52:55], v[174:177], v[182:185], v[52:55]
	v_mfma_f32_16x16x32_bf16 v[52:55], v[170:173], v[178:181], v[52:55]
	s_setprio 0
	s_barrier
	s_add_u32 s44, s44, 0x100
	s_addc_u32 s45, s45, 0
	s_add_u32 s65, s65, 0x100
	s_addc_u32 s67, s67, 0
	s_cmp_ge_i32 s72, s53
	s_mov_b32 s48, s72
	s_cbranch_scc1 .Lkloop_exit_4
.LBB0_1623:
	s_add_i32 s72, s48, 2
	s_add_u32 s73, s44, 0x80
	s_addc_u32 s49, s45, 0
	s_add_i32 s86, 0, 0x10000
	s_cmp_eq_u32 s57, s48
	s_cselect_b32 s49, s13, s49
	s_cselect_b32 s48, s12, s73
	s_cselect_b32 s77, s41, s67
	s_cselect_b32 s76, s40, s65
	s_add_i32 s73, 0, 0x14000
	v_add_u32_e32 v158, s86, v143
	v_add_u32_e32 v174, s73, v143
	ds_read_b128 v[146:149], v158
	ds_read_b128 v[150:153], v158 offset:1024
	ds_read_b128 v[154:157], v158 offset:2048
	ds_read_b128 v[158:161], v158 offset:3072
	ds_read_b128 v[162:165], v174
	ds_read_b128 v[166:169], v174 offset:1024
	ds_read_b128 v[170:173], v174 offset:2048
	ds_read_b128 v[174:177], v174 offset:3072
	v_lshl_add_u64 v[190:191], s[44:45], 0, v[138:139]
	s_add_i32 m0, s47, 0xc000
	ds_read_b128 v[178:181], v145
	ds_read_b128 v[182:185], v145 offset:1024
	ds_read_b128 v[186:189], v145 offset:2048
	ds_read_b128 v[204:207], v145 offset:3072
	ds_read_b128 v[208:211], v145 offset:4096
	ds_read_b128 v[212:215], v145 offset:5120
	ds_read_b128 v[216:219], v145 offset:6144
	ds_read_b128 v[220:223], v145 offset:7168
	global_load_lds_dwordx4 v[190:191], off
	v_lshl_add_u64 v[190:191], s[44:45], 0, v[140:141]
	s_add_i32 m0, s47, 0xe000
	s_nop 0
	global_load_lds_dwordx4 v[190:191], off
	s_waitcnt vmcnt(8)
	s_waitcnt lgkmcnt(0)
	s_barrier
	s_setprio 1
	s_waitcnt lgkmcnt(0)
	v_mfma_f32_16x16x32_bf16 v[124:127], v[146:149], v[178:181], v[124:127]
	v_mfma_f32_16x16x32_bf16 v[124:127], v[150:153], v[182:185], v[124:127]
	v_mfma_f32_16x16x32_bf16 v[112:115], v[150:153], v[204:207], v[112:115]
	v_mfma_f32_16x16x32_bf16 v[112:115], v[146:149], v[186:189], v[112:115]
	v_mfma_f32_16x16x32_bf16 v[96:99], v[146:149], v[208:211], v[96:99]
	v_mfma_f32_16x16x32_bf16 v[96:99], v[150:153], v[212:215], v[96:99]
	v_mfma_f32_16x16x32_bf16 v[80:83], v[150:153], v[220:223], v[80:83]
	v_mfma_f32_16x16x32_bf16 v[80:83], v[146:149], v[216:219], v[80:83]
	v_mfma_f32_16x16x32_bf16 v[76:79], v[154:157], v[216:219], v[76:79]
	v_mfma_f32_16x16x32_bf16 v[76:79], v[158:161], v[220:223], v[76:79]
	v_mfma_f32_16x16x32_bf16 v[92:95], v[158:161], v[212:215], v[92:95]
	v_mfma_f32_16x16x32_bf16 v[92:95], v[154:157], v[208:211], v[92:95]
	v_mfma_f32_16x16x32_bf16 v[108:111], v[154:157], v[186:189], v[108:111]
	v_mfma_f32_16x16x32_bf16 v[108:111], v[158:161], v[204:207], v[108:111]
	v_mfma_f32_16x16x32_bf16 v[128:131], v[158:161], v[182:185], v[128:131]
	v_mfma_f32_16x16x32_bf16 v[128:131], v[154:157], v[178:181], v[128:131]
	v_mfma_f32_16x16x32_bf16 v[120:123], v[162:165], v[178:181], v[120:123]
	v_mfma_f32_16x16x32_bf16 v[120:123], v[166:169], v[182:185], v[120:123]
	v_mfma_f32_16x16x32_bf16 v[104:107], v[166:169], v[204:207], v[104:107]
	v_mfma_f32_16x16x32_bf16 v[104:107], v[162:165], v[186:189], v[104:107]
	v_mfma_f32_16x16x32_bf16 v[88:91], v[162:165], v[208:211], v[88:91]
	v_mfma_f32_16x16x32_bf16 v[88:91], v[166:169], v[212:215], v[88:91]
	v_mfma_f32_16x16x32_bf16 v[72:75], v[166:169], v[220:223], v[72:75]
	v_mfma_f32_16x16x32_bf16 v[72:75], v[162:165], v[216:219], v[72:75]
	v_mfma_f32_16x16x32_bf16 v[68:71], v[170:173], v[216:219], v[68:71]
	v_mfma_f32_16x16x32_bf16 v[68:71], v[174:177], v[220:223], v[68:71]
	v_mfma_f32_16x16x32_bf16 v[84:87], v[174:177], v[212:215], v[84:87]
	v_mfma_f32_16x16x32_bf16 v[84:87], v[170:173], v[208:211], v[84:87]
	v_mfma_f32_16x16x32_bf16 v[100:103], v[170:173], v[186:189], v[100:103]
	v_mfma_f32_16x16x32_bf16 v[100:103], v[174:177], v[204:207], v[100:103]
	v_mfma_f32_16x16x32_bf16 v[116:119], v[174:177], v[182:185], v[116:119]
	v_mfma_f32_16x16x32_bf16 v[116:119], v[170:173], v[178:181], v[116:119]
	s_setprio 0
	s_barrier
; #define PG8_STAGE(bufoff, gbase, voff) do { _Pragma("unroll") for (int _i = 0; _i < 2; ++_i) \
;         __builtin_amdgcn_global_load_lds((const unsigned*)((const char*)(gbase) + (voff)[_i]), (PG8_LAS unsigned*)(lds + (bufoff) + ldsw + _i * 8192), 16, 0, 0); } while (0)
; #define PG8_LDA(dst, b, h) do { _Pragma("unroll") for (int m = 0; m < 4; ++m) _Pragma("unroll") for (int k = 0; k < 2; ++k) dst[m][k] = *(const PG8_LAS bf16x8*)(lds + PG8_SA(b, h) + aoff + m * 2048 + k * 1024); } while (0)
; #define PG8_LDB(dst, b, h) do { _Pragma("unroll") for (int n = 0; n < 2; ++n) _Pragma("unroll") for (int k = 0; k < 2; ++k) dst[n][k] = *(const PG8_LAS bf16x8*)(lds + PG8_SB(b, h) + boff + n * 2048 + k * 1024); } while (0)
; #define PG8_WAIT_V(n) asm volatile("s_waitcnt vmcnt(" #n ")" ::: "memory")
; #define PG8_WAIT_L(n) asm volatile("s_waitcnt lgkmcnt(" #n ")" ::: "memory")
; #define PG8_BAR __builtin_amdgcn_s_barrier()
; #define PG8_SCHED __builtin_amdgcn_sched_barrier(0)
; template <class Epi, class Sched, bool ALIGN_EPI = false, bool SP2 = false, bool I8 = false>
; __device__ __forceinline__ void gemm_phase(PG8_LAS unsigned char* lds, const Gemm g, const Sched& S, const Epi& E) {
;     ...
;             PG8_LDA(At, 0, 1); PG8_STAGE(PG8_SB(0, 0), b2, voffB); PG8_STAGE(PG8_SB(0, 1), b2 + hstep, voffB); PG8_STAGE(PG8_SA(0, 0), a2, voffA);
;             PG8_WAIT_V(8); PG8_WAIT_L(0); PG8_BAR; PG8_MMA(1, 0, At, B0); PG8_MMA(1, 1, At, B1); PG8_BAR; PG8_SCHED;
;             PG8_LDB(B0, 1, 0); PG8_LDB(B1, 1, 1); PG8_SCHED; PG8_LDA(At, 1, 0); PG8_STAGE(PG8_SA(0, 1), a2 + hstep, voffA);
;             PG8_WAIT_V(8); PG8_WAIT_L(0); PG8_BAR; PG8_MMA(0, 0, At, B0); PG8_MMA(0, 1, At, B1); PG8_BAR; PG8_SCHED;
	s_add_i32 s86, s86, s28
	v_lshl_add_u64 v[190:191], s[76:77], 0, v[2:3]
	s_mov_b32 m0, s86
	ds_read_b128 v[178:181], v145 offset:16384
	ds_read_b128 v[182:185], v145 offset:17408
	ds_read_b128 v[186:189], v145 offset:18432
	ds_read_b128 v[204:207], v145 offset:19456
	ds_read_b128 v[208:211], v145 offset:20480
	ds_read_b128 v[212:215], v145 offset:21504
	ds_read_b128 v[216:219], v145 offset:22528
	ds_read_b128 v[220:223], v145 offset:23552
	global_load_lds_dwordx4 v[190:191], off
	s_add_i32 m0, s86, 0x2000
	v_lshl_add_u64 v[224:225], s[76:77], 0, v[136:137]
	s_add_u32 s76, s76, s18
	s_addc_u32 s77, s77, s19
	s_add_i32 s73, s73, s28
	global_load_lds_dwordx4 v[224:225], off
	v_lshl_add_u64 v[226:227], s[76:77], 0, v[2:3]
	s_mov_b32 m0, s73
	v_lshl_add_u64 v[228:229], s[76:77], 0, v[136:137]
	global_load_lds_dwordx4 v[226:227], off
	s_add_i32 m0, s73, 0x2000
	v_lshl_add_u64 v[240:241], s[48:49], 0, v[132:133]
	global_load_lds_dwordx4 v[228:229], off
	v_lshl_add_u64 v[242:243], s[48:49], 0, v[134:135]
	s_waitcnt vmcnt(6)
	s_waitcnt lgkmcnt(0)
	s_barrier
	s_setprio 1
	s_waitcnt lgkmcnt(0)
	v_mfma_f32_16x16x32_bf16 v[64:67], v[146:149], v[178:181], v[64:67]
	v_mfma_f32_16x16x32_bf16 v[64:67], v[150:153], v[182:185], v[64:67]
	v_mfma_f32_16x16x32_bf16 v[48:51], v[150:153], v[204:207], v[48:51]
	v_mfma_f32_16x16x32_bf16 v[48:51], v[146:149], v[186:189], v[48:51]
	v_mfma_f32_16x16x32_bf16 v[32:35], v[146:149], v[208:211], v[32:35]
	v_mfma_f32_16x16x32_bf16 v[32:35], v[150:153], v[212:215], v[32:35]
	v_mfma_f32_16x16x32_bf16 v[16:19], v[150:153], v[220:223], v[16:19]
	v_mfma_f32_16x16x32_bf16 v[16:19], v[146:149], v[216:219], v[16:19]
	v_mfma_f32_16x16x32_bf16 v[12:15], v[154:157], v[216:219], v[12:15]
	v_mfma_f32_16x16x32_bf16 v[12:15], v[158:161], v[220:223], v[12:15]
	v_mfma_f32_16x16x32_bf16 v[28:31], v[158:161], v[212:215], v[28:31]
	v_mfma_f32_16x16x32_bf16 v[28:31], v[154:157], v[208:211], v[28:31]
	v_mfma_f32_16x16x32_bf16 v[44:47], v[154:157], v[186:189], v[44:47]
	v_mfma_f32_16x16x32_bf16 v[44:47], v[158:161], v[204:207], v[44:47]
	v_mfma_f32_16x16x32_bf16 v[60:63], v[158:161], v[182:185], v[60:63]
	v_mfma_f32_16x16x32_bf16 v[60:63], v[154:157], v[178:181], v[60:63]
	v_mfma_f32_16x16x32_bf16 v[56:59], v[162:165], v[178:181], v[56:59]
	v_mfma_f32_16x16x32_bf16 v[56:59], v[166:169], v[182:185], v[56:59]
	v_mfma_f32_16x16x32_bf16 v[40:43], v[166:169], v[204:207], v[40:43]
	v_mfma_f32_16x16x32_bf16 v[40:43], v[162:165], v[186:189], v[40:43]
	v_mfma_f32_16x16x32_bf16 v[24:27], v[162:165], v[208:211], v[24:27]
	v_mfma_f32_16x16x32_bf16 v[24:27], v[166:169], v[212:215], v[24:27]
	v_mfma_f32_16x16x32_bf16 v[8:11], v[166:169], v[220:223], v[8:11]
	v_mfma_f32_16x16x32_bf16 v[8:11], v[162:165], v[216:219], v[8:11]
	v_mfma_f32_16x16x32_bf16 v[4:7], v[170:173], v[216:219], v[4:7]
	v_mfma_f32_16x16x32_bf16 v[4:7], v[174:177], v[220:223], v[4:7]
	v_mfma_f32_16x16x32_bf16 v[20:23], v[174:177], v[212:215], v[20:23]
	v_mfma_f32_16x16x32_bf16 v[20:23], v[170:173], v[208:211], v[20:23]
	v_mfma_f32_16x16x32_bf16 v[36:39], v[170:173], v[186:189], v[36:39]
	v_mfma_f32_16x16x32_bf16 v[36:39], v[174:177], v[204:207], v[36:39]
	v_mfma_f32_16x16x32_bf16 v[52:55], v[174:177], v[182:185], v[52:55]
	v_mfma_f32_16x16x32_bf16 v[52:55], v[170:173], v[178:181], v[52:55]
	s_setprio 0
	s_barrier
	s_mov_b32 m0, s47
	s_nop 0
	global_load_lds_dwordx4 v[240:241], off
	s_mov_b32 m0, s50
	s_nop 0
	global_load_lds_dwordx4 v[242:243], off
	s_add_i32 s73, 0, 0x18000
	s_add_i32 s76, 0, 0x1c000
	v_add_u32_e32 v158, s73, v143
	v_add_u32_e32 v174, s76, v143
	ds_read_b128 v[146:149], v158
	ds_read_b128 v[150:153], v158 offset:1024
	ds_read_b128 v[154:157], v158 offset:2048
	ds_read_b128 v[158:161], v158 offset:3072
	ds_read_b128 v[162:165], v174
	ds_read_b128 v[166:169], v174 offset:1024
	ds_read_b128 v[170:173], v174 offset:2048
	ds_read_b128 v[174:177], v174 offset:3072
	s_add_u32 s48, s48, s18
	s_addc_u32 s49, s49, s19
	s_mov_b32 m0, s51
	v_lshl_add_u64 v[244:245], s[48:49], 0, v[132:133]
	ds_read_b128 v[178:181], v145 offset:32768
	ds_read_b128 v[182:185], v145 offset:33792
	ds_read_b128 v[186:189], v145 offset:34816
	ds_read_b128 v[204:207], v145 offset:35840
	ds_read_b128 v[208:211], v145 offset:36864
	ds_read_b128 v[212:215], v145 offset:37888
	ds_read_b128 v[216:219], v145 offset:38912
	ds_read_b128 v[220:223], v145 offset:39936
	global_load_lds_dwordx4 v[244:245], off
	v_lshl_add_u64 v[244:245], s[48:49], 0, v[134:135]
	s_mov_b32 m0, s52
	s_nop 0
	global_load_lds_dwordx4 v[244:245], off
	s_waitcnt vmcnt(8)
	s_waitcnt lgkmcnt(0)
	s_barrier
; #define PG8_STAGE(bufoff, gbase, voff) do { _Pragma("unroll") for (int _i = 0; _i < 2; ++_i) \
;         __builtin_amdgcn_global_load_lds((const unsigned*)((const char*)(gbase) + (voff)[_i]), (PG8_LAS unsigned*)(lds + (bufoff) + ldsw + _i * 8192), 16, 0, 0); } while (0)
; #define PG8_LDA(dst, b, h) do { _Pragma("unroll") for (int m = 0; m < 4; ++m) _Pragma("unroll") for (int k = 0; k < 2; ++k) dst[m][k] = *(const PG8_LAS bf16x8*)(lds + PG8_SA(b, h) + aoff + m * 2048 + k * 1024); } while (0)
; #define PG8_WAIT_V(n) asm volatile("s_waitcnt vmcnt(" #n ")" ::: "memory")
; #define PG8_WAIT_L(n) asm volatile("s_waitcnt lgkmcnt(" #n ")" ::: "memory")
; #define PG8_BAR __builtin_amdgcn_s_barrier()
; #define PG8_SCHED __builtin_amdgcn_sched_barrier(0)
; template <class Epi, class Sched, bool ALIGN_EPI = false, bool SP2 = false, bool I8 = false>
; __device__ __forceinline__ void gemm_phase(PG8_LAS unsigned char* lds, const Gemm g, const Sched& S, const Epi& E) {
;     ...
;             PG8_WAIT_V(8); PG8_WAIT_L(0); PG8_BAR; PG8_MMA(0, 0, At, B0); PG8_MMA(0, 1, At, B1); PG8_BAR; PG8_SCHED;
;             PG8_LDA(At, 1, 1); PG8_STAGE(PG8_SB(1, 0), b3, voffB); PG8_STAGE(PG8_SB(1, 1), b3 + hstep, voffB); PG8_STAGE(PG8_SA(1, 0), a3, voffA);
;             PG8_WAIT_V(8); PG8_WAIT_L(0); PG8_BAR; PG8_MMA(1, 0, At, B0); PG8_MMA(1, 1, At, B1); PG8_BAR; PG8_SCHED;
	s_setprio 1
	s_waitcnt lgkmcnt(0)
	v_mfma_f32_16x16x32_bf16 v[124:127], v[146:149], v[178:181], v[124:127]
	v_mfma_f32_16x16x32_bf16 v[124:127], v[150:153], v[182:185], v[124:127]
	v_mfma_f32_16x16x32_bf16 v[112:115], v[150:153], v[204:207], v[112:115]
	v_mfma_f32_16x16x32_bf16 v[112:115], v[146:149], v[186:189], v[112:115]
	v_mfma_f32_16x16x32_bf16 v[96:99], v[146:149], v[208:211], v[96:99]
	v_mfma_f32_16x16x32_bf16 v[96:99], v[150:153], v[212:215], v[96:99]
	v_mfma_f32_16x16x32_bf16 v[80:83], v[150:153], v[220:223], v[80:83]
	v_mfma_f32_16x16x32_bf16 v[80:83], v[146:149], v[216:219], v[80:83]
	v_mfma_f32_16x16x32_bf16 v[76:79], v[154:157], v[216:219], v[76:79]
	v_mfma_f32_16x16x32_bf16 v[76:79], v[158:161], v[220:223], v[76:79]
	v_mfma_f32_16x16x32_bf16 v[92:95], v[158:161], v[212:215], v[92:95]
	v_mfma_f32_16x16x32_bf16 v[92:95], v[154:157], v[208:211], v[92:95]
	v_mfma_f32_16x16x32_bf16 v[108:111], v[154:157], v[186:189], v[108:111]
	v_mfma_f32_16x16x32_bf16 v[108:111], v[158:161], v[204:207], v[108:111]
	v_mfma_f32_16x16x32_bf16 v[128:131], v[158:161], v[182:185], v[128:131]
	v_mfma_f32_16x16x32_bf16 v[128:131], v[154:157], v[178:181], v[128:131]
	v_mfma_f32_16x16x32_bf16 v[120:123], v[162:165], v[178:181], v[120:123]
	v_mfma_f32_16x16x32_bf16 v[120:123], v[166:169], v[182:185], v[120:123]
	v_mfma_f32_16x16x32_bf16 v[104:107], v[166:169], v[204:207], v[104:107]
	v_mfma_f32_16x16x32_bf16 v[104:107], v[162:165], v[186:189], v[104:107]
	v_mfma_f32_16x16x32_bf16 v[88:91], v[162:165], v[208:211], v[88:91]
	v_mfma_f32_16x16x32_bf16 v[88:91], v[166:169], v[212:215], v[88:91]
	v_mfma_f32_16x16x32_bf16 v[72:75], v[166:169], v[220:223], v[72:75]
	v_mfma_f32_16x16x32_bf16 v[72:75], v[162:165], v[216:219], v[72:75]
	v_mfma_f32_16x16x32_bf16 v[68:71], v[170:173], v[216:219], v[68:71]
	v_mfma_f32_16x16x32_bf16 v[68:71], v[174:177], v[220:223], v[68:71]
	v_mfma_f32_16x16x32_bf16 v[84:87], v[174:177], v[212:215], v[84:87]
	v_mfma_f32_16x16x32_bf16 v[84:87], v[170:173], v[208:211], v[84:87]
	v_mfma_f32_16x16x32_bf16 v[100:103], v[170:173], v[186:189], v[100:103]
	v_mfma_f32_16x16x32_bf16 v[100:103], v[174:177], v[204:207], v[100:103]
	v_mfma_f32_16x16x32_bf16 v[116:119], v[174:177], v[182:185], v[116:119]
	v_mfma_f32_16x16x32_bf16 v[116:119], v[170:173], v[178:181], v[116:119]
	s_setprio 0
	s_barrier
	s_add_i32 s48, s73, s28
	v_lshl_add_u64 v[190:191], v[190:191], 0, s[84:85]
	s_mov_b32 m0, s48
	ds_read_b128 v[178:181], v145 offset:49152
	ds_read_b128 v[182:185], v145 offset:50176
	ds_read_b128 v[186:189], v145 offset:51200
	ds_read_b128 v[204:207], v145 offset:52224
	ds_read_b128 v[208:211], v145 offset:53248
	ds_read_b128 v[212:215], v145 offset:54272
	ds_read_b128 v[216:219], v145 offset:55296
	ds_read_b128 v[220:223], v145 offset:56320
	global_load_lds_dwordx4 v[190:191], off
	v_lshl_add_u64 v[190:191], v[224:225], 0, s[84:85]
	s_add_i32 m0, s48, 0x2000
	s_add_i32 s48, s76, s28
	global_load_lds_dwordx4 v[190:191], off
	v_lshl_add_u64 v[190:191], v[226:227], 0, s[84:85]
	s_mov_b32 m0, s48
	s_nop 0
	global_load_lds_dwordx4 v[190:191], off
	v_lshl_add_u64 v[190:191], v[228:229], 0, s[84:85]
	s_add_i32 m0, s48, 0x2000
	s_nop 0
	global_load_lds_dwordx4 v[190:191], off
	v_lshl_add_u64 v[190:191], v[240:241], 0, s[84:85]
	s_mov_b32 m0, s55
	s_nop 0
	global_load_lds_dwordx4 v[190:191], off
	v_lshl_add_u64 v[190:191], v[242:243], 0, s[84:85]
	s_mov_b32 m0, s56
	s_nop 0
	global_load_lds_dwordx4 v[190:191], off
	s_waitcnt vmcnt(8)
	s_waitcnt lgkmcnt(0)
	s_barrier
	s_setprio 1
	s_waitcnt lgkmcnt(0)
	v_mfma_f32_16x16x32_bf16 v[64:67], v[146:149], v[178:181], v[64:67]
	v_mfma_f32_16x16x32_bf16 v[64:67], v[150:153], v[182:185], v[64:67]
	v_mfma_f32_16x16x32_bf16 v[48:51], v[150:153], v[204:207], v[48:51]
	v_mfma_f32_16x16x32_bf16 v[48:51], v[146:149], v[186:189], v[48:51]
	v_mfma_f32_16x16x32_bf16 v[32:35], v[146:149], v[208:211], v[32:35]
	v_mfma_f32_16x16x32_bf16 v[32:35], v[150:153], v[212:215], v[32:35]
	v_mfma_f32_16x16x32_bf16 v[16:19], v[150:153], v[220:223], v[16:19]
	v_mfma_f32_16x16x32_bf16 v[16:19], v[146:149], v[216:219], v[16:19]
	v_mfma_f32_16x16x32_bf16 v[12:15], v[154:157], v[216:219], v[12:15]
	v_mfma_f32_16x16x32_bf16 v[12:15], v[158:161], v[220:223], v[12:15]
	v_mfma_f32_16x16x32_bf16 v[28:31], v[158:161], v[212:215], v[28:31]
	v_mfma_f32_16x16x32_bf16 v[28:31], v[154:157], v[208:211], v[28:31]
	v_mfma_f32_16x16x32_bf16 v[44:47], v[154:157], v[186:189], v[44:47]
	v_mfma_f32_16x16x32_bf16 v[44:47], v[158:161], v[204:207], v[44:47]
	v_mfma_f32_16x16x32_bf16 v[60:63], v[158:161], v[182:185], v[60:63]
	v_mfma_f32_16x16x32_bf16 v[60:63], v[154:157], v[178:181], v[60:63]
	v_mfma_f32_16x16x32_bf16 v[56:59], v[162:165], v[178:181], v[56:59]
	v_mfma_f32_16x16x32_bf16 v[56:59], v[166:169], v[182:185], v[56:59]
	v_mfma_f32_16x16x32_bf16 v[40:43], v[166:169], v[204:207], v[40:43]
	v_mfma_f32_16x16x32_bf16 v[40:43], v[162:165], v[186:189], v[40:43]
	v_mfma_f32_16x16x32_bf16 v[24:27], v[162:165], v[208:211], v[24:27]
	v_mfma_f32_16x16x32_bf16 v[24:27], v[166:169], v[212:215], v[24:27]
	v_mfma_f32_16x16x32_bf16 v[8:11], v[166:169], v[220:223], v[8:11]
	v_mfma_f32_16x16x32_bf16 v[8:11], v[162:165], v[216:219], v[8:11]
	v_mfma_f32_16x16x32_bf16 v[4:7], v[170:173], v[216:219], v[4:7]
	v_mfma_f32_16x16x32_bf16 v[4:7], v[174:177], v[220:223], v[4:7]
	v_mfma_f32_16x16x32_bf16 v[20:23], v[174:177], v[212:215], v[20:23]
	v_mfma_f32_16x16x32_bf16 v[20:23], v[170:173], v[208:211], v[20:23]
	v_mfma_f32_16x16x32_bf16 v[36:39], v[170:173], v[186:189], v[36:39]
	v_mfma_f32_16x16x32_bf16 v[36:39], v[174:177], v[204:207], v[36:39]
	v_mfma_f32_16x16x32_bf16 v[52:55], v[174:177], v[182:185], v[52:55]
	v_mfma_f32_16x16x32_bf16 v[52:55], v[170:173], v[178:181], v[52:55]
	s_setprio 0
	s_barrier
	s_add_u32 s44, s44, 0x100
	s_addc_u32 s45, s45, 0
	s_add_u32 s65, s65, 0x100
	s_addc_u32 s67, s67, 0
	s_cmp_ge_i32 s72, s53
	s_mov_b32 s48, s72
	s_cbranch_scc0 .LBB0_1623

; #define PG8_STAGE(bufoff, gbase, voff) do { _Pragma("unroll") for (int _i = 0; _i < 2; ++_i) \
;         __builtin_amdgcn_global_load_lds((const unsigned*)((const char*)(gbase) + (voff)[_i]), (PG8_LAS unsigned*)(lds + (bufoff) + ldsw + _i * 8192), 16, 0, 0); } while (0)
; #define PG8_LDA(dst, b, h) do { _Pragma("unroll") for (int m = 0; m < 4; ++m) _Pragma("unroll") for (int k = 0; k < 2; ++k) dst[m][k] = *(const PG8_LAS bf16x8*)(lds + PG8_SA(b, h) + aoff + m * 2048 + k * 1024); } while (0)
; #define PG8_LDB(dst, b, h) do { _Pragma("unroll") for (int n = 0; n < 2; ++n) _Pragma("unroll") for (int k = 0; k < 2; ++k) dst[n][k] = *(const PG8_LAS bf16x8*)(lds + PG8_SB(b, h) + boff + n * 2048 + k * 1024); } while (0)
; #define PG8_WAIT_V(n) asm volatile("s_waitcnt vmcnt(" #n ")" ::: "memory")
; #define PG8_WAIT_L(n) asm volatile("s_waitcnt lgkmcnt(" #n ")" ::: "memory")
; #define PG8_BAR __builtin_amdgcn_s_barrier()
; #define PG8_SCHED __builtin_amdgcn_sched_barrier(0)
; template <class Epi, class Sched, bool ALIGN_EPI = false, bool SP2 = false, bool I8 = false>
; __device__ __forceinline__ void gemm_phase(PG8_LAS unsigned char* lds, const Gemm g, const Sched& S, const Epi& E) {
;     ...
;         const char* nA = has_next ? (const char*)g.A + (size_t)nxt.pm * tstep : cA; const char* nB = has_next ? (const char*)g.Bt + (size_t)nxt.pn * tstep : cB;
;         for (int t = 0; t < nt; t += 2) {
;             const bool last = (t == nt - 2);
;             const char* a1 = cA + (size_t)(t + 1) * kstep;
;             const char* a2 = last ? nA : cA + (size_t)(t + 2) * kstep; const char* b2 = last ? nB : cB + (size_t)(t + 2) * kstep;
;             const char* a3 = a2 + kstep; const char* b3 = b2 + kstep;
;             if (last && has_next) S.a_ready(nxt);
;             if constexpr (SP2) {
;             PG8_LDB(B0, 0, 0); PG8_LDB(B1, 0, 1); PG8_SCHED; PG8_LDA(At, 0, 0); PG8_STAGE(PG8_SA(1, 1), a1 + hstep, voffA);
;             PG8_WAIT_V(8); PG8_WAIT_L(0); PG8_BAR; PG8_MMA(0, 0, At, B0); PG8_MMA(0, 1, At, B1); PG8_BAR; PG8_SCHED;
;             PG8_LDA(At, 0, 1); PG8_STAGE(PG8_SB(0, 0), b2, voffB); PG8_STAGE(PG8_SB(0, 1), b2 + hstep, voffB); PG8_STAGE(PG8_SA(0, 0), a2, voffA);
;             PG8_WAIT_V(8); PG8_WAIT_L(0); PG8_BAR; PG8_MMA(1, 0, At, B0); PG8_MMA(1, 1, At, B1); PG8_BAR; PG8_SCHED;
.LBB0_1699:
	s_add_u32 s53, s24, 0x100
	s_addc_u32 s54, s25, 0
	s_mov_b32 s55, -2
	s_add_u32 s24, s22, 0x100
	s_addc_u32 s25, s23, 0
	s_add_i32 s56, 0, 0x10000
	s_cmpk_eq_i32 s55, 0xa8
	s_cselect_b32 s37, s13, s25
	s_cselect_b32 s36, s12, s24
	s_cselect_b32 s27, s21, s54
	s_cselect_b32 s26, s20, s53
	s_add_i32 s57, 0, 0x14000
	v_add_u32_e32 v144, s56, v240
	v_add_u32_e32 v160, s57, v240
	ds_read_b128 v[124:127], v144
	ds_read_b128 v[128:131], v144 offset:1024
	ds_read_b128 v[132:135], v144 offset:2048
	ds_read_b128 v[144:147], v144 offset:3072
	ds_read_b128 v[148:151], v160
	ds_read_b128 v[152:155], v160 offset:1024
	ds_read_b128 v[156:159], v160 offset:2048
	ds_read_b128 v[160:163], v160 offset:3072
	v_lshl_add_u64 v[218:219], s[22:23], 0, v[210:211]
	s_add_i32 m0, s42, 0xc000
	ds_read_b128 v[164:167], v242
	ds_read_b128 v[168:171], v242 offset:1024
	ds_read_b128 v[172:175], v242 offset:2048
	ds_read_b128 v[176:179], v242 offset:3072
	ds_read_b128 v[180:183], v242 offset:4096
	ds_read_b128 v[184:187], v242 offset:5120
	ds_read_b128 v[188:191], v242 offset:6144
	ds_read_b128 v[214:217], v242 offset:7168
	global_load_lds_dwordx4 v[218:219], off
	v_lshl_add_u64 v[218:219], s[22:23], 0, v[212:213]
	s_add_i32 m0, s42, 0xe000
	s_nop 0
	global_load_lds_dwordx4 v[218:219], off
	s_waitcnt vmcnt(8)
	s_waitcnt lgkmcnt(0)
	s_barrier
	s_setprio 1
	s_waitcnt lgkmcnt(0)
	v_mfma_f32_16x16x32_bf16 v[140:143], v[124:127], v[164:167], 0
	v_mfma_f32_16x16x32_bf16 v[140:143], v[128:131], v[168:171], v[140:143]
	v_mfma_f32_16x16x32_bf16 v[112:115], v[128:131], v[176:179], 0
	v_mfma_f32_16x16x32_bf16 v[112:115], v[124:127], v[172:175], v[112:115]
	v_mfma_f32_16x16x32_bf16 v[96:99], v[124:127], v[180:183], 0
	v_mfma_f32_16x16x32_bf16 v[96:99], v[128:131], v[184:187], v[96:99]
	v_mfma_f32_16x16x32_bf16 v[80:83], v[128:131], v[214:217], 0
	v_mfma_f32_16x16x32_bf16 v[80:83], v[124:127], v[188:191], v[80:83]
	v_mfma_f32_16x16x32_bf16 v[76:79], v[132:135], v[188:191], 0
	v_mfma_f32_16x16x32_bf16 v[76:79], v[144:147], v[214:217], v[76:79]
	v_mfma_f32_16x16x32_bf16 v[92:95], v[144:147], v[184:187], 0
	v_mfma_f32_16x16x32_bf16 v[92:95], v[132:135], v[180:183], v[92:95]
	v_mfma_f32_16x16x32_bf16 v[108:111], v[132:135], v[172:175], 0
	v_mfma_f32_16x16x32_bf16 v[108:111], v[144:147], v[176:179], v[108:111]
	v_mfma_f32_16x16x32_bf16 v[136:139], v[144:147], v[168:171], 0
	v_mfma_f32_16x16x32_bf16 v[136:139], v[132:135], v[164:167], v[136:139]
	v_mfma_f32_16x16x32_bf16 v[120:123], v[148:151], v[164:167], 0
	v_mfma_f32_16x16x32_bf16 v[120:123], v[152:155], v[168:171], v[120:123]
	v_mfma_f32_16x16x32_bf16 v[104:107], v[152:155], v[176:179], 0
	v_mfma_f32_16x16x32_bf16 v[104:107], v[148:151], v[172:175], v[104:107]
	v_mfma_f32_16x16x32_bf16 v[88:91], v[148:151], v[180:183], 0
	v_mfma_f32_16x16x32_bf16 v[88:91], v[152:155], v[184:187], v[88:91]
	v_mfma_f32_16x16x32_bf16 v[72:75], v[152:155], v[214:217], 0
	v_mfma_f32_16x16x32_bf16 v[72:75], v[148:151], v[188:191], v[72:75]
	v_mfma_f32_16x16x32_bf16 v[68:71], v[156:159], v[188:191], 0
	v_mfma_f32_16x16x32_bf16 v[68:71], v[160:163], v[214:217], v[68:71]
	v_mfma_f32_16x16x32_bf16 v[84:87], v[160:163], v[184:187], 0
	v_mfma_f32_16x16x32_bf16 v[84:87], v[156:159], v[180:183], v[84:87]
	v_mfma_f32_16x16x32_bf16 v[100:103], v[156:159], v[172:175], 0
	v_mfma_f32_16x16x32_bf16 v[100:103], v[160:163], v[176:179], v[100:103]
	v_mfma_f32_16x16x32_bf16 v[116:119], v[160:163], v[168:171], 0
	v_mfma_f32_16x16x32_bf16 v[116:119], v[156:159], v[164:167], v[116:119]
	s_setprio 0
	s_barrier
	s_add_i32 s22, s56, s41
	v_lshl_add_u64 v[218:219], s[26:27], 0, v[2:3]
	s_mov_b32 m0, s22
	ds_read_b128 v[164:167], v242 offset:16384
	ds_read_b128 v[168:171], v242 offset:17408
	ds_read_b128 v[172:175], v242 offset:18432
	ds_read_b128 v[176:179], v242 offset:19456
	ds_read_b128 v[180:183], v242 offset:20480
	ds_read_b128 v[184:187], v242 offset:21504
	ds_read_b128 v[188:191], v242 offset:22528
	ds_read_b128 v[214:217], v242 offset:23552
	global_load_lds_dwordx4 v[218:219], off
	s_add_i32 m0, s22, 0x2000
	s_add_u32 s22, s26, 0x2b0000
	v_lshl_add_u64 v[220:221], s[26:27], 0, v[204:205]
	s_addc_u32 s23, s27, 0
	s_add_i32 s56, s57, s41
	global_load_lds_dwordx4 v[220:221], off
	v_lshl_add_u64 v[222:223], s[22:23], 0, v[2:3]
	s_mov_b32 m0, s56
	v_lshl_add_u64 v[224:225], s[36:37], 0, v[206:207]
	global_load_lds_dwordx4 v[222:223], off
	v_lshl_add_u64 v[222:223], s[22:23], 0, v[204:205]
	s_add_i32 m0, s56, 0x2000
	s_nop 0
	global_load_lds_dwordx4 v[222:223], off
	v_lshl_add_u64 v[222:223], s[36:37], 0, v[208:209]
	s_waitcnt vmcnt(6)
	s_waitcnt lgkmcnt(0)
	s_barrier
; #define PG8_STAGE(bufoff, gbase, voff) do { _Pragma("unroll") for (int _i = 0; _i < 2; ++_i) \
;         __builtin_amdgcn_global_load_lds((const unsigned*)((const char*)(gbase) + (voff)[_i]), (PG8_LAS unsigned*)(lds + (bufoff) + ldsw + _i * 8192), 16, 0, 0); } while (0)
; #define PG8_LDA(dst, b, h) do { _Pragma("unroll") for (int m = 0; m < 4; ++m) _Pragma("unroll") for (int k = 0; k < 2; ++k) dst[m][k] = *(const PG8_LAS bf16x8*)(lds + PG8_SA(b, h) + aoff + m * 2048 + k * 1024); } while (0)
; #define PG8_LDB(dst, b, h) do { _Pragma("unroll") for (int n = 0; n < 2; ++n) _Pragma("unroll") for (int k = 0; k < 2; ++k) dst[n][k] = *(const PG8_LAS bf16x8*)(lds + PG8_SB(b, h) + boff + n * 2048 + k * 1024); } while (0)
; #define PG8_WAIT_V(n) asm volatile("s_waitcnt vmcnt(" #n ")" ::: "memory")
; #define PG8_WAIT_L(n) asm volatile("s_waitcnt lgkmcnt(" #n ")" ::: "memory")
; #define PG8_BAR __builtin_amdgcn_s_barrier()
; #define PG8_SCHED __builtin_amdgcn_sched_barrier(0)
; template <class Epi, class Sched, bool ALIGN_EPI = false, bool SP2 = false, bool I8 = false>
; __device__ __forceinline__ void gemm_phase(PG8_LAS unsigned char* lds, const Gemm g, const Sched& S, const Epi& E) {
;     ...
;             PG8_WAIT_V(8); PG8_WAIT_L(0); PG8_BAR; PG8_MMA(1, 0, At, B0); PG8_MMA(1, 1, At, B1); PG8_BAR; PG8_SCHED;
;             PG8_LDB(B0, 1, 0); PG8_LDB(B1, 1, 1); PG8_SCHED; PG8_LDA(At, 1, 0); PG8_STAGE(PG8_SA(0, 1), a2 + hstep, voffA);
;             PG8_WAIT_V(8); PG8_WAIT_L(0); PG8_BAR; PG8_MMA(0, 0, At, B0); PG8_MMA(0, 1, At, B1); PG8_BAR; PG8_SCHED;
	s_setprio 1
	s_waitcnt lgkmcnt(0)
	v_mfma_f32_16x16x32_bf16 v[64:67], v[124:127], v[164:167], 0
	v_mfma_f32_16x16x32_bf16 v[64:67], v[128:131], v[168:171], v[64:67]
	v_mfma_f32_16x16x32_bf16 v[48:51], v[128:131], v[176:179], 0
	v_mfma_f32_16x16x32_bf16 v[48:51], v[124:127], v[172:175], v[48:51]
	v_mfma_f32_16x16x32_bf16 v[32:35], v[124:127], v[180:183], 0
	v_mfma_f32_16x16x32_bf16 v[32:35], v[128:131], v[184:187], v[32:35]
	v_mfma_f32_16x16x32_bf16 v[16:19], v[128:131], v[214:217], 0
	v_mfma_f32_16x16x32_bf16 v[16:19], v[124:127], v[188:191], v[16:19]
	v_mfma_f32_16x16x32_bf16 v[12:15], v[132:135], v[188:191], 0
	v_mfma_f32_16x16x32_bf16 v[12:15], v[144:147], v[214:217], v[12:15]
	v_mfma_f32_16x16x32_bf16 v[28:31], v[144:147], v[184:187], 0
	v_mfma_f32_16x16x32_bf16 v[28:31], v[132:135], v[180:183], v[28:31]
	v_mfma_f32_16x16x32_bf16 v[44:47], v[132:135], v[172:175], 0
	v_mfma_f32_16x16x32_bf16 v[44:47], v[144:147], v[176:179], v[44:47]
	v_mfma_f32_16x16x32_bf16 v[60:63], v[144:147], v[168:171], 0
	v_mfma_f32_16x16x32_bf16 v[60:63], v[132:135], v[164:167], v[60:63]
	v_mfma_f32_16x16x32_bf16 v[56:59], v[148:151], v[164:167], 0
	v_mfma_f32_16x16x32_bf16 v[56:59], v[152:155], v[168:171], v[56:59]
	v_mfma_f32_16x16x32_bf16 v[40:43], v[152:155], v[176:179], 0
	v_mfma_f32_16x16x32_bf16 v[40:43], v[148:151], v[172:175], v[40:43]
	v_mfma_f32_16x16x32_bf16 v[24:27], v[148:151], v[180:183], 0
	v_mfma_f32_16x16x32_bf16 v[24:27], v[152:155], v[184:187], v[24:27]
	v_mfma_f32_16x16x32_bf16 v[8:11], v[152:155], v[214:217], 0
	v_mfma_f32_16x16x32_bf16 v[8:11], v[148:151], v[188:191], v[8:11]
	v_mfma_f32_16x16x32_bf16 v[4:7], v[156:159], v[188:191], 0
	v_mfma_f32_16x16x32_bf16 v[4:7], v[160:163], v[214:217], v[4:7]
	v_mfma_f32_16x16x32_bf16 v[20:23], v[160:163], v[184:187], 0
	v_mfma_f32_16x16x32_bf16 v[20:23], v[156:159], v[180:183], v[20:23]
	v_mfma_f32_16x16x32_bf16 v[36:39], v[156:159], v[172:175], 0
	v_mfma_f32_16x16x32_bf16 v[36:39], v[160:163], v[176:179], v[36:39]
	v_mfma_f32_16x16x32_bf16 v[52:55], v[160:163], v[168:171], 0
	v_mfma_f32_16x16x32_bf16 v[52:55], v[156:159], v[164:167], v[52:55]
	s_setprio 0
	s_barrier
	s_mov_b32 m0, s42
	s_nop 0
	global_load_lds_dwordx4 v[222:223], off
	s_mov_b32 m0, s43
	s_nop 0
	global_load_lds_dwordx4 v[224:225], off
	s_add_i32 s56, 0, 0x18000
	s_add_i32 s57, 0, 0x1c000
	v_add_u32_e32 v144, s56, v240
	v_add_u32_e32 v160, s57, v240
	ds_read_b128 v[124:127], v144
	ds_read_b128 v[128:131], v144 offset:1024
	ds_read_b128 v[132:135], v144 offset:2048
	ds_read_b128 v[144:147], v144 offset:3072
	ds_read_b128 v[148:151], v160
	ds_read_b128 v[152:155], v160 offset:1024
	ds_read_b128 v[156:159], v160 offset:2048
	ds_read_b128 v[160:163], v160 offset:3072
	s_add_u32 s22, s36, 0x2b0000
	s_addc_u32 s23, s37, 0
	s_mov_b32 m0, s44
	v_lshl_add_u64 v[226:227], s[22:23], 0, v[208:209]
	ds_read_b128 v[164:167], v242 offset:32768
	ds_read_b128 v[168:171], v242 offset:33792
	ds_read_b128 v[172:175], v242 offset:34816
	ds_read_b128 v[176:179], v242 offset:35840
	ds_read_b128 v[180:183], v242 offset:36864
	ds_read_b128 v[184:187], v242 offset:37888
	ds_read_b128 v[188:191], v242 offset:38912
	ds_read_b128 v[214:217], v242 offset:39936
	global_load_lds_dwordx4 v[226:227], off
	v_lshl_add_u64 v[226:227], s[22:23], 0, v[206:207]
	s_mov_b32 m0, s45
	s_nop 0
	global_load_lds_dwordx4 v[226:227], off
	s_waitcnt vmcnt(8)
	s_waitcnt lgkmcnt(0)
	s_barrier
	s_setprio 1
	s_waitcnt lgkmcnt(0)
	v_mfma_f32_16x16x32_bf16 v[140:143], v[124:127], v[164:167], v[140:143]
	v_mfma_f32_16x16x32_bf16 v[140:143], v[128:131], v[168:171], v[140:143]
	v_mfma_f32_16x16x32_bf16 v[112:115], v[128:131], v[176:179], v[112:115]
	v_mfma_f32_16x16x32_bf16 v[112:115], v[124:127], v[172:175], v[112:115]
	v_mfma_f32_16x16x32_bf16 v[96:99], v[124:127], v[180:183], v[96:99]
	v_mfma_f32_16x16x32_bf16 v[96:99], v[128:131], v[184:187], v[96:99]
	v_mfma_f32_16x16x32_bf16 v[80:83], v[128:131], v[214:217], v[80:83]
	v_mfma_f32_16x16x32_bf16 v[80:83], v[124:127], v[188:191], v[80:83]
	v_mfma_f32_16x16x32_bf16 v[76:79], v[132:135], v[188:191], v[76:79]
	v_mfma_f32_16x16x32_bf16 v[76:79], v[144:147], v[214:217], v[76:79]
	v_mfma_f32_16x16x32_bf16 v[92:95], v[144:147], v[184:187], v[92:95]
	v_mfma_f32_16x16x32_bf16 v[92:95], v[132:135], v[180:183], v[92:95]
	v_mfma_f32_16x16x32_bf16 v[108:111], v[132:135], v[172:175], v[108:111]
	v_mfma_f32_16x16x32_bf16 v[108:111], v[144:147], v[176:179], v[108:111]
	v_mfma_f32_16x16x32_bf16 v[136:139], v[144:147], v[168:171], v[136:139]
	v_mfma_f32_16x16x32_bf16 v[136:139], v[132:135], v[164:167], v[136:139]
	v_mfma_f32_16x16x32_bf16 v[120:123], v[148:151], v[164:167], v[120:123]
	v_mfma_f32_16x16x32_bf16 v[120:123], v[152:155], v[168:171], v[120:123]
	v_mfma_f32_16x16x32_bf16 v[104:107], v[152:155], v[176:179], v[104:107]
	v_mfma_f32_16x16x32_bf16 v[104:107], v[148:151], v[172:175], v[104:107]
	v_mfma_f32_16x16x32_bf16 v[88:91], v[148:151], v[180:183], v[88:91]
	v_mfma_f32_16x16x32_bf16 v[88:91], v[152:155], v[184:187], v[88:91]
	v_mfma_f32_16x16x32_bf16 v[72:75], v[152:155], v[214:217], v[72:75]
	v_mfma_f32_16x16x32_bf16 v[72:75], v[148:151], v[188:191], v[72:75]
	v_mfma_f32_16x16x32_bf16 v[68:71], v[156:159], v[188:191], v[68:71]
	v_mfma_f32_16x16x32_bf16 v[68:71], v[160:163], v[214:217], v[68:71]
	v_mfma_f32_16x16x32_bf16 v[84:87], v[160:163], v[184:187], v[84:87]
	v_mfma_f32_16x16x32_bf16 v[84:87], v[156:159], v[180:183], v[84:87]
	v_mfma_f32_16x16x32_bf16 v[100:103], v[156:159], v[172:175], v[100:103]
	v_mfma_f32_16x16x32_bf16 v[100:103], v[160:163], v[176:179], v[100:103]
	v_mfma_f32_16x16x32_bf16 v[116:119], v[160:163], v[168:171], v[116:119]
	v_mfma_f32_16x16x32_bf16 v[116:119], v[156:159], v[164:167], v[116:119]
	s_setprio 0
	s_barrier
; #define PG8_STAGE(bufoff, gbase, voff) do { _Pragma("unroll") for (int _i = 0; _i < 2; ++_i) \
;         __builtin_amdgcn_global_load_lds((const unsigned*)((const char*)(gbase) + (voff)[_i]), (PG8_LAS unsigned*)(lds + (bufoff) + ldsw + _i * 8192), 16, 0, 0); } while (0)
; #define PG8_LDA(dst, b, h) do { _Pragma("unroll") for (int m = 0; m < 4; ++m) _Pragma("unroll") for (int k = 0; k < 2; ++k) dst[m][k] = *(const PG8_LAS bf16x8*)(lds + PG8_SA(b, h) + aoff + m * 2048 + k * 1024); } while (0)
; #define PG8_WAIT_V(n) asm volatile("s_waitcnt vmcnt(" #n ")" ::: "memory")
; #define PG8_WAIT_L(n) asm volatile("s_waitcnt lgkmcnt(" #n ")" ::: "memory")
; #define PG8_BAR __builtin_amdgcn_s_barrier()
; template <class Epi, class Sched, bool ALIGN_EPI = false, bool SP2 = false, bool I8 = false>
; __device__ __forceinline__ void gemm_phase(PG8_LAS unsigned char* lds, const Gemm g, const Sched& S, const Epi& E) {
;     ...
;         for (int t = 0; t < nt; t += 2) {
;             const bool last = (t == nt - 2);
;             const char* a1 = cA + (size_t)(t + 1) * kstep;
;             const char* a2 = last ? nA : cA + (size_t)(t + 2) * kstep; const char* b2 = last ? nB : cB + (size_t)(t + 2) * kstep;
;             const char* a3 = a2 + kstep; const char* b3 = b2 + kstep;
;             if (last && has_next) S.a_ready(nxt);
;             if constexpr (SP2) {
;             PG8_LDB(B0, 0, 0); PG8_LDB(B1, 0, 1); PG8_SCHED; PG8_LDA(At, 0, 0); PG8_STAGE(PG8_SA(1, 1), a1 + hstep, voffA);
;             PG8_WAIT_V(8); PG8_WAIT_L(0); PG8_BAR; PG8_MMA(0, 0, At, B0); PG8_MMA(0, 1, At, B1); PG8_BAR; PG8_SCHED;
;             PG8_LDA(At, 0, 1); PG8_STAGE(PG8_SB(0, 0), b2, voffB); PG8_STAGE(PG8_SB(0, 1), b2 + hstep, voffB); PG8_STAGE(PG8_SA(0, 0), a2, voffA);
;             PG8_WAIT_V(8); PG8_WAIT_L(0); PG8_BAR; PG8_MMA(1, 0, At, B0); PG8_MMA(1, 1, At, B1); PG8_BAR; PG8_SCHED;
;             PG8_LDB(B0, 1, 0); PG8_LDB(B1, 1, 1); PG8_SCHED; PG8_LDA(At, 1, 0); PG8_STAGE(PG8_SA(0, 1), a2 + hstep, voffA);
;             PG8_WAIT_V(8); PG8_WAIT_L(0); PG8_BAR; PG8_MMA(0, 0, At, B0); PG8_MMA(0, 1, At, B1); PG8_BAR; PG8_SCHED;
;             PG8_LDA(At, 1, 1); PG8_STAGE(PG8_SB(1, 0), b3, voffB); PG8_STAGE(PG8_SB(1, 1), b3 + hstep, voffB); PG8_STAGE(PG8_SA(1, 0), a3, voffA);
;             PG8_WAIT_V(8); PG8_WAIT_L(0); PG8_BAR; PG8_MMA(1, 0, At, B0); PG8_MMA(1, 1, At, B1); PG8_BAR; PG8_SCHED;
	s_add_i32 s22, s56, s41
	v_lshl_add_u64 v[218:219], v[218:219], 0, s[84:85]
	s_mov_b32 m0, s22
	ds_read_b128 v[164:167], v242 offset:49152
	ds_read_b128 v[168:171], v242 offset:50176
	ds_read_b128 v[172:175], v242 offset:51200
	ds_read_b128 v[176:179], v242 offset:52224
	ds_read_b128 v[180:183], v242 offset:53248
	ds_read_b128 v[184:187], v242 offset:54272
	ds_read_b128 v[188:191], v242 offset:55296
	ds_read_b128 v[214:217], v242 offset:56320
	global_load_lds_dwordx4 v[218:219], off
	s_add_i32 m0, s22, 0x2000
	s_add_u32 s22, s26, 0x2b0080
	v_lshl_add_u64 v[218:219], v[220:221], 0, s[84:85]
	s_addc_u32 s23, s27, 0
	s_add_i32 s26, s57, s41
	global_load_lds_dwordx4 v[218:219], off
	v_lshl_add_u64 v[218:219], s[22:23], 0, v[2:3]
	s_mov_b32 m0, s26
	s_nop 0
	global_load_lds_dwordx4 v[218:219], off
	v_lshl_add_u64 v[218:219], s[22:23], 0, v[204:205]
	s_add_i32 m0, s26, 0x2000
	s_nop 0
	global_load_lds_dwordx4 v[218:219], off
	v_lshl_add_u64 v[218:219], v[222:223], 0, s[84:85]
	s_mov_b32 m0, s46
	s_nop 0
	global_load_lds_dwordx4 v[218:219], off
	v_lshl_add_u64 v[218:219], v[224:225], 0, s[84:85]
	s_mov_b32 m0, s47
	s_nop 0
	global_load_lds_dwordx4 v[218:219], off
	s_waitcnt vmcnt(8)
	s_waitcnt lgkmcnt(0)
	s_barrier
	s_setprio 1
	s_waitcnt lgkmcnt(0)
	v_mfma_f32_16x16x32_bf16 v[64:67], v[124:127], v[164:167], v[64:67]
	v_mfma_f32_16x16x32_bf16 v[64:67], v[128:131], v[168:171], v[64:67]
	v_mfma_f32_16x16x32_bf16 v[48:51], v[128:131], v[176:179], v[48:51]
	v_mfma_f32_16x16x32_bf16 v[48:51], v[124:127], v[172:175], v[48:51]
	v_mfma_f32_16x16x32_bf16 v[32:35], v[124:127], v[180:183], v[32:35]
	v_mfma_f32_16x16x32_bf16 v[32:35], v[128:131], v[184:187], v[32:35]
	v_mfma_f32_16x16x32_bf16 v[16:19], v[128:131], v[214:217], v[16:19]
	v_mfma_f32_16x16x32_bf16 v[16:19], v[124:127], v[188:191], v[16:19]
	v_mfma_f32_16x16x32_bf16 v[12:15], v[132:135], v[188:191], v[12:15]
	v_mfma_f32_16x16x32_bf16 v[12:15], v[144:147], v[214:217], v[12:15]
	v_mfma_f32_16x16x32_bf16 v[28:31], v[144:147], v[184:187], v[28:31]
	v_mfma_f32_16x16x32_bf16 v[28:31], v[132:135], v[180:183], v[28:31]
	v_mfma_f32_16x16x32_bf16 v[44:47], v[132:135], v[172:175], v[44:47]
	v_mfma_f32_16x16x32_bf16 v[44:47], v[144:147], v[176:179], v[44:47]
	v_mfma_f32_16x16x32_bf16 v[60:63], v[144:147], v[168:171], v[60:63]
	v_mfma_f32_16x16x32_bf16 v[60:63], v[132:135], v[164:167], v[60:63]
	v_mfma_f32_16x16x32_bf16 v[56:59], v[148:151], v[164:167], v[56:59]
	v_mfma_f32_16x16x32_bf16 v[56:59], v[152:155], v[168:171], v[56:59]
	v_mfma_f32_16x16x32_bf16 v[40:43], v[152:155], v[176:179], v[40:43]
	v_mfma_f32_16x16x32_bf16 v[40:43], v[148:151], v[172:175], v[40:43]
	v_mfma_f32_16x16x32_bf16 v[24:27], v[148:151], v[180:183], v[24:27]
	v_mfma_f32_16x16x32_bf16 v[24:27], v[152:155], v[184:187], v[24:27]
	v_mfma_f32_16x16x32_bf16 v[8:11], v[152:155], v[214:217], v[8:11]
	v_mfma_f32_16x16x32_bf16 v[8:11], v[148:151], v[188:191], v[8:11]
	v_mfma_f32_16x16x32_bf16 v[4:7], v[156:159], v[188:191], v[4:7]
	v_mfma_f32_16x16x32_bf16 v[4:7], v[160:163], v[214:217], v[4:7]
	v_mfma_f32_16x16x32_bf16 v[20:23], v[160:163], v[184:187], v[20:23]
	v_mfma_f32_16x16x32_bf16 v[20:23], v[156:159], v[180:183], v[20:23]
	v_mfma_f32_16x16x32_bf16 v[36:39], v[156:159], v[172:175], v[36:39]
	v_mfma_f32_16x16x32_bf16 v[36:39], v[160:163], v[176:179], v[36:39]
	v_mfma_f32_16x16x32_bf16 v[52:55], v[160:163], v[168:171], v[52:55]
	v_mfma_f32_16x16x32_bf16 v[52:55], v[156:159], v[164:167], v[52:55]
	s_setprio 0
	s_barrier
	s_add_i32 s55, s55, 2
	s_add_u32 s53, s53, 0x100
	s_addc_u32 s54, s54, 0
	s_cmpk_gt_u32 s55, 0xa9
	s_mov_b64 s[22:23], s[24:25]
	s_cbranch_scc1 .Lkloop_exit_5
.LBB0_1700:
	s_add_u32 s24, s22, 0x100
	s_addc_u32 s25, s23, 0
	s_add_i32 s56, 0, 0x10000
	s_cmpk_eq_i32 s55, 0xa8
	s_cselect_b32 s37, s13, s25
	s_cselect_b32 s36, s12, s24
	s_cselect_b32 s27, s21, s54
	s_cselect_b32 s26, s20, s53
	s_add_i32 s57, 0, 0x14000
	v_add_u32_e32 v144, s56, v240
	v_add_u32_e32 v160, s57, v240
	ds_read_b128 v[124:127], v144
	ds_read_b128 v[128:131], v144 offset:1024
	ds_read_b128 v[132:135], v144 offset:2048
	ds_read_b128 v[144:147], v144 offset:3072
	ds_read_b128 v[148:151], v160
	ds_read_b128 v[152:155], v160 offset:1024
	ds_read_b128 v[156:159], v160 offset:2048
	ds_read_b128 v[160:163], v160 offset:3072
	v_lshl_add_u64 v[218:219], s[22:23], 0, v[210:211]
	s_add_i32 m0, s42, 0xc000
	ds_read_b128 v[164:167], v242
	ds_read_b128 v[168:171], v242 offset:1024
	ds_read_b128 v[172:175], v242 offset:2048
	ds_read_b128 v[176:179], v242 offset:3072
	ds_read_b128 v[180:183], v242 offset:4096
	ds_read_b128 v[184:187], v242 offset:5120
	ds_read_b128 v[188:191], v242 offset:6144
	ds_read_b128 v[214:217], v242 offset:7168
	global_load_lds_dwordx4 v[218:219], off
	v_lshl_add_u64 v[218:219], s[22:23], 0, v[212:213]
	s_add_i32 m0, s42, 0xe000
	s_nop 0
	global_load_lds_dwordx4 v[218:219], off
	s_waitcnt vmcnt(8)
	s_waitcnt lgkmcnt(0)
	s_barrier
; #define PG8_STAGE(bufoff, gbase, voff) do { _Pragma("unroll") for (int _i = 0; _i < 2; ++_i) \
;         __builtin_amdgcn_global_load_lds((const unsigned*)((const char*)(gbase) + (voff)[_i]), (PG8_LAS unsigned*)(lds + (bufoff) + ldsw + _i * 8192), 16, 0, 0); } while (0)
; #define PG8_LDA(dst, b, h) do { _Pragma("unroll") for (int m = 0; m < 4; ++m) _Pragma("unroll") for (int k = 0; k < 2; ++k) dst[m][k] = *(const PG8_LAS bf16x8*)(lds + PG8_SA(b, h) + aoff + m * 2048 + k * 1024); } while (0)
; #define PG8_WAIT_V(n) asm volatile("s_waitcnt vmcnt(" #n ")" ::: "memory")
; #define PG8_WAIT_L(n) asm volatile("s_waitcnt lgkmcnt(" #n ")" ::: "memory")
; #define PG8_BAR __builtin_amdgcn_s_barrier()
; #define PG8_SCHED __builtin_amdgcn_sched_barrier(0)
; template <class Epi, class Sched, bool ALIGN_EPI = false, bool SP2 = false, bool I8 = false>
; __device__ __forceinline__ void gemm_phase(PG8_LAS unsigned char* lds, const Gemm g, const Sched& S, const Epi& E) {
;     ...
;             PG8_WAIT_V(8); PG8_WAIT_L(0); PG8_BAR; PG8_MMA(0, 0, At, B0); PG8_MMA(0, 1, At, B1); PG8_BAR; PG8_SCHED;
;             PG8_LDA(At, 0, 1); PG8_STAGE(PG8_SB(0, 0), b2, voffB); PG8_STAGE(PG8_SB(0, 1), b2 + hstep, voffB); PG8_STAGE(PG8_SA(0, 0), a2, voffA);
;             PG8_WAIT_V(8); PG8_WAIT_L(0); PG8_BAR; PG8_MMA(1, 0, At, B0); PG8_MMA(1, 1, At, B1); PG8_BAR; PG8_SCHED;
	s_setprio 1
	s_waitcnt lgkmcnt(0)
	v_mfma_f32_16x16x32_bf16 v[140:143], v[124:127], v[164:167], v[140:143]
	v_mfma_f32_16x16x32_bf16 v[140:143], v[128:131], v[168:171], v[140:143]
	v_mfma_f32_16x16x32_bf16 v[112:115], v[128:131], v[176:179], v[112:115]
	v_mfma_f32_16x16x32_bf16 v[112:115], v[124:127], v[172:175], v[112:115]
	v_mfma_f32_16x16x32_bf16 v[96:99], v[124:127], v[180:183], v[96:99]
	v_mfma_f32_16x16x32_bf16 v[96:99], v[128:131], v[184:187], v[96:99]
	v_mfma_f32_16x16x32_bf16 v[80:83], v[128:131], v[214:217], v[80:83]
	v_mfma_f32_16x16x32_bf16 v[80:83], v[124:127], v[188:191], v[80:83]
	v_mfma_f32_16x16x32_bf16 v[76:79], v[132:135], v[188:191], v[76:79]
	v_mfma_f32_16x16x32_bf16 v[76:79], v[144:147], v[214:217], v[76:79]
	v_mfma_f32_16x16x32_bf16 v[92:95], v[144:147], v[184:187], v[92:95]
	v_mfma_f32_16x16x32_bf16 v[92:95], v[132:135], v[180:183], v[92:95]
	v_mfma_f32_16x16x32_bf16 v[108:111], v[132:135], v[172:175], v[108:111]
	v_mfma_f32_16x16x32_bf16 v[108:111], v[144:147], v[176:179], v[108:111]
	v_mfma_f32_16x16x32_bf16 v[136:139], v[144:147], v[168:171], v[136:139]
	v_mfma_f32_16x16x32_bf16 v[136:139], v[132:135], v[164:167], v[136:139]
	v_mfma_f32_16x16x32_bf16 v[120:123], v[148:151], v[164:167], v[120:123]
	v_mfma_f32_16x16x32_bf16 v[120:123], v[152:155], v[168:171], v[120:123]
	v_mfma_f32_16x16x32_bf16 v[104:107], v[152:155], v[176:179], v[104:107]
	v_mfma_f32_16x16x32_bf16 v[104:107], v[148:151], v[172:175], v[104:107]
	v_mfma_f32_16x16x32_bf16 v[88:91], v[148:151], v[180:183], v[88:91]
	v_mfma_f32_16x16x32_bf16 v[88:91], v[152:155], v[184:187], v[88:91]
	v_mfma_f32_16x16x32_bf16 v[72:75], v[152:155], v[214:217], v[72:75]
	v_mfma_f32_16x16x32_bf16 v[72:75], v[148:151], v[188:191], v[72:75]
	v_mfma_f32_16x16x32_bf16 v[68:71], v[156:159], v[188:191], v[68:71]
	v_mfma_f32_16x16x32_bf16 v[68:71], v[160:163], v[214:217], v[68:71]
	v_mfma_f32_16x16x32_bf16 v[84:87], v[160:163], v[184:187], v[84:87]
	v_mfma_f32_16x16x32_bf16 v[84:87], v[156:159], v[180:183], v[84:87]
	v_mfma_f32_16x16x32_bf16 v[100:103], v[156:159], v[172:175], v[100:103]
	v_mfma_f32_16x16x32_bf16 v[100:103], v[160:163], v[176:179], v[100:103]
	v_mfma_f32_16x16x32_bf16 v[116:119], v[160:163], v[168:171], v[116:119]
	v_mfma_f32_16x16x32_bf16 v[116:119], v[156:159], v[164:167], v[116:119]
	s_setprio 0
	s_barrier
	s_add_i32 s22, s56, s41
	v_lshl_add_u64 v[218:219], s[26:27], 0, v[2:3]
	s_mov_b32 m0, s22
	ds_read_b128 v[164:167], v242 offset:16384
	ds_read_b128 v[168:171], v242 offset:17408
	ds_read_b128 v[172:175], v242 offset:18432
	ds_read_b128 v[176:179], v242 offset:19456
	ds_read_b128 v[180:183], v242 offset:20480
	ds_read_b128 v[184:187], v242 offset:21504
	ds_read_b128 v[188:191], v242 offset:22528
	ds_read_b128 v[214:217], v242 offset:23552
	global_load_lds_dwordx4 v[218:219], off
	s_add_i32 m0, s22, 0x2000
	s_add_u32 s22, s26, 0x2b0000
	v_lshl_add_u64 v[220:221], s[26:27], 0, v[204:205]
	s_addc_u32 s23, s27, 0
	s_add_i32 s56, s57, s41
	global_load_lds_dwordx4 v[220:221], off
	v_lshl_add_u64 v[222:223], s[22:23], 0, v[2:3]
	s_mov_b32 m0, s56
	v_lshl_add_u64 v[224:225], s[36:37], 0, v[206:207]
	global_load_lds_dwordx4 v[222:223], off
	v_lshl_add_u64 v[222:223], s[22:23], 0, v[204:205]
	s_add_i32 m0, s56, 0x2000
	s_nop 0
	global_load_lds_dwordx4 v[222:223], off
	v_lshl_add_u64 v[222:223], s[36:37], 0, v[208:209]
	s_waitcnt vmcnt(6)
	s_waitcnt lgkmcnt(0)
	s_barrier
	s_setprio 1
	s_waitcnt lgkmcnt(0)
	v_mfma_f32_16x16x32_bf16 v[64:67], v[124:127], v[164:167], v[64:67]
	v_mfma_f32_16x16x32_bf16 v[64:67], v[128:131], v[168:171], v[64:67]
	v_mfma_f32_16x16x32_bf16 v[48:51], v[128:131], v[176:179], v[48:51]
	v_mfma_f32_16x16x32_bf16 v[48:51], v[124:127], v[172:175], v[48:51]
	v_mfma_f32_16x16x32_bf16 v[32:35], v[124:127], v[180:183], v[32:35]
	v_mfma_f32_16x16x32_bf16 v[32:35], v[128:131], v[184:187], v[32:35]
	v_mfma_f32_16x16x32_bf16 v[16:19], v[128:131], v[214:217], v[16:19]
	v_mfma_f32_16x16x32_bf16 v[16:19], v[124:127], v[188:191], v[16:19]
	v_mfma_f32_16x16x32_bf16 v[12:15], v[132:135], v[188:191], v[12:15]
	v_mfma_f32_16x16x32_bf16 v[12:15], v[144:147], v[214:217], v[12:15]
	v_mfma_f32_16x16x32_bf16 v[28:31], v[144:147], v[184:187], v[28:31]
	v_mfma_f32_16x16x32_bf16 v[28:31], v[132:135], v[180:183], v[28:31]
	v_mfma_f32_16x16x32_bf16 v[44:47], v[132:135], v[172:175], v[44:47]
	v_mfma_f32_16x16x32_bf16 v[44:47], v[144:147], v[176:179], v[44:47]
	v_mfma_f32_16x16x32_bf16 v[60:63], v[144:147], v[168:171], v[60:63]
	v_mfma_f32_16x16x32_bf16 v[60:63], v[132:135], v[164:167], v[60:63]
	v_mfma_f32_16x16x32_bf16 v[56:59], v[148:151], v[164:167], v[56:59]
	v_mfma_f32_16x16x32_bf16 v[56:59], v[152:155], v[168:171], v[56:59]
	v_mfma_f32_16x16x32_bf16 v[40:43], v[152:155], v[176:179], v[40:43]
	v_mfma_f32_16x16x32_bf16 v[40:43], v[148:151], v[172:175], v[40:43]
	v_mfma_f32_16x16x32_bf16 v[24:27], v[148:151], v[180:183], v[24:27]
	v_mfma_f32_16x16x32_bf16 v[24:27], v[152:155], v[184:187], v[24:27]
	v_mfma_f32_16x16x32_bf16 v[8:11], v[152:155], v[214:217], v[8:11]
	v_mfma_f32_16x16x32_bf16 v[8:11], v[148:151], v[188:191], v[8:11]
	v_mfma_f32_16x16x32_bf16 v[4:7], v[156:159], v[188:191], v[4:7]
	v_mfma_f32_16x16x32_bf16 v[4:7], v[160:163], v[214:217], v[4:7]
	v_mfma_f32_16x16x32_bf16 v[20:23], v[160:163], v[184:187], v[20:23]
	v_mfma_f32_16x16x32_bf16 v[20:23], v[156:159], v[180:183], v[20:23]
	v_mfma_f32_16x16x32_bf16 v[36:39], v[156:159], v[172:175], v[36:39]
	v_mfma_f32_16x16x32_bf16 v[36:39], v[160:163], v[176:179], v[36:39]
	v_mfma_f32_16x16x32_bf16 v[52:55], v[160:163], v[168:171], v[52:55]
	v_mfma_f32_16x16x32_bf16 v[52:55], v[156:159], v[164:167], v[52:55]
	s_setprio 0
	s_barrier
; #define PG8_STAGE(bufoff, gbase, voff) do { _Pragma("unroll") for (int _i = 0; _i < 2; ++_i) \
;         __builtin_amdgcn_global_load_lds((const unsigned*)((const char*)(gbase) + (voff)[_i]), (PG8_LAS unsigned*)(lds + (bufoff) + ldsw + _i * 8192), 16, 0, 0); } while (0)
; #define PG8_LDA(dst, b, h) do { _Pragma("unroll") for (int m = 0; m < 4; ++m) _Pragma("unroll") for (int k = 0; k < 2; ++k) dst[m][k] = *(const PG8_LAS bf16x8*)(lds + PG8_SA(b, h) + aoff + m * 2048 + k * 1024); } while (0)
; #define PG8_LDB(dst, b, h) do { _Pragma("unroll") for (int n = 0; n < 2; ++n) _Pragma("unroll") for (int k = 0; k < 2; ++k) dst[n][k] = *(const PG8_LAS bf16x8*)(lds + PG8_SB(b, h) + boff + n * 2048 + k * 1024); } while (0)
; #define PG8_WAIT_V(n) asm volatile("s_waitcnt vmcnt(" #n ")" ::: "memory")
; #define PG8_WAIT_L(n) asm volatile("s_waitcnt lgkmcnt(" #n ")" ::: "memory")
; #define PG8_BAR __builtin_amdgcn_s_barrier()
; #define PG8_SCHED __builtin_amdgcn_sched_barrier(0)
; template <class Epi, class Sched, bool ALIGN_EPI = false, bool SP2 = false, bool I8 = false>
; __device__ __forceinline__ void gemm_phase(PG8_LAS unsigned char* lds, const Gemm g, const Sched& S, const Epi& E) {
;     ...
;             PG8_LDA(At, 0, 1); PG8_STAGE(PG8_SB(0, 0), b2, voffB); PG8_STAGE(PG8_SB(0, 1), b2 + hstep, voffB); PG8_STAGE(PG8_SA(0, 0), a2, voffA);
;             PG8_WAIT_V(8); PG8_WAIT_L(0); PG8_BAR; PG8_MMA(1, 0, At, B0); PG8_MMA(1, 1, At, B1); PG8_BAR; PG8_SCHED;
;             PG8_LDB(B0, 1, 0); PG8_LDB(B1, 1, 1); PG8_SCHED; PG8_LDA(At, 1, 0); PG8_STAGE(PG8_SA(0, 1), a2 + hstep, voffA);
;             PG8_WAIT_V(8); PG8_WAIT_L(0); PG8_BAR; PG8_MMA(0, 0, At, B0); PG8_MMA(0, 1, At, B1); PG8_BAR; PG8_SCHED;
	s_mov_b32 m0, s42
	s_nop 0
	global_load_lds_dwordx4 v[222:223], off
	s_mov_b32 m0, s43
	s_nop 0
	global_load_lds_dwordx4 v[224:225], off
	s_add_i32 s56, 0, 0x18000
	s_add_i32 s57, 0, 0x1c000
	v_add_u32_e32 v144, s56, v240
	v_add_u32_e32 v160, s57, v240
	ds_read_b128 v[124:127], v144
	ds_read_b128 v[128:131], v144 offset:1024
	ds_read_b128 v[132:135], v144 offset:2048
	ds_read_b128 v[144:147], v144 offset:3072
	ds_read_b128 v[148:151], v160
	ds_read_b128 v[152:155], v160 offset:1024
	ds_read_b128 v[156:159], v160 offset:2048
	ds_read_b128 v[160:163], v160 offset:3072
	s_add_u32 s22, s36, 0x2b0000
	s_addc_u32 s23, s37, 0
	s_mov_b32 m0, s44
	v_lshl_add_u64 v[226:227], s[22:23], 0, v[208:209]
	ds_read_b128 v[164:167], v242 offset:32768
	ds_read_b128 v[168:171], v242 offset:33792
	ds_read_b128 v[172:175], v242 offset:34816
	ds_read_b128 v[176:179], v242 offset:35840
	ds_read_b128 v[180:183], v242 offset:36864
	ds_read_b128 v[184:187], v242 offset:37888
	ds_read_b128 v[188:191], v242 offset:38912
	ds_read_b128 v[214:217], v242 offset:39936
	global_load_lds_dwordx4 v[226:227], off
	v_lshl_add_u64 v[226:227], s[22:23], 0, v[206:207]
	s_mov_b32 m0, s45
	s_nop 0
	global_load_lds_dwordx4 v[226:227], off
	s_waitcnt vmcnt(8)
	s_waitcnt lgkmcnt(0)
	s_barrier
	s_setprio 1
	s_waitcnt lgkmcnt(0)
	v_mfma_f32_16x16x32_bf16 v[140:143], v[124:127], v[164:167], v[140:143]
	v_mfma_f32_16x16x32_bf16 v[140:143], v[128:131], v[168:171], v[140:143]
	v_mfma_f32_16x16x32_bf16 v[112:115], v[128:131], v[176:179], v[112:115]
	v_mfma_f32_16x16x32_bf16 v[112:115], v[124:127], v[172:175], v[112:115]
	v_mfma_f32_16x16x32_bf16 v[96:99], v[124:127], v[180:183], v[96:99]
	v_mfma_f32_16x16x32_bf16 v[96:99], v[128:131], v[184:187], v[96:99]
	v_mfma_f32_16x16x32_bf16 v[80:83], v[128:131], v[214:217], v[80:83]
	v_mfma_f32_16x16x32_bf16 v[80:83], v[124:127], v[188:191], v[80:83]
	v_mfma_f32_16x16x32_bf16 v[76:79], v[132:135], v[188:191], v[76:79]
	v_mfma_f32_16x16x32_bf16 v[76:79], v[144:147], v[214:217], v[76:79]
	v_mfma_f32_16x16x32_bf16 v[92:95], v[144:147], v[184:187], v[92:95]
	v_mfma_f32_16x16x32_bf16 v[92:95], v[132:135], v[180:183], v[92:95]
	v_mfma_f32_16x16x32_bf16 v[108:111], v[132:135], v[172:175], v[108:111]
	v_mfma_f32_16x16x32_bf16 v[108:111], v[144:147], v[176:179], v[108:111]
	v_mfma_f32_16x16x32_bf16 v[136:139], v[144:147], v[168:171], v[136:139]
	v_mfma_f32_16x16x32_bf16 v[136:139], v[132:135], v[164:167], v[136:139]
	v_mfma_f32_16x16x32_bf16 v[120:123], v[148:151], v[164:167], v[120:123]
	v_mfma_f32_16x16x32_bf16 v[120:123], v[152:155], v[168:171], v[120:123]
	v_mfma_f32_16x16x32_bf16 v[104:107], v[152:155], v[176:179], v[104:107]
	v_mfma_f32_16x16x32_bf16 v[104:107], v[148:151], v[172:175], v[104:107]
	v_mfma_f32_16x16x32_bf16 v[88:91], v[148:151], v[180:183], v[88:91]
	v_mfma_f32_16x16x32_bf16 v[88:91], v[152:155], v[184:187], v[88:91]
	v_mfma_f32_16x16x32_bf16 v[72:75], v[152:155], v[214:217], v[72:75]
	v_mfma_f32_16x16x32_bf16 v[72:75], v[148:151], v[188:191], v[72:75]
	v_mfma_f32_16x16x32_bf16 v[68:71], v[156:159], v[188:191], v[68:71]
	v_mfma_f32_16x16x32_bf16 v[68:71], v[160:163], v[214:217], v[68:71]
	v_mfma_f32_16x16x32_bf16 v[84:87], v[160:163], v[184:187], v[84:87]
	v_mfma_f32_16x16x32_bf16 v[84:87], v[156:159], v[180:183], v[84:87]
	v_mfma_f32_16x16x32_bf16 v[100:103], v[156:159], v[172:175], v[100:103]
	v_mfma_f32_16x16x32_bf16 v[100:103], v[160:163], v[176:179], v[100:103]
	v_mfma_f32_16x16x32_bf16 v[116:119], v[160:163], v[168:171], v[116:119]
	v_mfma_f32_16x16x32_bf16 v[116:119], v[156:159], v[164:167], v[116:119]
	s_setprio 0
	s_barrier
; #define PG8_STAGE(bufoff, gbase, voff) do { _Pragma("unroll") for (int _i = 0; _i < 2; ++_i) \
;         __builtin_amdgcn_global_load_lds((const unsigned*)((const char*)(gbase) + (voff)[_i]), (PG8_LAS unsigned*)(lds + (bufoff) + ldsw + _i * 8192), 16, 0, 0); } while (0)
; #define PG8_LDA(dst, b, h) do { _Pragma("unroll") for (int m = 0; m < 4; ++m) _Pragma("unroll") for (int k = 0; k < 2; ++k) dst[m][k] = *(const PG8_LAS bf16x8*)(lds + PG8_SA(b, h) + aoff + m * 2048 + k * 1024); } while (0)
; #define PG8_WAIT_V(n) asm volatile("s_waitcnt vmcnt(" #n ")" ::: "memory")
; #define PG8_WAIT_L(n) asm volatile("s_waitcnt lgkmcnt(" #n ")" ::: "memory")
; #define PG8_BAR __builtin_amdgcn_s_barrier()
; #define PG8_SCHED __builtin_amdgcn_sched_barrier(0)
; template <class Epi, class Sched, bool ALIGN_EPI = false, bool SP2 = false, bool I8 = false>
; __device__ __forceinline__ void gemm_phase(PG8_LAS unsigned char* lds, const Gemm g, const Sched& S, const Epi& E) {
;     ...
;         for (int t = 0; t < nt; t += 2) {
;             const bool last = (t == nt - 2);
;             const char* a1 = cA + (size_t)(t + 1) * kstep;
;             const char* a2 = last ? nA : cA + (size_t)(t + 2) * kstep; const char* b2 = last ? nB : cB + (size_t)(t + 2) * kstep;
;     ...
;             PG8_LDA(At, 1, 1); PG8_STAGE(PG8_SB(1, 0), b3, voffB); PG8_STAGE(PG8_SB(1, 1), b3 + hstep, voffB); PG8_STAGE(PG8_SA(1, 0), a3, voffA);
;             PG8_WAIT_V(8); PG8_WAIT_L(0); PG8_BAR; PG8_MMA(1, 0, At, B0); PG8_MMA(1, 1, At, B1); PG8_BAR; PG8_SCHED;
	s_add_i32 s22, s56, s41
	v_lshl_add_u64 v[218:219], v[218:219], 0, s[84:85]
	s_mov_b32 m0, s22
	ds_read_b128 v[164:167], v242 offset:49152
	ds_read_b128 v[168:171], v242 offset:50176
	ds_read_b128 v[172:175], v242 offset:51200
	ds_read_b128 v[176:179], v242 offset:52224
	ds_read_b128 v[180:183], v242 offset:53248
	ds_read_b128 v[184:187], v242 offset:54272
	ds_read_b128 v[188:191], v242 offset:55296
	ds_read_b128 v[214:217], v242 offset:56320
	global_load_lds_dwordx4 v[218:219], off
	s_add_i32 m0, s22, 0x2000
	s_add_u32 s22, s26, 0x2b0080
	v_lshl_add_u64 v[218:219], v[220:221], 0, s[84:85]
	s_addc_u32 s23, s27, 0
	s_add_i32 s26, s57, s41
	global_load_lds_dwordx4 v[218:219], off
	v_lshl_add_u64 v[218:219], s[22:23], 0, v[2:3]
	s_mov_b32 m0, s26
	s_nop 0
	global_load_lds_dwordx4 v[218:219], off
	v_lshl_add_u64 v[218:219], s[22:23], 0, v[204:205]
	s_add_i32 m0, s26, 0x2000
	s_nop 0
	global_load_lds_dwordx4 v[218:219], off
	v_lshl_add_u64 v[218:219], v[222:223], 0, s[84:85]
	s_mov_b32 m0, s46
	s_nop 0
	global_load_lds_dwordx4 v[218:219], off
	v_lshl_add_u64 v[218:219], v[224:225], 0, s[84:85]
	s_mov_b32 m0, s47
	s_nop 0
	global_load_lds_dwordx4 v[218:219], off
	s_waitcnt vmcnt(8)
	s_waitcnt lgkmcnt(0)
	s_barrier
	s_setprio 1
	s_waitcnt lgkmcnt(0)
	v_mfma_f32_16x16x32_bf16 v[64:67], v[124:127], v[164:167], v[64:67]
	v_mfma_f32_16x16x32_bf16 v[64:67], v[128:131], v[168:171], v[64:67]
	v_mfma_f32_16x16x32_bf16 v[48:51], v[128:131], v[176:179], v[48:51]
	v_mfma_f32_16x16x32_bf16 v[48:51], v[124:127], v[172:175], v[48:51]
	v_mfma_f32_16x16x32_bf16 v[32:35], v[124:127], v[180:183], v[32:35]
	v_mfma_f32_16x16x32_bf16 v[32:35], v[128:131], v[184:187], v[32:35]
	v_mfma_f32_16x16x32_bf16 v[16:19], v[128:131], v[214:217], v[16:19]
	v_mfma_f32_16x16x32_bf16 v[16:19], v[124:127], v[188:191], v[16:19]
	v_mfma_f32_16x16x32_bf16 v[12:15], v[132:135], v[188:191], v[12:15]
	v_mfma_f32_16x16x32_bf16 v[12:15], v[144:147], v[214:217], v[12:15]
	v_mfma_f32_16x16x32_bf16 v[28:31], v[144:147], v[184:187], v[28:31]
	v_mfma_f32_16x16x32_bf16 v[28:31], v[132:135], v[180:183], v[28:31]
	v_mfma_f32_16x16x32_bf16 v[44:47], v[132:135], v[172:175], v[44:47]
	v_mfma_f32_16x16x32_bf16 v[44:47], v[144:147], v[176:179], v[44:47]
	v_mfma_f32_16x16x32_bf16 v[60:63], v[144:147], v[168:171], v[60:63]
	v_mfma_f32_16x16x32_bf16 v[60:63], v[132:135], v[164:167], v[60:63]
	v_mfma_f32_16x16x32_bf16 v[56:59], v[148:151], v[164:167], v[56:59]
	v_mfma_f32_16x16x32_bf16 v[56:59], v[152:155], v[168:171], v[56:59]
	v_mfma_f32_16x16x32_bf16 v[40:43], v[152:155], v[176:179], v[40:43]
	v_mfma_f32_16x16x32_bf16 v[40:43], v[148:151], v[172:175], v[40:43]
	v_mfma_f32_16x16x32_bf16 v[24:27], v[148:151], v[180:183], v[24:27]
	v_mfma_f32_16x16x32_bf16 v[24:27], v[152:155], v[184:187], v[24:27]
	v_mfma_f32_16x16x32_bf16 v[8:11], v[152:155], v[214:217], v[8:11]
	v_mfma_f32_16x16x32_bf16 v[8:11], v[148:151], v[188:191], v[8:11]
	v_mfma_f32_16x16x32_bf16 v[4:7], v[156:159], v[188:191], v[4:7]
	v_mfma_f32_16x16x32_bf16 v[4:7], v[160:163], v[214:217], v[4:7]
	v_mfma_f32_16x16x32_bf16 v[20:23], v[160:163], v[184:187], v[20:23]
	v_mfma_f32_16x16x32_bf16 v[20:23], v[156:159], v[180:183], v[20:23]
	v_mfma_f32_16x16x32_bf16 v[36:39], v[156:159], v[172:175], v[36:39]
	v_mfma_f32_16x16x32_bf16 v[36:39], v[160:163], v[176:179], v[36:39]
	v_mfma_f32_16x16x32_bf16 v[52:55], v[160:163], v[168:171], v[52:55]
	v_mfma_f32_16x16x32_bf16 v[52:55], v[156:159], v[164:167], v[52:55]
	s_setprio 0
	s_barrier
	s_add_i32 s55, s55, 2
	s_add_u32 s53, s53, 0x100
	s_addc_u32 s54, s54, 0
	s_cmpk_gt_u32 s55, 0xa9
	s_mov_b64 s[22:23], s[24:25]
	s_cbranch_scc0 .LBB0_1700

; #define PG8_STAGE(bufoff, gbase, voff) do { _Pragma("unroll") for (int _i = 0; _i < 2; ++_i) \
;         __builtin_amdgcn_global_load_lds((const unsigned*)((const char*)(gbase) + (voff)[_i]), (PG8_LAS unsigned*)(lds + (bufoff) + ldsw + _i * 8192), 16, 0, 0); } while (0)
; #define PG8_LDA(dst, b, h) do { _Pragma("unroll") for (int m = 0; m < 4; ++m) _Pragma("unroll") for (int k = 0; k < 2; ++k) dst[m][k] = *(const PG8_LAS bf16x8*)(lds + PG8_SA(b, h) + aoff + m * 2048 + k * 1024); } while (0)
; #define PG8_LDB(dst, b, h) do { _Pragma("unroll") for (int n = 0; n < 2; ++n) _Pragma("unroll") for (int k = 0; k < 2; ++k) dst[n][k] = *(const PG8_LAS bf16x8*)(lds + PG8_SB(b, h) + boff + n * 2048 + k * 1024); } while (0)
; #define PG8_WAIT_V(n) asm volatile("s_waitcnt vmcnt(" #n ")" ::: "memory")
; #define PG8_WAIT_L(n) asm volatile("s_waitcnt lgkmcnt(" #n ")" ::: "memory")
; #define PG8_BAR __builtin_amdgcn_s_barrier()
; #define PG8_SCHED __builtin_amdgcn_sched_barrier(0)
; template <class Epi, class Sched, bool ALIGN_EPI = false, bool SP2 = false, bool I8 = false>
; __device__ __forceinline__ void gemm_phase(PG8_LAS unsigned char* lds, const Gemm g, const Sched& S, const Epi& E) {
;     ...
;         const bool has_next = S.next(ui + 1, nxt);
;         const char* nA = has_next ? (const char*)g.A + (size_t)nxt.pm * tstep : cA; const char* nB = has_next ? (const char*)g.Bt + (size_t)nxt.pn * tstep : cB;
;         for (int t = 0; t < nt; t += 2) {
;             const bool last = (t == nt - 2);
;             const char* a1 = cA + (size_t)(t + 1) * kstep;
;             const char* a2 = last ? nA : cA + (size_t)(t + 2) * kstep; const char* b2 = last ? nB : cB + (size_t)(t + 2) * kstep;
;             const char* a3 = a2 + kstep; const char* b3 = b2 + kstep;
;             if (last && has_next) S.a_ready(nxt);
;             if constexpr (SP2) {
;             PG8_LDB(B0, 0, 0); PG8_LDB(B1, 0, 1); PG8_SCHED; PG8_LDA(At, 0, 0); PG8_STAGE(PG8_SA(1, 1), a1 + hstep, voffA);
;             PG8_WAIT_V(8); PG8_WAIT_L(0); PG8_BAR; PG8_MMA(0, 0, At, B0); PG8_MMA(0, 1, At, B1); PG8_BAR; PG8_SCHED;
;             PG8_LDA(At, 0, 1); PG8_STAGE(PG8_SB(0, 0), b2, voffB); PG8_STAGE(PG8_SB(0, 1), b2 + hstep, voffB); PG8_STAGE(PG8_SA(0, 0), a2, voffA);
;             PG8_WAIT_V(8); PG8_WAIT_L(0); PG8_BAR; PG8_MMA(1, 0, At, B0); PG8_MMA(1, 1, At, B1); PG8_BAR; PG8_SCHED;
.LBB0_1842:
	s_ashr_i32 s45, s44, 31
	s_lshl_b64 s[34:35], s[44:45], 20
	s_add_u32 s50, s47, s34
	s_addc_u32 s51, s52, s35
	s_and_b64 s[34:35], s[8:9], exec
	s_cselect_b32 s11, s51, s55
	s_cselect_b32 s13, s50, s54
	s_ashr_i32 s49, s48, 31
	s_lshl_b64 s[34:35], s[48:49], 20
	s_add_u32 s56, s53, s34
	s_addc_u32 s57, s64, s35
	s_and_b64 s[34:35], s[8:9], exec
	s_cselect_b32 s34, s57, s59
	s_cselect_b32 s35, s56, s58
	s_add_u32 s54, s54, 0x80080
	s_addc_u32 s55, s55, 0
	s_add_u32 s45, s58, 0x100
	s_addc_u32 s49, s59, 0
	s_mov_b32 s86, -2
	s_waitcnt lgkmcnt(0)
	s_add_u32 s58, s54, 0xfff80080
	s_addc_u32 s59, s55, -1
	s_add_i32 s87, 0, 0x10000
	s_cmp_eq_u32 s86, 28
	s_cselect_b32 s61, s11, s59
	s_cselect_b32 s60, s13, s58
	s_cselect_b32 s59, s34, s49
	s_cselect_b32 s58, s35, s45
	s_add_i32 vcc_lo, 0, 0x14000
	v_add_u32_e32 v40, s87, v217
	v_add_u32_e32 v160, vcc_lo, v217
	ds_read_b128 v[28:31], v40
	ds_read_b128 v[32:35], v40 offset:1024
	ds_read_b128 v[36:39], v40 offset:2048
	ds_read_b128 v[40:43], v40 offset:3072
	ds_read_b128 v[140:143], v160
	ds_read_b128 v[144:147], v160 offset:1024
	ds_read_b128 v[156:159], v160 offset:2048
	ds_read_b128 v[160:163], v160 offset:3072
	v_lshl_add_u64 v[190:191], s[54:55], 0, v[186:187]
	s_add_i32 m0, s65, 0xc000
	ds_read_b128 v[164:167], v219
	ds_read_b128 v[168:171], v219 offset:1024
	ds_read_b128 v[172:175], v219 offset:2048
	ds_read_b128 v[176:179], v219 offset:3072
	ds_read_b128 v[204:207], v219 offset:4096
	ds_read_b128 v[208:211], v219 offset:5120
	ds_read_b128 v[212:215], v219 offset:6144
	ds_read_b128 v[220:223], v219 offset:7168
	global_load_lds_dwordx4 v[190:191], off
	v_lshl_add_u64 v[190:191], s[54:55], 0, v[188:189]
	s_add_i32 m0, s65, 0xe000
	s_nop 0
	global_load_lds_dwordx4 v[190:191], off
	s_waitcnt vmcnt(8)
	s_waitcnt lgkmcnt(0)
	s_barrier
	s_setprio 1
	s_waitcnt lgkmcnt(0)
	v_mfma_i32_16x16x64_i8 v[152:155], v[28:31], v[164:167], 0
	v_mfma_i32_16x16x64_i8 v[152:155], v[32:35], v[168:171], v[152:155]
	v_mfma_i32_16x16x64_i8 v[128:131], v[32:35], v[176:179], 0
	v_mfma_i32_16x16x64_i8 v[128:131], v[28:31], v[172:175], v[128:131]
	v_mfma_i32_16x16x64_i8 v[112:115], v[28:31], v[204:207], 0
	v_mfma_i32_16x16x64_i8 v[112:115], v[32:35], v[208:211], v[112:115]
	v_mfma_i32_16x16x64_i8 v[96:99], v[32:35], v[220:223], 0
	v_mfma_i32_16x16x64_i8 v[96:99], v[28:31], v[212:215], v[96:99]
	v_mfma_i32_16x16x64_i8 v[92:95], v[36:39], v[212:215], 0
	v_mfma_i32_16x16x64_i8 v[92:95], v[40:43], v[220:223], v[92:95]
	v_mfma_i32_16x16x64_i8 v[108:111], v[40:43], v[208:211], 0
	v_mfma_i32_16x16x64_i8 v[108:111], v[36:39], v[204:207], v[108:111]
	v_mfma_i32_16x16x64_i8 v[124:127], v[36:39], v[172:175], 0
	v_mfma_i32_16x16x64_i8 v[124:127], v[40:43], v[176:179], v[124:127]
	v_mfma_i32_16x16x64_i8 v[148:151], v[40:43], v[168:171], 0
	v_mfma_i32_16x16x64_i8 v[148:151], v[36:39], v[164:167], v[148:151]
	v_mfma_i32_16x16x64_i8 v[136:139], v[140:143], v[164:167], 0
	v_mfma_i32_16x16x64_i8 v[136:139], v[144:147], v[168:171], v[136:139]
	v_mfma_i32_16x16x64_i8 v[120:123], v[144:147], v[176:179], 0
	v_mfma_i32_16x16x64_i8 v[120:123], v[140:143], v[172:175], v[120:123]
	v_mfma_i32_16x16x64_i8 v[104:107], v[140:143], v[204:207], 0
	v_mfma_i32_16x16x64_i8 v[104:107], v[144:147], v[208:211], v[104:107]
	v_mfma_i32_16x16x64_i8 v[88:91], v[144:147], v[220:223], 0
	v_mfma_i32_16x16x64_i8 v[88:91], v[140:143], v[212:215], v[88:91]
	v_mfma_i32_16x16x64_i8 v[84:87], v[156:159], v[212:215], 0
	v_mfma_i32_16x16x64_i8 v[84:87], v[160:163], v[220:223], v[84:87]
	v_mfma_i32_16x16x64_i8 v[100:103], v[160:163], v[208:211], 0
	v_mfma_i32_16x16x64_i8 v[100:103], v[156:159], v[204:207], v[100:103]
	v_mfma_i32_16x16x64_i8 v[116:119], v[156:159], v[172:175], 0
	v_mfma_i32_16x16x64_i8 v[116:119], v[160:163], v[176:179], v[116:119]
	v_mfma_i32_16x16x64_i8 v[132:135], v[160:163], v[168:171], 0
	v_mfma_i32_16x16x64_i8 v[132:135], v[156:159], v[164:167], v[132:135]
	s_setprio 0
	s_barrier
	s_add_i32 s87, s87, s46
	v_lshl_add_u64 v[190:191], s[58:59], 0, v[2:3]
	s_mov_b32 m0, s87
	ds_read_b128 v[164:167], v219 offset:16384
	ds_read_b128 v[168:171], v219 offset:17408
	ds_read_b128 v[172:175], v219 offset:18432
	ds_read_b128 v[176:179], v219 offset:19456
	ds_read_b128 v[204:207], v219 offset:20480
	ds_read_b128 v[208:211], v219 offset:21504
	ds_read_b128 v[212:215], v219 offset:22528
	ds_read_b128 v[220:223], v219 offset:23552
	global_load_lds_dwordx4 v[190:191], off
	s_add_i32 m0, s87, 0x2000
	s_add_u32 s96, s58, 0x80000
	v_lshl_add_u64 v[224:225], s[58:59], 0, v[184:185]
	s_addc_u32 s97, s59, 0
	s_add_i32 s87, vcc_lo, s46
	global_load_lds_dwordx4 v[224:225], off
	v_lshl_add_u64 v[226:227], s[96:97], 0, v[2:3]
	s_mov_b32 m0, s87
	v_lshl_add_u64 v[228:229], s[60:61], 0, v[182:183]
	global_load_lds_dwordx4 v[226:227], off
	v_lshl_add_u64 v[226:227], s[96:97], 0, v[184:185]
	s_add_i32 m0, s87, 0x2000
	s_nop 0
	global_load_lds_dwordx4 v[226:227], off
	v_lshl_add_u64 v[226:227], s[60:61], 0, v[180:181]
	s_waitcnt vmcnt(6)
	s_waitcnt lgkmcnt(0)
	s_barrier
; #define PG8_STAGE(bufoff, gbase, voff) do { _Pragma("unroll") for (int _i = 0; _i < 2; ++_i) \
;         __builtin_amdgcn_global_load_lds((const unsigned*)((const char*)(gbase) + (voff)[_i]), (PG8_LAS unsigned*)(lds + (bufoff) + ldsw + _i * 8192), 16, 0, 0); } while (0)
; #define PG8_LDA(dst, b, h) do { _Pragma("unroll") for (int m = 0; m < 4; ++m) _Pragma("unroll") for (int k = 0; k < 2; ++k) dst[m][k] = *(const PG8_LAS bf16x8*)(lds + PG8_SA(b, h) + aoff + m * 2048 + k * 1024); } while (0)
; #define PG8_LDB(dst, b, h) do { _Pragma("unroll") for (int n = 0; n < 2; ++n) _Pragma("unroll") for (int k = 0; k < 2; ++k) dst[n][k] = *(const PG8_LAS bf16x8*)(lds + PG8_SB(b, h) + boff + n * 2048 + k * 1024); } while (0)
; #define PG8_WAIT_V(n) asm volatile("s_waitcnt vmcnt(" #n ")" ::: "memory")
; #define PG8_WAIT_L(n) asm volatile("s_waitcnt lgkmcnt(" #n ")" ::: "memory")
; #define PG8_BAR __builtin_amdgcn_s_barrier()
; #define PG8_SCHED __builtin_amdgcn_sched_barrier(0)
; template <class Epi, class Sched, bool ALIGN_EPI = false, bool SP2 = false, bool I8 = false>
; __device__ __forceinline__ void gemm_phase(PG8_LAS unsigned char* lds, const Gemm g, const Sched& S, const Epi& E) {
;     ...
;             PG8_WAIT_V(8); PG8_WAIT_L(0); PG8_BAR; PG8_MMA(1, 0, At, B0); PG8_MMA(1, 1, At, B1); PG8_BAR; PG8_SCHED;
;             PG8_LDB(B0, 1, 0); PG8_LDB(B1, 1, 1); PG8_SCHED; PG8_LDA(At, 1, 0); PG8_STAGE(PG8_SA(0, 1), a2 + hstep, voffA);
;             PG8_WAIT_V(8); PG8_WAIT_L(0); PG8_BAR; PG8_MMA(0, 0, At, B0); PG8_MMA(0, 1, At, B1); PG8_BAR; PG8_SCHED;
	s_setprio 1
	s_waitcnt lgkmcnt(0)
	v_mfma_i32_16x16x64_i8 v[80:83], v[28:31], v[164:167], 0
	v_mfma_i32_16x16x64_i8 v[80:83], v[32:35], v[168:171], v[80:83]
	v_mfma_i32_16x16x64_i8 v[64:67], v[32:35], v[176:179], 0
	v_mfma_i32_16x16x64_i8 v[64:67], v[28:31], v[172:175], v[64:67]
	v_mfma_i32_16x16x64_i8 v[48:51], v[28:31], v[204:207], 0
	v_mfma_i32_16x16x64_i8 v[48:51], v[32:35], v[208:211], v[48:51]
	v_mfma_i32_16x16x64_i8 v[16:19], v[32:35], v[220:223], 0
	v_mfma_i32_16x16x64_i8 v[16:19], v[28:31], v[212:215], v[16:19]
	v_mfma_i32_16x16x64_i8 v[12:15], v[36:39], v[212:215], 0
	v_mfma_i32_16x16x64_i8 v[12:15], v[40:43], v[220:223], v[12:15]
	v_mfma_i32_16x16x64_i8 v[44:47], v[40:43], v[208:211], 0
	v_mfma_i32_16x16x64_i8 v[44:47], v[36:39], v[204:207], v[44:47]
	v_mfma_i32_16x16x64_i8 v[60:63], v[36:39], v[172:175], 0
	v_mfma_i32_16x16x64_i8 v[60:63], v[40:43], v[176:179], v[60:63]
	v_mfma_i32_16x16x64_i8 v[76:79], v[40:43], v[168:171], 0
	v_mfma_i32_16x16x64_i8 v[76:79], v[36:39], v[164:167], v[76:79]
	v_mfma_i32_16x16x64_i8 v[28:31], v[140:143], v[164:167], 0
	v_mfma_i32_16x16x64_i8 v[28:31], v[144:147], v[168:171], v[28:31]
	v_mfma_i32_16x16x64_i8 v[36:39], v[144:147], v[176:179], 0
	v_mfma_i32_16x16x64_i8 v[36:39], v[140:143], v[172:175], v[36:39]
	v_mfma_i32_16x16x64_i8 v[24:27], v[140:143], v[204:207], 0
	v_mfma_i32_16x16x64_i8 v[24:27], v[144:147], v[208:211], v[24:27]
	v_mfma_i32_16x16x64_i8 v[8:11], v[144:147], v[220:223], 0
	v_mfma_i32_16x16x64_i8 v[8:11], v[140:143], v[212:215], v[8:11]
	v_mfma_i32_16x16x64_i8 v[4:7], v[156:159], v[212:215], 0
	v_mfma_i32_16x16x64_i8 v[4:7], v[160:163], v[220:223], v[4:7]
	v_mfma_i32_16x16x64_i8 v[20:23], v[160:163], v[208:211], 0
	v_mfma_i32_16x16x64_i8 v[20:23], v[156:159], v[204:207], v[20:23]
	v_mfma_i32_16x16x64_i8 v[40:43], v[156:159], v[172:175], 0
	v_mfma_i32_16x16x64_i8 v[40:43], v[160:163], v[176:179], v[40:43]
	v_mfma_i32_16x16x64_i8 v[32:35], v[160:163], v[168:171], 0
	v_mfma_i32_16x16x64_i8 v[32:35], v[156:159], v[164:167], v[32:35]
	s_setprio 0
	s_barrier
	s_mov_b32 m0, s65
	s_nop 0
	global_load_lds_dwordx4 v[226:227], off
	s_mov_b32 m0, s67
	s_nop 0
	global_load_lds_dwordx4 v[228:229], off
	s_add_i32 s87, 0, 0x18000
	s_add_i32 s96, 0, 0x1c000
	v_add_u32_e32 v72, s87, v217
	v_add_u32_e32 v160, s96, v217
	ds_read_b128 v[52:55], v72
	ds_read_b128 v[56:59], v72 offset:1024
	ds_read_b128 v[68:71], v72 offset:2048
	ds_read_b128 v[72:75], v72 offset:3072
	ds_read_b128 v[140:143], v160
	ds_read_b128 v[144:147], v160 offset:1024
	ds_read_b128 v[156:159], v160 offset:2048
	ds_read_b128 v[160:163], v160 offset:3072
	s_add_u32 s60, s60, 0x80000
	s_addc_u32 s61, s61, 0
	s_mov_b32 m0, s72
	v_lshl_add_u64 v[240:241], s[60:61], 0, v[180:181]
	ds_read_b128 v[164:167], v219 offset:32768
	ds_read_b128 v[168:171], v219 offset:33792
	ds_read_b128 v[172:175], v219 offset:34816
	ds_read_b128 v[176:179], v219 offset:35840
	ds_read_b128 v[204:207], v219 offset:36864
	ds_read_b128 v[208:211], v219 offset:37888
	ds_read_b128 v[212:215], v219 offset:38912
	ds_read_b128 v[220:223], v219 offset:39936
	global_load_lds_dwordx4 v[240:241], off
	v_lshl_add_u64 v[240:241], s[60:61], 0, v[182:183]
	s_mov_b32 m0, s73
	s_nop 0
	global_load_lds_dwordx4 v[240:241], off
	s_waitcnt vmcnt(8)
	s_waitcnt lgkmcnt(0)
	s_barrier
	s_setprio 1
	s_waitcnt lgkmcnt(0)
	v_mfma_i32_16x16x64_i8 v[152:155], v[52:55], v[164:167], v[152:155]
	v_mfma_i32_16x16x64_i8 v[152:155], v[56:59], v[168:171], v[152:155]
	v_mfma_i32_16x16x64_i8 v[128:131], v[56:59], v[176:179], v[128:131]
	v_mfma_i32_16x16x64_i8 v[128:131], v[52:55], v[172:175], v[128:131]
	v_mfma_i32_16x16x64_i8 v[112:115], v[52:55], v[204:207], v[112:115]
	v_mfma_i32_16x16x64_i8 v[112:115], v[56:59], v[208:211], v[112:115]
	v_mfma_i32_16x16x64_i8 v[96:99], v[56:59], v[220:223], v[96:99]
	v_mfma_i32_16x16x64_i8 v[96:99], v[52:55], v[212:215], v[96:99]
	v_mfma_i32_16x16x64_i8 v[92:95], v[68:71], v[212:215], v[92:95]
	v_mfma_i32_16x16x64_i8 v[92:95], v[72:75], v[220:223], v[92:95]
	v_mfma_i32_16x16x64_i8 v[108:111], v[72:75], v[208:211], v[108:111]
	v_mfma_i32_16x16x64_i8 v[108:111], v[68:71], v[204:207], v[108:111]
	v_mfma_i32_16x16x64_i8 v[124:127], v[68:71], v[172:175], v[124:127]
	v_mfma_i32_16x16x64_i8 v[124:127], v[72:75], v[176:179], v[124:127]
	v_mfma_i32_16x16x64_i8 v[148:151], v[72:75], v[168:171], v[148:151]
	v_mfma_i32_16x16x64_i8 v[148:151], v[68:71], v[164:167], v[148:151]
	v_mfma_i32_16x16x64_i8 v[136:139], v[140:143], v[164:167], v[136:139]
	v_mfma_i32_16x16x64_i8 v[136:139], v[144:147], v[168:171], v[136:139]
	v_mfma_i32_16x16x64_i8 v[120:123], v[144:147], v[176:179], v[120:123]
	v_mfma_i32_16x16x64_i8 v[120:123], v[140:143], v[172:175], v[120:123]
	v_mfma_i32_16x16x64_i8 v[104:107], v[140:143], v[204:207], v[104:107]
	v_mfma_i32_16x16x64_i8 v[104:107], v[144:147], v[208:211], v[104:107]
	v_mfma_i32_16x16x64_i8 v[88:91], v[144:147], v[220:223], v[88:91]
	v_mfma_i32_16x16x64_i8 v[88:91], v[140:143], v[212:215], v[88:91]
	v_mfma_i32_16x16x64_i8 v[84:87], v[156:159], v[212:215], v[84:87]
	v_mfma_i32_16x16x64_i8 v[84:87], v[160:163], v[220:223], v[84:87]
	v_mfma_i32_16x16x64_i8 v[100:103], v[160:163], v[208:211], v[100:103]
	v_mfma_i32_16x16x64_i8 v[100:103], v[156:159], v[204:207], v[100:103]
	v_mfma_i32_16x16x64_i8 v[116:119], v[156:159], v[172:175], v[116:119]
	v_mfma_i32_16x16x64_i8 v[116:119], v[160:163], v[176:179], v[116:119]
	v_mfma_i32_16x16x64_i8 v[132:135], v[160:163], v[168:171], v[132:135]
	v_mfma_i32_16x16x64_i8 v[132:135], v[156:159], v[164:167], v[132:135]
	s_setprio 0
	s_barrier
; #define PG8_STAGE(bufoff, gbase, voff) do { _Pragma("unroll") for (int _i = 0; _i < 2; ++_i) \
;         __builtin_amdgcn_global_load_lds((const unsigned*)((const char*)(gbase) + (voff)[_i]), (PG8_LAS unsigned*)(lds + (bufoff) + ldsw + _i * 8192), 16, 0, 0); } while (0)
; #define PG8_LDA(dst, b, h) do { _Pragma("unroll") for (int m = 0; m < 4; ++m) _Pragma("unroll") for (int k = 0; k < 2; ++k) dst[m][k] = *(const PG8_LAS bf16x8*)(lds + PG8_SA(b, h) + aoff + m * 2048 + k * 1024); } while (0)
; #define PG8_WAIT_V(n) asm volatile("s_waitcnt vmcnt(" #n ")" ::: "memory")
; #define PG8_WAIT_L(n) asm volatile("s_waitcnt lgkmcnt(" #n ")" ::: "memory")
; #define PG8_BAR __builtin_amdgcn_s_barrier()
; template <class Epi, class Sched, bool ALIGN_EPI = false, bool SP2 = false, bool I8 = false>
; __device__ __forceinline__ void gemm_phase(PG8_LAS unsigned char* lds, const Gemm g, const Sched& S, const Epi& E) {
;     ...
;         for (int t = 0; t < nt; t += 2) {
;             const bool last = (t == nt - 2);
;             const char* a1 = cA + (size_t)(t + 1) * kstep;
;             const char* a2 = last ? nA : cA + (size_t)(t + 2) * kstep; const char* b2 = last ? nB : cB + (size_t)(t + 2) * kstep;
;             const char* a3 = a2 + kstep; const char* b3 = b2 + kstep;
;             if (last && has_next) S.a_ready(nxt);
;             if constexpr (SP2) {
;             PG8_LDB(B0, 0, 0); PG8_LDB(B1, 0, 1); PG8_SCHED; PG8_LDA(At, 0, 0); PG8_STAGE(PG8_SA(1, 1), a1 + hstep, voffA);
;             PG8_WAIT_V(8); PG8_WAIT_L(0); PG8_BAR; PG8_MMA(0, 0, At, B0); PG8_MMA(0, 1, At, B1); PG8_BAR; PG8_SCHED;
;             PG8_LDA(At, 0, 1); PG8_STAGE(PG8_SB(0, 0), b2, voffB); PG8_STAGE(PG8_SB(0, 1), b2 + hstep, voffB); PG8_STAGE(PG8_SA(0, 0), a2, voffA);
;             PG8_WAIT_V(8); PG8_WAIT_L(0); PG8_BAR; PG8_MMA(1, 0, At, B0); PG8_MMA(1, 1, At, B1); PG8_BAR; PG8_SCHED;
;             PG8_LDB(B0, 1, 0); PG8_LDB(B1, 1, 1); PG8_SCHED; PG8_LDA(At, 1, 0); PG8_STAGE(PG8_SA(0, 1), a2 + hstep, voffA);
;             PG8_WAIT_V(8); PG8_WAIT_L(0); PG8_BAR; PG8_MMA(0, 0, At, B0); PG8_MMA(0, 1, At, B1); PG8_BAR; PG8_SCHED;
;             PG8_LDA(At, 1, 1); PG8_STAGE(PG8_SB(1, 0), b3, voffB); PG8_STAGE(PG8_SB(1, 1), b3 + hstep, voffB); PG8_STAGE(PG8_SA(1, 0), a3, voffA);
;             PG8_WAIT_V(8); PG8_WAIT_L(0); PG8_BAR; PG8_MMA(1, 0, At, B0); PG8_MMA(1, 1, At, B1); PG8_BAR; PG8_SCHED;
	s_add_i32 s60, s87, s46
	v_lshl_add_u64 v[190:191], v[190:191], 0, s[84:85]
	s_mov_b32 m0, s60
	ds_read_b128 v[164:167], v219 offset:49152
	ds_read_b128 v[168:171], v219 offset:50176
	ds_read_b128 v[172:175], v219 offset:51200
	ds_read_b128 v[176:179], v219 offset:52224
	ds_read_b128 v[204:207], v219 offset:53248
	ds_read_b128 v[208:211], v219 offset:54272
	ds_read_b128 v[212:215], v219 offset:55296
	ds_read_b128 v[220:223], v219 offset:56320
	global_load_lds_dwordx4 v[190:191], off
	s_add_i32 m0, s60, 0x2000
	s_add_u32 s58, s58, 0x80080
	v_lshl_add_u64 v[190:191], v[224:225], 0, s[84:85]
	s_addc_u32 s59, s59, 0
	s_add_i32 s60, s96, s46
	global_load_lds_dwordx4 v[190:191], off
	v_lshl_add_u64 v[190:191], s[58:59], 0, v[2:3]
	s_mov_b32 m0, s60
	s_nop 0
	global_load_lds_dwordx4 v[190:191], off
	v_lshl_add_u64 v[190:191], s[58:59], 0, v[184:185]
	s_add_i32 m0, s60, 0x2000
	s_nop 0
	global_load_lds_dwordx4 v[190:191], off
	v_lshl_add_u64 v[190:191], v[226:227], 0, s[84:85]
	s_mov_b32 m0, s28
	s_nop 0
	global_load_lds_dwordx4 v[190:191], off
	v_lshl_add_u64 v[190:191], v[228:229], 0, s[84:85]
	s_mov_b32 m0, s77
	s_nop 0
	global_load_lds_dwordx4 v[190:191], off
	s_waitcnt vmcnt(8)
	s_waitcnt lgkmcnt(0)
	s_barrier
	s_setprio 1
	s_waitcnt lgkmcnt(0)
	v_mfma_i32_16x16x64_i8 v[80:83], v[52:55], v[164:167], v[80:83]
	v_mfma_i32_16x16x64_i8 v[80:83], v[56:59], v[168:171], v[80:83]
	v_mfma_i32_16x16x64_i8 v[64:67], v[56:59], v[176:179], v[64:67]
	v_mfma_i32_16x16x64_i8 v[64:67], v[52:55], v[172:175], v[64:67]
	v_mfma_i32_16x16x64_i8 v[48:51], v[52:55], v[204:207], v[48:51]
	v_mfma_i32_16x16x64_i8 v[48:51], v[56:59], v[208:211], v[48:51]
	v_mfma_i32_16x16x64_i8 v[16:19], v[56:59], v[220:223], v[16:19]
	v_mfma_i32_16x16x64_i8 v[16:19], v[52:55], v[212:215], v[16:19]
	v_mfma_i32_16x16x64_i8 v[12:15], v[68:71], v[212:215], v[12:15]
	v_mfma_i32_16x16x64_i8 v[12:15], v[72:75], v[220:223], v[12:15]
	v_mfma_i32_16x16x64_i8 v[44:47], v[72:75], v[208:211], v[44:47]
	v_mfma_i32_16x16x64_i8 v[44:47], v[68:71], v[204:207], v[44:47]
	v_mfma_i32_16x16x64_i8 v[60:63], v[68:71], v[172:175], v[60:63]
	v_mfma_i32_16x16x64_i8 v[60:63], v[72:75], v[176:179], v[60:63]
	v_mfma_i32_16x16x64_i8 v[76:79], v[72:75], v[168:171], v[76:79]
	v_mfma_i32_16x16x64_i8 v[76:79], v[68:71], v[164:167], v[76:79]
	v_mfma_i32_16x16x64_i8 v[28:31], v[140:143], v[164:167], v[28:31]
	v_mfma_i32_16x16x64_i8 v[72:75], v[144:147], v[168:171], v[28:31]
	v_mfma_i32_16x16x64_i8 v[28:31], v[144:147], v[176:179], v[36:39]
	v_mfma_i32_16x16x64_i8 v[56:59], v[140:143], v[172:175], v[28:31]
	v_mfma_i32_16x16x64_i8 v[24:27], v[140:143], v[204:207], v[24:27]
	v_mfma_i32_16x16x64_i8 v[24:27], v[144:147], v[208:211], v[24:27]
	v_mfma_i32_16x16x64_i8 v[8:11], v[144:147], v[220:223], v[8:11]
	v_mfma_i32_16x16x64_i8 v[8:11], v[140:143], v[212:215], v[8:11]
	v_mfma_i32_16x16x64_i8 v[4:7], v[156:159], v[212:215], v[4:7]
	v_mfma_i32_16x16x64_i8 v[4:7], v[160:163], v[220:223], v[4:7]
	v_mfma_i32_16x16x64_i8 v[20:23], v[160:163], v[208:211], v[20:23]
	v_mfma_i32_16x16x64_i8 v[20:23], v[156:159], v[204:207], v[20:23]
	v_mfma_i32_16x16x64_i8 v[28:31], v[156:159], v[172:175], v[40:43]
	v_mfma_i32_16x16x64_i8 v[52:55], v[160:163], v[176:179], v[28:31]
	v_mfma_i32_16x16x64_i8 v[28:31], v[160:163], v[168:171], v[32:35]
	v_mfma_i32_16x16x64_i8 v[68:71], v[156:159], v[164:167], v[28:31]
	s_setprio 0
	s_barrier
	s_add_i32 s86, s86, 2
	s_add_u32 s54, s54, 0x100
	s_addc_u32 s55, s55, 0
	s_add_u32 s45, s45, 0x100
	s_addc_u32 s49, s49, 0
	s_cmp_gt_u32 s86, 29
	s_cbranch_scc1 .Lkloop_exit_6
.LBB0_1843:
	s_add_u32 s58, s54, 0xfff80080
	s_addc_u32 s59, s55, -1
	s_add_i32 s87, 0, 0x10000
	s_cmp_eq_u32 s86, 28
	s_cselect_b32 s61, s11, s59
	s_cselect_b32 s60, s13, s58
	s_cselect_b32 s59, s34, s49
	s_cselect_b32 s58, s35, s45
	s_add_i32 vcc_lo, 0, 0x14000
	v_add_u32_e32 v40, s87, v217
	v_add_u32_e32 v160, vcc_lo, v217
	ds_read_b128 v[28:31], v40
	ds_read_b128 v[32:35], v40 offset:1024
	ds_read_b128 v[36:39], v40 offset:2048
	ds_read_b128 v[40:43], v40 offset:3072
	ds_read_b128 v[140:143], v160
	ds_read_b128 v[144:147], v160 offset:1024
	ds_read_b128 v[156:159], v160 offset:2048
	ds_read_b128 v[160:163], v160 offset:3072
	v_lshl_add_u64 v[190:191], s[54:55], 0, v[186:187]
	s_add_i32 m0, s65, 0xc000
	ds_read_b128 v[164:167], v219
	ds_read_b128 v[168:171], v219 offset:1024
	ds_read_b128 v[172:175], v219 offset:2048
	ds_read_b128 v[176:179], v219 offset:3072
	ds_read_b128 v[204:207], v219 offset:4096
	ds_read_b128 v[208:211], v219 offset:5120
	ds_read_b128 v[212:215], v219 offset:6144
	ds_read_b128 v[220:223], v219 offset:7168
	global_load_lds_dwordx4 v[190:191], off
	v_lshl_add_u64 v[190:191], s[54:55], 0, v[188:189]
	s_add_i32 m0, s65, 0xe000
	s_nop 0
	global_load_lds_dwordx4 v[190:191], off
	s_waitcnt vmcnt(8)
	s_waitcnt lgkmcnt(0)
	s_barrier
; #define PG8_STAGE(bufoff, gbase, voff) do { _Pragma("unroll") for (int _i = 0; _i < 2; ++_i) \
;         __builtin_amdgcn_global_load_lds((const unsigned*)((const char*)(gbase) + (voff)[_i]), (PG8_LAS unsigned*)(lds + (bufoff) + ldsw + _i * 8192), 16, 0, 0); } while (0)
; #define PG8_LDA(dst, b, h) do { _Pragma("unroll") for (int m = 0; m < 4; ++m) _Pragma("unroll") for (int k = 0; k < 2; ++k) dst[m][k] = *(const PG8_LAS bf16x8*)(lds + PG8_SA(b, h) + aoff + m * 2048 + k * 1024); } while (0)
; #define PG8_WAIT_V(n) asm volatile("s_waitcnt vmcnt(" #n ")" ::: "memory")
; #define PG8_WAIT_L(n) asm volatile("s_waitcnt lgkmcnt(" #n ")" ::: "memory")
; #define PG8_BAR __builtin_amdgcn_s_barrier()
; #define PG8_SCHED __builtin_amdgcn_sched_barrier(0)
; template <class Epi, class Sched, bool ALIGN_EPI = false, bool SP2 = false, bool I8 = false>
; __device__ __forceinline__ void gemm_phase(PG8_LAS unsigned char* lds, const Gemm g, const Sched& S, const Epi& E) {
;     ...
;             PG8_WAIT_V(8); PG8_WAIT_L(0); PG8_BAR; PG8_MMA(0, 0, At, B0); PG8_MMA(0, 1, At, B1); PG8_BAR; PG8_SCHED;
;             PG8_LDA(At, 0, 1); PG8_STAGE(PG8_SB(0, 0), b2, voffB); PG8_STAGE(PG8_SB(0, 1), b2 + hstep, voffB); PG8_STAGE(PG8_SA(0, 0), a2, voffA);
;             PG8_WAIT_V(8); PG8_WAIT_L(0); PG8_BAR; PG8_MMA(1, 0, At, B0); PG8_MMA(1, 1, At, B1); PG8_BAR; PG8_SCHED;
	s_setprio 1
	s_waitcnt lgkmcnt(0)
	v_mfma_i32_16x16x64_i8 v[152:155], v[28:31], v[164:167], v[152:155]
	v_mfma_i32_16x16x64_i8 v[152:155], v[32:35], v[168:171], v[152:155]
	v_mfma_i32_16x16x64_i8 v[128:131], v[32:35], v[176:179], v[128:131]
	v_mfma_i32_16x16x64_i8 v[128:131], v[28:31], v[172:175], v[128:131]
	v_mfma_i32_16x16x64_i8 v[112:115], v[28:31], v[204:207], v[112:115]
	v_mfma_i32_16x16x64_i8 v[112:115], v[32:35], v[208:211], v[112:115]
	v_mfma_i32_16x16x64_i8 v[96:99], v[32:35], v[220:223], v[96:99]
	v_mfma_i32_16x16x64_i8 v[96:99], v[28:31], v[212:215], v[96:99]
	v_mfma_i32_16x16x64_i8 v[92:95], v[36:39], v[212:215], v[92:95]
	v_mfma_i32_16x16x64_i8 v[92:95], v[40:43], v[220:223], v[92:95]
	v_mfma_i32_16x16x64_i8 v[108:111], v[40:43], v[208:211], v[108:111]
	v_mfma_i32_16x16x64_i8 v[108:111], v[36:39], v[204:207], v[108:111]
	v_mfma_i32_16x16x64_i8 v[124:127], v[36:39], v[172:175], v[124:127]
	v_mfma_i32_16x16x64_i8 v[124:127], v[40:43], v[176:179], v[124:127]
	v_mfma_i32_16x16x64_i8 v[148:151], v[40:43], v[168:171], v[148:151]
	v_mfma_i32_16x16x64_i8 v[148:151], v[36:39], v[164:167], v[148:151]
	v_mfma_i32_16x16x64_i8 v[136:139], v[140:143], v[164:167], v[136:139]
	v_mfma_i32_16x16x64_i8 v[136:139], v[144:147], v[168:171], v[136:139]
	v_mfma_i32_16x16x64_i8 v[120:123], v[144:147], v[176:179], v[120:123]
	v_mfma_i32_16x16x64_i8 v[120:123], v[140:143], v[172:175], v[120:123]
	v_mfma_i32_16x16x64_i8 v[104:107], v[140:143], v[204:207], v[104:107]
	v_mfma_i32_16x16x64_i8 v[104:107], v[144:147], v[208:211], v[104:107]
	v_mfma_i32_16x16x64_i8 v[88:91], v[144:147], v[220:223], v[88:91]
	v_mfma_i32_16x16x64_i8 v[88:91], v[140:143], v[212:215], v[88:91]
	v_mfma_i32_16x16x64_i8 v[84:87], v[156:159], v[212:215], v[84:87]
	v_mfma_i32_16x16x64_i8 v[84:87], v[160:163], v[220:223], v[84:87]
	v_mfma_i32_16x16x64_i8 v[100:103], v[160:163], v[208:211], v[100:103]
	v_mfma_i32_16x16x64_i8 v[100:103], v[156:159], v[204:207], v[100:103]
	v_mfma_i32_16x16x64_i8 v[116:119], v[156:159], v[172:175], v[116:119]
	v_mfma_i32_16x16x64_i8 v[116:119], v[160:163], v[176:179], v[116:119]
	v_mfma_i32_16x16x64_i8 v[132:135], v[160:163], v[168:171], v[132:135]
	v_mfma_i32_16x16x64_i8 v[132:135], v[156:159], v[164:167], v[132:135]
	s_setprio 0
	s_barrier
	s_add_i32 s87, s87, s46
	v_lshl_add_u64 v[190:191], s[58:59], 0, v[2:3]
	s_mov_b32 m0, s87
	ds_read_b128 v[164:167], v219 offset:16384
	ds_read_b128 v[168:171], v219 offset:17408
	ds_read_b128 v[172:175], v219 offset:18432
	ds_read_b128 v[176:179], v219 offset:19456
	ds_read_b128 v[204:207], v219 offset:20480
	ds_read_b128 v[208:211], v219 offset:21504
	ds_read_b128 v[212:215], v219 offset:22528
	ds_read_b128 v[220:223], v219 offset:23552
	global_load_lds_dwordx4 v[190:191], off
	s_add_i32 m0, s87, 0x2000
	s_add_u32 s96, s58, 0x80000
	v_lshl_add_u64 v[224:225], s[58:59], 0, v[184:185]
	s_addc_u32 s97, s59, 0
	s_add_i32 s87, vcc_lo, s46
	global_load_lds_dwordx4 v[224:225], off
	v_lshl_add_u64 v[226:227], s[96:97], 0, v[2:3]
	s_mov_b32 m0, s87
	v_lshl_add_u64 v[228:229], s[60:61], 0, v[182:183]
	global_load_lds_dwordx4 v[226:227], off
	v_lshl_add_u64 v[226:227], s[96:97], 0, v[184:185]
	s_add_i32 m0, s87, 0x2000
	s_nop 0
	global_load_lds_dwordx4 v[226:227], off
	v_lshl_add_u64 v[226:227], s[60:61], 0, v[180:181]
	s_waitcnt vmcnt(6)
	s_waitcnt lgkmcnt(0)
	s_barrier
	s_setprio 1
	s_waitcnt lgkmcnt(0)
	v_mfma_i32_16x16x64_i8 v[80:83], v[28:31], v[164:167], v[80:83]
	v_mfma_i32_16x16x64_i8 v[80:83], v[32:35], v[168:171], v[80:83]
	v_mfma_i32_16x16x64_i8 v[64:67], v[32:35], v[176:179], v[64:67]
	v_mfma_i32_16x16x64_i8 v[64:67], v[28:31], v[172:175], v[64:67]
	v_mfma_i32_16x16x64_i8 v[48:51], v[28:31], v[204:207], v[48:51]
	v_mfma_i32_16x16x64_i8 v[48:51], v[32:35], v[208:211], v[48:51]
	v_mfma_i32_16x16x64_i8 v[16:19], v[32:35], v[220:223], v[16:19]
	v_mfma_i32_16x16x64_i8 v[16:19], v[28:31], v[212:215], v[16:19]
	v_mfma_i32_16x16x64_i8 v[12:15], v[36:39], v[212:215], v[12:15]
	v_mfma_i32_16x16x64_i8 v[12:15], v[40:43], v[220:223], v[12:15]
	v_mfma_i32_16x16x64_i8 v[44:47], v[40:43], v[208:211], v[44:47]
	v_mfma_i32_16x16x64_i8 v[44:47], v[36:39], v[204:207], v[44:47]
	v_mfma_i32_16x16x64_i8 v[60:63], v[36:39], v[172:175], v[60:63]
	v_mfma_i32_16x16x64_i8 v[60:63], v[40:43], v[176:179], v[60:63]
	v_mfma_i32_16x16x64_i8 v[76:79], v[40:43], v[168:171], v[76:79]
	v_mfma_i32_16x16x64_i8 v[76:79], v[36:39], v[164:167], v[76:79]
	v_mfma_i32_16x16x64_i8 v[28:31], v[140:143], v[164:167], v[72:75]
	v_mfma_i32_16x16x64_i8 v[28:31], v[144:147], v[168:171], v[28:31]
	v_mfma_i32_16x16x64_i8 v[36:39], v[144:147], v[176:179], v[56:59]
	v_mfma_i32_16x16x64_i8 v[36:39], v[140:143], v[172:175], v[36:39]
	v_mfma_i32_16x16x64_i8 v[24:27], v[140:143], v[204:207], v[24:27]
	v_mfma_i32_16x16x64_i8 v[24:27], v[144:147], v[208:211], v[24:27]
	v_mfma_i32_16x16x64_i8 v[8:11], v[144:147], v[220:223], v[8:11]
	v_mfma_i32_16x16x64_i8 v[8:11], v[140:143], v[212:215], v[8:11]
	v_mfma_i32_16x16x64_i8 v[4:7], v[156:159], v[212:215], v[4:7]
	v_mfma_i32_16x16x64_i8 v[4:7], v[160:163], v[220:223], v[4:7]
	v_mfma_i32_16x16x64_i8 v[20:23], v[160:163], v[208:211], v[20:23]
	v_mfma_i32_16x16x64_i8 v[20:23], v[156:159], v[204:207], v[20:23]
	v_mfma_i32_16x16x64_i8 v[40:43], v[156:159], v[172:175], v[52:55]
	v_mfma_i32_16x16x64_i8 v[40:43], v[160:163], v[176:179], v[40:43]
	v_mfma_i32_16x16x64_i8 v[32:35], v[160:163], v[168:171], v[68:71]
	v_mfma_i32_16x16x64_i8 v[32:35], v[156:159], v[164:167], v[32:35]
	s_setprio 0
	s_barrier
; #define PG8_STAGE(bufoff, gbase, voff) do { _Pragma("unroll") for (int _i = 0; _i < 2; ++_i) \
;         __builtin_amdgcn_global_load_lds((const unsigned*)((const char*)(gbase) + (voff)[_i]), (PG8_LAS unsigned*)(lds + (bufoff) + ldsw + _i * 8192), 16, 0, 0); } while (0)
; #define PG8_LDA(dst, b, h) do { _Pragma("unroll") for (int m = 0; m < 4; ++m) _Pragma("unroll") for (int k = 0; k < 2; ++k) dst[m][k] = *(const PG8_LAS bf16x8*)(lds + PG8_SA(b, h) + aoff + m * 2048 + k * 1024); } while (0)
; #define PG8_LDB(dst, b, h) do { _Pragma("unroll") for (int n = 0; n < 2; ++n) _Pragma("unroll") for (int k = 0; k < 2; ++k) dst[n][k] = *(const PG8_LAS bf16x8*)(lds + PG8_SB(b, h) + boff + n * 2048 + k * 1024); } while (0)
; #define PG8_WAIT_V(n) asm volatile("s_waitcnt vmcnt(" #n ")" ::: "memory")
; #define PG8_WAIT_L(n) asm volatile("s_waitcnt lgkmcnt(" #n ")" ::: "memory")
; #define PG8_BAR __builtin_amdgcn_s_barrier()
; #define PG8_SCHED __builtin_amdgcn_sched_barrier(0)
; template <class Epi, class Sched, bool ALIGN_EPI = false, bool SP2 = false, bool I8 = false>
; __device__ __forceinline__ void gemm_phase(PG8_LAS unsigned char* lds, const Gemm g, const Sched& S, const Epi& E) {
;     ...
;             PG8_LDA(At, 0, 1); PG8_STAGE(PG8_SB(0, 0), b2, voffB); PG8_STAGE(PG8_SB(0, 1), b2 + hstep, voffB); PG8_STAGE(PG8_SA(0, 0), a2, voffA);
;             PG8_WAIT_V(8); PG8_WAIT_L(0); PG8_BAR; PG8_MMA(1, 0, At, B0); PG8_MMA(1, 1, At, B1); PG8_BAR; PG8_SCHED;
;             PG8_LDB(B0, 1, 0); PG8_LDB(B1, 1, 1); PG8_SCHED; PG8_LDA(At, 1, 0); PG8_STAGE(PG8_SA(0, 1), a2 + hstep, voffA);
;             PG8_WAIT_V(8); PG8_WAIT_L(0); PG8_BAR; PG8_MMA(0, 0, At, B0); PG8_MMA(0, 1, At, B1); PG8_BAR; PG8_SCHED;
	s_mov_b32 m0, s65
	s_nop 0
	global_load_lds_dwordx4 v[226:227], off
	s_mov_b32 m0, s67
	s_nop 0
	global_load_lds_dwordx4 v[228:229], off
	s_add_i32 s87, 0, 0x18000
	s_add_i32 s96, 0, 0x1c000
	v_add_u32_e32 v72, s87, v217
	v_add_u32_e32 v160, s96, v217
	ds_read_b128 v[52:55], v72
	ds_read_b128 v[56:59], v72 offset:1024
	ds_read_b128 v[68:71], v72 offset:2048
	ds_read_b128 v[72:75], v72 offset:3072
	ds_read_b128 v[140:143], v160
	ds_read_b128 v[144:147], v160 offset:1024
	ds_read_b128 v[156:159], v160 offset:2048
	ds_read_b128 v[160:163], v160 offset:3072
	s_add_u32 s60, s60, 0x80000
	s_addc_u32 s61, s61, 0
	s_mov_b32 m0, s72
	v_lshl_add_u64 v[240:241], s[60:61], 0, v[180:181]
	ds_read_b128 v[164:167], v219 offset:32768
	ds_read_b128 v[168:171], v219 offset:33792
	ds_read_b128 v[172:175], v219 offset:34816
	ds_read_b128 v[176:179], v219 offset:35840
	ds_read_b128 v[204:207], v219 offset:36864
	ds_read_b128 v[208:211], v219 offset:37888
	ds_read_b128 v[212:215], v219 offset:38912
	ds_read_b128 v[220:223], v219 offset:39936
	global_load_lds_dwordx4 v[240:241], off
	v_lshl_add_u64 v[240:241], s[60:61], 0, v[182:183]
	s_mov_b32 m0, s73
	s_nop 0
	global_load_lds_dwordx4 v[240:241], off
	s_waitcnt vmcnt(8)
	s_waitcnt lgkmcnt(0)
	s_barrier
	s_setprio 1
	s_waitcnt lgkmcnt(0)
	v_mfma_i32_16x16x64_i8 v[152:155], v[52:55], v[164:167], v[152:155]
	v_mfma_i32_16x16x64_i8 v[152:155], v[56:59], v[168:171], v[152:155]
	v_mfma_i32_16x16x64_i8 v[128:131], v[56:59], v[176:179], v[128:131]
	v_mfma_i32_16x16x64_i8 v[128:131], v[52:55], v[172:175], v[128:131]
	v_mfma_i32_16x16x64_i8 v[112:115], v[52:55], v[204:207], v[112:115]
	v_mfma_i32_16x16x64_i8 v[112:115], v[56:59], v[208:211], v[112:115]
	v_mfma_i32_16x16x64_i8 v[96:99], v[56:59], v[220:223], v[96:99]
	v_mfma_i32_16x16x64_i8 v[96:99], v[52:55], v[212:215], v[96:99]
	v_mfma_i32_16x16x64_i8 v[92:95], v[68:71], v[212:215], v[92:95]
	v_mfma_i32_16x16x64_i8 v[92:95], v[72:75], v[220:223], v[92:95]
	v_mfma_i32_16x16x64_i8 v[108:111], v[72:75], v[208:211], v[108:111]
	v_mfma_i32_16x16x64_i8 v[108:111], v[68:71], v[204:207], v[108:111]
	v_mfma_i32_16x16x64_i8 v[124:127], v[68:71], v[172:175], v[124:127]
	v_mfma_i32_16x16x64_i8 v[124:127], v[72:75], v[176:179], v[124:127]
	v_mfma_i32_16x16x64_i8 v[148:151], v[72:75], v[168:171], v[148:151]
	v_mfma_i32_16x16x64_i8 v[148:151], v[68:71], v[164:167], v[148:151]
	v_mfma_i32_16x16x64_i8 v[136:139], v[140:143], v[164:167], v[136:139]
	v_mfma_i32_16x16x64_i8 v[136:139], v[144:147], v[168:171], v[136:139]
	v_mfma_i32_16x16x64_i8 v[120:123], v[144:147], v[176:179], v[120:123]
	v_mfma_i32_16x16x64_i8 v[120:123], v[140:143], v[172:175], v[120:123]
	v_mfma_i32_16x16x64_i8 v[104:107], v[140:143], v[204:207], v[104:107]
	v_mfma_i32_16x16x64_i8 v[104:107], v[144:147], v[208:211], v[104:107]
	v_mfma_i32_16x16x64_i8 v[88:91], v[144:147], v[220:223], v[88:91]
	v_mfma_i32_16x16x64_i8 v[88:91], v[140:143], v[212:215], v[88:91]
	v_mfma_i32_16x16x64_i8 v[84:87], v[156:159], v[212:215], v[84:87]
	v_mfma_i32_16x16x64_i8 v[84:87], v[160:163], v[220:223], v[84:87]
	v_mfma_i32_16x16x64_i8 v[100:103], v[160:163], v[208:211], v[100:103]
	v_mfma_i32_16x16x64_i8 v[100:103], v[156:159], v[204:207], v[100:103]
	v_mfma_i32_16x16x64_i8 v[116:119], v[156:159], v[172:175], v[116:119]
	v_mfma_i32_16x16x64_i8 v[116:119], v[160:163], v[176:179], v[116:119]
	v_mfma_i32_16x16x64_i8 v[132:135], v[160:163], v[168:171], v[132:135]
	v_mfma_i32_16x16x64_i8 v[132:135], v[156:159], v[164:167], v[132:135]
	s_setprio 0
	s_barrier
; #define PG8_STAGE(bufoff, gbase, voff) do { _Pragma("unroll") for (int _i = 0; _i < 2; ++_i) \
;         __builtin_amdgcn_global_load_lds((const unsigned*)((const char*)(gbase) + (voff)[_i]), (PG8_LAS unsigned*)(lds + (bufoff) + ldsw + _i * 8192), 16, 0, 0); } while (0)
; #define PG8_LDA(dst, b, h) do { _Pragma("unroll") for (int m = 0; m < 4; ++m) _Pragma("unroll") for (int k = 0; k < 2; ++k) dst[m][k] = *(const PG8_LAS bf16x8*)(lds + PG8_SA(b, h) + aoff + m * 2048 + k * 1024); } while (0)
; #define PG8_WAIT_V(n) asm volatile("s_waitcnt vmcnt(" #n ")" ::: "memory")
; #define PG8_WAIT_L(n) asm volatile("s_waitcnt lgkmcnt(" #n ")" ::: "memory")
; #define PG8_BAR __builtin_amdgcn_s_barrier()
; #define PG8_SCHED __builtin_amdgcn_sched_barrier(0)
; template <class Epi, class Sched, bool ALIGN_EPI = false, bool SP2 = false, bool I8 = false>
; __device__ __forceinline__ void gemm_phase(PG8_LAS unsigned char* lds, const Gemm g, const Sched& S, const Epi& E) {
;     ...
;             PG8_LDA(At, 1, 1); PG8_STAGE(PG8_SB(1, 0), b3, voffB); PG8_STAGE(PG8_SB(1, 1), b3 + hstep, voffB); PG8_STAGE(PG8_SA(1, 0), a3, voffA);
;             PG8_WAIT_V(8); PG8_WAIT_L(0); PG8_BAR; PG8_MMA(1, 0, At, B0); PG8_MMA(1, 1, At, B1); PG8_BAR; PG8_SCHED;
	s_add_i32 s60, s87, s46
	v_lshl_add_u64 v[190:191], v[190:191], 0, s[84:85]
	s_mov_b32 m0, s60
	ds_read_b128 v[164:167], v219 offset:49152
	ds_read_b128 v[168:171], v219 offset:50176
	ds_read_b128 v[172:175], v219 offset:51200
	ds_read_b128 v[176:179], v219 offset:52224
	ds_read_b128 v[204:207], v219 offset:53248
	ds_read_b128 v[208:211], v219 offset:54272
	ds_read_b128 v[212:215], v219 offset:55296
	ds_read_b128 v[220:223], v219 offset:56320
	global_load_lds_dwordx4 v[190:191], off
	s_add_i32 m0, s60, 0x2000
	s_add_u32 s58, s58, 0x80080
	v_lshl_add_u64 v[190:191], v[224:225], 0, s[84:85]
	s_addc_u32 s59, s59, 0
	s_add_i32 s60, s96, s46
	global_load_lds_dwordx4 v[190:191], off
	v_lshl_add_u64 v[190:191], s[58:59], 0, v[2:3]
	s_mov_b32 m0, s60
	s_nop 0
	global_load_lds_dwordx4 v[190:191], off
	v_lshl_add_u64 v[190:191], s[58:59], 0, v[184:185]
	s_add_i32 m0, s60, 0x2000
	s_nop 0
	global_load_lds_dwordx4 v[190:191], off
	v_lshl_add_u64 v[190:191], v[226:227], 0, s[84:85]
	s_mov_b32 m0, s28
	s_nop 0
	global_load_lds_dwordx4 v[190:191], off
	v_lshl_add_u64 v[190:191], v[228:229], 0, s[84:85]
	s_mov_b32 m0, s77
	s_nop 0
	global_load_lds_dwordx4 v[190:191], off
	s_waitcnt vmcnt(8)
	s_waitcnt lgkmcnt(0)
	s_barrier
	s_setprio 1
	s_waitcnt lgkmcnt(0)
	v_mfma_i32_16x16x64_i8 v[80:83], v[52:55], v[164:167], v[80:83]
	v_mfma_i32_16x16x64_i8 v[80:83], v[56:59], v[168:171], v[80:83]
	v_mfma_i32_16x16x64_i8 v[64:67], v[56:59], v[176:179], v[64:67]
	v_mfma_i32_16x16x64_i8 v[64:67], v[52:55], v[172:175], v[64:67]
	v_mfma_i32_16x16x64_i8 v[48:51], v[52:55], v[204:207], v[48:51]
	v_mfma_i32_16x16x64_i8 v[48:51], v[56:59], v[208:211], v[48:51]
	v_mfma_i32_16x16x64_i8 v[16:19], v[56:59], v[220:223], v[16:19]
	v_mfma_i32_16x16x64_i8 v[16:19], v[52:55], v[212:215], v[16:19]
	v_mfma_i32_16x16x64_i8 v[12:15], v[68:71], v[212:215], v[12:15]
	v_mfma_i32_16x16x64_i8 v[12:15], v[72:75], v[220:223], v[12:15]
	v_mfma_i32_16x16x64_i8 v[44:47], v[72:75], v[208:211], v[44:47]
	v_mfma_i32_16x16x64_i8 v[44:47], v[68:71], v[204:207], v[44:47]
	v_mfma_i32_16x16x64_i8 v[60:63], v[68:71], v[172:175], v[60:63]
	v_mfma_i32_16x16x64_i8 v[60:63], v[72:75], v[176:179], v[60:63]
	v_mfma_i32_16x16x64_i8 v[76:79], v[72:75], v[168:171], v[76:79]
	v_mfma_i32_16x16x64_i8 v[76:79], v[68:71], v[164:167], v[76:79]
	v_mfma_i32_16x16x64_i8 v[28:31], v[140:143], v[164:167], v[28:31]
	v_mfma_i32_16x16x64_i8 v[72:75], v[144:147], v[168:171], v[28:31]
	v_mfma_i32_16x16x64_i8 v[28:31], v[144:147], v[176:179], v[36:39]
	v_mfma_i32_16x16x64_i8 v[56:59], v[140:143], v[172:175], v[28:31]
	v_mfma_i32_16x16x64_i8 v[24:27], v[140:143], v[204:207], v[24:27]
	v_mfma_i32_16x16x64_i8 v[24:27], v[144:147], v[208:211], v[24:27]
	v_mfma_i32_16x16x64_i8 v[8:11], v[144:147], v[220:223], v[8:11]
	v_mfma_i32_16x16x64_i8 v[8:11], v[140:143], v[212:215], v[8:11]
	v_mfma_i32_16x16x64_i8 v[4:7], v[156:159], v[212:215], v[4:7]
	v_mfma_i32_16x16x64_i8 v[4:7], v[160:163], v[220:223], v[4:7]
	v_mfma_i32_16x16x64_i8 v[20:23], v[160:163], v[208:211], v[20:23]
	v_mfma_i32_16x16x64_i8 v[20:23], v[156:159], v[204:207], v[20:23]
	v_mfma_i32_16x16x64_i8 v[28:31], v[156:159], v[172:175], v[40:43]
	v_mfma_i32_16x16x64_i8 v[52:55], v[160:163], v[176:179], v[28:31]
	v_mfma_i32_16x16x64_i8 v[28:31], v[160:163], v[168:171], v[32:35]
	v_mfma_i32_16x16x64_i8 v[68:71], v[156:159], v[164:167], v[28:31]
	s_setprio 0
	s_barrier
	s_add_i32 s86, s86, 2
	s_add_u32 s54, s54, 0x100
	s_addc_u32 s55, s55, 0
	s_add_u32 s45, s45, 0x100
	s_addc_u32 s49, s49, 0
	s_cmp_gt_u32 s86, 29
	s_cbranch_scc0 .LBB0_1843
